# GEMM K-loops: load segments run at s_setprio 2 (above the partner half's MFMA segment at 1), on top of v22
# baseline (speedup 1.0000x reference)
; #define PG8_STAGE(bufoff, gbase, voff) do { _Pragma("unroll") for (int _i = 0; _i < 2; ++_i) \
;         __builtin_amdgcn_global_load_lds((const unsigned*)((const char*)(gbase) + (voff)[_i]), (PG8_LAS unsigned*)(lds + (bufoff) + ldsw + _i * 8192), 16, 0, 0); } while (0)
; #define PG8_LDA(dst, b, h) do { _Pragma("unroll") for (int m = 0; m < 4; ++m) _Pragma("unroll") for (int k = 0; k < 2; ++k) dst[m][k] = *(const PG8_LAS bf16x8*)(lds + PG8_SA(b, h) + aoff + m * 2048 + k * 1024); } while (0)
; #define PG8_LDB(dst, b, h) do { _Pragma("unroll") for (int n = 0; n < 2; ++n) _Pragma("unroll") for (int k = 0; k < 2; ++k) dst[n][k] = *(const PG8_LAS bf16x8*)(lds + PG8_SB(b, h) + boff + n * 2048 + k * 1024); } while (0)
; #define PG8_MMA(ai, bj, At, Bt) do { __builtin_amdgcn_s_setprio(1); _Pragma("unroll") for (int m = 0; m < 4; ++m) _Pragma("unroll") for (int n = 0; n < 2; ++n) _Pragma("unroll") for (int k = 0; k < 2; ++k) \
;         acc[ai][bj][m][n] = __builtin_amdgcn_mfma_f32_16x16x32_bf16(Bt[n][k], At[m][k], acc[ai][bj][m][n], 0, 0, 0); __builtin_amdgcn_s_setprio(0); } while (0)
; #define PG8_WAIT_V(n) asm volatile("s_waitcnt vmcnt(" #n ")" ::: "memory")
; #define PG8_WAIT_L(n) asm volatile("s_waitcnt lgkmcnt(" #n ")" ::: "memory")
; #define PG8_BAR __builtin_amdgcn_s_barrier()
; #define PG8_SCHED __builtin_amdgcn_sched_barrier(0)
; template <class Epi, class Sched, bool ALIGN_EPI = false, bool SP2 = false>
; __device__ __forceinline__ void gemm_phase(PG8_LAS unsigned char* lds, const Gemm g, const Sched& S, const Epi& E, const int tid_in) {
;     ...
;             PG8_LDB(B0, 0, 0); PG8_LDB(B1, 0, 1); PG8_SCHED; PG8_LDA(At, 0, 0); PG8_STAGE(PG8_SA(1, 1), a1 + hstepA, voffA);
;             PG8_WAIT_V(8); PG8_WAIT_L(0); PG8_BAR; PG8_MMA(0, 0, At, B0); PG8_MMA(0, 1, At, B1); PG8_BAR; PG8_SCHED;
;             PG8_LDA(At, 0, 1); PG8_STAGE(PG8_SB(0, 0), b2, voffB); PG8_STAGE(PG8_SB(0, 1), b2 + hstep, voffB); PG8_STAGE(PG8_SA(0, 0), a2, voffA);
.LBB0_320:
	s_add_u32 s58, s36, 0xfffc0080
	s_addc_u32 s59, s37, -1
	s_and_b64 s[38:39], s[38:39], exec
	s_cselect_b32 s59, s3, s59
	s_cselect_b32 s58, s12, s58
	s_cselect_b32 s39, s14, s53
	s_cselect_b32 s38, s15, s52
	s_add_i32 s64, 0, 0x10000
	v_add_u32_e32 v140, s64, v143
	s_add_i32 s77, 0, 0x14000
	ds_read_b128 v[144:147], v140
	ds_read_b128 v[150:153], v140 offset:1024
	ds_read_b128 v[154:157], v140 offset:2048
	ds_read_b128 v[158:161], v140 offset:3072
	v_add_u32_e32 v140, s77, v143
	ds_read_b128 v[162:165], v140
	ds_read_b128 v[166:169], v140 offset:1024
	ds_read_b128 v[170:173], v140 offset:2048
	ds_read_b128 v[174:177], v140 offset:3072
	v_lshl_add_u64 v[140:141], s[36:37], 0, v[136:137]
	s_add_i32 m0, s17, 0xc000
	ds_read_b128 v[178:181], v148
	ds_read_b128 v[194:197], v148 offset:1024
	ds_read_b128 v[198:201], v148 offset:2048
	ds_read_b128 v[202:205], v148 offset:3072
	ds_read_b128 v[206:209], v148 offset:4096
	ds_read_b128 v[210:213], v148 offset:5120
	ds_read_b128 v[214:217], v148 offset:6144
	ds_read_b128 v[218:221], v148 offset:7168
	global_load_lds_dwordx4 v[140:141], off
	v_lshl_add_u64 v[140:141], s[36:37], 0, v[138:139]
	s_add_i32 m0, s17, 0xe000
	s_nop 0
	global_load_lds_dwordx4 v[140:141], off
	s_waitcnt vmcnt(8)
	s_waitcnt lgkmcnt(0)
	s_barrier
	s_setprio 1
	s_waitcnt lgkmcnt(0)
	v_mfma_f32_16x16x32_bf16 v[124:127], v[144:147], v[178:181], v[124:127]
	v_mfma_f32_16x16x32_bf16 v[120:123], v[154:157], v[178:181], v[120:123]
	v_mfma_f32_16x16x32_bf16 v[108:111], v[144:147], v[198:201], v[108:111]
	v_mfma_f32_16x16x32_bf16 v[104:107], v[154:157], v[198:201], v[104:107]
	v_mfma_f32_16x16x32_bf16 v[92:95], v[144:147], v[206:209], v[92:95]
	v_mfma_f32_16x16x32_bf16 v[88:91], v[154:157], v[206:209], v[88:91]
	v_mfma_f32_16x16x32_bf16 v[76:79], v[144:147], v[214:217], v[76:79]
	v_mfma_f32_16x16x32_bf16 v[72:75], v[154:157], v[214:217], v[72:75]
	v_mfma_f32_16x16x32_bf16 v[124:127], v[150:153], v[194:197], v[124:127]
	v_mfma_f32_16x16x32_bf16 v[120:123], v[158:161], v[194:197], v[120:123]
	v_mfma_f32_16x16x32_bf16 v[108:111], v[150:153], v[202:205], v[108:111]
	v_mfma_f32_16x16x32_bf16 v[104:107], v[158:161], v[202:205], v[104:107]
	v_mfma_f32_16x16x32_bf16 v[92:95], v[150:153], v[210:213], v[92:95]
	v_mfma_f32_16x16x32_bf16 v[88:91], v[158:161], v[210:213], v[88:91]
	v_mfma_f32_16x16x32_bf16 v[76:79], v[150:153], v[218:221], v[76:79]
	v_mfma_f32_16x16x32_bf16 v[72:75], v[158:161], v[218:221], v[72:75]
	s_setprio 0
	s_setprio 1
	v_mfma_f32_16x16x32_bf16 v[116:119], v[162:165], v[178:181], v[116:119]
	v_mfma_f32_16x16x32_bf16 v[112:115], v[170:173], v[178:181], v[112:115]
	v_mfma_f32_16x16x32_bf16 v[100:103], v[162:165], v[198:201], v[100:103]
	v_mfma_f32_16x16x32_bf16 v[96:99], v[170:173], v[198:201], v[96:99]
	v_mfma_f32_16x16x32_bf16 v[84:87], v[162:165], v[206:209], v[84:87]
	v_mfma_f32_16x16x32_bf16 v[80:83], v[170:173], v[206:209], v[80:83]
	v_mfma_f32_16x16x32_bf16 v[68:71], v[162:165], v[214:217], v[68:71]
	v_mfma_f32_16x16x32_bf16 v[64:67], v[170:173], v[214:217], v[64:67]
	v_mfma_f32_16x16x32_bf16 v[116:119], v[166:169], v[194:197], v[116:119]
	v_mfma_f32_16x16x32_bf16 v[112:115], v[174:177], v[194:197], v[112:115]
	v_mfma_f32_16x16x32_bf16 v[100:103], v[166:169], v[202:205], v[100:103]
	v_mfma_f32_16x16x32_bf16 v[96:99], v[174:177], v[202:205], v[96:99]
	v_mfma_f32_16x16x32_bf16 v[84:87], v[166:169], v[210:213], v[84:87]
	v_mfma_f32_16x16x32_bf16 v[80:83], v[174:177], v[210:213], v[80:83]
	v_mfma_f32_16x16x32_bf16 v[68:71], v[166:169], v[218:221], v[68:71]
	v_mfma_f32_16x16x32_bf16 v[64:67], v[174:177], v[218:221], v[64:67]
	s_setprio 2
	s_barrier
	s_add_i32 s64, s64, s16
	v_lshl_add_u64 v[140:141], s[38:39], 0, v[130:131]
	s_mov_b32 m0, s64
	ds_read_b128 v[178:181], v148 offset:16384
	ds_read_b128 v[194:197], v148 offset:17408
	ds_read_b128 v[198:201], v148 offset:18432
	ds_read_b128 v[202:205], v148 offset:19456
	ds_read_b128 v[206:209], v148 offset:20480
	ds_read_b128 v[210:213], v148 offset:21504
	ds_read_b128 v[214:217], v148 offset:22528
	ds_read_b128 v[218:221], v148 offset:23552
	global_load_lds_dwordx4 v[140:141], off
	s_add_i32 m0, s64, 0x2000
	s_add_u32 s64, s38, 0x40000
	v_lshl_add_u64 v[182:183], s[38:39], 0, v[134:135]
	s_addc_u32 s65, s39, 0
	s_add_i32 s77, s77, s16
	global_load_lds_dwordx4 v[182:183], off
	v_lshl_add_u64 v[186:187], s[64:65], 0, v[130:131]
	s_mov_b32 m0, s77
	v_lshl_add_u64 v[188:189], s[58:59], 0, v[132:133]
	global_load_lds_dwordx4 v[186:187], off
	v_lshl_add_u64 v[186:187], s[64:65], 0, v[134:135]
	s_add_i32 m0, s77, 0x2000
	s_nop 0
	global_load_lds_dwordx4 v[186:187], off
	v_lshl_add_u64 v[186:187], s[58:59], 0, v[128:129]
	s_mov_b32 m0, s17
	s_nop 0
	global_load_lds_dwordx4 v[186:187], off
	s_mov_b32 m0, s54
	s_nop 0
	global_load_lds_dwordx4 v[188:189], off
	s_waitcnt vmcnt(8)
	s_waitcnt lgkmcnt(0)
	s_barrier
; #define PG8_STAGE(bufoff, gbase, voff) do { _Pragma("unroll") for (int _i = 0; _i < 2; ++_i) \
;         __builtin_amdgcn_global_load_lds((const unsigned*)((const char*)(gbase) + (voff)[_i]), (PG8_LAS unsigned*)(lds + (bufoff) + ldsw + _i * 8192), 16, 0, 0); } while (0)
; #define PG8_LDA(dst, b, h) do { _Pragma("unroll") for (int m = 0; m < 4; ++m) _Pragma("unroll") for (int k = 0; k < 2; ++k) dst[m][k] = *(const PG8_LAS bf16x8*)(lds + PG8_SA(b, h) + aoff + m * 2048 + k * 1024); } while (0)
; #define PG8_LDB(dst, b, h) do { _Pragma("unroll") for (int n = 0; n < 2; ++n) _Pragma("unroll") for (int k = 0; k < 2; ++k) dst[n][k] = *(const PG8_LAS bf16x8*)(lds + PG8_SB(b, h) + boff + n * 2048 + k * 1024); } while (0)
; #define PG8_MMA(ai, bj, At, Bt) do { __builtin_amdgcn_s_setprio(1); _Pragma("unroll") for (int m = 0; m < 4; ++m) _Pragma("unroll") for (int n = 0; n < 2; ++n) _Pragma("unroll") for (int k = 0; k < 2; ++k) \
;         acc[ai][bj][m][n] = __builtin_amdgcn_mfma_f32_16x16x32_bf16(Bt[n][k], At[m][k], acc[ai][bj][m][n], 0, 0, 0); __builtin_amdgcn_s_setprio(0); } while (0)
; #define PG8_WAIT_V(n) asm volatile("s_waitcnt vmcnt(" #n ")" ::: "memory")
; #define PG8_WAIT_L(n) asm volatile("s_waitcnt lgkmcnt(" #n ")" ::: "memory")
; #define PG8_BAR __builtin_amdgcn_s_barrier()
; #define PG8_SCHED __builtin_amdgcn_sched_barrier(0)
; template <class Epi, class Sched, bool ALIGN_EPI = false, bool SP2 = false>
; __device__ __forceinline__ void gemm_phase(PG8_LAS unsigned char* lds, const Gemm g, const Sched& S, const Epi& E, const int tid_in) {
;     ...
;             PG8_WAIT_V(8); PG8_WAIT_L(0); PG8_BAR; PG8_MMA(1, 0, At, B0); PG8_MMA(1, 1, At, B1); PG8_BAR; PG8_SCHED;
;             PG8_LDB(B0, 1, 0); PG8_LDB(B1, 1, 1); PG8_SCHED; PG8_LDA(At, 1, 0); PG8_STAGE(PG8_SA(0, 1), a2 + hstepA, voffA);
;             PG8_WAIT_V(8); PG8_WAIT_L(0); PG8_BAR; PG8_MMA(0, 0, At, B0); PG8_MMA(0, 1, At, B1); PG8_BAR; PG8_SCHED;
	s_setprio 1
	s_waitcnt lgkmcnt(0)
	v_mfma_f32_16x16x32_bf16 v[60:63], v[144:147], v[178:181], v[60:63]
	v_mfma_f32_16x16x32_bf16 v[56:59], v[154:157], v[178:181], v[56:59]
	v_mfma_f32_16x16x32_bf16 v[44:47], v[144:147], v[198:201], v[44:47]
	v_mfma_f32_16x16x32_bf16 v[40:43], v[154:157], v[198:201], v[40:43]
	v_mfma_f32_16x16x32_bf16 v[28:31], v[144:147], v[206:209], v[28:31]
	v_mfma_f32_16x16x32_bf16 v[24:27], v[154:157], v[206:209], v[24:27]
	v_mfma_f32_16x16x32_bf16 v[12:15], v[144:147], v[214:217], v[12:15]
	v_mfma_f32_16x16x32_bf16 v[8:11], v[154:157], v[214:217], v[8:11]
	v_mfma_f32_16x16x32_bf16 v[60:63], v[150:153], v[194:197], v[60:63]
	v_mfma_f32_16x16x32_bf16 v[56:59], v[158:161], v[194:197], v[56:59]
	v_mfma_f32_16x16x32_bf16 v[44:47], v[150:153], v[202:205], v[44:47]
	v_mfma_f32_16x16x32_bf16 v[40:43], v[158:161], v[202:205], v[40:43]
	v_mfma_f32_16x16x32_bf16 v[28:31], v[150:153], v[210:213], v[28:31]
	v_mfma_f32_16x16x32_bf16 v[24:27], v[158:161], v[210:213], v[24:27]
	v_mfma_f32_16x16x32_bf16 v[12:15], v[150:153], v[218:221], v[12:15]
	v_mfma_f32_16x16x32_bf16 v[8:11], v[158:161], v[218:221], v[8:11]
	s_setprio 0
	s_setprio 1
	v_mfma_f32_16x16x32_bf16 v[52:55], v[162:165], v[178:181], v[52:55]
	v_mfma_f32_16x16x32_bf16 v[48:51], v[170:173], v[178:181], v[48:51]
	v_mfma_f32_16x16x32_bf16 v[36:39], v[162:165], v[198:201], v[36:39]
	v_mfma_f32_16x16x32_bf16 v[32:35], v[170:173], v[198:201], v[32:35]
	v_mfma_f32_16x16x32_bf16 v[20:23], v[162:165], v[206:209], v[20:23]
	v_mfma_f32_16x16x32_bf16 v[16:19], v[170:173], v[206:209], v[16:19]
	v_mfma_f32_16x16x32_bf16 v[4:7], v[162:165], v[214:217], v[4:7]
	v_mfma_f32_16x16x32_bf16 v[0:3], v[170:173], v[214:217], v[0:3]
	v_mfma_f32_16x16x32_bf16 v[52:55], v[166:169], v[194:197], v[52:55]
	v_mfma_f32_16x16x32_bf16 v[48:51], v[174:177], v[194:197], v[48:51]
	v_mfma_f32_16x16x32_bf16 v[36:39], v[166:169], v[202:205], v[36:39]
	v_mfma_f32_16x16x32_bf16 v[32:35], v[174:177], v[202:205], v[32:35]
	v_mfma_f32_16x16x32_bf16 v[20:23], v[166:169], v[210:213], v[20:23]
	v_mfma_f32_16x16x32_bf16 v[16:19], v[174:177], v[210:213], v[16:19]
	v_mfma_f32_16x16x32_bf16 v[4:7], v[166:169], v[218:221], v[4:7]
	v_mfma_f32_16x16x32_bf16 v[0:3], v[174:177], v[218:221], v[0:3]
	s_setprio 2
	s_barrier
	s_add_i32 s64, 0, 0x18000
	v_add_u32_e32 v142, s64, v143
	s_add_i32 s65, 0, 0x1c000
	ds_read_b128 v[144:147], v142
	ds_read_b128 v[150:153], v142 offset:1024
	ds_read_b128 v[154:157], v142 offset:2048
	ds_read_b128 v[158:161], v142 offset:3072
	v_add_u32_e32 v142, s65, v143
	ds_read_b128 v[162:165], v142
	ds_read_b128 v[166:169], v142 offset:1024
	ds_read_b128 v[170:173], v142 offset:2048
	ds_read_b128 v[174:177], v142 offset:3072
	s_add_u32 s58, s58, 0x40000
	s_addc_u32 s59, s59, 0
	s_mov_b32 m0, s66
	v_lshl_add_u64 v[190:191], s[58:59], 0, v[128:129]
	ds_read_b128 v[178:181], v148 offset:32768
	ds_read_b128 v[194:197], v148 offset:33792
	ds_read_b128 v[198:201], v148 offset:34816
	ds_read_b128 v[202:205], v148 offset:35840
	ds_read_b128 v[206:209], v148 offset:36864
	ds_read_b128 v[210:213], v148 offset:37888
	ds_read_b128 v[214:217], v148 offset:38912
	ds_read_b128 v[218:221], v148 offset:39936
	global_load_lds_dwordx4 v[190:191], off
	v_lshl_add_u64 v[190:191], s[58:59], 0, v[132:133]
	s_mov_b32 m0, s67
	s_nop 0
	global_load_lds_dwordx4 v[190:191], off
	s_waitcnt vmcnt(8)
	s_waitcnt lgkmcnt(0)
	s_barrier
	s_setprio 1
	s_waitcnt lgkmcnt(0)
	v_mfma_f32_16x16x32_bf16 v[124:127], v[144:147], v[178:181], v[124:127]
	v_mfma_f32_16x16x32_bf16 v[120:123], v[154:157], v[178:181], v[120:123]
	v_mfma_f32_16x16x32_bf16 v[108:111], v[144:147], v[198:201], v[108:111]
	v_mfma_f32_16x16x32_bf16 v[104:107], v[154:157], v[198:201], v[104:107]
	v_mfma_f32_16x16x32_bf16 v[92:95], v[144:147], v[206:209], v[92:95]
	v_mfma_f32_16x16x32_bf16 v[88:91], v[154:157], v[206:209], v[88:91]
	v_mfma_f32_16x16x32_bf16 v[76:79], v[144:147], v[214:217], v[76:79]
	v_mfma_f32_16x16x32_bf16 v[72:75], v[154:157], v[214:217], v[72:75]
	v_mfma_f32_16x16x32_bf16 v[124:127], v[150:153], v[194:197], v[124:127]
	v_mfma_f32_16x16x32_bf16 v[120:123], v[158:161], v[194:197], v[120:123]
	v_mfma_f32_16x16x32_bf16 v[108:111], v[150:153], v[202:205], v[108:111]
	v_mfma_f32_16x16x32_bf16 v[104:107], v[158:161], v[202:205], v[104:107]
	v_mfma_f32_16x16x32_bf16 v[92:95], v[150:153], v[210:213], v[92:95]
	v_mfma_f32_16x16x32_bf16 v[88:91], v[158:161], v[210:213], v[88:91]
	v_mfma_f32_16x16x32_bf16 v[76:79], v[150:153], v[218:221], v[76:79]
	v_mfma_f32_16x16x32_bf16 v[72:75], v[158:161], v[218:221], v[72:75]
	s_setprio 0
	s_setprio 1
	v_mfma_f32_16x16x32_bf16 v[116:119], v[162:165], v[178:181], v[116:119]
	v_mfma_f32_16x16x32_bf16 v[112:115], v[170:173], v[178:181], v[112:115]
	v_mfma_f32_16x16x32_bf16 v[100:103], v[162:165], v[198:201], v[100:103]
	v_mfma_f32_16x16x32_bf16 v[96:99], v[170:173], v[198:201], v[96:99]
	v_mfma_f32_16x16x32_bf16 v[84:87], v[162:165], v[206:209], v[84:87]
	v_mfma_f32_16x16x32_bf16 v[80:83], v[170:173], v[206:209], v[80:83]
	v_mfma_f32_16x16x32_bf16 v[68:71], v[162:165], v[214:217], v[68:71]
	v_mfma_f32_16x16x32_bf16 v[64:67], v[170:173], v[214:217], v[64:67]
	v_mfma_f32_16x16x32_bf16 v[116:119], v[166:169], v[194:197], v[116:119]
	v_mfma_f32_16x16x32_bf16 v[112:115], v[174:177], v[194:197], v[112:115]
	v_mfma_f32_16x16x32_bf16 v[100:103], v[166:169], v[202:205], v[100:103]
	v_mfma_f32_16x16x32_bf16 v[96:99], v[174:177], v[202:205], v[96:99]
	v_mfma_f32_16x16x32_bf16 v[84:87], v[166:169], v[210:213], v[84:87]
	v_mfma_f32_16x16x32_bf16 v[80:83], v[174:177], v[210:213], v[80:83]
	v_mfma_f32_16x16x32_bf16 v[68:71], v[166:169], v[218:221], v[68:71]
	v_mfma_f32_16x16x32_bf16 v[64:67], v[174:177], v[218:221], v[64:67]
	s_setprio 2
	s_barrier
; #define PG8_STAGE(bufoff, gbase, voff) do { _Pragma("unroll") for (int _i = 0; _i < 2; ++_i) \
;         __builtin_amdgcn_global_load_lds((const unsigned*)((const char*)(gbase) + (voff)[_i]), (PG8_LAS unsigned*)(lds + (bufoff) + ldsw + _i * 8192), 16, 0, 0); } while (0)
; #define PG8_LDA(dst, b, h) do { _Pragma("unroll") for (int m = 0; m < 4; ++m) _Pragma("unroll") for (int k = 0; k < 2; ++k) dst[m][k] = *(const PG8_LAS bf16x8*)(lds + PG8_SA(b, h) + aoff + m * 2048 + k * 1024); } while (0)
; #define PG8_MMA(ai, bj, At, Bt) do { __builtin_amdgcn_s_setprio(1); _Pragma("unroll") for (int m = 0; m < 4; ++m) _Pragma("unroll") for (int n = 0; n < 2; ++n) _Pragma("unroll") for (int k = 0; k < 2; ++k) \
;         acc[ai][bj][m][n] = __builtin_amdgcn_mfma_f32_16x16x32_bf16(Bt[n][k], At[m][k], acc[ai][bj][m][n], 0, 0, 0); __builtin_amdgcn_s_setprio(0); } while (0)
; #define PG8_WAIT_V(n) asm volatile("s_waitcnt vmcnt(" #n ")" ::: "memory")
; #define PG8_WAIT_L(n) asm volatile("s_waitcnt lgkmcnt(" #n ")" ::: "memory")
; #define PG8_BAR __builtin_amdgcn_s_barrier()
; #define PG8_SCHED __builtin_amdgcn_sched_barrier(0)
; template <class Epi, class Sched, bool ALIGN_EPI = false, bool SP2 = false>
; __device__ __forceinline__ void gemm_phase(PG8_LAS unsigned char* lds, const Gemm g, const Sched& S, const Epi& E, const int tid_in) {
;     ...
;             PG8_LDA(At, 1, 1); PG8_STAGE(PG8_SB(1, 0), b3, voffB); PG8_STAGE(PG8_SB(1, 1), b3 + hstep, voffB); PG8_STAGE(PG8_SA(1, 0), a3, voffA);
;             PG8_WAIT_V(8); PG8_WAIT_L(0); PG8_BAR; PG8_MMA(1, 0, At, B0); PG8_MMA(1, 1, At, B1); PG8_BAR; PG8_SCHED;
	s_add_i32 s58, s64, s16
	v_lshl_add_u64 v[140:141], v[140:141], 0, s[84:85]
	s_mov_b32 m0, s58
	ds_read_b128 v[178:181], v148 offset:49152
	ds_read_b128 v[194:197], v148 offset:50176
	ds_read_b128 v[198:201], v148 offset:51200
	ds_read_b128 v[202:205], v148 offset:52224
	ds_read_b128 v[206:209], v148 offset:53248
	ds_read_b128 v[210:213], v148 offset:54272
	ds_read_b128 v[214:217], v148 offset:55296
	ds_read_b128 v[218:221], v148 offset:56320
	global_load_lds_dwordx4 v[140:141], off
	s_add_i32 m0, s58, 0x2000
	s_add_u32 s38, s38, 0x40080
	v_lshl_add_u64 v[140:141], v[182:183], 0, s[84:85]
	s_addc_u32 s39, s39, 0
	s_add_i32 s58, s65, s16
	global_load_lds_dwordx4 v[140:141], off
	v_lshl_add_u64 v[140:141], s[38:39], 0, v[130:131]
	s_mov_b32 m0, s58
	s_nop 0
	global_load_lds_dwordx4 v[140:141], off
	v_lshl_add_u64 v[140:141], s[38:39], 0, v[134:135]
	s_add_i32 m0, s58, 0x2000
	s_nop 0
	global_load_lds_dwordx4 v[140:141], off
	v_lshl_add_u64 v[140:141], v[186:187], 0, s[84:85]
	s_mov_b32 m0, s70
	s_nop 0
	global_load_lds_dwordx4 v[140:141], off
	v_lshl_add_u64 v[140:141], v[188:189], 0, s[84:85]
	s_mov_b32 m0, s71
	s_nop 0
	global_load_lds_dwordx4 v[140:141], off
	s_waitcnt vmcnt(8)
	s_waitcnt lgkmcnt(0)
	s_barrier
	s_setprio 1
	s_waitcnt lgkmcnt(0)
	v_mfma_f32_16x16x32_bf16 v[60:63], v[144:147], v[178:181], v[60:63]
	v_mfma_f32_16x16x32_bf16 v[56:59], v[154:157], v[178:181], v[56:59]
	v_mfma_f32_16x16x32_bf16 v[44:47], v[144:147], v[198:201], v[44:47]
	v_mfma_f32_16x16x32_bf16 v[40:43], v[154:157], v[198:201], v[40:43]
	v_mfma_f32_16x16x32_bf16 v[28:31], v[144:147], v[206:209], v[28:31]
	v_mfma_f32_16x16x32_bf16 v[24:27], v[154:157], v[206:209], v[24:27]
	v_mfma_f32_16x16x32_bf16 v[12:15], v[144:147], v[214:217], v[12:15]
	v_mfma_f32_16x16x32_bf16 v[8:11], v[154:157], v[214:217], v[8:11]
	v_mfma_f32_16x16x32_bf16 v[60:63], v[150:153], v[194:197], v[60:63]
	v_mfma_f32_16x16x32_bf16 v[56:59], v[158:161], v[194:197], v[56:59]
	v_mfma_f32_16x16x32_bf16 v[44:47], v[150:153], v[202:205], v[44:47]
	v_mfma_f32_16x16x32_bf16 v[40:43], v[158:161], v[202:205], v[40:43]
	v_mfma_f32_16x16x32_bf16 v[28:31], v[150:153], v[210:213], v[28:31]
	v_mfma_f32_16x16x32_bf16 v[24:27], v[158:161], v[210:213], v[24:27]
	v_mfma_f32_16x16x32_bf16 v[12:15], v[150:153], v[218:221], v[12:15]
	v_mfma_f32_16x16x32_bf16 v[8:11], v[158:161], v[218:221], v[8:11]
	s_setprio 0
	s_setprio 1
	v_mfma_f32_16x16x32_bf16 v[52:55], v[162:165], v[178:181], v[52:55]
	v_mfma_f32_16x16x32_bf16 v[48:51], v[170:173], v[178:181], v[48:51]
	v_mfma_f32_16x16x32_bf16 v[36:39], v[162:165], v[198:201], v[36:39]
	v_mfma_f32_16x16x32_bf16 v[32:35], v[170:173], v[198:201], v[32:35]
	v_mfma_f32_16x16x32_bf16 v[20:23], v[162:165], v[206:209], v[20:23]
	v_mfma_f32_16x16x32_bf16 v[16:19], v[170:173], v[206:209], v[16:19]
	v_mfma_f32_16x16x32_bf16 v[4:7], v[162:165], v[214:217], v[4:7]
	v_mfma_f32_16x16x32_bf16 v[0:3], v[170:173], v[214:217], v[0:3]
	v_mfma_f32_16x16x32_bf16 v[52:55], v[166:169], v[194:197], v[52:55]
	v_mfma_f32_16x16x32_bf16 v[48:51], v[174:177], v[194:197], v[48:51]
	v_mfma_f32_16x16x32_bf16 v[36:39], v[166:169], v[202:205], v[36:39]
	v_mfma_f32_16x16x32_bf16 v[32:35], v[174:177], v[202:205], v[32:35]
	v_mfma_f32_16x16x32_bf16 v[20:23], v[166:169], v[210:213], v[20:23]
	v_mfma_f32_16x16x32_bf16 v[16:19], v[174:177], v[210:213], v[16:19]
	v_mfma_f32_16x16x32_bf16 v[4:7], v[166:169], v[218:221], v[4:7]
	v_mfma_f32_16x16x32_bf16 v[0:3], v[174:177], v[218:221], v[0:3]
	s_setprio 2
	s_barrier
	s_add_i32 s63, s63, 2
	s_add_u32 s36, s36, 0x100
	s_addc_u32 s37, s37, 0
	s_add_u32 s52, s52, 0x100
	s_addc_u32 s53, s53, 0
	s_cmp_gt_u32 s63, 13
	s_cbranch_scc1 .LBB0_324

; #define PG8_STAGE(bufoff, gbase, voff) do { _Pragma("unroll") for (int _i = 0; _i < 2; ++_i) \
;         __builtin_amdgcn_global_load_lds((const unsigned*)((const char*)(gbase) + (voff)[_i]), (PG8_LAS unsigned*)(lds + (bufoff) + ldsw + _i * 8192), 16, 0, 0); } while (0)
; #define PG8_LDA(dst, b, h) do { _Pragma("unroll") for (int m = 0; m < 4; ++m) _Pragma("unroll") for (int k = 0; k < 2; ++k) dst[m][k] = *(const PG8_LAS bf16x8*)(lds + PG8_SA(b, h) + aoff + m * 2048 + k * 1024); } while (0)
; #define PG8_LDB(dst, b, h) do { _Pragma("unroll") for (int n = 0; n < 2; ++n) _Pragma("unroll") for (int k = 0; k < 2; ++k) dst[n][k] = *(const PG8_LAS bf16x8*)(lds + PG8_SB(b, h) + boff + n * 2048 + k * 1024); } while (0)
; #define PG8_MMA(ai, bj, At, Bt) do { __builtin_amdgcn_s_setprio(1); _Pragma("unroll") for (int m = 0; m < 4; ++m) _Pragma("unroll") for (int n = 0; n < 2; ++n) _Pragma("unroll") for (int k = 0; k < 2; ++k) \
;         acc[ai][bj][m][n] = __builtin_amdgcn_mfma_f32_16x16x32_bf16(Bt[n][k], At[m][k], acc[ai][bj][m][n], 0, 0, 0); __builtin_amdgcn_s_setprio(0); } while (0)
; #define PG8_WAIT_V(n) asm volatile("s_waitcnt vmcnt(" #n ")" ::: "memory")
; #define PG8_WAIT_L(n) asm volatile("s_waitcnt lgkmcnt(" #n ")" ::: "memory")
; #define PG8_BAR __builtin_amdgcn_s_barrier()
; #define PG8_SCHED __builtin_amdgcn_sched_barrier(0)
; template <class Epi, class Sched, bool ALIGN_EPI = false, bool SP2 = false>
; __device__ __forceinline__ void gemm_phase(PG8_LAS unsigned char* lds, const Gemm g, const Sched& S, const Epi& E, const int tid_in) {
;     ...
;             PG8_LDB(B0, 0, 0); PG8_LDB(B1, 0, 1); PG8_SCHED; PG8_LDA(At, 0, 0); PG8_STAGE(PG8_SA(1, 1), a1 + hstepA, voffA);
;             PG8_WAIT_V(8); PG8_WAIT_L(0); PG8_BAR; PG8_MMA(0, 0, At, B0); PG8_MMA(0, 1, At, B1); PG8_BAR; PG8_SCHED;
;             PG8_LDA(At, 0, 1); PG8_STAGE(PG8_SB(0, 0), b2, voffB); PG8_STAGE(PG8_SB(0, 1), b2 + hstep, voffB); PG8_STAGE(PG8_SA(0, 0), a2, voffA);
;             PG8_WAIT_V(8); PG8_WAIT_L(0); PG8_BAR; PG8_MMA(1, 0, At, B0); PG8_MMA(1, 1, At, B1); PG8_BAR; PG8_SCHED;
.LBB0_559:
	s_add_i32 s52, 0, 0x10000
	s_add_i32 s36, 0, 0x14000
	v_add_u32_e32 v8, s52, v141
	v_add_u32_e32 v9, s36, v141
	ds_read_b128 v[10:13], v8
	ds_read_b128 v[14:17], v8 offset:1024
	ds_read_b128 v[18:21], v8 offset:2048
	ds_read_b128 v[22:25], v8 offset:3072
	ds_read_b128 v[26:29], v9
	ds_read_b128 v[30:33], v9 offset:1024
	ds_read_b128 v[34:37], v9 offset:2048
	ds_read_b128 v[38:41], v9 offset:3072
	s_add_u32 s14, s56, 0x18080
	s_addc_u32 s15, s57, 0
	s_add_i32 s70, s59, 0xc000
	v_lshl_add_u64 v[66:67], s[14:15], 0, v[132:133]
	s_mov_b32 m0, s70
	ds_read_b128 v[0:3], v145
	ds_read_b128 v[4:7], v145 offset:1024
	ds_read_b128 v[42:45], v145 offset:2048
	ds_read_b128 v[46:49], v145 offset:3072
	ds_read_b128 v[50:53], v145 offset:4096
	ds_read_b128 v[54:57], v145 offset:5120
	ds_read_b128 v[58:61], v145 offset:6144
	ds_read_b128 v[62:65], v145 offset:7168
	global_load_lds_dwordx4 v[66:67], off
	v_lshl_add_u64 v[66:67], s[14:15], 0, v[130:131]
	s_add_i32 s14, s59, 0xe000
	s_mov_b32 m0, s14
	s_nop 0
	global_load_lds_dwordx4 v[66:67], off
	s_waitcnt vmcnt(8)
	s_waitcnt lgkmcnt(0)
	s_barrier
	s_setprio 1
	s_waitcnt lgkmcnt(0)
	v_mfma_f32_16x16x32_bf16 v[66:69], v[10:13], v[0:3], 0
	v_mfma_f32_16x16x32_bf16 v[70:73], v[18:21], v[0:3], 0
	v_mfma_f32_16x16x32_bf16 v[74:77], v[10:13], v[42:45], 0
	v_mfma_f32_16x16x32_bf16 v[78:81], v[18:21], v[42:45], 0
	v_mfma_f32_16x16x32_bf16 v[82:85], v[10:13], v[50:53], 0
	v_mfma_f32_16x16x32_bf16 v[86:89], v[18:21], v[50:53], 0
	v_mfma_f32_16x16x32_bf16 v[90:93], v[10:13], v[58:61], 0
	v_mfma_f32_16x16x32_bf16 v[94:97], v[18:21], v[58:61], 0
	v_mfma_f32_16x16x32_bf16 v[66:69], v[14:17], v[4:7], v[66:69]
	v_mfma_f32_16x16x32_bf16 v[70:73], v[22:25], v[4:7], v[70:73]
	v_mfma_f32_16x16x32_bf16 v[74:77], v[14:17], v[46:49], v[74:77]
	v_mfma_f32_16x16x32_bf16 v[78:81], v[22:25], v[46:49], v[78:81]
	v_mfma_f32_16x16x32_bf16 v[82:85], v[14:17], v[54:57], v[82:85]
	v_mfma_f32_16x16x32_bf16 v[86:89], v[22:25], v[54:57], v[86:89]
	v_mfma_f32_16x16x32_bf16 v[90:93], v[14:17], v[62:65], v[90:93]
	v_mfma_f32_16x16x32_bf16 v[94:97], v[22:25], v[62:65], v[94:97]
	s_setprio 0
	s_setprio 1
	v_mfma_f32_16x16x32_bf16 v[98:101], v[26:29], v[0:3], 0
	v_mfma_f32_16x16x32_bf16 v[0:3], v[34:37], v[0:3], 0
	v_mfma_f32_16x16x32_bf16 v[102:105], v[38:41], v[4:7], v[0:3]
	v_mfma_f32_16x16x32_bf16 v[0:3], v[26:29], v[42:45], 0
	v_mfma_f32_16x16x32_bf16 v[106:109], v[30:33], v[46:49], v[0:3]
	v_mfma_f32_16x16x32_bf16 v[0:3], v[34:37], v[42:45], 0
	v_mfma_f32_16x16x32_bf16 v[42:45], v[38:41], v[46:49], v[0:3]
	v_mfma_f32_16x16x32_bf16 v[0:3], v[26:29], v[50:53], 0
	v_mfma_f32_16x16x32_bf16 v[46:49], v[30:33], v[54:57], v[0:3]
	v_mfma_f32_16x16x32_bf16 v[0:3], v[34:37], v[50:53], 0
	v_mfma_f32_16x16x32_bf16 v[50:53], v[38:41], v[54:57], v[0:3]
	v_mfma_f32_16x16x32_bf16 v[0:3], v[26:29], v[58:61], 0
	v_mfma_f32_16x16x32_bf16 v[54:57], v[30:33], v[62:65], v[0:3]
	v_mfma_f32_16x16x32_bf16 v[0:3], v[34:37], v[58:61], 0
	v_mfma_f32_16x16x32_bf16 v[98:101], v[30:33], v[4:7], v[98:101]
	v_mfma_f32_16x16x32_bf16 v[58:61], v[38:41], v[62:65], v[0:3]
	s_setprio 2
	s_barrier
	s_nop 3
	v_lshl_add_u64 v[0:1], s[50:51], 0, v[184:185]
	s_add_i32 s52, s52, s58
	v_lshl_add_u64 v[2:3], v[0:1], 0, s[80:81]
	s_mov_b32 m0, s52
	s_add_i32 s15, s52, 0x2000
	ds_read_b128 v[62:65], v145 offset:16384
	ds_read_b128 v[110:113], v145 offset:17408
	ds_read_b128 v[114:117], v145 offset:18432
	ds_read_b128 v[118:121], v145 offset:19456
	ds_read_b128 v[122:125], v145 offset:20480
	ds_read_b128 v[134:137], v145 offset:21504
	ds_read_b128 v[146:149], v145 offset:22528
	ds_read_b128 v[150:153], v145 offset:23552
	global_load_lds_dwordx4 v[2:3], off
	v_lshl_add_u64 v[2:3], s[50:51], 0, v[128:129]
	s_add_u32 s78, s50, 0x18100
	v_lshl_add_u64 v[4:5], v[2:3], 0, s[80:81]
	s_mov_b32 m0, s15
	s_addc_u32 s79, s51, 0
	s_add_i32 s36, s36, s58
	global_load_lds_dwordx4 v[4:5], off
	v_lshl_add_u64 v[4:5], s[78:79], 0, v[184:185]
	s_mov_b32 m0, s36
	s_add_i32 s37, s36, 0x2000
	global_load_lds_dwordx4 v[4:5], off
	v_lshl_add_u64 v[4:5], s[78:79], 0, v[128:129]
	s_mov_b32 m0, s37
	s_nop 0
	global_load_lds_dwordx4 v[4:5], off
	v_lshl_add_u64 v[4:5], s[56:57], 0, v[132:133]
	v_lshl_add_u64 v[6:7], v[4:5], 0, s[80:81]
	s_mov_b32 m0, s59
	s_nop 0
	global_load_lds_dwordx4 v[6:7], off
	v_lshl_add_u64 v[6:7], s[56:57], 0, v[130:131]
	v_lshl_add_u64 v[126:127], v[6:7], 0, s[80:81]
	s_mov_b32 m0, s60
	s_nop 0
	global_load_lds_dwordx4 v[126:127], off
	s_waitcnt vmcnt(8)
	s_waitcnt lgkmcnt(0)
	s_barrier
	s_setprio 1
	s_waitcnt lgkmcnt(0)
	v_mfma_f32_16x16x32_bf16 v[154:157], v[10:13], v[62:65], 0
	v_mfma_f32_16x16x32_bf16 v[162:165], v[10:13], v[114:117], 0
	v_mfma_f32_16x16x32_bf16 v[170:173], v[10:13], v[122:125], 0
	v_mfma_f32_16x16x32_bf16 v[10:13], v[10:13], v[146:149], 0
	v_mfma_f32_16x16x32_bf16 v[154:157], v[14:17], v[110:113], v[154:157]
	v_mfma_f32_16x16x32_bf16 v[158:161], v[18:21], v[62:65], 0
	v_mfma_f32_16x16x32_bf16 v[162:165], v[14:17], v[118:121], v[162:165]
	v_mfma_f32_16x16x32_bf16 v[166:169], v[18:21], v[114:117], 0
	v_mfma_f32_16x16x32_bf16 v[170:173], v[14:17], v[134:137], v[170:173]
	v_mfma_f32_16x16x32_bf16 v[174:177], v[18:21], v[122:125], 0
	v_mfma_f32_16x16x32_bf16 v[12:15], v[14:17], v[150:153], v[10:13]
	v_mfma_f32_16x16x32_bf16 v[16:19], v[18:21], v[146:149], 0
	v_mfma_f32_16x16x32_bf16 v[16:19], v[22:25], v[150:153], v[16:19]
	v_mfma_f32_16x16x32_bf16 v[158:161], v[22:25], v[110:113], v[158:161]
	v_mfma_f32_16x16x32_bf16 v[166:169], v[22:25], v[118:121], v[166:169]
	v_mfma_f32_16x16x32_bf16 v[174:177], v[22:25], v[134:137], v[174:177]
	s_setprio 0
	s_setprio 1
	v_mfma_f32_16x16x32_bf16 v[20:23], v[26:29], v[62:65], 0
	v_mfma_f32_16x16x32_bf16 v[62:65], v[34:37], v[62:65], 0
	v_mfma_f32_16x16x32_bf16 v[20:23], v[30:33], v[110:113], v[20:23]
	v_mfma_f32_16x16x32_bf16 v[62:65], v[38:41], v[110:113], v[62:65]
	v_mfma_f32_16x16x32_bf16 v[110:113], v[26:29], v[114:117], 0
	v_mfma_f32_16x16x32_bf16 v[114:117], v[34:37], v[114:117], 0
	v_mfma_f32_16x16x32_bf16 v[110:113], v[30:33], v[118:121], v[110:113]
	v_mfma_f32_16x16x32_bf16 v[114:117], v[38:41], v[118:121], v[114:117]
	v_mfma_f32_16x16x32_bf16 v[118:121], v[26:29], v[122:125], 0
	v_mfma_f32_16x16x32_bf16 v[24:27], v[26:29], v[146:149], 0
	v_mfma_f32_16x16x32_bf16 v[118:121], v[30:33], v[134:137], v[118:121]
	v_mfma_f32_16x16x32_bf16 v[122:125], v[34:37], v[122:125], 0
	v_mfma_f32_16x16x32_bf16 v[24:27], v[30:33], v[150:153], v[24:27]
	v_mfma_f32_16x16x32_bf16 v[28:31], v[34:37], v[146:149], 0
	v_mfma_f32_16x16x32_bf16 v[122:125], v[38:41], v[134:137], v[122:125]
	v_mfma_f32_16x16x32_bf16 v[28:31], v[38:41], v[150:153], v[28:31]
	s_setprio 2
	s_barrier
; #define PG8_STAGE(bufoff, gbase, voff) do { _Pragma("unroll") for (int _i = 0; _i < 2; ++_i) \
;         __builtin_amdgcn_global_load_lds((const unsigned*)((const char*)(gbase) + (voff)[_i]), (PG8_LAS unsigned*)(lds + (bufoff) + ldsw + _i * 8192), 16, 0, 0); } while (0)
; #define PG8_LDA(dst, b, h) do { _Pragma("unroll") for (int m = 0; m < 4; ++m) _Pragma("unroll") for (int k = 0; k < 2; ++k) dst[m][k] = *(const PG8_LAS bf16x8*)(lds + PG8_SA(b, h) + aoff + m * 2048 + k * 1024); } while (0)
; #define PG8_LDB(dst, b, h) do { _Pragma("unroll") for (int n = 0; n < 2; ++n) _Pragma("unroll") for (int k = 0; k < 2; ++k) dst[n][k] = *(const PG8_LAS bf16x8*)(lds + PG8_SB(b, h) + boff + n * 2048 + k * 1024); } while (0)
; #define PG8_MMA(ai, bj, At, Bt) do { __builtin_amdgcn_s_setprio(1); _Pragma("unroll") for (int m = 0; m < 4; ++m) _Pragma("unroll") for (int n = 0; n < 2; ++n) _Pragma("unroll") for (int k = 0; k < 2; ++k) \
;         acc[ai][bj][m][n] = __builtin_amdgcn_mfma_f32_16x16x32_bf16(Bt[n][k], At[m][k], acc[ai][bj][m][n], 0, 0, 0); __builtin_amdgcn_s_setprio(0); } while (0)
; #define PG8_WAIT_V(n) asm volatile("s_waitcnt vmcnt(" #n ")" ::: "memory")
; #define PG8_WAIT_L(n) asm volatile("s_waitcnt lgkmcnt(" #n ")" ::: "memory")
; #define PG8_BAR __builtin_amdgcn_s_barrier()
; #define PG8_SCHED __builtin_amdgcn_sched_barrier(0)
; template <class Epi, class Sched, bool ALIGN_EPI = false, bool SP2 = false>
; __device__ __forceinline__ void gemm_phase(PG8_LAS unsigned char* lds, const Gemm g, const Sched& S, const Epi& E, const int tid_in) {
;     ...
;             PG8_LDB(B0, 1, 0); PG8_LDB(B1, 1, 1); PG8_SCHED; PG8_LDA(At, 1, 0); PG8_STAGE(PG8_SA(0, 1), a2 + hstepA, voffA);
;             PG8_WAIT_V(8); PG8_WAIT_L(0); PG8_BAR; PG8_MMA(0, 0, At, B0); PG8_MMA(0, 1, At, B1); PG8_BAR; PG8_SCHED;
;             PG8_LDA(At, 1, 1); PG8_STAGE(PG8_SB(1, 0), b3, voffB); PG8_STAGE(PG8_SB(1, 1), b3 + hstep, voffB); PG8_STAGE(PG8_SA(1, 0), a3, voffA);
;             PG8_WAIT_V(8); PG8_WAIT_L(0); PG8_BAR; PG8_MMA(1, 0, At, B0); PG8_MMA(1, 1, At, B1); PG8_BAR; PG8_SCHED;
	s_add_i32 s77, 0, 0x18000
	s_add_i32 s69, 0, 0x1c000
	v_add_u32_e32 v10, s77, v141
	v_add_u32_e32 v11, s69, v141
	ds_read_b128 v[32:35], v10
	ds_read_b128 v[36:39], v10 offset:1024
	ds_read_b128 v[134:137], v10 offset:2048
	ds_read_b128 v[146:149], v10 offset:3072
	ds_read_b128 v[150:153], v11
	ds_read_b128 v[178:181], v11 offset:1024
	ds_read_b128 v[194:197], v11 offset:2048
	ds_read_b128 v[198:201], v11 offset:3072
	s_add_u32 s78, s56, 0x18100
	s_addc_u32 s79, s57, 0
	s_mov_b32 m0, s61
	v_lshl_add_u64 v[40:41], s[78:79], 0, v[132:133]
	ds_read_b128 v[202:205], v145 offset:32768
	ds_read_b128 v[206:209], v145 offset:33792
	ds_read_b128 v[210:213], v145 offset:34816
	ds_read_b128 v[214:217], v145 offset:35840
	ds_read_b128 v[218:221], v145 offset:36864
	ds_read_b128 v[222:225], v145 offset:37888
	ds_read_b128 v[226:229], v145 offset:38912
	ds_read_b128 v[230:233], v145 offset:39936
	global_load_lds_dwordx4 v[40:41], off
	v_lshl_add_u64 v[40:41], s[78:79], 0, v[130:131]
	s_mov_b32 m0, s62
	s_nop 0
	global_load_lds_dwordx4 v[40:41], off
	s_waitcnt vmcnt(8)
	s_waitcnt lgkmcnt(0)
	s_barrier
	s_setprio 1
	s_waitcnt lgkmcnt(0)
	v_mfma_f32_16x16x32_bf16 v[66:69], v[32:35], v[202:205], v[66:69]
	v_mfma_f32_16x16x32_bf16 v[70:73], v[134:137], v[202:205], v[70:73]
	v_mfma_f32_16x16x32_bf16 v[74:77], v[32:35], v[210:213], v[74:77]
	v_mfma_f32_16x16x32_bf16 v[78:81], v[134:137], v[210:213], v[78:81]
	v_mfma_f32_16x16x32_bf16 v[82:85], v[32:35], v[218:221], v[82:85]
	v_mfma_f32_16x16x32_bf16 v[86:89], v[134:137], v[218:221], v[86:89]
	v_mfma_f32_16x16x32_bf16 v[90:93], v[32:35], v[226:229], v[90:93]
	v_mfma_f32_16x16x32_bf16 v[94:97], v[134:137], v[226:229], v[94:97]
	v_mfma_f32_16x16x32_bf16 v[66:69], v[36:39], v[206:209], v[66:69]
	v_mfma_f32_16x16x32_bf16 v[70:73], v[146:149], v[206:209], v[70:73]
	v_mfma_f32_16x16x32_bf16 v[74:77], v[36:39], v[214:217], v[74:77]
	v_mfma_f32_16x16x32_bf16 v[78:81], v[146:149], v[214:217], v[78:81]
	v_mfma_f32_16x16x32_bf16 v[82:85], v[36:39], v[222:225], v[82:85]
	v_mfma_f32_16x16x32_bf16 v[86:89], v[146:149], v[222:225], v[86:89]
	v_mfma_f32_16x16x32_bf16 v[90:93], v[36:39], v[230:233], v[90:93]
	v_mfma_f32_16x16x32_bf16 v[94:97], v[146:149], v[230:233], v[94:97]
	s_setprio 0
	s_setprio 1
	v_mfma_f32_16x16x32_bf16 v[98:101], v[150:153], v[202:205], v[98:101]
	v_mfma_f32_16x16x32_bf16 v[102:105], v[194:197], v[202:205], v[102:105]
	v_mfma_f32_16x16x32_bf16 v[106:109], v[150:153], v[210:213], v[106:109]
	v_mfma_f32_16x16x32_bf16 v[40:43], v[194:197], v[210:213], v[42:45]
	v_mfma_f32_16x16x32_bf16 v[44:47], v[150:153], v[218:221], v[46:49]
	v_mfma_f32_16x16x32_bf16 v[48:51], v[194:197], v[218:221], v[50:53]
	v_mfma_f32_16x16x32_bf16 v[52:55], v[150:153], v[226:229], v[54:57]
	v_mfma_f32_16x16x32_bf16 v[56:59], v[194:197], v[226:229], v[58:61]
	v_mfma_f32_16x16x32_bf16 v[98:101], v[178:181], v[206:209], v[98:101]
	v_mfma_f32_16x16x32_bf16 v[102:105], v[198:201], v[206:209], v[102:105]
	v_mfma_f32_16x16x32_bf16 v[106:109], v[178:181], v[214:217], v[106:109]
	v_mfma_f32_16x16x32_bf16 v[40:43], v[198:201], v[214:217], v[40:43]
	v_mfma_f32_16x16x32_bf16 v[44:47], v[178:181], v[222:225], v[44:47]
	v_mfma_f32_16x16x32_bf16 v[48:51], v[198:201], v[222:225], v[48:51]
	v_mfma_f32_16x16x32_bf16 v[52:55], v[178:181], v[230:233], v[52:55]
	v_mfma_f32_16x16x32_bf16 v[56:59], v[198:201], v[230:233], v[56:59]
	s_setprio 2
	s_barrier
	s_add_i32 s77, s77, s58
	s_mov_b64 s[6:7], 0x180
	s_add_i32 s53, s77, 0x2000
	v_lshl_add_u64 v[60:61], v[0:1], 0, s[6:7]
	s_mov_b32 m0, s77
	s_add_u32 s78, s50, 0x18180
	ds_read_b128 v[202:205], v145 offset:49152
	ds_read_b128 v[206:209], v145 offset:50176
	ds_read_b128 v[210:213], v145 offset:51200
	ds_read_b128 v[214:217], v145 offset:52224
	ds_read_b128 v[218:221], v145 offset:53248
	ds_read_b128 v[222:225], v145 offset:54272
	ds_read_b128 v[226:229], v145 offset:55296
	ds_read_b128 v[230:233], v145 offset:56320
	global_load_lds_dwordx4 v[60:61], off
	v_lshl_add_u64 v[60:61], v[2:3], 0, s[6:7]
	s_mov_b32 m0, s53
	s_addc_u32 s79, s51, 0
	s_add_i32 s69, s69, s58
	global_load_lds_dwordx4 v[60:61], off
	v_lshl_add_u64 v[60:61], s[78:79], 0, v[184:185]
	s_mov_b32 m0, s69
	s_add_i32 s71, s69, 0x2000
	global_load_lds_dwordx4 v[60:61], off
	v_lshl_add_u64 v[60:61], s[78:79], 0, v[128:129]
	s_mov_b32 m0, s71
	s_nop 0
	global_load_lds_dwordx4 v[60:61], off
	v_lshl_add_u64 v[60:61], v[4:5], 0, s[6:7]
	s_mov_b32 m0, s65
	s_nop 0
	global_load_lds_dwordx4 v[60:61], off
	v_lshl_add_u64 v[60:61], v[6:7], 0, s[6:7]
	s_mov_b32 m0, s66
	s_nop 0
	global_load_lds_dwordx4 v[60:61], off
	s_waitcnt vmcnt(8)
	s_waitcnt lgkmcnt(0)
	s_barrier
; #define PG8_STAGE(bufoff, gbase, voff) do { _Pragma("unroll") for (int _i = 0; _i < 2; ++_i) \
;         __builtin_amdgcn_global_load_lds((const unsigned*)((const char*)(gbase) + (voff)[_i]), (PG8_LAS unsigned*)(lds + (bufoff) + ldsw + _i * 8192), 16, 0, 0); } while (0)
; #define PG8_LDA(dst, b, h) do { _Pragma("unroll") for (int m = 0; m < 4; ++m) _Pragma("unroll") for (int k = 0; k < 2; ++k) dst[m][k] = *(const PG8_LAS bf16x8*)(lds + PG8_SA(b, h) + aoff + m * 2048 + k * 1024); } while (0)
; #define PG8_LDB(dst, b, h) do { _Pragma("unroll") for (int n = 0; n < 2; ++n) _Pragma("unroll") for (int k = 0; k < 2; ++k) dst[n][k] = *(const PG8_LAS bf16x8*)(lds + PG8_SB(b, h) + boff + n * 2048 + k * 1024); } while (0)
; #define PG8_MMA(ai, bj, At, Bt) do { __builtin_amdgcn_s_setprio(1); _Pragma("unroll") for (int m = 0; m < 4; ++m) _Pragma("unroll") for (int n = 0; n < 2; ++n) _Pragma("unroll") for (int k = 0; k < 2; ++k) \
;         acc[ai][bj][m][n] = __builtin_amdgcn_mfma_f32_16x16x32_bf16(Bt[n][k], At[m][k], acc[ai][bj][m][n], 0, 0, 0); __builtin_amdgcn_s_setprio(0); } while (0)
; #define PG8_WAIT_V(n) asm volatile("s_waitcnt vmcnt(" #n ")" ::: "memory")
; #define PG8_WAIT_L(n) asm volatile("s_waitcnt lgkmcnt(" #n ")" ::: "memory")
; #define PG8_BAR __builtin_amdgcn_s_barrier()
; #define PG8_SCHED __builtin_amdgcn_sched_barrier(0)
; template <class Epi, class Sched, bool ALIGN_EPI = false, bool SP2 = false>
; __device__ __forceinline__ void gemm_phase(PG8_LAS unsigned char* lds, const Gemm g, const Sched& S, const Epi& E, const int tid_in) {
;     ...
;             PG8_LDB(B0, 0, 0); PG8_LDB(B1, 0, 1); PG8_SCHED; PG8_LDA(At, 0, 0); PG8_STAGE(PG8_SA(1, 1), a1 + hstepA, voffA);
;             PG8_WAIT_V(8); PG8_WAIT_L(0); PG8_BAR; PG8_MMA(0, 0, At, B0); PG8_MMA(0, 1, At, B1); PG8_BAR; PG8_SCHED;
;     ...
;             PG8_WAIT_V(8); PG8_WAIT_L(0); PG8_BAR; PG8_MMA(1, 0, At, B0); PG8_MMA(1, 1, At, B1); PG8_BAR; PG8_SCHED;
	s_setprio 1
	s_waitcnt lgkmcnt(0)
	v_mfma_f32_16x16x32_bf16 v[12:15], v[32:35], v[226:229], v[12:15]
	v_mfma_f32_16x16x32_bf16 v[16:19], v[134:137], v[226:229], v[16:19]
	v_mfma_f32_16x16x32_bf16 v[154:157], v[32:35], v[202:205], v[154:157]
	v_mfma_f32_16x16x32_bf16 v[158:161], v[134:137], v[202:205], v[158:161]
	v_mfma_f32_16x16x32_bf16 v[162:165], v[32:35], v[210:213], v[162:165]
	v_mfma_f32_16x16x32_bf16 v[166:169], v[134:137], v[210:213], v[166:169]
	v_mfma_f32_16x16x32_bf16 v[170:173], v[32:35], v[218:221], v[170:173]
	v_mfma_f32_16x16x32_bf16 v[174:177], v[134:137], v[218:221], v[174:177]
	v_mfma_f32_16x16x32_bf16 v[12:15], v[36:39], v[230:233], v[12:15]
	v_mfma_f32_16x16x32_bf16 v[16:19], v[146:149], v[230:233], v[16:19]
	v_mfma_f32_16x16x32_bf16 v[154:157], v[36:39], v[206:209], v[154:157]
	v_mfma_f32_16x16x32_bf16 v[158:161], v[146:149], v[206:209], v[158:161]
	v_mfma_f32_16x16x32_bf16 v[162:165], v[36:39], v[214:217], v[162:165]
	v_mfma_f32_16x16x32_bf16 v[166:169], v[146:149], v[214:217], v[166:169]
	v_mfma_f32_16x16x32_bf16 v[170:173], v[36:39], v[222:225], v[170:173]
	v_mfma_f32_16x16x32_bf16 v[174:177], v[146:149], v[222:225], v[174:177]
	s_setprio 0
	s_setprio 1
	v_mfma_f32_16x16x32_bf16 v[20:23], v[150:153], v[202:205], v[20:23]
	v_mfma_f32_16x16x32_bf16 v[32:35], v[194:197], v[202:205], v[62:65]
	v_mfma_f32_16x16x32_bf16 v[36:39], v[150:153], v[210:213], v[110:113]
	v_mfma_f32_16x16x32_bf16 v[60:63], v[194:197], v[210:213], v[114:117]
	v_mfma_f32_16x16x32_bf16 v[110:113], v[150:153], v[218:221], v[118:121]
	v_mfma_f32_16x16x32_bf16 v[114:117], v[194:197], v[218:221], v[122:125]
	v_mfma_f32_16x16x32_bf16 v[24:27], v[150:153], v[226:229], v[24:27]
	v_mfma_f32_16x16x32_bf16 v[28:31], v[194:197], v[226:229], v[28:31]
	v_mfma_f32_16x16x32_bf16 v[20:23], v[178:181], v[206:209], v[20:23]
	v_mfma_f32_16x16x32_bf16 v[32:35], v[198:201], v[206:209], v[32:35]
	v_mfma_f32_16x16x32_bf16 v[36:39], v[178:181], v[214:217], v[36:39]
	v_mfma_f32_16x16x32_bf16 v[60:63], v[198:201], v[214:217], v[60:63]
	v_mfma_f32_16x16x32_bf16 v[110:113], v[178:181], v[222:225], v[110:113]
	v_mfma_f32_16x16x32_bf16 v[114:117], v[198:201], v[222:225], v[114:117]
	v_mfma_f32_16x16x32_bf16 v[24:27], v[178:181], v[230:233], v[24:27]
	v_mfma_f32_16x16x32_bf16 v[28:31], v[198:201], v[230:233], v[28:31]
	s_setprio 2
	s_barrier
	ds_read_b128 v[118:121], v8
	ds_read_b128 v[122:125], v8 offset:1024
	ds_read_b128 v[134:137], v8 offset:2048
	ds_read_b128 v[146:149], v8 offset:3072
	ds_read_b128 v[150:153], v9
	ds_read_b128 v[178:181], v9 offset:1024
	ds_read_b128 v[194:197], v9 offset:2048
	ds_read_b128 v[198:201], v9 offset:3072
	s_add_u32 s78, s56, 0x18180
	s_addc_u32 s79, s57, 0
	s_mov_b32 m0, s70
	v_lshl_add_u64 v[64:65], s[78:79], 0, v[132:133]
	ds_read_b128 v[202:205], v145
	ds_read_b128 v[206:209], v145 offset:1024
	ds_read_b128 v[210:213], v145 offset:2048
	ds_read_b128 v[214:217], v145 offset:3072
	ds_read_b128 v[218:221], v145 offset:4096
	ds_read_b128 v[222:225], v145 offset:5120
	ds_read_b128 v[226:229], v145 offset:6144
	ds_read_b128 v[230:233], v145 offset:7168
	global_load_lds_dwordx4 v[64:65], off
	v_lshl_add_u64 v[64:65], s[78:79], 0, v[130:131]
	s_mov_b32 m0, s14
	s_nop 0
	global_load_lds_dwordx4 v[64:65], off
	s_waitcnt vmcnt(8)
	s_waitcnt lgkmcnt(0)
	s_barrier
	s_setprio 1
	s_waitcnt lgkmcnt(0)
	v_mfma_f32_16x16x32_bf16 v[64:67], v[118:121], v[202:205], v[66:69]
	v_mfma_f32_16x16x32_bf16 v[68:71], v[134:137], v[202:205], v[70:73]
	v_mfma_f32_16x16x32_bf16 v[72:75], v[118:121], v[210:213], v[74:77]
	v_mfma_f32_16x16x32_bf16 v[76:79], v[134:137], v[210:213], v[78:81]
	v_mfma_f32_16x16x32_bf16 v[80:83], v[118:121], v[218:221], v[82:85]
	v_mfma_f32_16x16x32_bf16 v[84:87], v[134:137], v[218:221], v[86:89]
	v_mfma_f32_16x16x32_bf16 v[88:91], v[118:121], v[226:229], v[90:93]
	v_mfma_f32_16x16x32_bf16 v[92:95], v[134:137], v[226:229], v[94:97]
	v_mfma_f32_16x16x32_bf16 v[64:67], v[122:125], v[206:209], v[64:67]
	v_mfma_f32_16x16x32_bf16 v[68:71], v[146:149], v[206:209], v[68:71]
	v_mfma_f32_16x16x32_bf16 v[72:75], v[122:125], v[214:217], v[72:75]
	v_mfma_f32_16x16x32_bf16 v[76:79], v[146:149], v[214:217], v[76:79]
	v_mfma_f32_16x16x32_bf16 v[80:83], v[122:125], v[222:225], v[80:83]
	v_mfma_f32_16x16x32_bf16 v[84:87], v[146:149], v[222:225], v[84:87]
	v_mfma_f32_16x16x32_bf16 v[88:91], v[122:125], v[230:233], v[88:91]
	v_mfma_f32_16x16x32_bf16 v[92:95], v[146:149], v[230:233], v[92:95]
	s_setprio 0
	s_setprio 1
	v_mfma_f32_16x16x32_bf16 v[96:99], v[150:153], v[202:205], v[98:101]
	v_mfma_f32_16x16x32_bf16 v[100:103], v[194:197], v[202:205], v[102:105]
	v_mfma_f32_16x16x32_bf16 v[104:107], v[150:153], v[210:213], v[106:109]
	v_mfma_f32_16x16x32_bf16 v[40:43], v[194:197], v[210:213], v[40:43]
	v_mfma_f32_16x16x32_bf16 v[44:47], v[150:153], v[218:221], v[44:47]
	v_mfma_f32_16x16x32_bf16 v[48:51], v[194:197], v[218:221], v[48:51]
	v_mfma_f32_16x16x32_bf16 v[52:55], v[150:153], v[226:229], v[52:55]
	v_mfma_f32_16x16x32_bf16 v[56:59], v[194:197], v[226:229], v[56:59]
	v_mfma_f32_16x16x32_bf16 v[96:99], v[178:181], v[206:209], v[96:99]
	v_mfma_f32_16x16x32_bf16 v[100:103], v[198:201], v[206:209], v[100:103]
	v_mfma_f32_16x16x32_bf16 v[104:107], v[178:181], v[214:217], v[104:107]
	v_mfma_f32_16x16x32_bf16 v[40:43], v[198:201], v[214:217], v[40:43]
	v_mfma_f32_16x16x32_bf16 v[44:47], v[178:181], v[222:225], v[44:47]
	v_mfma_f32_16x16x32_bf16 v[48:51], v[198:201], v[222:225], v[48:51]
	v_mfma_f32_16x16x32_bf16 v[52:55], v[178:181], v[230:233], v[52:55]
	v_mfma_f32_16x16x32_bf16 v[56:59], v[198:201], v[230:233], v[56:59]
	s_setprio 2
	s_barrier
; #define PG8_STAGE(bufoff, gbase, voff) do { _Pragma("unroll") for (int _i = 0; _i < 2; ++_i) \
;         __builtin_amdgcn_global_load_lds((const unsigned*)((const char*)(gbase) + (voff)[_i]), (PG8_LAS unsigned*)(lds + (bufoff) + ldsw + _i * 8192), 16, 0, 0); } while (0)
; #define PG8_LDA(dst, b, h) do { _Pragma("unroll") for (int m = 0; m < 4; ++m) _Pragma("unroll") for (int k = 0; k < 2; ++k) dst[m][k] = *(const PG8_LAS bf16x8*)(lds + PG8_SA(b, h) + aoff + m * 2048 + k * 1024); } while (0)
; #define PG8_LDB(dst, b, h) do { _Pragma("unroll") for (int n = 0; n < 2; ++n) _Pragma("unroll") for (int k = 0; k < 2; ++k) dst[n][k] = *(const PG8_LAS bf16x8*)(lds + PG8_SB(b, h) + boff + n * 2048 + k * 1024); } while (0)
; #define PG8_MMA(ai, bj, At, Bt) do { __builtin_amdgcn_s_setprio(1); _Pragma("unroll") for (int m = 0; m < 4; ++m) _Pragma("unroll") for (int n = 0; n < 2; ++n) _Pragma("unroll") for (int k = 0; k < 2; ++k) \
;         acc[ai][bj][m][n] = __builtin_amdgcn_mfma_f32_16x16x32_bf16(Bt[n][k], At[m][k], acc[ai][bj][m][n], 0, 0, 0); __builtin_amdgcn_s_setprio(0); } while (0)
; #define PG8_WAIT_V(n) asm volatile("s_waitcnt vmcnt(" #n ")" ::: "memory")
; #define PG8_WAIT_L(n) asm volatile("s_waitcnt lgkmcnt(" #n ")" ::: "memory")
; #define PG8_BAR __builtin_amdgcn_s_barrier()
; #define PG8_SCHED __builtin_amdgcn_sched_barrier(0)
; template <class Epi, class Sched, bool ALIGN_EPI = false, bool SP2 = false>
; __device__ __forceinline__ void gemm_phase(PG8_LAS unsigned char* lds, const Gemm g, const Sched& S, const Epi& E, const int tid_in) {
;     ...
;             PG8_LDA(At, 0, 1); PG8_STAGE(PG8_SB(0, 0), b2, voffB); PG8_STAGE(PG8_SB(0, 1), b2 + hstep, voffB); PG8_STAGE(PG8_SA(0, 0), a2, voffA);
;             PG8_WAIT_V(8); PG8_WAIT_L(0); PG8_BAR; PG8_MMA(1, 0, At, B0); PG8_MMA(1, 1, At, B1); PG8_BAR; PG8_SCHED;
;             PG8_LDB(B0, 1, 0); PG8_LDB(B1, 1, 1); PG8_SCHED; PG8_LDA(At, 1, 0); PG8_STAGE(PG8_SA(0, 1), a2 + hstepA, voffA);
	s_mov_b64 s[6:7], 0x200
	s_mov_b32 m0, s52
	v_lshl_add_u64 v[108:109], v[0:1], 0, s[6:7]
	s_add_u32 s78, s50, 0x18200
	ds_read_b128 v[202:205], v145 offset:16384
	ds_read_b128 v[206:209], v145 offset:17408
	ds_read_b128 v[210:213], v145 offset:18432
	ds_read_b128 v[214:217], v145 offset:19456
	ds_read_b128 v[218:221], v145 offset:20480
	ds_read_b128 v[222:225], v145 offset:21504
	ds_read_b128 v[226:229], v145 offset:22528
	ds_read_b128 v[230:233], v145 offset:23552
	global_load_lds_dwordx4 v[108:109], off
	v_lshl_add_u64 v[108:109], v[2:3], 0, s[6:7]
	s_mov_b32 m0, s15
	s_addc_u32 s79, s51, 0
	global_load_lds_dwordx4 v[108:109], off
	v_lshl_add_u64 v[108:109], s[78:79], 0, v[184:185]
	s_mov_b32 m0, s36
	s_nop 0
	global_load_lds_dwordx4 v[108:109], off
	v_lshl_add_u64 v[108:109], s[78:79], 0, v[128:129]
	s_mov_b32 m0, s37
	s_nop 0
	global_load_lds_dwordx4 v[108:109], off
	v_lshl_add_u64 v[108:109], v[4:5], 0, s[6:7]
	s_mov_b32 m0, s59
	s_nop 0
	global_load_lds_dwordx4 v[108:109], off
	v_lshl_add_u64 v[108:109], v[6:7], 0, s[6:7]
	s_mov_b32 m0, s60
	s_nop 0
	global_load_lds_dwordx4 v[108:109], off
	s_waitcnt vmcnt(8)
	s_waitcnt lgkmcnt(0)
	s_barrier
	s_setprio 1
	s_waitcnt lgkmcnt(0)
	v_mfma_f32_16x16x32_bf16 v[12:15], v[118:121], v[226:229], v[12:15]
	v_mfma_f32_16x16x32_bf16 v[16:19], v[134:137], v[226:229], v[16:19]
	v_mfma_f32_16x16x32_bf16 v[154:157], v[118:121], v[202:205], v[154:157]
	v_mfma_f32_16x16x32_bf16 v[158:161], v[134:137], v[202:205], v[158:161]
	v_mfma_f32_16x16x32_bf16 v[162:165], v[118:121], v[210:213], v[162:165]
	v_mfma_f32_16x16x32_bf16 v[166:169], v[134:137], v[210:213], v[166:169]
	v_mfma_f32_16x16x32_bf16 v[170:173], v[118:121], v[218:221], v[170:173]
	v_mfma_f32_16x16x32_bf16 v[174:177], v[134:137], v[218:221], v[174:177]
	v_mfma_f32_16x16x32_bf16 v[12:15], v[122:125], v[230:233], v[12:15]
	v_mfma_f32_16x16x32_bf16 v[16:19], v[146:149], v[230:233], v[16:19]
	v_mfma_f32_16x16x32_bf16 v[154:157], v[122:125], v[206:209], v[154:157]
	v_mfma_f32_16x16x32_bf16 v[158:161], v[146:149], v[206:209], v[158:161]
	v_mfma_f32_16x16x32_bf16 v[162:165], v[122:125], v[214:217], v[162:165]
	v_mfma_f32_16x16x32_bf16 v[166:169], v[146:149], v[214:217], v[166:169]
	v_mfma_f32_16x16x32_bf16 v[170:173], v[122:125], v[222:225], v[170:173]
	v_mfma_f32_16x16x32_bf16 v[174:177], v[146:149], v[222:225], v[174:177]
	s_setprio 0
	s_setprio 1
	v_mfma_f32_16x16x32_bf16 v[20:23], v[150:153], v[202:205], v[20:23]
	v_mfma_f32_16x16x32_bf16 v[32:35], v[194:197], v[202:205], v[32:35]
	v_mfma_f32_16x16x32_bf16 v[36:39], v[150:153], v[210:213], v[36:39]
	v_mfma_f32_16x16x32_bf16 v[60:63], v[194:197], v[210:213], v[60:63]
	v_mfma_f32_16x16x32_bf16 v[108:111], v[150:153], v[218:221], v[110:113]
	v_mfma_f32_16x16x32_bf16 v[112:115], v[194:197], v[218:221], v[114:117]
	v_mfma_f32_16x16x32_bf16 v[24:27], v[150:153], v[226:229], v[24:27]
	v_mfma_f32_16x16x32_bf16 v[28:31], v[194:197], v[226:229], v[28:31]
	v_mfma_f32_16x16x32_bf16 v[20:23], v[178:181], v[206:209], v[20:23]
	v_mfma_f32_16x16x32_bf16 v[32:35], v[198:201], v[206:209], v[32:35]
	v_mfma_f32_16x16x32_bf16 v[36:39], v[178:181], v[214:217], v[36:39]
	v_mfma_f32_16x16x32_bf16 v[60:63], v[198:201], v[214:217], v[60:63]
	v_mfma_f32_16x16x32_bf16 v[108:111], v[178:181], v[222:225], v[108:111]
	v_mfma_f32_16x16x32_bf16 v[112:115], v[198:201], v[222:225], v[112:115]
	v_mfma_f32_16x16x32_bf16 v[24:27], v[178:181], v[230:233], v[24:27]
	v_mfma_f32_16x16x32_bf16 v[28:31], v[198:201], v[230:233], v[28:31]
	s_setprio 2
	s_barrier
	ds_read_b128 v[116:119], v10
	ds_read_b128 v[120:123], v10 offset:1024
	ds_read_b128 v[124:127], v10 offset:2048
	ds_read_b128 v[134:137], v10 offset:3072
	ds_read_b128 v[146:149], v11
	ds_read_b128 v[150:153], v11 offset:1024
	ds_read_b128 v[178:181], v11 offset:2048
	ds_read_b128 v[194:197], v11 offset:3072
	s_add_u32 s78, s56, 0x18200
	s_addc_u32 s79, s57, 0
	s_mov_b32 m0, s61
	v_lshl_add_u64 v[138:139], s[78:79], 0, v[132:133]
	ds_read_b128 v[198:201], v145 offset:32768
	ds_read_b128 v[202:205], v145 offset:33792
	ds_read_b128 v[206:209], v145 offset:34816
	ds_read_b128 v[210:213], v145 offset:35840
	ds_read_b128 v[214:217], v145 offset:36864
	ds_read_b128 v[218:221], v145 offset:37888
	ds_read_b128 v[222:225], v145 offset:38912
	ds_read_b128 v[226:229], v145 offset:39936
	global_load_lds_dwordx4 v[138:139], off
	v_lshl_add_u64 v[138:139], s[78:79], 0, v[130:131]
	s_mov_b32 m0, s62
	s_nop 0
	global_load_lds_dwordx4 v[138:139], off
	s_waitcnt vmcnt(8)
	s_waitcnt lgkmcnt(0)
	s_barrier
; #define PG8_STAGE(bufoff, gbase, voff) do { _Pragma("unroll") for (int _i = 0; _i < 2; ++_i) \
;         __builtin_amdgcn_global_load_lds((const unsigned*)((const char*)(gbase) + (voff)[_i]), (PG8_LAS unsigned*)(lds + (bufoff) + ldsw + _i * 8192), 16, 0, 0); } while (0)
; #define PG8_LDA(dst, b, h) do { _Pragma("unroll") for (int m = 0; m < 4; ++m) _Pragma("unroll") for (int k = 0; k < 2; ++k) dst[m][k] = *(const PG8_LAS bf16x8*)(lds + PG8_SA(b, h) + aoff + m * 2048 + k * 1024); } while (0)
; #define PG8_MMA(ai, bj, At, Bt) do { __builtin_amdgcn_s_setprio(1); _Pragma("unroll") for (int m = 0; m < 4; ++m) _Pragma("unroll") for (int n = 0; n < 2; ++n) _Pragma("unroll") for (int k = 0; k < 2; ++k) \
;         acc[ai][bj][m][n] = __builtin_amdgcn_mfma_f32_16x16x32_bf16(Bt[n][k], At[m][k], acc[ai][bj][m][n], 0, 0, 0); __builtin_amdgcn_s_setprio(0); } while (0)
; #define PG8_WAIT_V(n) asm volatile("s_waitcnt vmcnt(" #n ")" ::: "memory")
; #define PG8_WAIT_L(n) asm volatile("s_waitcnt lgkmcnt(" #n ")" ::: "memory")
; #define PG8_BAR __builtin_amdgcn_s_barrier()
; #define PG8_SCHED __builtin_amdgcn_sched_barrier(0)
; template <class Epi, class Sched, bool ALIGN_EPI = false, bool SP2 = false>
; __device__ __forceinline__ void gemm_phase(PG8_LAS unsigned char* lds, const Gemm g, const Sched& S, const Epi& E, const int tid_in) {
;     ...
;             PG8_WAIT_V(8); PG8_WAIT_L(0); PG8_BAR; PG8_MMA(0, 0, At, B0); PG8_MMA(0, 1, At, B1); PG8_BAR; PG8_SCHED;
;             PG8_LDA(At, 1, 1); PG8_STAGE(PG8_SB(1, 0), b3, voffB); PG8_STAGE(PG8_SB(1, 1), b3 + hstep, voffB); PG8_STAGE(PG8_SA(1, 0), a3, voffA);
;             PG8_WAIT_V(8); PG8_WAIT_L(0); PG8_BAR; PG8_MMA(1, 0, At, B0); PG8_MMA(1, 1, At, B1); PG8_BAR; PG8_SCHED;
	s_setprio 1
	s_waitcnt lgkmcnt(0)
	v_mfma_f32_16x16x32_bf16 v[64:67], v[116:119], v[198:201], v[64:67]
	v_mfma_f32_16x16x32_bf16 v[68:71], v[124:127], v[198:201], v[68:71]
	v_mfma_f32_16x16x32_bf16 v[72:75], v[116:119], v[206:209], v[72:75]
	v_mfma_f32_16x16x32_bf16 v[76:79], v[124:127], v[206:209], v[76:79]
	v_mfma_f32_16x16x32_bf16 v[80:83], v[116:119], v[214:217], v[80:83]
	v_mfma_f32_16x16x32_bf16 v[84:87], v[124:127], v[214:217], v[84:87]
	v_mfma_f32_16x16x32_bf16 v[88:91], v[116:119], v[222:225], v[88:91]
	v_mfma_f32_16x16x32_bf16 v[92:95], v[124:127], v[222:225], v[92:95]
	v_mfma_f32_16x16x32_bf16 v[64:67], v[120:123], v[202:205], v[64:67]
	v_mfma_f32_16x16x32_bf16 v[68:71], v[134:137], v[202:205], v[68:71]
	v_mfma_f32_16x16x32_bf16 v[72:75], v[120:123], v[210:213], v[72:75]
	v_mfma_f32_16x16x32_bf16 v[76:79], v[134:137], v[210:213], v[76:79]
	v_mfma_f32_16x16x32_bf16 v[80:83], v[120:123], v[218:221], v[80:83]
	v_mfma_f32_16x16x32_bf16 v[84:87], v[134:137], v[218:221], v[84:87]
	v_mfma_f32_16x16x32_bf16 v[88:91], v[120:123], v[226:229], v[88:91]
	v_mfma_f32_16x16x32_bf16 v[92:95], v[134:137], v[226:229], v[92:95]
	s_setprio 0
	s_setprio 1
	v_mfma_f32_16x16x32_bf16 v[96:99], v[146:149], v[198:201], v[96:99]
	v_mfma_f32_16x16x32_bf16 v[100:103], v[178:181], v[198:201], v[100:103]
	v_mfma_f32_16x16x32_bf16 v[104:107], v[146:149], v[206:209], v[104:107]
	v_mfma_f32_16x16x32_bf16 v[40:43], v[178:181], v[206:209], v[40:43]
	v_mfma_f32_16x16x32_bf16 v[44:47], v[146:149], v[214:217], v[44:47]
	v_mfma_f32_16x16x32_bf16 v[48:51], v[178:181], v[214:217], v[48:51]
	v_mfma_f32_16x16x32_bf16 v[52:55], v[146:149], v[222:225], v[52:55]
	v_mfma_f32_16x16x32_bf16 v[56:59], v[178:181], v[222:225], v[56:59]
	v_mfma_f32_16x16x32_bf16 v[96:99], v[150:153], v[202:205], v[96:99]
	v_mfma_f32_16x16x32_bf16 v[100:103], v[194:197], v[202:205], v[100:103]
	v_mfma_f32_16x16x32_bf16 v[104:107], v[150:153], v[210:213], v[104:107]
	v_mfma_f32_16x16x32_bf16 v[40:43], v[194:197], v[210:213], v[40:43]
	v_mfma_f32_16x16x32_bf16 v[44:47], v[150:153], v[218:221], v[44:47]
	v_mfma_f32_16x16x32_bf16 v[48:51], v[194:197], v[218:221], v[48:51]
	v_mfma_f32_16x16x32_bf16 v[52:55], v[150:153], v[226:229], v[52:55]
	v_mfma_f32_16x16x32_bf16 v[56:59], v[194:197], v[226:229], v[56:59]
	s_setprio 2
	s_barrier
	s_mov_b64 s[6:7], 0x280
	s_mov_b32 m0, s77
	v_lshl_add_u64 v[0:1], v[0:1], 0, s[6:7]
	s_add_u32 s50, s50, 0x18280
	ds_read_b128 v[198:201], v145 offset:49152
	ds_read_b128 v[202:205], v145 offset:50176
	ds_read_b128 v[206:209], v145 offset:51200
	ds_read_b128 v[210:213], v145 offset:52224
	ds_read_b128 v[214:217], v145 offset:53248
	ds_read_b128 v[218:221], v145 offset:54272
	ds_read_b128 v[222:225], v145 offset:55296
	ds_read_b128 v[226:229], v145 offset:56320
	global_load_lds_dwordx4 v[0:1], off
	v_lshl_add_u64 v[0:1], v[2:3], 0, s[6:7]
	s_mov_b32 m0, s53
	s_addc_u32 s51, s51, 0
	global_load_lds_dwordx4 v[0:1], off
	v_lshl_add_u64 v[0:1], s[50:51], 0, v[184:185]
	s_mov_b32 m0, s69
	s_nop 0
	global_load_lds_dwordx4 v[0:1], off
	v_lshl_add_u64 v[0:1], s[50:51], 0, v[128:129]
	s_mov_b32 m0, s71
	s_nop 0
	global_load_lds_dwordx4 v[0:1], off
	v_lshl_add_u64 v[0:1], v[4:5], 0, s[6:7]
	s_mov_b32 m0, s65
	s_nop 0
	global_load_lds_dwordx4 v[0:1], off
	v_lshl_add_u64 v[0:1], v[6:7], 0, s[6:7]
	s_mov_b32 m0, s66
	s_nop 0
	global_load_lds_dwordx4 v[0:1], off
	s_waitcnt vmcnt(8)
	s_waitcnt lgkmcnt(0)
	s_barrier
	s_setprio 1
	s_waitcnt lgkmcnt(0)
	v_mfma_f32_16x16x32_bf16 v[0:3], v[116:119], v[198:201], v[154:157]
	v_mfma_f32_16x16x32_bf16 v[4:7], v[124:127], v[198:201], v[158:161]
	v_mfma_f32_16x16x32_bf16 v[12:15], v[116:119], v[222:225], v[12:15]
	v_mfma_f32_16x16x32_bf16 v[16:19], v[124:127], v[222:225], v[16:19]
	v_mfma_f32_16x16x32_bf16 v[0:3], v[120:123], v[202:205], v[0:3]
	v_mfma_f32_16x16x32_bf16 v[4:7], v[134:137], v[202:205], v[4:7]
	v_mfma_f32_16x16x32_bf16 v[154:157], v[116:119], v[206:209], v[162:165]
	v_mfma_f32_16x16x32_bf16 v[158:161], v[124:127], v[206:209], v[166:169]
	v_mfma_f32_16x16x32_bf16 v[162:165], v[116:119], v[214:217], v[170:173]
	v_mfma_f32_16x16x32_bf16 v[166:169], v[124:127], v[214:217], v[174:177]
	v_mfma_f32_16x16x32_bf16 v[12:15], v[120:123], v[226:229], v[12:15]
	v_mfma_f32_16x16x32_bf16 v[16:19], v[134:137], v[226:229], v[16:19]
	v_mfma_f32_16x16x32_bf16 v[154:157], v[120:123], v[210:213], v[154:157]
	v_mfma_f32_16x16x32_bf16 v[158:161], v[134:137], v[210:213], v[158:161]
	v_mfma_f32_16x16x32_bf16 v[162:165], v[120:123], v[218:221], v[162:165]
	v_mfma_f32_16x16x32_bf16 v[166:169], v[134:137], v[218:221], v[166:169]
	s_setprio 0
	s_setprio 1
	v_mfma_f32_16x16x32_bf16 v[20:23], v[146:149], v[198:201], v[20:23]
	v_mfma_f32_16x16x32_bf16 v[32:35], v[178:181], v[198:201], v[32:35]
	v_mfma_f32_16x16x32_bf16 v[36:39], v[146:149], v[206:209], v[36:39]
	v_mfma_f32_16x16x32_bf16 v[60:63], v[178:181], v[206:209], v[60:63]
	v_mfma_f32_16x16x32_bf16 v[108:111], v[146:149], v[214:217], v[108:111]
	v_mfma_f32_16x16x32_bf16 v[112:115], v[178:181], v[214:217], v[112:115]
	v_mfma_f32_16x16x32_bf16 v[24:27], v[146:149], v[222:225], v[24:27]
	v_mfma_f32_16x16x32_bf16 v[28:31], v[178:181], v[222:225], v[28:31]
	v_mfma_f32_16x16x32_bf16 v[20:23], v[150:153], v[202:205], v[20:23]
	v_mfma_f32_16x16x32_bf16 v[32:35], v[194:197], v[202:205], v[32:35]
	v_mfma_f32_16x16x32_bf16 v[36:39], v[150:153], v[210:213], v[36:39]
	v_mfma_f32_16x16x32_bf16 v[60:63], v[194:197], v[210:213], v[60:63]
	v_mfma_f32_16x16x32_bf16 v[108:111], v[150:153], v[218:221], v[108:111]
	v_mfma_f32_16x16x32_bf16 v[112:115], v[194:197], v[218:221], v[112:115]
	v_mfma_f32_16x16x32_bf16 v[24:27], v[150:153], v[226:229], v[24:27]
	v_mfma_f32_16x16x32_bf16 v[28:31], v[194:197], v[226:229], v[28:31]
	s_setprio 2
	s_barrier
; #define PG8_STAGE(bufoff, gbase, voff) do { _Pragma("unroll") for (int _i = 0; _i < 2; ++_i) \
;         __builtin_amdgcn_global_load_lds((const unsigned*)((const char*)(gbase) + (voff)[_i]), (PG8_LAS unsigned*)(lds + (bufoff) + ldsw + _i * 8192), 16, 0, 0); } while (0)
; #define PG8_LDA(dst, b, h) do { _Pragma("unroll") for (int m = 0; m < 4; ++m) _Pragma("unroll") for (int k = 0; k < 2; ++k) dst[m][k] = *(const PG8_LAS bf16x8*)(lds + PG8_SA(b, h) + aoff + m * 2048 + k * 1024); } while (0)
; #define PG8_LDB(dst, b, h) do { _Pragma("unroll") for (int n = 0; n < 2; ++n) _Pragma("unroll") for (int k = 0; k < 2; ++k) dst[n][k] = *(const PG8_LAS bf16x8*)(lds + PG8_SB(b, h) + boff + n * 2048 + k * 1024); } while (0)
; #define PG8_MMA(ai, bj, At, Bt) do { __builtin_amdgcn_s_setprio(1); _Pragma("unroll") for (int m = 0; m < 4; ++m) _Pragma("unroll") for (int n = 0; n < 2; ++n) _Pragma("unroll") for (int k = 0; k < 2; ++k) \
;         acc[ai][bj][m][n] = __builtin_amdgcn_mfma_f32_16x16x32_bf16(Bt[n][k], At[m][k], acc[ai][bj][m][n], 0, 0, 0); __builtin_amdgcn_s_setprio(0); } while (0)
; #define PG8_WAIT_V(n) asm volatile("s_waitcnt vmcnt(" #n ")" ::: "memory")
; #define PG8_WAIT_L(n) asm volatile("s_waitcnt lgkmcnt(" #n ")" ::: "memory")
; #define PG8_BAR __builtin_amdgcn_s_barrier()
; #define PG8_SCHED __builtin_amdgcn_sched_barrier(0)
; template <class Epi, class Sched, bool ALIGN_EPI = false, bool SP2 = false>
; __device__ __forceinline__ void gemm_phase(PG8_LAS unsigned char* lds, const Gemm g, const Sched& S, const Epi& E, const int tid_in) {
;     ...
;             PG8_LDB(B0, 0, 0); PG8_LDB(B1, 0, 1); PG8_SCHED; PG8_LDA(At, 0, 0); PG8_STAGE(PG8_SA(1, 1), a1 + hstepA, voffA);
;             PG8_WAIT_V(8); PG8_WAIT_L(0); PG8_BAR; PG8_MMA(0, 0, At, B0); PG8_MMA(0, 1, At, B1); PG8_BAR; PG8_SCHED;
;             PG8_LDA(At, 0, 1); PG8_STAGE(PG8_SB(0, 0), b2, voffB); PG8_STAGE(PG8_SB(0, 1), b2 + hstep, voffB); PG8_STAGE(PG8_SA(0, 0), a2, voffA);
;             PG8_WAIT_V(8); PG8_WAIT_L(0); PG8_BAR; PG8_MMA(1, 0, At, B0); PG8_MMA(1, 1, At, B1); PG8_BAR; PG8_SCHED;
	ds_read_b128 v[116:119], v8
	ds_read_b128 v[120:123], v8 offset:1024
	ds_read_b128 v[124:127], v8 offset:2048
	ds_read_b128 v[134:137], v8 offset:3072
	ds_read_b128 v[146:149], v9
	ds_read_b128 v[150:153], v9 offset:1024
	ds_read_b128 v[170:173], v9 offset:2048
	ds_read_b128 v[174:177], v9 offset:3072
	s_add_u32 s50, s56, 0x18280
	s_addc_u32 s51, s57, 0
	s_mov_b32 m0, s70
	v_lshl_add_u64 v[8:9], s[50:51], 0, v[132:133]
	ds_read_b128 v[178:181], v145
	ds_read_b128 v[194:197], v145 offset:1024
	ds_read_b128 v[198:201], v145 offset:2048
	ds_read_b128 v[202:205], v145 offset:3072
	ds_read_b128 v[206:209], v145 offset:4096
	ds_read_b128 v[210:213], v145 offset:5120
	ds_read_b128 v[214:217], v145 offset:6144
	ds_read_b128 v[218:221], v145 offset:7168
	global_load_lds_dwordx4 v[8:9], off
	v_lshl_add_u64 v[8:9], s[50:51], 0, v[130:131]
	s_mov_b32 m0, s14
	s_nop 0
	global_load_lds_dwordx4 v[8:9], off
	s_waitcnt vmcnt(8)
	s_waitcnt lgkmcnt(0)
	s_barrier
	s_setprio 1
	s_waitcnt lgkmcnt(0)
	v_mfma_f32_16x16x32_bf16 v[64:67], v[116:119], v[178:181], v[64:67]
	v_mfma_f32_16x16x32_bf16 v[68:71], v[124:127], v[178:181], v[68:71]
	v_mfma_f32_16x16x32_bf16 v[72:75], v[116:119], v[198:201], v[72:75]
	v_mfma_f32_16x16x32_bf16 v[76:79], v[124:127], v[198:201], v[76:79]
	v_mfma_f32_16x16x32_bf16 v[80:83], v[116:119], v[206:209], v[80:83]
	v_mfma_f32_16x16x32_bf16 v[84:87], v[124:127], v[206:209], v[84:87]
	v_mfma_f32_16x16x32_bf16 v[88:91], v[116:119], v[214:217], v[88:91]
	v_mfma_f32_16x16x32_bf16 v[64:67], v[120:123], v[194:197], v[64:67]
	v_mfma_f32_16x16x32_bf16 v[68:71], v[134:137], v[194:197], v[68:71]
	v_mfma_f32_16x16x32_bf16 v[72:75], v[120:123], v[202:205], v[72:75]
	v_mfma_f32_16x16x32_bf16 v[76:79], v[134:137], v[202:205], v[76:79]
	v_mfma_f32_16x16x32_bf16 v[80:83], v[120:123], v[210:213], v[80:83]
	v_mfma_f32_16x16x32_bf16 v[84:87], v[134:137], v[210:213], v[84:87]
	v_mfma_f32_16x16x32_bf16 v[222:225], v[120:123], v[218:221], v[88:91]
	v_mfma_f32_16x16x32_bf16 v[88:91], v[124:127], v[214:217], v[92:95]
	v_mfma_f32_16x16x32_bf16 v[226:229], v[134:137], v[218:221], v[88:91]
	s_setprio 0
	s_setprio 1
	v_mfma_f32_16x16x32_bf16 v[88:91], v[146:149], v[178:181], v[96:99]
	v_mfma_f32_16x16x32_bf16 v[96:99], v[150:153], v[194:197], v[88:91]
	v_mfma_f32_16x16x32_bf16 v[88:91], v[170:173], v[178:181], v[100:103]
	v_mfma_f32_16x16x32_bf16 v[40:43], v[170:173], v[198:201], v[40:43]
	v_mfma_f32_16x16x32_bf16 v[44:47], v[146:149], v[206:209], v[44:47]
	v_mfma_f32_16x16x32_bf16 v[48:51], v[170:173], v[206:209], v[48:51]
	v_mfma_f32_16x16x32_bf16 v[52:55], v[146:149], v[214:217], v[52:55]
	v_mfma_f32_16x16x32_bf16 v[56:59], v[170:173], v[214:217], v[56:59]
	v_mfma_f32_16x16x32_bf16 v[100:103], v[174:177], v[194:197], v[88:91]
	v_mfma_f32_16x16x32_bf16 v[88:91], v[146:149], v[198:201], v[104:107]
	v_mfma_f32_16x16x32_bf16 v[40:43], v[174:177], v[202:205], v[40:43]
	v_mfma_f32_16x16x32_bf16 v[44:47], v[150:153], v[210:213], v[44:47]
	v_mfma_f32_16x16x32_bf16 v[48:51], v[174:177], v[210:213], v[48:51]
	v_mfma_f32_16x16x32_bf16 v[52:55], v[150:153], v[218:221], v[52:55]
	v_mfma_f32_16x16x32_bf16 v[56:59], v[174:177], v[218:221], v[56:59]
	v_mfma_f32_16x16x32_bf16 v[178:181], v[150:153], v[202:205], v[88:91]
	s_setprio 2
	s_barrier
	s_mov_b32 m0, s52
	v_lshl_add_u64 v[138:139], s[46:47], 0, v[184:185]
	s_add_u32 s14, s46, 0x18000
	ds_read_b128 v[88:91], v145 offset:16384
	ds_read_b128 v[92:95], v145 offset:17408
	ds_read_b128 v[104:107], v145 offset:18432
	ds_read_b128 v[194:197], v145 offset:19456
	ds_read_b128 v[198:201], v145 offset:20480
	ds_read_b128 v[202:205], v145 offset:21504
	ds_read_b128 v[206:209], v145 offset:22528
	ds_read_b128 v[210:213], v145 offset:23552
	global_load_lds_dwordx4 v[138:139], off
	v_lshl_add_u64 v[142:143], s[46:47], 0, v[128:129]
	s_mov_b32 m0, s15
	s_addc_u32 s15, s47, 0
	global_load_lds_dwordx4 v[142:143], off
	v_lshl_add_u64 v[8:9], s[14:15], 0, v[184:185]
	s_mov_b32 m0, s36
	v_lshl_add_u64 v[182:183], s[44:45], 0, v[132:133]
	global_load_lds_dwordx4 v[8:9], off
	v_lshl_add_u64 v[8:9], s[14:15], 0, v[128:129]
	s_mov_b32 m0, s37
	v_lshl_add_u64 v[190:191], s[44:45], 0, v[130:131]
	global_load_lds_dwordx4 v[8:9], off
	s_mov_b32 m0, s59
	s_nop 0
	global_load_lds_dwordx4 v[182:183], off
	s_mov_b32 m0, s60
	s_nop 0
	global_load_lds_dwordx4 v[190:191], off
	s_waitcnt vmcnt(8)
	s_waitcnt lgkmcnt(0)
	s_barrier
	s_setprio 1
	s_waitcnt lgkmcnt(0)
	v_mfma_f32_16x16x32_bf16 v[0:3], v[116:119], v[88:91], v[0:3]
	v_mfma_f32_16x16x32_bf16 v[4:7], v[124:127], v[88:91], v[4:7]
	v_mfma_f32_16x16x32_bf16 v[12:15], v[116:119], v[206:209], v[12:15]
	v_mfma_f32_16x16x32_bf16 v[16:19], v[124:127], v[206:209], v[16:19]
	v_mfma_f32_16x16x32_bf16 v[0:3], v[120:123], v[92:95], v[0:3]
	v_mfma_f32_16x16x32_bf16 v[4:7], v[134:137], v[92:95], v[4:7]
	v_mfma_f32_16x16x32_bf16 v[154:157], v[116:119], v[104:107], v[154:157]
	v_mfma_f32_16x16x32_bf16 v[158:161], v[124:127], v[104:107], v[158:161]
	v_mfma_f32_16x16x32_bf16 v[162:165], v[116:119], v[198:201], v[162:165]
	v_mfma_f32_16x16x32_bf16 v[166:169], v[124:127], v[198:201], v[166:169]
	v_mfma_f32_16x16x32_bf16 v[12:15], v[120:123], v[210:213], v[12:15]
	v_mfma_f32_16x16x32_bf16 v[16:19], v[134:137], v[210:213], v[16:19]
	v_mfma_f32_16x16x32_bf16 v[154:157], v[120:123], v[194:197], v[154:157]
	v_mfma_f32_16x16x32_bf16 v[158:161], v[134:137], v[194:197], v[158:161]
	v_mfma_f32_16x16x32_bf16 v[162:165], v[120:123], v[202:205], v[162:165]
	v_mfma_f32_16x16x32_bf16 v[166:169], v[134:137], v[202:205], v[166:169]
	s_setprio 0
	s_setprio 1
	v_mfma_f32_16x16x32_bf16 v[60:63], v[170:173], v[104:107], v[60:63]
	v_mfma_f32_16x16x32_bf16 v[20:23], v[146:149], v[88:91], v[20:23]
	v_mfma_f32_16x16x32_bf16 v[32:35], v[170:173], v[88:91], v[32:35]
	v_mfma_f32_16x16x32_bf16 v[36:39], v[146:149], v[104:107], v[36:39]
	v_mfma_f32_16x16x32_bf16 v[134:137], v[174:177], v[194:197], v[60:63]
	v_mfma_f32_16x16x32_bf16 v[60:63], v[146:149], v[198:201], v[108:111]
	v_mfma_f32_16x16x32_bf16 v[24:27], v[146:149], v[206:209], v[24:27]
	v_mfma_f32_16x16x32_bf16 v[20:23], v[150:153], v[92:95], v[20:23]
	v_mfma_f32_16x16x32_bf16 v[32:35], v[174:177], v[92:95], v[32:35]
	v_mfma_f32_16x16x32_bf16 v[36:39], v[150:153], v[194:197], v[36:39]
	v_mfma_f32_16x16x32_bf16 v[194:197], v[150:153], v[202:205], v[60:63]
	v_mfma_f32_16x16x32_bf16 v[60:63], v[170:173], v[198:201], v[112:115]
	v_mfma_f32_16x16x32_bf16 v[146:149], v[150:153], v[210:213], v[24:27]
	v_mfma_f32_16x16x32_bf16 v[24:27], v[170:173], v[206:209], v[28:31]
	v_mfma_f32_16x16x32_bf16 v[198:201], v[174:177], v[202:205], v[60:63]
	v_mfma_f32_16x16x32_bf16 v[150:153], v[174:177], v[210:213], v[24:27]
	s_setprio 2
	s_barrier
; #define PG8_STAGE(bufoff, gbase, voff) do { _Pragma("unroll") for (int _i = 0; _i < 2; ++_i) \
;         __builtin_amdgcn_global_load_lds((const unsigned*)((const char*)(gbase) + (voff)[_i]), (PG8_LAS unsigned*)(lds + (bufoff) + ldsw + _i * 8192), 16, 0, 0); } while (0)
; #define PG8_LDA(dst, b, h) do { _Pragma("unroll") for (int m = 0; m < 4; ++m) _Pragma("unroll") for (int k = 0; k < 2; ++k) dst[m][k] = *(const PG8_LAS bf16x8*)(lds + PG8_SA(b, h) + aoff + m * 2048 + k * 1024); } while (0)
; #define PG8_LDB(dst, b, h) do { _Pragma("unroll") for (int n = 0; n < 2; ++n) _Pragma("unroll") for (int k = 0; k < 2; ++k) dst[n][k] = *(const PG8_LAS bf16x8*)(lds + PG8_SB(b, h) + boff + n * 2048 + k * 1024); } while (0)
; #define PG8_MMA(ai, bj, At, Bt) do { __builtin_amdgcn_s_setprio(1); _Pragma("unroll") for (int m = 0; m < 4; ++m) _Pragma("unroll") for (int n = 0; n < 2; ++n) _Pragma("unroll") for (int k = 0; k < 2; ++k) \
;         acc[ai][bj][m][n] = __builtin_amdgcn_mfma_f32_16x16x32_bf16(Bt[n][k], At[m][k], acc[ai][bj][m][n], 0, 0, 0); __builtin_amdgcn_s_setprio(0); } while (0)
; #define PG8_WAIT_V(n) asm volatile("s_waitcnt vmcnt(" #n ")" ::: "memory")
; #define PG8_WAIT_L(n) asm volatile("s_waitcnt lgkmcnt(" #n ")" ::: "memory")
; #define PG8_BAR __builtin_amdgcn_s_barrier()
; #define PG8_SCHED __builtin_amdgcn_sched_barrier(0)
; template <class Epi, class Sched, bool ALIGN_EPI = false, bool SP2 = false>
; __device__ __forceinline__ void gemm_phase(PG8_LAS unsigned char* lds, const Gemm g, const Sched& S, const Epi& E, const int tid_in) {
;     ...
;             PG8_LDB(B0, 1, 0); PG8_LDB(B1, 1, 1); PG8_SCHED; PG8_LDA(At, 1, 0); PG8_STAGE(PG8_SA(0, 1), a2 + hstepA, voffA);
;             PG8_WAIT_V(8); PG8_WAIT_L(0); PG8_BAR; PG8_MMA(0, 0, At, B0); PG8_MMA(0, 1, At, B1); PG8_BAR; PG8_SCHED;
;             PG8_LDA(At, 1, 1); PG8_STAGE(PG8_SB(1, 0), b3, voffB); PG8_STAGE(PG8_SB(1, 1), b3 + hstep, voffB); PG8_STAGE(PG8_SA(1, 0), a3, voffA);
;             PG8_WAIT_V(8); PG8_WAIT_L(0); PG8_BAR; PG8_MMA(1, 0, At, B0); PG8_MMA(1, 1, At, B1); PG8_BAR; PG8_SCHED;
;     ...
;         if constexpr (ALIGN_EPI) { if (wr == 0) PG8_BAR; }
	ds_read_b128 v[170:173], v10
	ds_read_b128 v[174:177], v10 offset:1024
	ds_read_b128 v[202:205], v10 offset:2048
	ds_read_b128 v[206:209], v10 offset:3072
	ds_read_b128 v[210:213], v11
	ds_read_b128 v[214:217], v11 offset:1024
	ds_read_b128 v[218:221], v11 offset:2048
	ds_read_b128 v[230:233], v11 offset:3072
	s_add_u32 s14, s44, 0x18000
	s_addc_u32 s15, s45, 0
	s_mov_b32 m0, s61
	v_lshl_add_u64 v[88:89], s[14:15], 0, v[132:133]
	ds_read_b128 v[8:11], v145 offset:32768
	ds_read_b128 v[24:27], v145 offset:33792
	ds_read_b128 v[28:31], v145 offset:34816
	ds_read_b128 v[60:63], v145 offset:35840
	ds_read_b128 v[234:237], v145 offset:36864
	ds_read_b128 v[238:241], v145 offset:37888
	ds_read_b128 v[242:245], v145 offset:38912
	ds_read_b128 v[186:189], v145 offset:39936
	global_load_lds_dwordx4 v[88:89], off
	v_lshl_add_u64 v[88:89], s[14:15], 0, v[130:131]
	s_mov_b32 m0, s62
	s_nop 0
	global_load_lds_dwordx4 v[88:89], off
	s_waitcnt vmcnt(8)
	s_waitcnt lgkmcnt(0)
	s_barrier
	s_setprio 1
	s_waitcnt lgkmcnt(0)
	v_mfma_f32_16x16x32_bf16 v[64:67], v[170:173], v[8:11], v[64:67]
	v_mfma_f32_16x16x32_bf16 v[124:127], v[174:177], v[24:27], v[64:67]
	v_mfma_f32_16x16x32_bf16 v[64:67], v[202:205], v[8:11], v[68:71]
	v_mfma_f32_16x16x32_bf16 v[120:123], v[206:209], v[24:27], v[64:67]
	v_mfma_f32_16x16x32_bf16 v[64:67], v[170:173], v[28:31], v[72:75]
	v_mfma_f32_16x16x32_bf16 v[108:111], v[174:177], v[60:63], v[64:67]
	v_mfma_f32_16x16x32_bf16 v[64:67], v[202:205], v[28:31], v[76:79]
	v_mfma_f32_16x16x32_bf16 v[104:107], v[206:209], v[60:63], v[64:67]
	v_mfma_f32_16x16x32_bf16 v[64:67], v[170:173], v[234:237], v[80:83]
	v_mfma_f32_16x16x32_bf16 v[92:95], v[174:177], v[238:241], v[64:67]
	v_mfma_f32_16x16x32_bf16 v[64:67], v[202:205], v[234:237], v[84:87]
	v_mfma_f32_16x16x32_bf16 v[88:91], v[206:209], v[238:241], v[64:67]
	v_mfma_f32_16x16x32_bf16 v[64:67], v[170:173], v[242:245], v[222:225]
	v_mfma_f32_16x16x32_bf16 v[76:79], v[174:177], v[186:189], v[64:67]
	v_mfma_f32_16x16x32_bf16 v[64:67], v[202:205], v[242:245], v[226:229]
	v_mfma_f32_16x16x32_bf16 v[72:75], v[206:209], v[186:189], v[64:67]
	s_setprio 0
	s_setprio 1
	v_mfma_f32_16x16x32_bf16 v[64:67], v[210:213], v[8:11], v[96:99]
	v_mfma_f32_16x16x32_bf16 v[8:11], v[218:221], v[8:11], v[100:103]
	v_mfma_f32_16x16x32_bf16 v[112:115], v[230:233], v[24:27], v[8:11]
	v_mfma_f32_16x16x32_bf16 v[8:11], v[210:213], v[28:31], v[178:181]
	v_mfma_f32_16x16x32_bf16 v[100:103], v[214:217], v[60:63], v[8:11]
	v_mfma_f32_16x16x32_bf16 v[8:11], v[218:221], v[28:31], v[40:43]
	v_mfma_f32_16x16x32_bf16 v[96:99], v[230:233], v[60:63], v[8:11]
	v_mfma_f32_16x16x32_bf16 v[8:11], v[210:213], v[234:237], v[44:47]
	v_mfma_f32_16x16x32_bf16 v[84:87], v[214:217], v[238:241], v[8:11]
	v_mfma_f32_16x16x32_bf16 v[8:11], v[218:221], v[234:237], v[48:51]
	v_mfma_f32_16x16x32_bf16 v[80:83], v[230:233], v[238:241], v[8:11]
	v_mfma_f32_16x16x32_bf16 v[8:11], v[210:213], v[242:245], v[52:55]
	v_mfma_f32_16x16x32_bf16 v[68:71], v[214:217], v[186:189], v[8:11]
	v_mfma_f32_16x16x32_bf16 v[8:11], v[218:221], v[242:245], v[56:59]
	v_mfma_f32_16x16x32_bf16 v[116:119], v[214:217], v[24:27], v[64:67]
	v_mfma_f32_16x16x32_bf16 v[64:67], v[230:233], v[186:189], v[8:11]
	s_setprio 2
	s_barrier
	s_mov_b32 m0, s77
	s_nop 2
	v_lshl_add_u64 v[8:9], v[138:139], 0, s[84:85]
	s_add_u32 s14, s46, 0x18080
	ds_read_b128 v[48:51], v145 offset:49152
	ds_read_b128 v[178:181], v145 offset:50176
	ds_read_b128 v[186:189], v145 offset:51200
	ds_read_b128 v[222:225], v145 offset:52224
	ds_read_b128 v[226:229], v145 offset:53248
	ds_read_b128 v[234:237], v145 offset:54272
	ds_read_b128 v[238:241], v145 offset:55296
	ds_read_b128 v[242:245], v145 offset:56320
	global_load_lds_dwordx4 v[8:9], off
	v_lshl_add_u64 v[8:9], v[142:143], 0, s[84:85]
	s_mov_b32 m0, s53
	s_addc_u32 s15, s47, 0
	global_load_lds_dwordx4 v[8:9], off
	v_lshl_add_u64 v[8:9], s[14:15], 0, v[184:185]
	s_mov_b32 m0, s69
	s_nop 0
	global_load_lds_dwordx4 v[8:9], off
	v_lshl_add_u64 v[8:9], s[14:15], 0, v[128:129]
	s_mov_b32 m0, s71
	s_nop 0
	global_load_lds_dwordx4 v[8:9], off
	v_lshl_add_u64 v[8:9], v[182:183], 0, s[84:85]
	s_mov_b32 m0, s65
	s_nop 0
	global_load_lds_dwordx4 v[8:9], off
	v_lshl_add_u64 v[8:9], v[190:191], 0, s[84:85]
	s_mov_b32 m0, s66
	s_nop 0
	global_load_lds_dwordx4 v[8:9], off
	s_waitcnt vmcnt(8)
	s_waitcnt lgkmcnt(0)
	s_barrier
	s_setprio 1
	s_waitcnt lgkmcnt(0)
	v_mfma_f32_16x16x32_bf16 v[0:3], v[170:173], v[48:51], v[0:3]
	v_mfma_f32_16x16x32_bf16 v[60:63], v[174:177], v[178:181], v[0:3]
	v_mfma_f32_16x16x32_bf16 v[0:3], v[202:205], v[48:51], v[4:7]
	v_mfma_f32_16x16x32_bf16 v[56:59], v[206:209], v[178:181], v[0:3]
	v_mfma_f32_16x16x32_bf16 v[0:3], v[170:173], v[186:189], v[154:157]
	v_mfma_f32_16x16x32_bf16 v[44:47], v[174:177], v[222:225], v[0:3]
	v_mfma_f32_16x16x32_bf16 v[0:3], v[202:205], v[186:189], v[158:161]
	v_mfma_f32_16x16x32_bf16 v[40:43], v[206:209], v[222:225], v[0:3]
	v_mfma_f32_16x16x32_bf16 v[0:3], v[170:173], v[226:229], v[162:165]
	v_mfma_f32_16x16x32_bf16 v[28:31], v[174:177], v[234:237], v[0:3]
	v_mfma_f32_16x16x32_bf16 v[0:3], v[202:205], v[226:229], v[166:169]
	v_mfma_f32_16x16x32_bf16 v[24:27], v[206:209], v[234:237], v[0:3]
	v_mfma_f32_16x16x32_bf16 v[0:3], v[170:173], v[238:241], v[12:15]
	v_mfma_f32_16x16x32_bf16 v[12:15], v[174:177], v[242:245], v[0:3]
	v_mfma_f32_16x16x32_bf16 v[0:3], v[202:205], v[238:241], v[16:19]
	v_mfma_f32_16x16x32_bf16 v[8:11], v[206:209], v[242:245], v[0:3]
	s_setprio 0
	s_setprio 1
	v_mfma_f32_16x16x32_bf16 v[0:3], v[210:213], v[48:51], v[20:23]
	v_mfma_f32_16x16x32_bf16 v[52:55], v[214:217], v[178:181], v[0:3]
	v_mfma_f32_16x16x32_bf16 v[0:3], v[218:221], v[48:51], v[32:35]
	v_mfma_f32_16x16x32_bf16 v[48:51], v[230:233], v[178:181], v[0:3]
	v_mfma_f32_16x16x32_bf16 v[0:3], v[210:213], v[186:189], v[36:39]
	v_mfma_f32_16x16x32_bf16 v[36:39], v[214:217], v[222:225], v[0:3]
	v_mfma_f32_16x16x32_bf16 v[0:3], v[218:221], v[186:189], v[134:137]
	v_mfma_f32_16x16x32_bf16 v[32:35], v[230:233], v[222:225], v[0:3]
	v_mfma_f32_16x16x32_bf16 v[0:3], v[210:213], v[226:229], v[194:197]
	v_mfma_f32_16x16x32_bf16 v[20:23], v[214:217], v[234:237], v[0:3]
	v_mfma_f32_16x16x32_bf16 v[0:3], v[218:221], v[226:229], v[198:201]
	v_mfma_f32_16x16x32_bf16 v[16:19], v[230:233], v[234:237], v[0:3]
	v_mfma_f32_16x16x32_bf16 v[0:3], v[210:213], v[238:241], v[146:149]
	v_mfma_f32_16x16x32_bf16 v[4:7], v[214:217], v[242:245], v[0:3]
	v_mfma_f32_16x16x32_bf16 v[0:3], v[218:221], v[238:241], v[150:153]
	v_mfma_f32_16x16x32_bf16 v[0:3], v[230:233], v[242:245], v[0:3]
	s_setprio 2
	s_barrier
	s_andn2_b64 vcc, exec, s[40:41]
	s_cbranch_vccnz .LBB0_561
	s_barrier

; #define PG8_STAGE(bufoff, gbase, voff) do { _Pragma("unroll") for (int _i = 0; _i < 2; ++_i) \
;         __builtin_amdgcn_global_load_lds((const unsigned*)((const char*)(gbase) + (voff)[_i]), (PG8_LAS unsigned*)(lds + (bufoff) + ldsw + _i * 8192), 16, 0, 0); } while (0)
; #define PG8_LDA(dst, b, h) do { _Pragma("unroll") for (int m = 0; m < 4; ++m) _Pragma("unroll") for (int k = 0; k < 2; ++k) dst[m][k] = *(const PG8_LAS bf16x8*)(lds + PG8_SA(b, h) + aoff + m * 2048 + k * 1024); } while (0)
; #define PG8_LDB(dst, b, h) do { _Pragma("unroll") for (int n = 0; n < 2; ++n) _Pragma("unroll") for (int k = 0; k < 2; ++k) dst[n][k] = *(const PG8_LAS bf16x8*)(lds + PG8_SB(b, h) + boff + n * 2048 + k * 1024); } while (0)
; #define PG8_MMA(ai, bj, At, Bt) do { __builtin_amdgcn_s_setprio(1); _Pragma("unroll") for (int m = 0; m < 4; ++m) _Pragma("unroll") for (int n = 0; n < 2; ++n) _Pragma("unroll") for (int k = 0; k < 2; ++k) \
;         acc[ai][bj][m][n] = __builtin_amdgcn_mfma_f32_16x16x32_bf16(Bt[n][k], At[m][k], acc[ai][bj][m][n], 0, 0, 0); __builtin_amdgcn_s_setprio(0); } while (0)
; #define PG8_WAIT_V(n) asm volatile("s_waitcnt vmcnt(" #n ")" ::: "memory")
; #define PG8_WAIT_L(n) asm volatile("s_waitcnt lgkmcnt(" #n ")" ::: "memory")
; #define PG8_BAR __builtin_amdgcn_s_barrier()
; #define PG8_SCHED __builtin_amdgcn_sched_barrier(0)
; template <class Epi, class Sched, bool ALIGN_EPI = false, bool SP2 = false>
; __device__ __forceinline__ void gemm_phase(PG8_LAS unsigned char* lds, const Gemm g, const Sched& S, const Epi& E, const int tid_in) {
;     ...
;         const char* nA = has_next ? (const char*)((g.A2 && nxt.ph) ? g.A2 : g.A) + (size_t)nxt.pm * tstepA : cA; const char* nB = has_next ? (const char*)((g.A2 && nxt.ph) ? g.Bt2 : g.Bt) + (size_t)nxt.pn * tstep : cB;
;     ...
;             PG8_LDB(B0, 0, 0); PG8_LDB(B1, 0, 1); PG8_SCHED; PG8_LDA(At, 0, 0); PG8_STAGE(PG8_SA(1, 1), a1 + hstepA, voffA);
;             PG8_WAIT_V(8); PG8_WAIT_L(0); PG8_BAR; PG8_MMA(0, 0, At, B0); PG8_MMA(0, 1, At, B1); PG8_BAR; PG8_SCHED;
;             PG8_LDA(At, 0, 1); PG8_STAGE(PG8_SB(0, 0), b2, voffB); PG8_STAGE(PG8_SB(0, 1), b2 + hstep, voffB); PG8_STAGE(PG8_SA(0, 0), a2, voffA);
;             PG8_WAIT_V(8); PG8_WAIT_L(0); PG8_BAR; PG8_MMA(1, 0, At, B0); PG8_MMA(1, 1, At, B1); PG8_BAR; PG8_SCHED;
.LBB0_577:
	s_ashr_i32 s51, s50, 31
	s_lshl_b64 s[14:15], s[50:51], 17
	v_readlane_b32 s6, v255, 30
	v_readlane_b32 s7, v255, 31
	s_add_u32 s56, s6, s14
	s_addc_u32 s57, s7, s15
	s_and_b64 s[14:15], s[36:37], exec
	s_cselect_b32 s63, s57, s65
	s_cselect_b32 s62, s56, s64
	s_ashr_i32 s47, s46, 31
	s_lshl_b64 s[14:15], s[46:47], 17
	s_add_u32 s6, s17, s14
	s_addc_u32 s7, s66, s15
	s_and_b64 s[14:15], s[36:37], exec
	s_cselect_b32 s61, s7, s59
	s_cselect_b32 s60, s6, s58
	s_add_i32 s52, 0, 0x10000
	s_add_i32 s47, 0, 0x14000
	v_add_u32_e32 v138, s52, v139
	v_add_u32_e32 v140, s47, v139
	ds_read_b128 v[0:3], v138
	ds_read_b128 v[4:7], v138 offset:1024
	ds_read_b128 v[8:11], v138 offset:2048
	ds_read_b128 v[12:15], v138 offset:3072
	ds_read_b128 v[16:19], v140
	ds_read_b128 v[20:23], v140 offset:1024
	ds_read_b128 v[24:27], v140 offset:2048
	ds_read_b128 v[28:31], v140 offset:3072
	s_add_u32 s14, s64, 0x10080
	s_addc_u32 s15, s65, 0
	s_add_i32 s77, s67, 0xc000
	v_lshl_add_u64 v[64:65], s[14:15], 0, v[132:133]
	s_mov_b32 m0, s77
	ds_read_b128 v[32:35], v141
	ds_read_b128 v[36:39], v141 offset:1024
	ds_read_b128 v[40:43], v141 offset:2048
	ds_read_b128 v[44:47], v141 offset:3072
	ds_read_b128 v[48:51], v141 offset:4096
	ds_read_b128 v[52:55], v141 offset:5120
	ds_read_b128 v[56:59], v141 offset:6144
	ds_read_b128 v[60:63], v141 offset:7168
	global_load_lds_dwordx4 v[64:65], off
	v_lshl_add_u64 v[64:65], s[14:15], 0, v[130:131]
	s_add_i32 s14, s67, 0xe000
	s_mov_b32 m0, s14
	s_nop 0
	global_load_lds_dwordx4 v[64:65], off
	s_waitcnt vmcnt(8)
	s_waitcnt lgkmcnt(0)
	s_barrier
	s_setprio 1
	s_waitcnt lgkmcnt(0)
	v_mfma_f32_16x16x32_bf16 v[64:67], v[0:3], v[32:35], 0
	v_mfma_f32_16x16x32_bf16 v[68:71], v[8:11], v[32:35], 0
	v_mfma_f32_16x16x32_bf16 v[72:75], v[0:3], v[40:43], 0
	v_mfma_f32_16x16x32_bf16 v[76:79], v[8:11], v[40:43], 0
	v_mfma_f32_16x16x32_bf16 v[80:83], v[0:3], v[48:51], 0
	v_mfma_f32_16x16x32_bf16 v[84:87], v[8:11], v[48:51], 0
	v_mfma_f32_16x16x32_bf16 v[88:91], v[0:3], v[56:59], 0
	v_mfma_f32_16x16x32_bf16 v[92:95], v[8:11], v[56:59], 0
	v_mfma_f32_16x16x32_bf16 v[64:67], v[4:7], v[36:39], v[64:67]
	v_mfma_f32_16x16x32_bf16 v[68:71], v[12:15], v[36:39], v[68:71]
	v_mfma_f32_16x16x32_bf16 v[72:75], v[4:7], v[44:47], v[72:75]
	v_mfma_f32_16x16x32_bf16 v[76:79], v[12:15], v[44:47], v[76:79]
	v_mfma_f32_16x16x32_bf16 v[80:83], v[4:7], v[52:55], v[80:83]
	v_mfma_f32_16x16x32_bf16 v[84:87], v[12:15], v[52:55], v[84:87]
	v_mfma_f32_16x16x32_bf16 v[88:91], v[4:7], v[60:63], v[88:91]
	v_mfma_f32_16x16x32_bf16 v[92:95], v[12:15], v[60:63], v[92:95]
	s_setprio 0
	s_setprio 1
	v_mfma_f32_16x16x32_bf16 v[96:99], v[16:19], v[32:35], 0
	v_mfma_f32_16x16x32_bf16 v[32:35], v[24:27], v[32:35], 0
	v_mfma_f32_16x16x32_bf16 v[96:99], v[20:23], v[36:39], v[96:99]
	v_mfma_f32_16x16x32_bf16 v[32:35], v[28:31], v[36:39], v[32:35]
	v_mfma_f32_16x16x32_bf16 v[36:39], v[16:19], v[40:43], 0
	v_mfma_f32_16x16x32_bf16 v[40:43], v[24:27], v[40:43], 0
	v_mfma_f32_16x16x32_bf16 v[36:39], v[20:23], v[44:47], v[36:39]
	v_mfma_f32_16x16x32_bf16 v[40:43], v[28:31], v[44:47], v[40:43]
	v_mfma_f32_16x16x32_bf16 v[44:47], v[16:19], v[48:51], 0
	v_mfma_f32_16x16x32_bf16 v[48:51], v[24:27], v[48:51], 0
	v_mfma_f32_16x16x32_bf16 v[44:47], v[20:23], v[52:55], v[44:47]
	v_mfma_f32_16x16x32_bf16 v[48:51], v[28:31], v[52:55], v[48:51]
	v_mfma_f32_16x16x32_bf16 v[52:55], v[16:19], v[56:59], 0
	v_mfma_f32_16x16x32_bf16 v[56:59], v[24:27], v[56:59], 0
	v_mfma_f32_16x16x32_bf16 v[52:55], v[20:23], v[60:63], v[52:55]
	v_mfma_f32_16x16x32_bf16 v[56:59], v[28:31], v[60:63], v[56:59]
	s_setprio 2
	s_barrier
	s_add_i32 s52, s52, s16
	v_lshl_add_u64 v[182:183], s[58:59], 0, v[184:185]
	s_add_i32 s15, s52, 0x2000
	v_lshl_add_u64 v[134:135], v[182:183], 0, s[80:81]
	s_mov_b32 m0, s52
	v_lshl_add_u64 v[190:191], s[58:59], 0, v[128:129]
	s_add_u32 vcc_lo, s58, 0x10100
	ds_read_b128 v[60:63], v141 offset:16384
	ds_read_b128 v[100:103], v141 offset:17408
	ds_read_b128 v[104:107], v141 offset:18432
	ds_read_b128 v[108:111], v141 offset:19456
	ds_read_b128 v[112:115], v141 offset:20480
	ds_read_b128 v[116:119], v141 offset:21504
	ds_read_b128 v[120:123], v141 offset:22528
	ds_read_b128 v[124:127], v141 offset:23552
	global_load_lds_dwordx4 v[134:135], off
	v_lshl_add_u64 v[134:135], v[190:191], 0, s[80:81]
	s_mov_b32 m0, s15
	s_addc_u32 vcc_hi, s59, 0
	s_add_i32 s47, s47, s16
	global_load_lds_dwordx4 v[134:135], off
	v_lshl_add_u64 v[134:135], vcc, 0, v[184:185]
	s_mov_b32 m0, s47
	s_add_i32 s51, s47, 0x2000
	global_load_lds_dwordx4 v[134:135], off
	v_lshl_add_u64 v[134:135], vcc, 0, v[128:129]
	s_mov_b32 m0, s51
	v_lshl_add_u64 v[210:211], s[64:65], 0, v[132:133]
	global_load_lds_dwordx4 v[134:135], off
	v_lshl_add_u64 v[134:135], v[210:211], 0, s[80:81]
	s_mov_b32 m0, s67
	v_lshl_add_u64 v[212:213], s[64:65], 0, v[130:131]
	global_load_lds_dwordx4 v[134:135], off
	v_lshl_add_u64 v[134:135], v[212:213], 0, s[80:81]
	s_mov_b32 m0, s68
	s_nop 0
	global_load_lds_dwordx4 v[134:135], off
	s_waitcnt vmcnt(8)
	s_waitcnt lgkmcnt(0)
	s_barrier
; #define PG8_STAGE(bufoff, gbase, voff) do { _Pragma("unroll") for (int _i = 0; _i < 2; ++_i) \
;         __builtin_amdgcn_global_load_lds((const unsigned*)((const char*)(gbase) + (voff)[_i]), (PG8_LAS unsigned*)(lds + (bufoff) + ldsw + _i * 8192), 16, 0, 0); } while (0)
; #define PG8_LDA(dst, b, h) do { _Pragma("unroll") for (int m = 0; m < 4; ++m) _Pragma("unroll") for (int k = 0; k < 2; ++k) dst[m][k] = *(const PG8_LAS bf16x8*)(lds + PG8_SA(b, h) + aoff + m * 2048 + k * 1024); } while (0)
; #define PG8_LDB(dst, b, h) do { _Pragma("unroll") for (int n = 0; n < 2; ++n) _Pragma("unroll") for (int k = 0; k < 2; ++k) dst[n][k] = *(const PG8_LAS bf16x8*)(lds + PG8_SB(b, h) + boff + n * 2048 + k * 1024); } while (0)
; #define PG8_MMA(ai, bj, At, Bt) do { __builtin_amdgcn_s_setprio(1); _Pragma("unroll") for (int m = 0; m < 4; ++m) _Pragma("unroll") for (int n = 0; n < 2; ++n) _Pragma("unroll") for (int k = 0; k < 2; ++k) \
;         acc[ai][bj][m][n] = __builtin_amdgcn_mfma_f32_16x16x32_bf16(Bt[n][k], At[m][k], acc[ai][bj][m][n], 0, 0, 0); __builtin_amdgcn_s_setprio(0); } while (0)
; #define PG8_WAIT_V(n) asm volatile("s_waitcnt vmcnt(" #n ")" ::: "memory")
; #define PG8_WAIT_L(n) asm volatile("s_waitcnt lgkmcnt(" #n ")" ::: "memory")
; #define PG8_BAR __builtin_amdgcn_s_barrier()
; #define PG8_SCHED __builtin_amdgcn_sched_barrier(0)
; template <class Epi, class Sched, bool ALIGN_EPI = false, bool SP2 = false>
; __device__ __forceinline__ void gemm_phase(PG8_LAS unsigned char* lds, const Gemm g, const Sched& S, const Epi& E, const int tid_in) {
;     ...
;             PG8_WAIT_V(8); PG8_WAIT_L(0); PG8_BAR; PG8_MMA(1, 0, At, B0); PG8_MMA(1, 1, At, B1); PG8_BAR; PG8_SCHED;
;             PG8_LDB(B0, 1, 0); PG8_LDB(B1, 1, 1); PG8_SCHED; PG8_LDA(At, 1, 0); PG8_STAGE(PG8_SA(0, 1), a2 + hstepA, voffA);
;             PG8_WAIT_V(8); PG8_WAIT_L(0); PG8_BAR; PG8_MMA(0, 0, At, B0); PG8_MMA(0, 1, At, B1); PG8_BAR; PG8_SCHED;
	s_setprio 1
	s_waitcnt lgkmcnt(0)
	v_mfma_f32_16x16x32_bf16 v[134:137], v[0:3], v[60:63], 0
	v_mfma_f32_16x16x32_bf16 v[146:149], v[0:3], v[104:107], 0
	v_mfma_f32_16x16x32_bf16 v[154:157], v[0:3], v[112:115], 0
	v_mfma_f32_16x16x32_bf16 v[0:3], v[0:3], v[120:123], 0
	v_mfma_f32_16x16x32_bf16 v[134:137], v[4:7], v[100:103], v[134:137]
	v_mfma_f32_16x16x32_bf16 v[146:149], v[4:7], v[108:111], v[146:149]
	v_mfma_f32_16x16x32_bf16 v[154:157], v[4:7], v[116:119], v[154:157]
	v_mfma_f32_16x16x32_bf16 v[0:3], v[4:7], v[124:127], v[0:3]
	v_mfma_f32_16x16x32_bf16 v[4:7], v[8:11], v[120:123], 0
	v_mfma_f32_16x16x32_bf16 v[142:145], v[8:11], v[60:63], 0
	v_mfma_f32_16x16x32_bf16 v[150:153], v[8:11], v[104:107], 0
	v_mfma_f32_16x16x32_bf16 v[158:161], v[8:11], v[112:115], 0
	v_mfma_f32_16x16x32_bf16 v[4:7], v[12:15], v[124:127], v[4:7]
	v_mfma_f32_16x16x32_bf16 v[142:145], v[12:15], v[100:103], v[142:145]
	v_mfma_f32_16x16x32_bf16 v[150:153], v[12:15], v[108:111], v[150:153]
	v_mfma_f32_16x16x32_bf16 v[158:161], v[12:15], v[116:119], v[158:161]
	s_setprio 0
	s_setprio 1
	v_mfma_f32_16x16x32_bf16 v[8:11], v[16:19], v[60:63], 0
	v_mfma_f32_16x16x32_bf16 v[12:15], v[24:27], v[60:63], 0
	v_mfma_f32_16x16x32_bf16 v[8:11], v[20:23], v[100:103], v[8:11]
	v_mfma_f32_16x16x32_bf16 v[12:15], v[28:31], v[100:103], v[12:15]
	v_mfma_f32_16x16x32_bf16 v[60:63], v[16:19], v[104:107], 0
	v_mfma_f32_16x16x32_bf16 v[100:103], v[24:27], v[104:107], 0
	v_mfma_f32_16x16x32_bf16 v[104:107], v[16:19], v[112:115], 0
	v_mfma_f32_16x16x32_bf16 v[16:19], v[16:19], v[120:123], 0
	v_mfma_f32_16x16x32_bf16 v[60:63], v[20:23], v[108:111], v[60:63]
	v_mfma_f32_16x16x32_bf16 v[100:103], v[28:31], v[108:111], v[100:103]
	v_mfma_f32_16x16x32_bf16 v[104:107], v[20:23], v[116:119], v[104:107]
	v_mfma_f32_16x16x32_bf16 v[108:111], v[24:27], v[112:115], 0
	v_mfma_f32_16x16x32_bf16 v[16:19], v[20:23], v[124:127], v[16:19]
	v_mfma_f32_16x16x32_bf16 v[20:23], v[24:27], v[120:123], 0
	v_mfma_f32_16x16x32_bf16 v[108:111], v[28:31], v[116:119], v[108:111]
	v_mfma_f32_16x16x32_bf16 v[20:23], v[28:31], v[124:127], v[20:23]
	s_setprio 2
	s_barrier
	s_add_i32 s34, 0, 0x18000
	s_add_i32 s38, 0, 0x1c000
	v_add_u32_e32 v222, s34, v139
	v_add_u32_e32 v223, s38, v139
	ds_read_b128 v[24:27], v222
	ds_read_b128 v[28:31], v222 offset:1024
	ds_read_b128 v[112:115], v222 offset:2048
	ds_read_b128 v[116:119], v222 offset:3072
	ds_read_b128 v[120:123], v223
	ds_read_b128 v[124:127], v223 offset:1024
	ds_read_b128 v[162:165], v223 offset:2048
	ds_read_b128 v[166:169], v223 offset:3072
	s_add_u32 vcc_lo, s64, 0x10100
	s_addc_u32 vcc_hi, s65, 0
	s_mov_b32 m0, s69
	v_lshl_add_u64 v[214:215], vcc, 0, v[132:133]
	ds_read_b128 v[170:173], v141 offset:32768
	ds_read_b128 v[174:177], v141 offset:33792
	ds_read_b128 v[178:181], v141 offset:34816
	ds_read_b128 v[186:189], v141 offset:35840
	ds_read_b128 v[194:197], v141 offset:36864
	ds_read_b128 v[198:201], v141 offset:37888
	ds_read_b128 v[202:205], v141 offset:38912
	ds_read_b128 v[206:209], v141 offset:39936
	global_load_lds_dwordx4 v[214:215], off
	v_lshl_add_u64 v[214:215], vcc, 0, v[130:131]
	s_mov_b32 m0, s70
	s_nop 0
	global_load_lds_dwordx4 v[214:215], off
	s_waitcnt vmcnt(8)
	s_waitcnt lgkmcnt(0)
	s_barrier
	s_setprio 1
	s_waitcnt lgkmcnt(0)
	v_mfma_f32_16x16x32_bf16 v[64:67], v[24:27], v[170:173], v[64:67]
	v_mfma_f32_16x16x32_bf16 v[68:71], v[112:115], v[170:173], v[68:71]
	v_mfma_f32_16x16x32_bf16 v[72:75], v[24:27], v[178:181], v[72:75]
	v_mfma_f32_16x16x32_bf16 v[76:79], v[112:115], v[178:181], v[76:79]
	v_mfma_f32_16x16x32_bf16 v[80:83], v[24:27], v[194:197], v[80:83]
	v_mfma_f32_16x16x32_bf16 v[84:87], v[112:115], v[194:197], v[84:87]
	v_mfma_f32_16x16x32_bf16 v[88:91], v[24:27], v[202:205], v[88:91]
	v_mfma_f32_16x16x32_bf16 v[92:95], v[112:115], v[202:205], v[92:95]
	v_mfma_f32_16x16x32_bf16 v[64:67], v[28:31], v[174:177], v[64:67]
	v_mfma_f32_16x16x32_bf16 v[68:71], v[116:119], v[174:177], v[68:71]
	v_mfma_f32_16x16x32_bf16 v[72:75], v[28:31], v[186:189], v[72:75]
	v_mfma_f32_16x16x32_bf16 v[76:79], v[116:119], v[186:189], v[76:79]
	v_mfma_f32_16x16x32_bf16 v[80:83], v[28:31], v[198:201], v[80:83]
	v_mfma_f32_16x16x32_bf16 v[84:87], v[116:119], v[198:201], v[84:87]
	v_mfma_f32_16x16x32_bf16 v[88:91], v[28:31], v[206:209], v[88:91]
	v_mfma_f32_16x16x32_bf16 v[92:95], v[116:119], v[206:209], v[92:95]
	s_setprio 0
	s_setprio 1
	v_mfma_f32_16x16x32_bf16 v[96:99], v[120:123], v[170:173], v[96:99]
	v_mfma_f32_16x16x32_bf16 v[32:35], v[162:165], v[170:173], v[32:35]
	v_mfma_f32_16x16x32_bf16 v[36:39], v[120:123], v[178:181], v[36:39]
	v_mfma_f32_16x16x32_bf16 v[40:43], v[162:165], v[178:181], v[40:43]
	v_mfma_f32_16x16x32_bf16 v[44:47], v[120:123], v[194:197], v[44:47]
	v_mfma_f32_16x16x32_bf16 v[48:51], v[162:165], v[194:197], v[48:51]
	v_mfma_f32_16x16x32_bf16 v[52:55], v[120:123], v[202:205], v[52:55]
	v_mfma_f32_16x16x32_bf16 v[56:59], v[162:165], v[202:205], v[56:59]
	v_mfma_f32_16x16x32_bf16 v[96:99], v[124:127], v[174:177], v[96:99]
	v_mfma_f32_16x16x32_bf16 v[32:35], v[166:169], v[174:177], v[32:35]
	v_mfma_f32_16x16x32_bf16 v[36:39], v[124:127], v[186:189], v[36:39]
	v_mfma_f32_16x16x32_bf16 v[40:43], v[166:169], v[186:189], v[40:43]
	v_mfma_f32_16x16x32_bf16 v[44:47], v[124:127], v[198:201], v[44:47]
	v_mfma_f32_16x16x32_bf16 v[48:51], v[166:169], v[198:201], v[48:51]
	v_mfma_f32_16x16x32_bf16 v[52:55], v[124:127], v[206:209], v[52:55]
	v_mfma_f32_16x16x32_bf16 v[56:59], v[166:169], v[206:209], v[56:59]
	s_setprio 2
	s_barrier
; #define PG8_STAGE(bufoff, gbase, voff) do { _Pragma("unroll") for (int _i = 0; _i < 2; ++_i) \
;         __builtin_amdgcn_global_load_lds((const unsigned*)((const char*)(gbase) + (voff)[_i]), (PG8_LAS unsigned*)(lds + (bufoff) + ldsw + _i * 8192), 16, 0, 0); } while (0)
; #define PG8_LDA(dst, b, h) do { _Pragma("unroll") for (int m = 0; m < 4; ++m) _Pragma("unroll") for (int k = 0; k < 2; ++k) dst[m][k] = *(const PG8_LAS bf16x8*)(lds + PG8_SA(b, h) + aoff + m * 2048 + k * 1024); } while (0)
; #define PG8_LDB(dst, b, h) do { _Pragma("unroll") for (int n = 0; n < 2; ++n) _Pragma("unroll") for (int k = 0; k < 2; ++k) dst[n][k] = *(const PG8_LAS bf16x8*)(lds + PG8_SB(b, h) + boff + n * 2048 + k * 1024); } while (0)
; #define PG8_MMA(ai, bj, At, Bt) do { __builtin_amdgcn_s_setprio(1); _Pragma("unroll") for (int m = 0; m < 4; ++m) _Pragma("unroll") for (int n = 0; n < 2; ++n) _Pragma("unroll") for (int k = 0; k < 2; ++k) \
;         acc[ai][bj][m][n] = __builtin_amdgcn_mfma_f32_16x16x32_bf16(Bt[n][k], At[m][k], acc[ai][bj][m][n], 0, 0, 0); __builtin_amdgcn_s_setprio(0); } while (0)
; #define PG8_WAIT_V(n) asm volatile("s_waitcnt vmcnt(" #n ")" ::: "memory")
; #define PG8_WAIT_L(n) asm volatile("s_waitcnt lgkmcnt(" #n ")" ::: "memory")
; #define PG8_BAR __builtin_amdgcn_s_barrier()
; #define PG8_SCHED __builtin_amdgcn_sched_barrier(0)
; template <class Epi, class Sched, bool ALIGN_EPI = false, bool SP2 = false>
; __device__ __forceinline__ void gemm_phase(PG8_LAS unsigned char* lds, const Gemm g, const Sched& S, const Epi& E, const int tid_in) {
;     ...
;             PG8_LDB(B0, 0, 0); PG8_LDB(B1, 0, 1); PG8_SCHED; PG8_LDA(At, 0, 0); PG8_STAGE(PG8_SA(1, 1), a1 + hstepA, voffA);
;             PG8_WAIT_V(8); PG8_WAIT_L(0); PG8_BAR; PG8_MMA(0, 0, At, B0); PG8_MMA(0, 1, At, B1); PG8_BAR; PG8_SCHED;
;     ...
;             PG8_LDA(At, 1, 1); PG8_STAGE(PG8_SB(1, 0), b3, voffB); PG8_STAGE(PG8_SB(1, 1), b3 + hstep, voffB); PG8_STAGE(PG8_SA(1, 0), a3, voffA);
;             PG8_WAIT_V(8); PG8_WAIT_L(0); PG8_BAR; PG8_MMA(1, 0, At, B0); PG8_MMA(1, 1, At, B1); PG8_BAR; PG8_SCHED;
	s_add_i32 vcc_lo, s34, s16
	s_mov_b64 s[8:9], 0x180
	s_add_i32 s53, vcc_lo, 0x2000
	v_lshl_add_u64 v[182:183], v[182:183], 0, s[8:9]
	s_mov_b32 m0, vcc_lo
	s_add_u32 s34, s58, 0x10180
	ds_read_b128 v[170:173], v141 offset:49152
	ds_read_b128 v[174:177], v141 offset:50176
	ds_read_b128 v[178:181], v141 offset:51200
	ds_read_b128 v[186:189], v141 offset:52224
	ds_read_b128 v[194:197], v141 offset:53248
	ds_read_b128 v[198:201], v141 offset:54272
	ds_read_b128 v[202:205], v141 offset:55296
	ds_read_b128 v[206:209], v141 offset:56320
	global_load_lds_dwordx4 v[182:183], off
	v_lshl_add_u64 v[182:183], v[190:191], 0, s[8:9]
	s_mov_b32 m0, s53
	s_addc_u32 s35, s59, 0
	s_add_i32 s38, s38, s16
	global_load_lds_dwordx4 v[182:183], off
	v_lshl_add_u64 v[182:183], s[34:35], 0, v[184:185]
	s_mov_b32 m0, s38
	s_add_i32 s39, s38, 0x2000
	global_load_lds_dwordx4 v[182:183], off
	v_lshl_add_u64 v[182:183], s[34:35], 0, v[128:129]
	s_mov_b32 m0, s39
	s_nop 0
	global_load_lds_dwordx4 v[182:183], off
	v_lshl_add_u64 v[182:183], v[210:211], 0, s[8:9]
	s_mov_b32 m0, s79
	s_nop 0
	global_load_lds_dwordx4 v[182:183], off
	v_lshl_add_u64 v[182:183], v[212:213], 0, s[8:9]
	s_mov_b32 m0, s88
	s_nop 0
	global_load_lds_dwordx4 v[182:183], off
	s_waitcnt vmcnt(8)
	s_waitcnt lgkmcnt(0)
	s_barrier
	s_setprio 1
	s_waitcnt lgkmcnt(0)
	v_mfma_f32_16x16x32_bf16 v[0:3], v[24:27], v[202:205], v[0:3]
	v_mfma_f32_16x16x32_bf16 v[4:7], v[112:115], v[202:205], v[4:7]
	v_mfma_f32_16x16x32_bf16 v[134:137], v[24:27], v[170:173], v[134:137]
	v_mfma_f32_16x16x32_bf16 v[142:145], v[112:115], v[170:173], v[142:145]
	v_mfma_f32_16x16x32_bf16 v[146:149], v[24:27], v[178:181], v[146:149]
	v_mfma_f32_16x16x32_bf16 v[150:153], v[112:115], v[178:181], v[150:153]
	v_mfma_f32_16x16x32_bf16 v[154:157], v[24:27], v[194:197], v[154:157]
	v_mfma_f32_16x16x32_bf16 v[158:161], v[112:115], v[194:197], v[158:161]
	v_mfma_f32_16x16x32_bf16 v[0:3], v[28:31], v[206:209], v[0:3]
	v_mfma_f32_16x16x32_bf16 v[4:7], v[116:119], v[206:209], v[4:7]
	v_mfma_f32_16x16x32_bf16 v[134:137], v[28:31], v[174:177], v[134:137]
	v_mfma_f32_16x16x32_bf16 v[142:145], v[116:119], v[174:177], v[142:145]
	v_mfma_f32_16x16x32_bf16 v[146:149], v[28:31], v[186:189], v[146:149]
	v_mfma_f32_16x16x32_bf16 v[150:153], v[116:119], v[186:189], v[150:153]
	v_mfma_f32_16x16x32_bf16 v[154:157], v[28:31], v[198:201], v[154:157]
	v_mfma_f32_16x16x32_bf16 v[158:161], v[116:119], v[198:201], v[158:161]
	s_setprio 0
	s_setprio 1
	v_mfma_f32_16x16x32_bf16 v[8:11], v[120:123], v[170:173], v[8:11]
	v_mfma_f32_16x16x32_bf16 v[12:15], v[162:165], v[170:173], v[12:15]
	v_mfma_f32_16x16x32_bf16 v[24:27], v[120:123], v[178:181], v[60:63]
	v_mfma_f32_16x16x32_bf16 v[28:31], v[162:165], v[178:181], v[100:103]
	v_mfma_f32_16x16x32_bf16 v[60:63], v[120:123], v[194:197], v[104:107]
	v_mfma_f32_16x16x32_bf16 v[100:103], v[162:165], v[194:197], v[108:111]
	v_mfma_f32_16x16x32_bf16 v[16:19], v[120:123], v[202:205], v[16:19]
	v_mfma_f32_16x16x32_bf16 v[20:23], v[162:165], v[202:205], v[20:23]
	v_mfma_f32_16x16x32_bf16 v[8:11], v[124:127], v[174:177], v[8:11]
	v_mfma_f32_16x16x32_bf16 v[12:15], v[166:169], v[174:177], v[12:15]
	v_mfma_f32_16x16x32_bf16 v[24:27], v[124:127], v[186:189], v[24:27]
	v_mfma_f32_16x16x32_bf16 v[28:31], v[166:169], v[186:189], v[28:31]
	v_mfma_f32_16x16x32_bf16 v[60:63], v[124:127], v[198:201], v[60:63]
	v_mfma_f32_16x16x32_bf16 v[100:103], v[166:169], v[198:201], v[100:103]
	v_mfma_f32_16x16x32_bf16 v[16:19], v[124:127], v[206:209], v[16:19]
	v_mfma_f32_16x16x32_bf16 v[20:23], v[166:169], v[206:209], v[20:23]
	s_setprio 2
	s_barrier
	ds_read_b128 v[104:107], v138
	ds_read_b128 v[108:111], v138 offset:1024
	ds_read_b128 v[112:115], v138 offset:2048
	ds_read_b128 v[116:119], v138 offset:3072
	ds_read_b128 v[120:123], v140
	ds_read_b128 v[124:127], v140 offset:1024
	ds_read_b128 v[162:165], v140 offset:2048
	ds_read_b128 v[166:169], v140 offset:3072
	s_add_u32 s34, s64, 0x10180
	s_addc_u32 s35, s65, 0
	s_mov_b32 m0, s77
	v_lshl_add_u64 v[182:183], s[34:35], 0, v[132:133]
	ds_read_b128 v[170:173], v141
	ds_read_b128 v[174:177], v141 offset:1024
	ds_read_b128 v[178:181], v141 offset:2048
	ds_read_b128 v[186:189], v141 offset:3072
	ds_read_b128 v[194:197], v141 offset:4096
	ds_read_b128 v[198:201], v141 offset:5120
	ds_read_b128 v[202:205], v141 offset:6144
	ds_read_b128 v[206:209], v141 offset:7168
	global_load_lds_dwordx4 v[182:183], off
	v_lshl_add_u64 v[182:183], s[34:35], 0, v[130:131]
	s_mov_b32 m0, s14
	s_nop 0
	global_load_lds_dwordx4 v[182:183], off
	s_waitcnt vmcnt(8)
	s_waitcnt lgkmcnt(0)
	s_barrier
; #define PG8_STAGE(bufoff, gbase, voff) do { _Pragma("unroll") for (int _i = 0; _i < 2; ++_i) \
;         __builtin_amdgcn_global_load_lds((const unsigned*)((const char*)(gbase) + (voff)[_i]), (PG8_LAS unsigned*)(lds + (bufoff) + ldsw + _i * 8192), 16, 0, 0); } while (0)
; #define PG8_LDA(dst, b, h) do { _Pragma("unroll") for (int m = 0; m < 4; ++m) _Pragma("unroll") for (int k = 0; k < 2; ++k) dst[m][k] = *(const PG8_LAS bf16x8*)(lds + PG8_SA(b, h) + aoff + m * 2048 + k * 1024); } while (0)
; #define PG8_MMA(ai, bj, At, Bt) do { __builtin_amdgcn_s_setprio(1); _Pragma("unroll") for (int m = 0; m < 4; ++m) _Pragma("unroll") for (int n = 0; n < 2; ++n) _Pragma("unroll") for (int k = 0; k < 2; ++k) \
;         acc[ai][bj][m][n] = __builtin_amdgcn_mfma_f32_16x16x32_bf16(Bt[n][k], At[m][k], acc[ai][bj][m][n], 0, 0, 0); __builtin_amdgcn_s_setprio(0); } while (0)
; #define PG8_WAIT_V(n) asm volatile("s_waitcnt vmcnt(" #n ")" ::: "memory")
; #define PG8_WAIT_L(n) asm volatile("s_waitcnt lgkmcnt(" #n ")" ::: "memory")
; #define PG8_BAR __builtin_amdgcn_s_barrier()
; #define PG8_SCHED __builtin_amdgcn_sched_barrier(0)
; template <class Epi, class Sched, bool ALIGN_EPI = false, bool SP2 = false>
; __device__ __forceinline__ void gemm_phase(PG8_LAS unsigned char* lds, const Gemm g, const Sched& S, const Epi& E, const int tid_in) {
;     ...
;             PG8_WAIT_V(8); PG8_WAIT_L(0); PG8_BAR; PG8_MMA(0, 0, At, B0); PG8_MMA(0, 1, At, B1); PG8_BAR; PG8_SCHED;
;             PG8_LDA(At, 0, 1); PG8_STAGE(PG8_SB(0, 0), b2, voffB); PG8_STAGE(PG8_SB(0, 1), b2 + hstep, voffB); PG8_STAGE(PG8_SA(0, 0), a2, voffA);
;             PG8_WAIT_V(8); PG8_WAIT_L(0); PG8_BAR; PG8_MMA(1, 0, At, B0); PG8_MMA(1, 1, At, B1); PG8_BAR; PG8_SCHED;
	s_setprio 1
	s_waitcnt lgkmcnt(0)
	v_mfma_f32_16x16x32_bf16 v[64:67], v[104:107], v[170:173], v[64:67]
	v_mfma_f32_16x16x32_bf16 v[68:71], v[112:115], v[170:173], v[68:71]
	v_mfma_f32_16x16x32_bf16 v[72:75], v[104:107], v[178:181], v[72:75]
	v_mfma_f32_16x16x32_bf16 v[76:79], v[112:115], v[178:181], v[76:79]
	v_mfma_f32_16x16x32_bf16 v[80:83], v[104:107], v[194:197], v[80:83]
	v_mfma_f32_16x16x32_bf16 v[84:87], v[112:115], v[194:197], v[84:87]
	v_mfma_f32_16x16x32_bf16 v[88:91], v[104:107], v[202:205], v[88:91]
	v_mfma_f32_16x16x32_bf16 v[64:67], v[108:111], v[174:177], v[64:67]
	v_mfma_f32_16x16x32_bf16 v[68:71], v[116:119], v[174:177], v[68:71]
	v_mfma_f32_16x16x32_bf16 v[72:75], v[108:111], v[186:189], v[72:75]
	v_mfma_f32_16x16x32_bf16 v[76:79], v[116:119], v[186:189], v[76:79]
	v_mfma_f32_16x16x32_bf16 v[80:83], v[108:111], v[198:201], v[80:83]
	v_mfma_f32_16x16x32_bf16 v[84:87], v[116:119], v[198:201], v[84:87]
	v_mfma_f32_16x16x32_bf16 v[210:213], v[108:111], v[206:209], v[88:91]
	v_mfma_f32_16x16x32_bf16 v[88:91], v[112:115], v[202:205], v[92:95]
	v_mfma_f32_16x16x32_bf16 v[214:217], v[116:119], v[206:209], v[88:91]
	s_setprio 0
	s_setprio 1
	v_mfma_f32_16x16x32_bf16 v[88:91], v[120:123], v[170:173], v[96:99]
	v_mfma_f32_16x16x32_bf16 v[32:35], v[162:165], v[170:173], v[32:35]
	v_mfma_f32_16x16x32_bf16 v[36:39], v[120:123], v[178:181], v[36:39]
	v_mfma_f32_16x16x32_bf16 v[40:43], v[162:165], v[178:181], v[40:43]
	v_mfma_f32_16x16x32_bf16 v[44:47], v[120:123], v[194:197], v[44:47]
	v_mfma_f32_16x16x32_bf16 v[48:51], v[162:165], v[194:197], v[48:51]
	v_mfma_f32_16x16x32_bf16 v[52:55], v[120:123], v[202:205], v[52:55]
	v_mfma_f32_16x16x32_bf16 v[56:59], v[162:165], v[202:205], v[56:59]
	v_mfma_f32_16x16x32_bf16 v[96:99], v[124:127], v[174:177], v[88:91]
	v_mfma_f32_16x16x32_bf16 v[32:35], v[166:169], v[174:177], v[32:35]
	v_mfma_f32_16x16x32_bf16 v[36:39], v[124:127], v[186:189], v[36:39]
	v_mfma_f32_16x16x32_bf16 v[40:43], v[166:169], v[186:189], v[40:43]
	v_mfma_f32_16x16x32_bf16 v[44:47], v[124:127], v[198:201], v[44:47]
	v_mfma_f32_16x16x32_bf16 v[48:51], v[166:169], v[198:201], v[48:51]
	v_mfma_f32_16x16x32_bf16 v[52:55], v[124:127], v[206:209], v[52:55]
	v_mfma_f32_16x16x32_bf16 v[56:59], v[166:169], v[206:209], v[56:59]
	s_setprio 2
	s_barrier
	s_mov_b32 m0, s52
	v_lshl_add_u64 v[182:183], s[60:61], 0, v[184:185]
	s_add_u32 s14, s60, 0x10000
	ds_read_b128 v[88:91], v141 offset:16384
	ds_read_b128 v[92:95], v141 offset:17408
	ds_read_b128 v[170:173], v141 offset:18432
	ds_read_b128 v[174:177], v141 offset:19456
	ds_read_b128 v[178:181], v141 offset:20480
	ds_read_b128 v[186:189], v141 offset:21504
	ds_read_b128 v[194:197], v141 offset:22528
	ds_read_b128 v[198:201], v141 offset:23552
	global_load_lds_dwordx4 v[182:183], off
	v_lshl_add_u64 v[190:191], s[60:61], 0, v[128:129]
	s_mov_b32 m0, s15
	s_addc_u32 s15, s61, 0
	global_load_lds_dwordx4 v[190:191], off
	v_lshl_add_u64 v[202:203], s[14:15], 0, v[184:185]
	s_mov_b32 m0, s47
	v_lshl_add_u64 v[246:247], s[62:63], 0, v[132:133]
	global_load_lds_dwordx4 v[202:203], off
	v_lshl_add_u64 v[202:203], s[14:15], 0, v[128:129]
	s_mov_b32 m0, s51
	v_lshl_add_u64 v[192:193], s[62:63], 0, v[130:131]
	global_load_lds_dwordx4 v[202:203], off
	s_mov_b32 m0, s67
	s_nop 0
	global_load_lds_dwordx4 v[246:247], off
	s_mov_b32 m0, s68
	s_nop 0
	global_load_lds_dwordx4 v[192:193], off
	s_waitcnt vmcnt(8)
	s_waitcnt lgkmcnt(0)
	s_barrier
	s_setprio 1
	s_waitcnt lgkmcnt(0)
	v_mfma_f32_16x16x32_bf16 v[0:3], v[104:107], v[194:197], v[0:3]
	v_mfma_f32_16x16x32_bf16 v[4:7], v[112:115], v[194:197], v[4:7]
	v_mfma_f32_16x16x32_bf16 v[134:137], v[104:107], v[88:91], v[134:137]
	v_mfma_f32_16x16x32_bf16 v[142:145], v[112:115], v[88:91], v[142:145]
	v_mfma_f32_16x16x32_bf16 v[146:149], v[104:107], v[170:173], v[146:149]
	v_mfma_f32_16x16x32_bf16 v[150:153], v[112:115], v[170:173], v[150:153]
	v_mfma_f32_16x16x32_bf16 v[154:157], v[104:107], v[178:181], v[154:157]
	v_mfma_f32_16x16x32_bf16 v[158:161], v[112:115], v[178:181], v[158:161]
	v_mfma_f32_16x16x32_bf16 v[0:3], v[108:111], v[198:201], v[0:3]
	v_mfma_f32_16x16x32_bf16 v[4:7], v[116:119], v[198:201], v[4:7]
	v_mfma_f32_16x16x32_bf16 v[134:137], v[108:111], v[92:95], v[134:137]
	v_mfma_f32_16x16x32_bf16 v[142:145], v[116:119], v[92:95], v[142:145]
	v_mfma_f32_16x16x32_bf16 v[146:149], v[108:111], v[174:177], v[146:149]
	v_mfma_f32_16x16x32_bf16 v[150:153], v[116:119], v[174:177], v[150:153]
	v_mfma_f32_16x16x32_bf16 v[154:157], v[108:111], v[186:189], v[154:157]
	v_mfma_f32_16x16x32_bf16 v[158:161], v[116:119], v[186:189], v[158:161]
	s_setprio 0
	s_setprio 1
	v_mfma_f32_16x16x32_bf16 v[8:11], v[120:123], v[88:91], v[8:11]
	v_mfma_f32_16x16x32_bf16 v[202:205], v[124:127], v[92:95], v[8:11]
	v_mfma_f32_16x16x32_bf16 v[8:11], v[162:165], v[88:91], v[12:15]
	v_mfma_f32_16x16x32_bf16 v[206:209], v[166:169], v[92:95], v[8:11]
	v_mfma_f32_16x16x32_bf16 v[8:11], v[120:123], v[170:173], v[24:27]
	v_mfma_f32_16x16x32_bf16 v[218:221], v[124:127], v[174:177], v[8:11]
	v_mfma_f32_16x16x32_bf16 v[8:11], v[162:165], v[170:173], v[28:31]
	v_mfma_f32_16x16x32_bf16 v[170:173], v[166:169], v[174:177], v[8:11]
	v_mfma_f32_16x16x32_bf16 v[8:11], v[120:123], v[178:181], v[60:63]
	v_mfma_f32_16x16x32_bf16 v[174:177], v[124:127], v[186:189], v[8:11]
	v_mfma_f32_16x16x32_bf16 v[8:11], v[162:165], v[178:181], v[100:103]
	v_mfma_f32_16x16x32_bf16 v[178:181], v[166:169], v[186:189], v[8:11]
	v_mfma_f32_16x16x32_bf16 v[8:11], v[120:123], v[194:197], v[16:19]
	v_mfma_f32_16x16x32_bf16 v[186:189], v[124:127], v[198:201], v[8:11]
	v_mfma_f32_16x16x32_bf16 v[8:11], v[162:165], v[194:197], v[20:23]
	v_mfma_f32_16x16x32_bf16 v[162:165], v[166:169], v[198:201], v[8:11]
	s_setprio 2
	s_barrier
; #define PG8_STAGE(bufoff, gbase, voff) do { _Pragma("unroll") for (int _i = 0; _i < 2; ++_i) \
;         __builtin_amdgcn_global_load_lds((const unsigned*)((const char*)(gbase) + (voff)[_i]), (PG8_LAS unsigned*)(lds + (bufoff) + ldsw + _i * 8192), 16, 0, 0); } while (0)
; #define PG8_LDA(dst, b, h) do { _Pragma("unroll") for (int m = 0; m < 4; ++m) _Pragma("unroll") for (int k = 0; k < 2; ++k) dst[m][k] = *(const PG8_LAS bf16x8*)(lds + PG8_SA(b, h) + aoff + m * 2048 + k * 1024); } while (0)
; #define PG8_LDB(dst, b, h) do { _Pragma("unroll") for (int n = 0; n < 2; ++n) _Pragma("unroll") for (int k = 0; k < 2; ++k) dst[n][k] = *(const PG8_LAS bf16x8*)(lds + PG8_SB(b, h) + boff + n * 2048 + k * 1024); } while (0)
; #define PG8_MMA(ai, bj, At, Bt) do { __builtin_amdgcn_s_setprio(1); _Pragma("unroll") for (int m = 0; m < 4; ++m) _Pragma("unroll") for (int n = 0; n < 2; ++n) _Pragma("unroll") for (int k = 0; k < 2; ++k) \
;         acc[ai][bj][m][n] = __builtin_amdgcn_mfma_f32_16x16x32_bf16(Bt[n][k], At[m][k], acc[ai][bj][m][n], 0, 0, 0); __builtin_amdgcn_s_setprio(0); } while (0)
; #define PG8_WAIT_V(n) asm volatile("s_waitcnt vmcnt(" #n ")" ::: "memory")
; #define PG8_WAIT_L(n) asm volatile("s_waitcnt lgkmcnt(" #n ")" ::: "memory")
; #define PG8_BAR __builtin_amdgcn_s_barrier()
; #define PG8_SCHED __builtin_amdgcn_sched_barrier(0)
; template <class Epi, class Sched, bool ALIGN_EPI = false, bool SP2 = false>
; __device__ __forceinline__ void gemm_phase(PG8_LAS unsigned char* lds, const Gemm g, const Sched& S, const Epi& E, const int tid_in) {
;     ...
;             PG8_LDB(B0, 1, 0); PG8_LDB(B1, 1, 1); PG8_SCHED; PG8_LDA(At, 1, 0); PG8_STAGE(PG8_SA(0, 1), a2 + hstepA, voffA);
;             PG8_WAIT_V(8); PG8_WAIT_L(0); PG8_BAR; PG8_MMA(0, 0, At, B0); PG8_MMA(0, 1, At, B1); PG8_BAR; PG8_SCHED;
;             PG8_LDA(At, 1, 1); PG8_STAGE(PG8_SB(1, 0), b3, voffB); PG8_STAGE(PG8_SB(1, 1), b3 + hstep, voffB); PG8_STAGE(PG8_SA(1, 0), a3, voffA);
;             PG8_WAIT_V(8); PG8_WAIT_L(0); PG8_BAR; PG8_MMA(1, 0, At, B0); PG8_MMA(1, 1, At, B1); PG8_BAR; PG8_SCHED;
;     ...
;         if constexpr (ALIGN_EPI) { if (wr == 0) PG8_BAR; }
	s_nop 4
	ds_read_b128 v[8:11], v222
	ds_read_b128 v[12:15], v222 offset:1024
	ds_read_b128 v[16:19], v222 offset:2048
	ds_read_b128 v[20:23], v222 offset:3072
	ds_read_b128 v[166:169], v223
	ds_read_b128 v[194:197], v223 offset:1024
	ds_read_b128 v[198:201], v223 offset:2048
	ds_read_b128 v[222:225], v223 offset:3072
	s_add_u32 s14, s62, 0x10000
	s_addc_u32 s15, s63, 0
	s_mov_b32 m0, s69
	v_lshl_add_u64 v[88:89], s[14:15], 0, v[132:133]
	ds_read_b128 v[24:27], v141 offset:32768
	ds_read_b128 v[28:31], v141 offset:33792
	ds_read_b128 v[60:63], v141 offset:34816
	ds_read_b128 v[226:229], v141 offset:35840
	ds_read_b128 v[230:233], v141 offset:36864
	ds_read_b128 v[234:237], v141 offset:37888
	ds_read_b128 v[238:241], v141 offset:38912
	ds_read_b128 v[242:245], v141 offset:39936
	global_load_lds_dwordx4 v[88:89], off
	v_lshl_add_u64 v[88:89], s[14:15], 0, v[130:131]
	s_mov_b32 m0, s70
	s_nop 0
	global_load_lds_dwordx4 v[88:89], off
	s_waitcnt vmcnt(8)
	s_waitcnt lgkmcnt(0)
	s_barrier
	s_setprio 1
	s_waitcnt lgkmcnt(0)
	v_mfma_f32_16x16x32_bf16 v[64:67], v[8:11], v[24:27], v[64:67]
	v_mfma_f32_16x16x32_bf16 v[112:115], v[12:15], v[28:31], v[64:67]
	v_mfma_f32_16x16x32_bf16 v[64:67], v[16:19], v[24:27], v[68:71]
	v_mfma_f32_16x16x32_bf16 v[116:119], v[20:23], v[28:31], v[64:67]
	v_mfma_f32_16x16x32_bf16 v[64:67], v[8:11], v[60:63], v[72:75]
	v_mfma_f32_16x16x32_bf16 v[108:111], v[12:15], v[226:229], v[64:67]
	v_mfma_f32_16x16x32_bf16 v[64:67], v[16:19], v[60:63], v[76:79]
	v_mfma_f32_16x16x32_bf16 v[104:107], v[20:23], v[226:229], v[64:67]
	v_mfma_f32_16x16x32_bf16 v[64:67], v[8:11], v[230:233], v[80:83]
	v_mfma_f32_16x16x32_bf16 v[92:95], v[12:15], v[234:237], v[64:67]
	v_mfma_f32_16x16x32_bf16 v[64:67], v[16:19], v[230:233], v[84:87]
	v_mfma_f32_16x16x32_bf16 v[88:91], v[20:23], v[234:237], v[64:67]
	v_mfma_f32_16x16x32_bf16 v[64:67], v[8:11], v[238:241], v[210:213]
	v_mfma_f32_16x16x32_bf16 v[76:79], v[12:15], v[242:245], v[64:67]
	v_mfma_f32_16x16x32_bf16 v[64:67], v[16:19], v[238:241], v[214:217]
	v_mfma_f32_16x16x32_bf16 v[72:75], v[20:23], v[242:245], v[64:67]
	s_setprio 0
	s_setprio 1
	v_mfma_f32_16x16x32_bf16 v[64:67], v[166:169], v[24:27], v[96:99]
	v_mfma_f32_16x16x32_bf16 v[24:27], v[198:201], v[24:27], v[32:35]
	v_mfma_f32_16x16x32_bf16 v[124:127], v[222:225], v[28:31], v[24:27]
	v_mfma_f32_16x16x32_bf16 v[24:27], v[166:169], v[60:63], v[36:39]
	v_mfma_f32_16x16x32_bf16 v[100:103], v[194:197], v[226:229], v[24:27]
	v_mfma_f32_16x16x32_bf16 v[24:27], v[198:201], v[60:63], v[40:43]
	v_mfma_f32_16x16x32_bf16 v[96:99], v[222:225], v[226:229], v[24:27]
	v_mfma_f32_16x16x32_bf16 v[24:27], v[166:169], v[230:233], v[44:47]
	v_mfma_f32_16x16x32_bf16 v[84:87], v[194:197], v[234:237], v[24:27]
	v_mfma_f32_16x16x32_bf16 v[24:27], v[198:201], v[230:233], v[48:51]
	v_mfma_f32_16x16x32_bf16 v[80:83], v[222:225], v[234:237], v[24:27]
	v_mfma_f32_16x16x32_bf16 v[24:27], v[166:169], v[238:241], v[52:55]
	v_mfma_f32_16x16x32_bf16 v[68:71], v[194:197], v[242:245], v[24:27]
	v_mfma_f32_16x16x32_bf16 v[24:27], v[198:201], v[238:241], v[56:59]
	v_mfma_f32_16x16x32_bf16 v[120:123], v[194:197], v[28:31], v[64:67]
	v_mfma_f32_16x16x32_bf16 v[64:67], v[222:225], v[242:245], v[24:27]
	s_setprio 2
	s_barrier
	s_mov_b32 m0, vcc_lo
	s_nop 2
	v_lshl_add_u64 v[24:25], v[182:183], 0, s[84:85]
	s_add_u32 s14, s60, 0x10080
	ds_read_b128 v[32:35], v141 offset:49152
	ds_read_b128 v[36:39], v141 offset:50176
	ds_read_b128 v[210:213], v141 offset:51200
	ds_read_b128 v[214:217], v141 offset:52224
	ds_read_b128 v[226:229], v141 offset:53248
	ds_read_b128 v[230:233], v141 offset:54272
	ds_read_b128 v[234:237], v141 offset:55296
	ds_read_b128 v[238:241], v141 offset:56320
	global_load_lds_dwordx4 v[24:25], off
	v_lshl_add_u64 v[24:25], v[190:191], 0, s[84:85]
	s_mov_b32 m0, s53
	s_addc_u32 s15, s61, 0
	global_load_lds_dwordx4 v[24:25], off
	v_lshl_add_u64 v[24:25], s[14:15], 0, v[184:185]
	s_mov_b32 m0, s38
	s_nop 0
	global_load_lds_dwordx4 v[24:25], off
	v_lshl_add_u64 v[24:25], s[14:15], 0, v[128:129]
	s_mov_b32 m0, s39
	s_nop 0
	global_load_lds_dwordx4 v[24:25], off
	v_lshl_add_u64 v[24:25], v[246:247], 0, s[84:85]
	s_mov_b32 m0, s79
	s_nop 0
	global_load_lds_dwordx4 v[24:25], off
	v_lshl_add_u64 v[24:25], v[192:193], 0, s[84:85]
	s_mov_b32 m0, s88
	s_nop 0
	global_load_lds_dwordx4 v[24:25], off
	s_waitcnt vmcnt(8)
	s_waitcnt lgkmcnt(0)
	s_barrier
	s_setprio 1
	s_waitcnt lgkmcnt(0)
	v_mfma_f32_16x16x32_bf16 v[24:27], v[8:11], v[32:35], v[134:137]
	v_mfma_f32_16x16x32_bf16 v[60:63], v[12:15], v[36:39], v[24:27]
	v_mfma_f32_16x16x32_bf16 v[24:27], v[16:19], v[32:35], v[142:145]
	v_mfma_f32_16x16x32_bf16 v[56:59], v[20:23], v[36:39], v[24:27]
	v_mfma_f32_16x16x32_bf16 v[24:27], v[8:11], v[210:213], v[146:149]
	v_mfma_f32_16x16x32_bf16 v[44:47], v[12:15], v[214:217], v[24:27]
	v_mfma_f32_16x16x32_bf16 v[24:27], v[16:19], v[210:213], v[150:153]
	v_mfma_f32_16x16x32_bf16 v[40:43], v[20:23], v[214:217], v[24:27]
	v_mfma_f32_16x16x32_bf16 v[24:27], v[8:11], v[226:229], v[154:157]
	v_mfma_f32_16x16x32_bf16 v[0:3], v[8:11], v[234:237], v[0:3]
	v_mfma_f32_16x16x32_bf16 v[28:31], v[12:15], v[230:233], v[24:27]
	v_mfma_f32_16x16x32_bf16 v[24:27], v[16:19], v[226:229], v[158:161]
	v_mfma_f32_16x16x32_bf16 v[12:15], v[12:15], v[238:241], v[0:3]
	v_mfma_f32_16x16x32_bf16 v[0:3], v[16:19], v[234:237], v[4:7]
	v_mfma_f32_16x16x32_bf16 v[24:27], v[20:23], v[230:233], v[24:27]
	v_mfma_f32_16x16x32_bf16 v[8:11], v[20:23], v[238:241], v[0:3]
	s_setprio 0
	s_setprio 1
	v_mfma_f32_16x16x32_bf16 v[0:3], v[166:169], v[32:35], v[202:205]
	v_mfma_f32_16x16x32_bf16 v[52:55], v[194:197], v[36:39], v[0:3]
	v_mfma_f32_16x16x32_bf16 v[0:3], v[198:201], v[32:35], v[206:209]
	v_mfma_f32_16x16x32_bf16 v[48:51], v[222:225], v[36:39], v[0:3]
	v_mfma_f32_16x16x32_bf16 v[0:3], v[166:169], v[210:213], v[218:221]
	v_mfma_f32_16x16x32_bf16 v[36:39], v[194:197], v[214:217], v[0:3]
	v_mfma_f32_16x16x32_bf16 v[0:3], v[198:201], v[210:213], v[170:173]
	v_mfma_f32_16x16x32_bf16 v[32:35], v[222:225], v[214:217], v[0:3]
	v_mfma_f32_16x16x32_bf16 v[0:3], v[166:169], v[226:229], v[174:177]
	v_mfma_f32_16x16x32_bf16 v[20:23], v[194:197], v[230:233], v[0:3]
	v_mfma_f32_16x16x32_bf16 v[0:3], v[198:201], v[226:229], v[178:181]
	v_mfma_f32_16x16x32_bf16 v[16:19], v[222:225], v[230:233], v[0:3]
	v_mfma_f32_16x16x32_bf16 v[0:3], v[166:169], v[234:237], v[186:189]
	v_mfma_f32_16x16x32_bf16 v[4:7], v[194:197], v[238:241], v[0:3]
	v_mfma_f32_16x16x32_bf16 v[0:3], v[198:201], v[234:237], v[162:165]
	v_mfma_f32_16x16x32_bf16 v[0:3], v[222:225], v[238:241], v[0:3]
	s_setprio 2
	s_barrier
	s_andn2_b64 vcc, exec, s[42:43]
	s_cbranch_vccnz .LBB0_579
	s_barrier

; #define PG8_STAGE(bufoff, gbase, voff) do { _Pragma("unroll") for (int _i = 0; _i < 2; ++_i) \
;         __builtin_amdgcn_global_load_lds((const unsigned*)((const char*)(gbase) + (voff)[_i]), (PG8_LAS unsigned*)(lds + (bufoff) + ldsw + _i * 8192), 16, 0, 0); } while (0)
; #define PG8_LDA(dst, b, h) do { _Pragma("unroll") for (int m = 0; m < 4; ++m) _Pragma("unroll") for (int k = 0; k < 2; ++k) dst[m][k] = *(const PG8_LAS bf16x8*)(lds + PG8_SA(b, h) + aoff + m * 2048 + k * 1024); } while (0)
; #define PG8_LDB(dst, b, h) do { _Pragma("unroll") for (int n = 0; n < 2; ++n) _Pragma("unroll") for (int k = 0; k < 2; ++k) dst[n][k] = *(const PG8_LAS bf16x8*)(lds + PG8_SB(b, h) + boff + n * 2048 + k * 1024); } while (0)
; #define PG8_MMA(ai, bj, At, Bt) do { __builtin_amdgcn_s_setprio(1); _Pragma("unroll") for (int m = 0; m < 4; ++m) _Pragma("unroll") for (int n = 0; n < 2; ++n) _Pragma("unroll") for (int k = 0; k < 2; ++k) \
;         acc[ai][bj][m][n] = __builtin_amdgcn_mfma_f32_16x16x32_bf16(Bt[n][k], At[m][k], acc[ai][bj][m][n], 0, 0, 0); __builtin_amdgcn_s_setprio(0); } while (0)
; #define PG8_WAIT_V(n) asm volatile("s_waitcnt vmcnt(" #n ")" ::: "memory")
; #define PG8_WAIT_L(n) asm volatile("s_waitcnt lgkmcnt(" #n ")" ::: "memory")
; #define PG8_BAR __builtin_amdgcn_s_barrier()
; #define PG8_SCHED __builtin_amdgcn_sched_barrier(0)
; template <class Epi, class Sched, bool ALIGN_EPI = false, bool SP2 = false>
; __device__ __forceinline__ void gemm_phase(PG8_LAS unsigned char* lds, const Gemm g, const Sched& S, const Epi& E, const int tid_in) {
;     ...
;         const char* nA = has_next ? (const char*)((g.A2 && nxt.ph) ? g.A2 : g.A) + (size_t)nxt.pm * tstepA : cA; const char* nB = has_next ? (const char*)((g.A2 && nxt.ph) ? g.Bt2 : g.Bt) + (size_t)nxt.pn * tstep : cB;
;     ...
;             PG8_LDB(B0, 0, 0); PG8_LDB(B1, 0, 1); PG8_SCHED; PG8_LDA(At, 0, 0); PG8_STAGE(PG8_SA(1, 1), a1 + hstepA, voffA);
;             PG8_WAIT_V(8); PG8_WAIT_L(0); PG8_BAR; PG8_MMA(0, 0, At, B0); PG8_MMA(0, 1, At, B1); PG8_BAR; PG8_SCHED;
;             PG8_LDA(At, 0, 1); PG8_STAGE(PG8_SB(0, 0), b2, voffB); PG8_STAGE(PG8_SB(0, 1), b2 + hstep, voffB); PG8_STAGE(PG8_SA(0, 0), a2, voffA);
;             PG8_WAIT_V(8); PG8_WAIT_L(0); PG8_BAR; PG8_MMA(1, 0, At, B0); PG8_MMA(1, 1, At, B1); PG8_BAR; PG8_SCHED;
.LBB0_595:
	s_ashr_i32 s47, s46, 31
	s_lshl_b64 s[14:15], s[46:47], 17
	s_add_u32 s50, s17, s14
	s_addc_u32 s51, s64, s15
	s_and_b64 s[14:15], s[34:35], exec
	s_cselect_b32 s61, s51, s37
	s_cselect_b32 s60, s50, s36
	s_ashr_i32 s45, s44, 31
	s_lshl_b64 s[14:15], s[44:45], 17
	v_readlane_b32 s6, v255, 30
	v_readlane_b32 s7, v255, 31
	s_add_u32 s56, s6, s14
	s_addc_u32 s57, s7, s15
	s_and_b64 s[14:15], s[34:35], exec
	s_cselect_b32 s59, s57, s63
	s_cselect_b32 s58, s56, s62
	s_add_i32 s47, 0, 0x10000
	s_add_i32 s6, 0, 0x14000
	v_add_u32_e32 v184, s47, v164
	v_add_u32_e32 v214, s6, v164
	ds_read_b128 v[0:3], v184
	ds_read_b128 v[4:7], v184 offset:1024
	ds_read_b128 v[8:11], v184 offset:2048
	ds_read_b128 v[12:15], v184 offset:3072
	ds_read_b128 v[16:19], v214
	ds_read_b128 v[20:23], v214 offset:1024
	ds_read_b128 v[24:27], v214 offset:2048
	ds_read_b128 v[28:31], v214 offset:3072
	s_mov_b32 s55, s77
	s_add_u32 s14, s36, 0x10080
	s_addc_u32 s15, s37, 0
	s_add_i32 s53, s65, 0xc000
	v_lshl_add_u64 v[64:65], s[14:15], 0, v[142:143]
	s_mov_b32 m0, s53
	s_add_i32 s12, s65, 0xe000
	ds_read_b128 v[32:35], v165
	ds_read_b128 v[36:39], v165 offset:1024
	ds_read_b128 v[40:43], v165 offset:2048
	ds_read_b128 v[44:47], v165 offset:3072
	ds_read_b128 v[48:51], v165 offset:4096
	ds_read_b128 v[52:55], v165 offset:5120
	ds_read_b128 v[56:59], v165 offset:6144
	ds_read_b128 v[60:63], v165 offset:7168
	global_load_lds_dwordx4 v[64:65], off
	v_lshl_add_u64 v[64:65], s[14:15], 0, v[138:139]
	s_mov_b32 m0, s12
	s_nop 0
	global_load_lds_dwordx4 v[64:65], off
	s_waitcnt vmcnt(8)
	s_waitcnt lgkmcnt(0)
	s_barrier
	s_setprio 1
	s_waitcnt lgkmcnt(0)
	v_mfma_f32_16x16x32_bf16 v[64:67], v[0:3], v[32:35], 0
	v_mfma_f32_16x16x32_bf16 v[68:71], v[8:11], v[32:35], 0
	v_mfma_f32_16x16x32_bf16 v[72:75], v[0:3], v[40:43], 0
	v_mfma_f32_16x16x32_bf16 v[76:79], v[8:11], v[40:43], 0
	v_mfma_f32_16x16x32_bf16 v[80:83], v[0:3], v[48:51], 0
	v_mfma_f32_16x16x32_bf16 v[84:87], v[8:11], v[48:51], 0
	v_mfma_f32_16x16x32_bf16 v[88:91], v[0:3], v[56:59], 0
	v_mfma_f32_16x16x32_bf16 v[92:95], v[8:11], v[56:59], 0
	v_mfma_f32_16x16x32_bf16 v[64:67], v[4:7], v[36:39], v[64:67]
	v_mfma_f32_16x16x32_bf16 v[68:71], v[12:15], v[36:39], v[68:71]
	v_mfma_f32_16x16x32_bf16 v[72:75], v[4:7], v[44:47], v[72:75]
	v_mfma_f32_16x16x32_bf16 v[76:79], v[12:15], v[44:47], v[76:79]
	v_mfma_f32_16x16x32_bf16 v[80:83], v[4:7], v[52:55], v[80:83]
	v_mfma_f32_16x16x32_bf16 v[84:87], v[12:15], v[52:55], v[84:87]
	v_mfma_f32_16x16x32_bf16 v[88:91], v[4:7], v[60:63], v[88:91]
	v_mfma_f32_16x16x32_bf16 v[92:95], v[12:15], v[60:63], v[92:95]
	s_setprio 0
	s_setprio 1
	v_mfma_f32_16x16x32_bf16 v[96:99], v[16:19], v[32:35], 0
	v_mfma_f32_16x16x32_bf16 v[32:35], v[24:27], v[32:35], 0
	v_mfma_f32_16x16x32_bf16 v[96:99], v[20:23], v[36:39], v[96:99]
	v_mfma_f32_16x16x32_bf16 v[32:35], v[28:31], v[36:39], v[32:35]
	v_mfma_f32_16x16x32_bf16 v[36:39], v[16:19], v[40:43], 0
	v_mfma_f32_16x16x32_bf16 v[40:43], v[24:27], v[40:43], 0
	v_mfma_f32_16x16x32_bf16 v[36:39], v[20:23], v[44:47], v[36:39]
	v_mfma_f32_16x16x32_bf16 v[40:43], v[28:31], v[44:47], v[40:43]
	v_mfma_f32_16x16x32_bf16 v[44:47], v[16:19], v[48:51], 0
	v_mfma_f32_16x16x32_bf16 v[48:51], v[24:27], v[48:51], 0
	v_mfma_f32_16x16x32_bf16 v[44:47], v[20:23], v[52:55], v[44:47]
	v_mfma_f32_16x16x32_bf16 v[48:51], v[28:31], v[52:55], v[48:51]
	v_mfma_f32_16x16x32_bf16 v[52:55], v[16:19], v[56:59], 0
	v_mfma_f32_16x16x32_bf16 v[56:59], v[24:27], v[56:59], 0
	v_mfma_f32_16x16x32_bf16 v[52:55], v[20:23], v[60:63], v[52:55]
	v_mfma_f32_16x16x32_bf16 v[56:59], v[28:31], v[60:63], v[56:59]
	s_setprio 2
	s_barrier
	s_add_i32 s47, s47, s16
	v_lshl_add_u64 v[182:183], s[62:63], 0, v[140:141]
	s_add_i32 s14, s47, 0x2000
	v_lshl_add_u64 v[128:129], v[182:183], 0, s[80:81]
	s_mov_b32 m0, s47
	v_lshl_add_u64 v[190:191], s[62:63], 0, v[136:137]
	s_add_u32 vcc_lo, s62, 0x10100
	ds_read_b128 v[60:63], v165 offset:16384
	ds_read_b128 v[100:103], v165 offset:17408
	ds_read_b128 v[104:107], v165 offset:18432
	ds_read_b128 v[108:111], v165 offset:19456
	ds_read_b128 v[112:115], v165 offset:20480
	ds_read_b128 v[116:119], v165 offset:21504
	ds_read_b128 v[120:123], v165 offset:22528
	ds_read_b128 v[124:127], v165 offset:23552
	global_load_lds_dwordx4 v[128:129], off
	v_lshl_add_u64 v[128:129], v[190:191], 0, s[80:81]
	s_mov_b32 m0, s14
	s_addc_u32 vcc_hi, s63, 0
	s_add_i32 s15, s6, s16
	global_load_lds_dwordx4 v[128:129], off
	v_lshl_add_u64 v[128:129], vcc, 0, v[140:141]
	s_mov_b32 m0, s15
	s_add_i32 s45, s15, 0x2000
	global_load_lds_dwordx4 v[128:129], off
	v_lshl_add_u64 v[128:129], vcc, 0, v[136:137]
	s_mov_b32 m0, s45
	v_lshl_add_u64 v[192:193], s[36:37], 0, v[142:143]
	global_load_lds_dwordx4 v[128:129], off
	v_lshl_add_u64 v[128:129], v[192:193], 0, s[80:81]
	s_mov_b32 m0, s65
	v_lshl_add_u64 v[210:211], s[36:37], 0, v[138:139]
	global_load_lds_dwordx4 v[128:129], off
	v_lshl_add_u64 v[128:129], v[210:211], 0, s[80:81]
	s_mov_b32 m0, s66
	s_nop 0
	global_load_lds_dwordx4 v[128:129], off
	s_waitcnt vmcnt(8)
	s_waitcnt lgkmcnt(0)
	s_barrier
; #define PG8_STAGE(bufoff, gbase, voff) do { _Pragma("unroll") for (int _i = 0; _i < 2; ++_i) \
;         __builtin_amdgcn_global_load_lds((const unsigned*)((const char*)(gbase) + (voff)[_i]), (PG8_LAS unsigned*)(lds + (bufoff) + ldsw + _i * 8192), 16, 0, 0); } while (0)
; #define PG8_LDA(dst, b, h) do { _Pragma("unroll") for (int m = 0; m < 4; ++m) _Pragma("unroll") for (int k = 0; k < 2; ++k) dst[m][k] = *(const PG8_LAS bf16x8*)(lds + PG8_SA(b, h) + aoff + m * 2048 + k * 1024); } while (0)
; #define PG8_LDB(dst, b, h) do { _Pragma("unroll") for (int n = 0; n < 2; ++n) _Pragma("unroll") for (int k = 0; k < 2; ++k) dst[n][k] = *(const PG8_LAS bf16x8*)(lds + PG8_SB(b, h) + boff + n * 2048 + k * 1024); } while (0)
; #define PG8_MMA(ai, bj, At, Bt) do { __builtin_amdgcn_s_setprio(1); _Pragma("unroll") for (int m = 0; m < 4; ++m) _Pragma("unroll") for (int n = 0; n < 2; ++n) _Pragma("unroll") for (int k = 0; k < 2; ++k) \
;         acc[ai][bj][m][n] = __builtin_amdgcn_mfma_f32_16x16x32_bf16(Bt[n][k], At[m][k], acc[ai][bj][m][n], 0, 0, 0); __builtin_amdgcn_s_setprio(0); } while (0)
; #define PG8_WAIT_V(n) asm volatile("s_waitcnt vmcnt(" #n ")" ::: "memory")
; #define PG8_WAIT_L(n) asm volatile("s_waitcnt lgkmcnt(" #n ")" ::: "memory")
; #define PG8_BAR __builtin_amdgcn_s_barrier()
; #define PG8_SCHED __builtin_amdgcn_sched_barrier(0)
; template <class Epi, class Sched, bool ALIGN_EPI = false, bool SP2 = false>
; __device__ __forceinline__ void gemm_phase(PG8_LAS unsigned char* lds, const Gemm g, const Sched& S, const Epi& E, const int tid_in) {
;     ...
;             PG8_WAIT_V(8); PG8_WAIT_L(0); PG8_BAR; PG8_MMA(1, 0, At, B0); PG8_MMA(1, 1, At, B1); PG8_BAR; PG8_SCHED;
;             PG8_LDB(B0, 1, 0); PG8_LDB(B1, 1, 1); PG8_SCHED; PG8_LDA(At, 1, 0); PG8_STAGE(PG8_SA(0, 1), a2 + hstepA, voffA);
;             PG8_WAIT_V(8); PG8_WAIT_L(0); PG8_BAR; PG8_MMA(0, 0, At, B0); PG8_MMA(0, 1, At, B1); PG8_BAR; PG8_SCHED;
	s_setprio 1
	s_waitcnt lgkmcnt(0)
	v_mfma_f32_16x16x32_bf16 v[128:131], v[0:3], v[60:63], 0
	v_mfma_f32_16x16x32_bf16 v[144:147], v[0:3], v[104:107], 0
	v_mfma_f32_16x16x32_bf16 v[152:155], v[0:3], v[112:115], 0
	v_mfma_f32_16x16x32_bf16 v[0:3], v[0:3], v[120:123], 0
	v_mfma_f32_16x16x32_bf16 v[128:131], v[4:7], v[100:103], v[128:131]
	v_mfma_f32_16x16x32_bf16 v[144:147], v[4:7], v[108:111], v[144:147]
	v_mfma_f32_16x16x32_bf16 v[152:155], v[4:7], v[116:119], v[152:155]
	v_mfma_f32_16x16x32_bf16 v[0:3], v[4:7], v[124:127], v[0:3]
	v_mfma_f32_16x16x32_bf16 v[4:7], v[8:11], v[120:123], 0
	v_mfma_f32_16x16x32_bf16 v[132:135], v[8:11], v[60:63], 0
	v_mfma_f32_16x16x32_bf16 v[148:151], v[8:11], v[104:107], 0
	v_mfma_f32_16x16x32_bf16 v[156:159], v[8:11], v[112:115], 0
	v_mfma_f32_16x16x32_bf16 v[4:7], v[12:15], v[124:127], v[4:7]
	v_mfma_f32_16x16x32_bf16 v[132:135], v[12:15], v[100:103], v[132:135]
	v_mfma_f32_16x16x32_bf16 v[148:151], v[12:15], v[108:111], v[148:151]
	v_mfma_f32_16x16x32_bf16 v[156:159], v[12:15], v[116:119], v[156:159]
	s_setprio 0
	s_setprio 1
	v_mfma_f32_16x16x32_bf16 v[8:11], v[16:19], v[60:63], 0
	v_mfma_f32_16x16x32_bf16 v[12:15], v[24:27], v[60:63], 0
	v_mfma_f32_16x16x32_bf16 v[8:11], v[20:23], v[100:103], v[8:11]
	v_mfma_f32_16x16x32_bf16 v[12:15], v[28:31], v[100:103], v[12:15]
	v_mfma_f32_16x16x32_bf16 v[60:63], v[16:19], v[104:107], 0
	v_mfma_f32_16x16x32_bf16 v[100:103], v[24:27], v[104:107], 0
	v_mfma_f32_16x16x32_bf16 v[104:107], v[16:19], v[112:115], 0
	v_mfma_f32_16x16x32_bf16 v[16:19], v[16:19], v[120:123], 0
	v_mfma_f32_16x16x32_bf16 v[60:63], v[20:23], v[108:111], v[60:63]
	v_mfma_f32_16x16x32_bf16 v[100:103], v[28:31], v[108:111], v[100:103]
	v_mfma_f32_16x16x32_bf16 v[104:107], v[20:23], v[116:119], v[104:107]
	v_mfma_f32_16x16x32_bf16 v[108:111], v[24:27], v[112:115], 0
	v_mfma_f32_16x16x32_bf16 v[16:19], v[20:23], v[124:127], v[16:19]
	v_mfma_f32_16x16x32_bf16 v[20:23], v[24:27], v[120:123], 0
	v_mfma_f32_16x16x32_bf16 v[108:111], v[28:31], v[116:119], v[108:111]
	v_mfma_f32_16x16x32_bf16 v[20:23], v[28:31], v[124:127], v[20:23]
	s_setprio 2
	s_barrier
	s_add_i32 s77, 0, 0x18000
	s_add_i32 s6, 0, 0x1c000
	v_add_u32_e32 v222, s77, v164
	v_add_u32_e32 v223, s6, v164
	ds_read_b128 v[24:27], v222
	ds_read_b128 v[28:31], v222 offset:1024
	ds_read_b128 v[112:115], v222 offset:2048
	ds_read_b128 v[116:119], v222 offset:3072
	ds_read_b128 v[120:123], v223
	ds_read_b128 v[124:127], v223 offset:1024
	ds_read_b128 v[160:163], v223 offset:2048
	ds_read_b128 v[166:169], v223 offset:3072
	s_add_u32 vcc_lo, s36, 0x10100
	s_addc_u32 vcc_hi, s37, 0
	s_mov_b32 m0, s67
	v_lshl_add_u64 v[212:213], vcc, 0, v[142:143]
	ds_read_b128 v[170:173], v165 offset:32768
	ds_read_b128 v[174:177], v165 offset:33792
	ds_read_b128 v[178:181], v165 offset:34816
	ds_read_b128 v[186:189], v165 offset:35840
	ds_read_b128 v[194:197], v165 offset:36864
	ds_read_b128 v[198:201], v165 offset:37888
	ds_read_b128 v[202:205], v165 offset:38912
	ds_read_b128 v[206:209], v165 offset:39936
	global_load_lds_dwordx4 v[212:213], off
	v_lshl_add_u64 v[212:213], vcc, 0, v[138:139]
	s_mov_b32 m0, s68
	s_nop 0
	global_load_lds_dwordx4 v[212:213], off
	s_waitcnt vmcnt(8)
	s_waitcnt lgkmcnt(0)
	s_barrier
	s_setprio 1
	s_waitcnt lgkmcnt(0)
	v_mfma_f32_16x16x32_bf16 v[64:67], v[24:27], v[170:173], v[64:67]
	v_mfma_f32_16x16x32_bf16 v[68:71], v[112:115], v[170:173], v[68:71]
	v_mfma_f32_16x16x32_bf16 v[72:75], v[24:27], v[178:181], v[72:75]
	v_mfma_f32_16x16x32_bf16 v[76:79], v[112:115], v[178:181], v[76:79]
	v_mfma_f32_16x16x32_bf16 v[80:83], v[24:27], v[194:197], v[80:83]
	v_mfma_f32_16x16x32_bf16 v[84:87], v[112:115], v[194:197], v[84:87]
	v_mfma_f32_16x16x32_bf16 v[88:91], v[24:27], v[202:205], v[88:91]
	v_mfma_f32_16x16x32_bf16 v[92:95], v[112:115], v[202:205], v[92:95]
	v_mfma_f32_16x16x32_bf16 v[64:67], v[28:31], v[174:177], v[64:67]
	v_mfma_f32_16x16x32_bf16 v[68:71], v[116:119], v[174:177], v[68:71]
	v_mfma_f32_16x16x32_bf16 v[72:75], v[28:31], v[186:189], v[72:75]
	v_mfma_f32_16x16x32_bf16 v[76:79], v[116:119], v[186:189], v[76:79]
	v_mfma_f32_16x16x32_bf16 v[80:83], v[28:31], v[198:201], v[80:83]
	v_mfma_f32_16x16x32_bf16 v[84:87], v[116:119], v[198:201], v[84:87]
	v_mfma_f32_16x16x32_bf16 v[88:91], v[28:31], v[206:209], v[88:91]
	v_mfma_f32_16x16x32_bf16 v[92:95], v[116:119], v[206:209], v[92:95]
	s_setprio 0
	s_setprio 1
	v_mfma_f32_16x16x32_bf16 v[96:99], v[120:123], v[170:173], v[96:99]
	v_mfma_f32_16x16x32_bf16 v[32:35], v[160:163], v[170:173], v[32:35]
	v_mfma_f32_16x16x32_bf16 v[36:39], v[120:123], v[178:181], v[36:39]
	v_mfma_f32_16x16x32_bf16 v[40:43], v[160:163], v[178:181], v[40:43]
	v_mfma_f32_16x16x32_bf16 v[44:47], v[120:123], v[194:197], v[44:47]
	v_mfma_f32_16x16x32_bf16 v[48:51], v[160:163], v[194:197], v[48:51]
	v_mfma_f32_16x16x32_bf16 v[52:55], v[120:123], v[202:205], v[52:55]
	v_mfma_f32_16x16x32_bf16 v[56:59], v[160:163], v[202:205], v[56:59]
	v_mfma_f32_16x16x32_bf16 v[96:99], v[124:127], v[174:177], v[96:99]
	v_mfma_f32_16x16x32_bf16 v[32:35], v[166:169], v[174:177], v[32:35]
	v_mfma_f32_16x16x32_bf16 v[36:39], v[124:127], v[186:189], v[36:39]
	v_mfma_f32_16x16x32_bf16 v[40:43], v[166:169], v[186:189], v[40:43]
	v_mfma_f32_16x16x32_bf16 v[44:47], v[124:127], v[198:201], v[44:47]
	v_mfma_f32_16x16x32_bf16 v[48:51], v[166:169], v[198:201], v[48:51]
	v_mfma_f32_16x16x32_bf16 v[52:55], v[124:127], v[206:209], v[52:55]
	v_mfma_f32_16x16x32_bf16 v[56:59], v[166:169], v[206:209], v[56:59]
	s_setprio 2
	s_barrier
; #define PG8_STAGE(bufoff, gbase, voff) do { _Pragma("unroll") for (int _i = 0; _i < 2; ++_i) \
;         __builtin_amdgcn_global_load_lds((const unsigned*)((const char*)(gbase) + (voff)[_i]), (PG8_LAS unsigned*)(lds + (bufoff) + ldsw + _i * 8192), 16, 0, 0); } while (0)
; #define PG8_LDA(dst, b, h) do { _Pragma("unroll") for (int m = 0; m < 4; ++m) _Pragma("unroll") for (int k = 0; k < 2; ++k) dst[m][k] = *(const PG8_LAS bf16x8*)(lds + PG8_SA(b, h) + aoff + m * 2048 + k * 1024); } while (0)
; #define PG8_LDB(dst, b, h) do { _Pragma("unroll") for (int n = 0; n < 2; ++n) _Pragma("unroll") for (int k = 0; k < 2; ++k) dst[n][k] = *(const PG8_LAS bf16x8*)(lds + PG8_SB(b, h) + boff + n * 2048 + k * 1024); } while (0)
; #define PG8_MMA(ai, bj, At, Bt) do { __builtin_amdgcn_s_setprio(1); _Pragma("unroll") for (int m = 0; m < 4; ++m) _Pragma("unroll") for (int n = 0; n < 2; ++n) _Pragma("unroll") for (int k = 0; k < 2; ++k) \
;         acc[ai][bj][m][n] = __builtin_amdgcn_mfma_f32_16x16x32_bf16(Bt[n][k], At[m][k], acc[ai][bj][m][n], 0, 0, 0); __builtin_amdgcn_s_setprio(0); } while (0)
; #define PG8_WAIT_V(n) asm volatile("s_waitcnt vmcnt(" #n ")" ::: "memory")
; #define PG8_WAIT_L(n) asm volatile("s_waitcnt lgkmcnt(" #n ")" ::: "memory")
; #define PG8_BAR __builtin_amdgcn_s_barrier()
; #define PG8_SCHED __builtin_amdgcn_sched_barrier(0)
; template <class Epi, class Sched, bool ALIGN_EPI = false, bool SP2 = false>
; __device__ __forceinline__ void gemm_phase(PG8_LAS unsigned char* lds, const Gemm g, const Sched& S, const Epi& E, const int tid_in) {
;     ...
;             PG8_LDB(B0, 0, 0); PG8_LDB(B1, 0, 1); PG8_SCHED; PG8_LDA(At, 0, 0); PG8_STAGE(PG8_SA(1, 1), a1 + hstepA, voffA);
;             PG8_WAIT_V(8); PG8_WAIT_L(0); PG8_BAR; PG8_MMA(0, 0, At, B0); PG8_MMA(0, 1, At, B1); PG8_BAR; PG8_SCHED;
;     ...
;             PG8_LDA(At, 1, 1); PG8_STAGE(PG8_SB(1, 0), b3, voffB); PG8_STAGE(PG8_SB(1, 1), b3 + hstep, voffB); PG8_STAGE(PG8_SA(1, 0), a3, voffA);
;             PG8_WAIT_V(8); PG8_WAIT_L(0); PG8_BAR; PG8_MMA(1, 0, At, B0); PG8_MMA(1, 1, At, B1); PG8_BAR; PG8_SCHED;
	s_add_i32 s77, s77, s16
	s_mov_b64 s[8:9], 0x180
	s_add_i32 s52, s77, 0x2000
	v_lshl_add_u64 v[182:183], v[182:183], 0, s[8:9]
	s_mov_b32 m0, s77
	s_add_u32 vcc_lo, s62, 0x10180
	ds_read_b128 v[170:173], v165 offset:49152
	ds_read_b128 v[174:177], v165 offset:50176
	ds_read_b128 v[178:181], v165 offset:51200
	ds_read_b128 v[186:189], v165 offset:52224
	ds_read_b128 v[194:197], v165 offset:53248
	ds_read_b128 v[198:201], v165 offset:54272
	ds_read_b128 v[202:205], v165 offset:55296
	ds_read_b128 v[206:209], v165 offset:56320
	global_load_lds_dwordx4 v[182:183], off
	v_lshl_add_u64 v[182:183], v[190:191], 0, s[8:9]
	s_mov_b32 m0, s52
	s_addc_u32 vcc_hi, s63, 0
	s_add_i32 s62, s6, s16
	global_load_lds_dwordx4 v[182:183], off
	v_lshl_add_u64 v[182:183], vcc, 0, v[140:141]
	s_mov_b32 m0, s62
	s_add_i32 s63, s62, 0x2000
	global_load_lds_dwordx4 v[182:183], off
	v_lshl_add_u64 v[182:183], vcc, 0, v[136:137]
	s_mov_b32 m0, s63
	s_nop 0
	global_load_lds_dwordx4 v[182:183], off
	v_lshl_add_u64 v[182:183], v[192:193], 0, s[8:9]
	s_mov_b32 m0, s71
	s_nop 0
	global_load_lds_dwordx4 v[182:183], off
	v_lshl_add_u64 v[182:183], v[210:211], 0, s[8:9]
	s_mov_b32 m0, s88
	s_nop 0
	global_load_lds_dwordx4 v[182:183], off
	s_waitcnt vmcnt(8)
	s_waitcnt lgkmcnt(0)
	s_barrier
	s_setprio 1
	s_waitcnt lgkmcnt(0)
	v_mfma_f32_16x16x32_bf16 v[0:3], v[24:27], v[202:205], v[0:3]
	v_mfma_f32_16x16x32_bf16 v[4:7], v[112:115], v[202:205], v[4:7]
	v_mfma_f32_16x16x32_bf16 v[128:131], v[24:27], v[170:173], v[128:131]
	v_mfma_f32_16x16x32_bf16 v[132:135], v[112:115], v[170:173], v[132:135]
	v_mfma_f32_16x16x32_bf16 v[144:147], v[24:27], v[178:181], v[144:147]
	v_mfma_f32_16x16x32_bf16 v[148:151], v[112:115], v[178:181], v[148:151]
	v_mfma_f32_16x16x32_bf16 v[152:155], v[24:27], v[194:197], v[152:155]
	v_mfma_f32_16x16x32_bf16 v[156:159], v[112:115], v[194:197], v[156:159]
	v_mfma_f32_16x16x32_bf16 v[0:3], v[28:31], v[206:209], v[0:3]
	v_mfma_f32_16x16x32_bf16 v[4:7], v[116:119], v[206:209], v[4:7]
	v_mfma_f32_16x16x32_bf16 v[128:131], v[28:31], v[174:177], v[128:131]
	v_mfma_f32_16x16x32_bf16 v[132:135], v[116:119], v[174:177], v[132:135]
	v_mfma_f32_16x16x32_bf16 v[144:147], v[28:31], v[186:189], v[144:147]
	v_mfma_f32_16x16x32_bf16 v[148:151], v[116:119], v[186:189], v[148:151]
	v_mfma_f32_16x16x32_bf16 v[152:155], v[28:31], v[198:201], v[152:155]
	v_mfma_f32_16x16x32_bf16 v[156:159], v[116:119], v[198:201], v[156:159]
	s_setprio 0
	s_setprio 1
	v_mfma_f32_16x16x32_bf16 v[8:11], v[120:123], v[170:173], v[8:11]
	v_mfma_f32_16x16x32_bf16 v[12:15], v[160:163], v[170:173], v[12:15]
	v_mfma_f32_16x16x32_bf16 v[24:27], v[120:123], v[178:181], v[60:63]
	v_mfma_f32_16x16x32_bf16 v[28:31], v[160:163], v[178:181], v[100:103]
	v_mfma_f32_16x16x32_bf16 v[60:63], v[120:123], v[194:197], v[104:107]
	v_mfma_f32_16x16x32_bf16 v[100:103], v[160:163], v[194:197], v[108:111]
	v_mfma_f32_16x16x32_bf16 v[16:19], v[120:123], v[202:205], v[16:19]
	v_mfma_f32_16x16x32_bf16 v[20:23], v[160:163], v[202:205], v[20:23]
	v_mfma_f32_16x16x32_bf16 v[8:11], v[124:127], v[174:177], v[8:11]
	v_mfma_f32_16x16x32_bf16 v[12:15], v[166:169], v[174:177], v[12:15]
	v_mfma_f32_16x16x32_bf16 v[24:27], v[124:127], v[186:189], v[24:27]
	v_mfma_f32_16x16x32_bf16 v[28:31], v[166:169], v[186:189], v[28:31]
	v_mfma_f32_16x16x32_bf16 v[60:63], v[124:127], v[198:201], v[60:63]
	v_mfma_f32_16x16x32_bf16 v[100:103], v[166:169], v[198:201], v[100:103]
	v_mfma_f32_16x16x32_bf16 v[16:19], v[124:127], v[206:209], v[16:19]
	v_mfma_f32_16x16x32_bf16 v[20:23], v[166:169], v[206:209], v[20:23]
	s_setprio 2
	s_barrier
	ds_read_b128 v[104:107], v184
	ds_read_b128 v[108:111], v184 offset:1024
	ds_read_b128 v[112:115], v184 offset:2048
	ds_read_b128 v[116:119], v184 offset:3072
	ds_read_b128 v[120:123], v214
	ds_read_b128 v[124:127], v214 offset:1024
	ds_read_b128 v[160:163], v214 offset:2048
	ds_read_b128 v[166:169], v214 offset:3072
	s_add_u32 s36, s36, 0x10180
	s_addc_u32 s37, s37, 0
	s_mov_b32 m0, s53
	v_lshl_add_u64 v[182:183], s[36:37], 0, v[142:143]
	ds_read_b128 v[170:173], v165
	ds_read_b128 v[174:177], v165 offset:1024
	ds_read_b128 v[178:181], v165 offset:2048
	ds_read_b128 v[186:189], v165 offset:3072
	ds_read_b128 v[194:197], v165 offset:4096
	ds_read_b128 v[198:201], v165 offset:5120
	ds_read_b128 v[202:205], v165 offset:6144
	ds_read_b128 v[206:209], v165 offset:7168
	global_load_lds_dwordx4 v[182:183], off
	v_lshl_add_u64 v[182:183], s[36:37], 0, v[138:139]
	s_mov_b32 m0, s12
	s_nop 0
	global_load_lds_dwordx4 v[182:183], off
	s_waitcnt vmcnt(8)
	s_waitcnt lgkmcnt(0)
	s_barrier
; #define PG8_STAGE(bufoff, gbase, voff) do { _Pragma("unroll") for (int _i = 0; _i < 2; ++_i) \
;         __builtin_amdgcn_global_load_lds((const unsigned*)((const char*)(gbase) + (voff)[_i]), (PG8_LAS unsigned*)(lds + (bufoff) + ldsw + _i * 8192), 16, 0, 0); } while (0)
; #define PG8_LDA(dst, b, h) do { _Pragma("unroll") for (int m = 0; m < 4; ++m) _Pragma("unroll") for (int k = 0; k < 2; ++k) dst[m][k] = *(const PG8_LAS bf16x8*)(lds + PG8_SA(b, h) + aoff + m * 2048 + k * 1024); } while (0)
; #define PG8_MMA(ai, bj, At, Bt) do { __builtin_amdgcn_s_setprio(1); _Pragma("unroll") for (int m = 0; m < 4; ++m) _Pragma("unroll") for (int n = 0; n < 2; ++n) _Pragma("unroll") for (int k = 0; k < 2; ++k) \
;         acc[ai][bj][m][n] = __builtin_amdgcn_mfma_f32_16x16x32_bf16(Bt[n][k], At[m][k], acc[ai][bj][m][n], 0, 0, 0); __builtin_amdgcn_s_setprio(0); } while (0)
; #define PG8_WAIT_V(n) asm volatile("s_waitcnt vmcnt(" #n ")" ::: "memory")
; #define PG8_WAIT_L(n) asm volatile("s_waitcnt lgkmcnt(" #n ")" ::: "memory")
; #define PG8_BAR __builtin_amdgcn_s_barrier()
; #define PG8_SCHED __builtin_amdgcn_sched_barrier(0)
; template <class Epi, class Sched, bool ALIGN_EPI = false, bool SP2 = false>
; __device__ __forceinline__ void gemm_phase(PG8_LAS unsigned char* lds, const Gemm g, const Sched& S, const Epi& E, const int tid_in) {
;     ...
;             PG8_WAIT_V(8); PG8_WAIT_L(0); PG8_BAR; PG8_MMA(0, 0, At, B0); PG8_MMA(0, 1, At, B1); PG8_BAR; PG8_SCHED;
;             PG8_LDA(At, 0, 1); PG8_STAGE(PG8_SB(0, 0), b2, voffB); PG8_STAGE(PG8_SB(0, 1), b2 + hstep, voffB); PG8_STAGE(PG8_SA(0, 0), a2, voffA);
;             PG8_WAIT_V(8); PG8_WAIT_L(0); PG8_BAR; PG8_MMA(1, 0, At, B0); PG8_MMA(1, 1, At, B1); PG8_BAR; PG8_SCHED;
	s_setprio 1
	s_waitcnt lgkmcnt(0)
	v_mfma_f32_16x16x32_bf16 v[64:67], v[104:107], v[170:173], v[64:67]
	v_mfma_f32_16x16x32_bf16 v[68:71], v[112:115], v[170:173], v[68:71]
	v_mfma_f32_16x16x32_bf16 v[72:75], v[104:107], v[178:181], v[72:75]
	v_mfma_f32_16x16x32_bf16 v[76:79], v[112:115], v[178:181], v[76:79]
	v_mfma_f32_16x16x32_bf16 v[80:83], v[104:107], v[194:197], v[80:83]
	v_mfma_f32_16x16x32_bf16 v[84:87], v[112:115], v[194:197], v[84:87]
	v_mfma_f32_16x16x32_bf16 v[88:91], v[104:107], v[202:205], v[88:91]
	v_mfma_f32_16x16x32_bf16 v[64:67], v[108:111], v[174:177], v[64:67]
	v_mfma_f32_16x16x32_bf16 v[68:71], v[116:119], v[174:177], v[68:71]
	v_mfma_f32_16x16x32_bf16 v[72:75], v[108:111], v[186:189], v[72:75]
	v_mfma_f32_16x16x32_bf16 v[76:79], v[116:119], v[186:189], v[76:79]
	v_mfma_f32_16x16x32_bf16 v[80:83], v[108:111], v[198:201], v[80:83]
	v_mfma_f32_16x16x32_bf16 v[84:87], v[116:119], v[198:201], v[84:87]
	v_mfma_f32_16x16x32_bf16 v[210:213], v[108:111], v[206:209], v[88:91]
	v_mfma_f32_16x16x32_bf16 v[88:91], v[112:115], v[202:205], v[92:95]
	v_mfma_f32_16x16x32_bf16 v[214:217], v[116:119], v[206:209], v[88:91]
	s_setprio 0
	s_setprio 1
	v_mfma_f32_16x16x32_bf16 v[88:91], v[120:123], v[170:173], v[96:99]
	v_mfma_f32_16x16x32_bf16 v[32:35], v[160:163], v[170:173], v[32:35]
	v_mfma_f32_16x16x32_bf16 v[36:39], v[120:123], v[178:181], v[36:39]
	v_mfma_f32_16x16x32_bf16 v[40:43], v[160:163], v[178:181], v[40:43]
	v_mfma_f32_16x16x32_bf16 v[44:47], v[120:123], v[194:197], v[44:47]
	v_mfma_f32_16x16x32_bf16 v[48:51], v[160:163], v[194:197], v[48:51]
	v_mfma_f32_16x16x32_bf16 v[52:55], v[120:123], v[202:205], v[52:55]
	v_mfma_f32_16x16x32_bf16 v[56:59], v[160:163], v[202:205], v[56:59]
	v_mfma_f32_16x16x32_bf16 v[96:99], v[124:127], v[174:177], v[88:91]
	v_mfma_f32_16x16x32_bf16 v[32:35], v[166:169], v[174:177], v[32:35]
	v_mfma_f32_16x16x32_bf16 v[36:39], v[124:127], v[186:189], v[36:39]
	v_mfma_f32_16x16x32_bf16 v[40:43], v[166:169], v[186:189], v[40:43]
	v_mfma_f32_16x16x32_bf16 v[44:47], v[124:127], v[198:201], v[44:47]
	v_mfma_f32_16x16x32_bf16 v[48:51], v[166:169], v[198:201], v[48:51]
	v_mfma_f32_16x16x32_bf16 v[52:55], v[124:127], v[206:209], v[52:55]
	v_mfma_f32_16x16x32_bf16 v[56:59], v[166:169], v[206:209], v[56:59]
	s_setprio 2
	s_barrier
	s_mov_b32 m0, s47
	v_lshl_add_u64 v[182:183], s[58:59], 0, v[140:141]
	s_add_u32 s36, s58, 0x10000
	ds_read_b128 v[88:91], v165 offset:16384
	ds_read_b128 v[92:95], v165 offset:17408
	ds_read_b128 v[170:173], v165 offset:18432
	ds_read_b128 v[174:177], v165 offset:19456
	ds_read_b128 v[178:181], v165 offset:20480
	ds_read_b128 v[186:189], v165 offset:21504
	ds_read_b128 v[194:197], v165 offset:22528
	ds_read_b128 v[198:201], v165 offset:23552
	global_load_lds_dwordx4 v[182:183], off
	v_lshl_add_u64 v[190:191], s[58:59], 0, v[136:137]
	s_mov_b32 m0, s14
	s_addc_u32 s37, s59, 0
	global_load_lds_dwordx4 v[190:191], off
	v_lshl_add_u64 v[192:193], s[36:37], 0, v[140:141]
	s_mov_b32 m0, s15
	v_lshl_add_u64 v[246:247], s[60:61], 0, v[138:139]
	global_load_lds_dwordx4 v[192:193], off
	v_lshl_add_u64 v[192:193], s[36:37], 0, v[136:137]
	s_mov_b32 m0, s45
	s_nop 0
	global_load_lds_dwordx4 v[192:193], off
	v_lshl_add_u64 v[192:193], s[60:61], 0, v[142:143]
	s_mov_b32 m0, s65
	s_nop 0
	global_load_lds_dwordx4 v[192:193], off
	s_mov_b32 m0, s66
	s_nop 0
	global_load_lds_dwordx4 v[246:247], off
	s_waitcnt vmcnt(8)
	s_waitcnt lgkmcnt(0)
	s_barrier
	s_setprio 1
	s_waitcnt lgkmcnt(0)
	v_mfma_f32_16x16x32_bf16 v[0:3], v[104:107], v[194:197], v[0:3]
	v_mfma_f32_16x16x32_bf16 v[4:7], v[112:115], v[194:197], v[4:7]
	v_mfma_f32_16x16x32_bf16 v[128:131], v[104:107], v[88:91], v[128:131]
	v_mfma_f32_16x16x32_bf16 v[132:135], v[112:115], v[88:91], v[132:135]
	v_mfma_f32_16x16x32_bf16 v[144:147], v[104:107], v[170:173], v[144:147]
	v_mfma_f32_16x16x32_bf16 v[148:151], v[112:115], v[170:173], v[148:151]
	v_mfma_f32_16x16x32_bf16 v[152:155], v[104:107], v[178:181], v[152:155]
	v_mfma_f32_16x16x32_bf16 v[156:159], v[112:115], v[178:181], v[156:159]
	v_mfma_f32_16x16x32_bf16 v[0:3], v[108:111], v[198:201], v[0:3]
	v_mfma_f32_16x16x32_bf16 v[4:7], v[116:119], v[198:201], v[4:7]
	v_mfma_f32_16x16x32_bf16 v[128:131], v[108:111], v[92:95], v[128:131]
	v_mfma_f32_16x16x32_bf16 v[132:135], v[116:119], v[92:95], v[132:135]
	v_mfma_f32_16x16x32_bf16 v[144:147], v[108:111], v[174:177], v[144:147]
	v_mfma_f32_16x16x32_bf16 v[148:151], v[116:119], v[174:177], v[148:151]
	v_mfma_f32_16x16x32_bf16 v[152:155], v[108:111], v[186:189], v[152:155]
	v_mfma_f32_16x16x32_bf16 v[156:159], v[116:119], v[186:189], v[156:159]
	s_setprio 0
	s_setprio 1
	v_mfma_f32_16x16x32_bf16 v[8:11], v[120:123], v[88:91], v[8:11]
	v_mfma_f32_16x16x32_bf16 v[202:205], v[124:127], v[92:95], v[8:11]
	v_mfma_f32_16x16x32_bf16 v[8:11], v[160:163], v[88:91], v[12:15]
	v_mfma_f32_16x16x32_bf16 v[206:209], v[166:169], v[92:95], v[8:11]
	v_mfma_f32_16x16x32_bf16 v[8:11], v[120:123], v[170:173], v[24:27]
	v_mfma_f32_16x16x32_bf16 v[218:221], v[124:127], v[174:177], v[8:11]
	v_mfma_f32_16x16x32_bf16 v[8:11], v[160:163], v[170:173], v[28:31]
	v_mfma_f32_16x16x32_bf16 v[170:173], v[166:169], v[174:177], v[8:11]
	v_mfma_f32_16x16x32_bf16 v[8:11], v[120:123], v[178:181], v[60:63]
	v_mfma_f32_16x16x32_bf16 v[174:177], v[124:127], v[186:189], v[8:11]
	v_mfma_f32_16x16x32_bf16 v[8:11], v[160:163], v[178:181], v[100:103]
	v_mfma_f32_16x16x32_bf16 v[178:181], v[166:169], v[186:189], v[8:11]
	v_mfma_f32_16x16x32_bf16 v[8:11], v[120:123], v[194:197], v[16:19]
	v_mfma_f32_16x16x32_bf16 v[186:189], v[124:127], v[198:201], v[8:11]
	v_mfma_f32_16x16x32_bf16 v[8:11], v[160:163], v[194:197], v[20:23]
	v_mfma_f32_16x16x32_bf16 v[160:163], v[166:169], v[198:201], v[8:11]
	s_setprio 2
	s_barrier
; #define PG8_STAGE(bufoff, gbase, voff) do { _Pragma("unroll") for (int _i = 0; _i < 2; ++_i) \
;         __builtin_amdgcn_global_load_lds((const unsigned*)((const char*)(gbase) + (voff)[_i]), (PG8_LAS unsigned*)(lds + (bufoff) + ldsw + _i * 8192), 16, 0, 0); } while (0)
; #define PG8_LDA(dst, b, h) do { _Pragma("unroll") for (int m = 0; m < 4; ++m) _Pragma("unroll") for (int k = 0; k < 2; ++k) dst[m][k] = *(const PG8_LAS bf16x8*)(lds + PG8_SA(b, h) + aoff + m * 2048 + k * 1024); } while (0)
; #define PG8_LDB(dst, b, h) do { _Pragma("unroll") for (int n = 0; n < 2; ++n) _Pragma("unroll") for (int k = 0; k < 2; ++k) dst[n][k] = *(const PG8_LAS bf16x8*)(lds + PG8_SB(b, h) + boff + n * 2048 + k * 1024); } while (0)
; #define PG8_MMA(ai, bj, At, Bt) do { __builtin_amdgcn_s_setprio(1); _Pragma("unroll") for (int m = 0; m < 4; ++m) _Pragma("unroll") for (int n = 0; n < 2; ++n) _Pragma("unroll") for (int k = 0; k < 2; ++k) \
;         acc[ai][bj][m][n] = __builtin_amdgcn_mfma_f32_16x16x32_bf16(Bt[n][k], At[m][k], acc[ai][bj][m][n], 0, 0, 0); __builtin_amdgcn_s_setprio(0); } while (0)
; #define PG8_WAIT_V(n) asm volatile("s_waitcnt vmcnt(" #n ")" ::: "memory")
; #define PG8_WAIT_L(n) asm volatile("s_waitcnt lgkmcnt(" #n ")" ::: "memory")
; #define PG8_BAR __builtin_amdgcn_s_barrier()
; #define PG8_SCHED __builtin_amdgcn_sched_barrier(0)
; template <class Epi, class Sched, bool ALIGN_EPI = false, bool SP2 = false>
; __device__ __forceinline__ void gemm_phase(PG8_LAS unsigned char* lds, const Gemm g, const Sched& S, const Epi& E, const int tid_in) {
;     ...
;             PG8_LDB(B0, 1, 0); PG8_LDB(B1, 1, 1); PG8_SCHED; PG8_LDA(At, 1, 0); PG8_STAGE(PG8_SA(0, 1), a2 + hstepA, voffA);
;             PG8_WAIT_V(8); PG8_WAIT_L(0); PG8_BAR; PG8_MMA(0, 0, At, B0); PG8_MMA(0, 1, At, B1); PG8_BAR; PG8_SCHED;
;             PG8_LDA(At, 1, 1); PG8_STAGE(PG8_SB(1, 0), b3, voffB); PG8_STAGE(PG8_SB(1, 1), b3 + hstep, voffB); PG8_STAGE(PG8_SA(1, 0), a3, voffA);
;             PG8_WAIT_V(8); PG8_WAIT_L(0); PG8_BAR; PG8_MMA(1, 0, At, B0); PG8_MMA(1, 1, At, B1); PG8_BAR; PG8_SCHED;
;     ...
;         if constexpr (ALIGN_EPI) { if (wr == 0) PG8_BAR; }
	s_nop 4
	ds_read_b128 v[8:11], v222
	ds_read_b128 v[12:15], v222 offset:1024
	ds_read_b128 v[16:19], v222 offset:2048
	ds_read_b128 v[20:23], v222 offset:3072
	ds_read_b128 v[166:169], v223
	ds_read_b128 v[194:197], v223 offset:1024
	ds_read_b128 v[198:201], v223 offset:2048
	ds_read_b128 v[222:225], v223 offset:3072
	s_add_u32 s14, s60, 0x10000
	s_addc_u32 s15, s61, 0
	s_mov_b32 m0, s67
	v_lshl_add_u64 v[88:89], s[14:15], 0, v[142:143]
	ds_read_b128 v[24:27], v165 offset:32768
	ds_read_b128 v[28:31], v165 offset:33792
	ds_read_b128 v[60:63], v165 offset:34816
	ds_read_b128 v[226:229], v165 offset:35840
	ds_read_b128 v[230:233], v165 offset:36864
	ds_read_b128 v[234:237], v165 offset:37888
	ds_read_b128 v[238:241], v165 offset:38912
	ds_read_b128 v[242:245], v165 offset:39936
	global_load_lds_dwordx4 v[88:89], off
	v_lshl_add_u64 v[88:89], s[14:15], 0, v[138:139]
	s_mov_b32 m0, s68
	s_nop 0
	global_load_lds_dwordx4 v[88:89], off
	s_waitcnt vmcnt(8)
	s_waitcnt lgkmcnt(0)
	s_barrier
	s_setprio 1
	s_waitcnt lgkmcnt(0)
	v_mfma_f32_16x16x32_bf16 v[64:67], v[8:11], v[24:27], v[64:67]
	v_mfma_f32_16x16x32_bf16 v[124:127], v[12:15], v[28:31], v[64:67]
	v_mfma_f32_16x16x32_bf16 v[64:67], v[16:19], v[24:27], v[68:71]
	v_mfma_f32_16x16x32_bf16 v[120:123], v[20:23], v[28:31], v[64:67]
	v_mfma_f32_16x16x32_bf16 v[64:67], v[8:11], v[60:63], v[72:75]
	v_mfma_f32_16x16x32_bf16 v[108:111], v[12:15], v[226:229], v[64:67]
	v_mfma_f32_16x16x32_bf16 v[64:67], v[16:19], v[60:63], v[76:79]
	v_mfma_f32_16x16x32_bf16 v[104:107], v[20:23], v[226:229], v[64:67]
	v_mfma_f32_16x16x32_bf16 v[64:67], v[8:11], v[230:233], v[80:83]
	v_mfma_f32_16x16x32_bf16 v[92:95], v[12:15], v[234:237], v[64:67]
	v_mfma_f32_16x16x32_bf16 v[64:67], v[16:19], v[230:233], v[84:87]
	v_mfma_f32_16x16x32_bf16 v[88:91], v[20:23], v[234:237], v[64:67]
	v_mfma_f32_16x16x32_bf16 v[64:67], v[8:11], v[238:241], v[210:213]
	v_mfma_f32_16x16x32_bf16 v[76:79], v[12:15], v[242:245], v[64:67]
	v_mfma_f32_16x16x32_bf16 v[64:67], v[16:19], v[238:241], v[214:217]
	v_mfma_f32_16x16x32_bf16 v[72:75], v[20:23], v[242:245], v[64:67]
	s_setprio 0
	s_setprio 1
	v_mfma_f32_16x16x32_bf16 v[64:67], v[166:169], v[24:27], v[96:99]
	v_mfma_f32_16x16x32_bf16 v[24:27], v[198:201], v[24:27], v[32:35]
	v_mfma_f32_16x16x32_bf16 v[112:115], v[222:225], v[28:31], v[24:27]
	v_mfma_f32_16x16x32_bf16 v[24:27], v[166:169], v[60:63], v[36:39]
	v_mfma_f32_16x16x32_bf16 v[100:103], v[194:197], v[226:229], v[24:27]
	v_mfma_f32_16x16x32_bf16 v[24:27], v[198:201], v[60:63], v[40:43]
	v_mfma_f32_16x16x32_bf16 v[96:99], v[222:225], v[226:229], v[24:27]
	v_mfma_f32_16x16x32_bf16 v[24:27], v[166:169], v[230:233], v[44:47]
	v_mfma_f32_16x16x32_bf16 v[84:87], v[194:197], v[234:237], v[24:27]
	v_mfma_f32_16x16x32_bf16 v[24:27], v[198:201], v[230:233], v[48:51]
	v_mfma_f32_16x16x32_bf16 v[80:83], v[222:225], v[234:237], v[24:27]
	v_mfma_f32_16x16x32_bf16 v[24:27], v[166:169], v[238:241], v[52:55]
	v_mfma_f32_16x16x32_bf16 v[68:71], v[194:197], v[242:245], v[24:27]
	v_mfma_f32_16x16x32_bf16 v[24:27], v[198:201], v[238:241], v[56:59]
	v_mfma_f32_16x16x32_bf16 v[116:119], v[194:197], v[28:31], v[64:67]
	v_mfma_f32_16x16x32_bf16 v[64:67], v[222:225], v[242:245], v[24:27]
	s_setprio 2
	s_barrier
	s_mov_b32 m0, s77
	s_nop 2
	v_lshl_add_u64 v[24:25], v[182:183], 0, s[84:85]
	s_add_u32 s14, s58, 0x10080
	ds_read_b128 v[32:35], v165 offset:49152
	ds_read_b128 v[36:39], v165 offset:50176
	ds_read_b128 v[210:213], v165 offset:51200
	ds_read_b128 v[214:217], v165 offset:52224
	ds_read_b128 v[226:229], v165 offset:53248
	ds_read_b128 v[230:233], v165 offset:54272
	ds_read_b128 v[234:237], v165 offset:55296
	ds_read_b128 v[238:241], v165 offset:56320
	global_load_lds_dwordx4 v[24:25], off
	v_lshl_add_u64 v[24:25], v[190:191], 0, s[84:85]
	s_mov_b32 m0, s52
	s_addc_u32 s15, s59, 0
	global_load_lds_dwordx4 v[24:25], off
	v_lshl_add_u64 v[24:25], s[14:15], 0, v[140:141]
	s_mov_b32 m0, s62
	s_nop 0
	global_load_lds_dwordx4 v[24:25], off
	v_lshl_add_u64 v[24:25], s[14:15], 0, v[136:137]
	s_mov_b32 m0, s63
	s_nop 0
	global_load_lds_dwordx4 v[24:25], off
	v_lshl_add_u64 v[24:25], v[192:193], 0, s[84:85]
	s_mov_b32 m0, s71
	s_nop 0
	global_load_lds_dwordx4 v[24:25], off
	v_lshl_add_u64 v[24:25], v[246:247], 0, s[84:85]
	s_mov_b32 m0, s88
	s_nop 0
	global_load_lds_dwordx4 v[24:25], off
	s_waitcnt vmcnt(8)
	s_waitcnt lgkmcnt(0)
	s_barrier
	s_setprio 1
	s_waitcnt lgkmcnt(0)
	v_mfma_f32_16x16x32_bf16 v[24:27], v[8:11], v[32:35], v[128:131]
	v_mfma_f32_16x16x32_bf16 v[60:63], v[12:15], v[36:39], v[24:27]
	v_mfma_f32_16x16x32_bf16 v[24:27], v[16:19], v[32:35], v[132:135]
	v_mfma_f32_16x16x32_bf16 v[56:59], v[20:23], v[36:39], v[24:27]
	v_mfma_f32_16x16x32_bf16 v[24:27], v[8:11], v[210:213], v[144:147]
	v_mfma_f32_16x16x32_bf16 v[44:47], v[12:15], v[214:217], v[24:27]
	v_mfma_f32_16x16x32_bf16 v[24:27], v[16:19], v[210:213], v[148:151]
	v_mfma_f32_16x16x32_bf16 v[40:43], v[20:23], v[214:217], v[24:27]
	v_mfma_f32_16x16x32_bf16 v[24:27], v[8:11], v[226:229], v[152:155]
	v_mfma_f32_16x16x32_bf16 v[0:3], v[8:11], v[234:237], v[0:3]
	v_mfma_f32_16x16x32_bf16 v[28:31], v[12:15], v[230:233], v[24:27]
	v_mfma_f32_16x16x32_bf16 v[24:27], v[16:19], v[226:229], v[156:159]
	v_mfma_f32_16x16x32_bf16 v[12:15], v[12:15], v[238:241], v[0:3]
	v_mfma_f32_16x16x32_bf16 v[0:3], v[16:19], v[234:237], v[4:7]
	v_mfma_f32_16x16x32_bf16 v[24:27], v[20:23], v[230:233], v[24:27]
	v_mfma_f32_16x16x32_bf16 v[8:11], v[20:23], v[238:241], v[0:3]
	s_setprio 0
	s_setprio 1
	v_mfma_f32_16x16x32_bf16 v[0:3], v[166:169], v[32:35], v[202:205]
	v_mfma_f32_16x16x32_bf16 v[52:55], v[194:197], v[36:39], v[0:3]
	v_mfma_f32_16x16x32_bf16 v[0:3], v[198:201], v[32:35], v[206:209]
	v_mfma_f32_16x16x32_bf16 v[48:51], v[222:225], v[36:39], v[0:3]
	v_mfma_f32_16x16x32_bf16 v[0:3], v[166:169], v[210:213], v[218:221]
	v_mfma_f32_16x16x32_bf16 v[36:39], v[194:197], v[214:217], v[0:3]
	v_mfma_f32_16x16x32_bf16 v[0:3], v[198:201], v[210:213], v[170:173]
	v_mfma_f32_16x16x32_bf16 v[32:35], v[222:225], v[214:217], v[0:3]
	v_mfma_f32_16x16x32_bf16 v[0:3], v[166:169], v[226:229], v[174:177]
	v_mfma_f32_16x16x32_bf16 v[20:23], v[194:197], v[230:233], v[0:3]
	v_mfma_f32_16x16x32_bf16 v[0:3], v[198:201], v[226:229], v[178:181]
	v_mfma_f32_16x16x32_bf16 v[16:19], v[222:225], v[230:233], v[0:3]
	v_mfma_f32_16x16x32_bf16 v[0:3], v[166:169], v[234:237], v[186:189]
	v_mfma_f32_16x16x32_bf16 v[4:7], v[194:197], v[238:241], v[0:3]
	v_mfma_f32_16x16x32_bf16 v[0:3], v[198:201], v[234:237], v[160:163]
	v_mfma_f32_16x16x32_bf16 v[0:3], v[222:225], v[238:241], v[0:3]
	s_setprio 2
	s_barrier
	s_andn2_b64 vcc, exec, s[40:41]
	s_cbranch_vccnz .LBB0_597
	s_barrier

; #define PG8_STAGE(bufoff, gbase, voff) do { _Pragma("unroll") for (int _i = 0; _i < 2; ++_i) \
;         __builtin_amdgcn_global_load_lds((const unsigned*)((const char*)(gbase) + (voff)[_i]), (PG8_LAS unsigned*)(lds + (bufoff) + ldsw + _i * 8192), 16, 0, 0); } while (0)
; #define PG8_LDA(dst, b, h) do { _Pragma("unroll") for (int m = 0; m < 4; ++m) _Pragma("unroll") for (int k = 0; k < 2; ++k) dst[m][k] = *(const PG8_LAS bf16x8*)(lds + PG8_SA(b, h) + aoff + m * 2048 + k * 1024); } while (0)
; #define PG8_LDB(dst, b, h) do { _Pragma("unroll") for (int n = 0; n < 2; ++n) _Pragma("unroll") for (int k = 0; k < 2; ++k) dst[n][k] = *(const PG8_LAS bf16x8*)(lds + PG8_SB(b, h) + boff + n * 2048 + k * 1024); } while (0)
; #define PG8_MMA(ai, bj, At, Bt) do { __builtin_amdgcn_s_setprio(1); _Pragma("unroll") for (int m = 0; m < 4; ++m) _Pragma("unroll") for (int n = 0; n < 2; ++n) _Pragma("unroll") for (int k = 0; k < 2; ++k) \
;         acc[ai][bj][m][n] = __builtin_amdgcn_mfma_f32_16x16x32_bf16(Bt[n][k], At[m][k], acc[ai][bj][m][n], 0, 0, 0); __builtin_amdgcn_s_setprio(0); } while (0)
; #define PG8_WAIT_V(n) asm volatile("s_waitcnt vmcnt(" #n ")" ::: "memory")
; #define PG8_WAIT_L(n) asm volatile("s_waitcnt lgkmcnt(" #n ")" ::: "memory")
; template <class Epi, class Sched, bool ALIGN_EPI = false, bool SP2 = false>
; __device__ __forceinline__ void gemm_phase(PG8_LAS unsigned char* lds, const Gemm g, const Sched& S, const Epi& E, const int tid_in) {
;     ...
;             const bool last = (t == nt - 2);
;             const char* a1 = cA + (size_t)(t + 1) * kstepA;
;             const char* a2 = last ? nA : cA + (size_t)(t + 2) * kstepA; const char* b2 = last ? nB : cB + (size_t)(t + 2) * kstep;
;             const char* a3 = a2 + kstepA; const char* b3 = b2 + kstep;
;             if (last && has_next) S.a_ready(nxt, ui + 1);
;             if constexpr (SP2) {
;             PG8_LDB(B0, 0, 0); PG8_LDB(B1, 0, 1); PG8_SCHED; PG8_LDA(At, 0, 0); PG8_STAGE(PG8_SA(1, 1), a1 + hstepA, voffA);
;             PG8_WAIT_V(8); PG8_WAIT_L(0); PG8_BAR; PG8_MMA(0, 0, At, B0); PG8_MMA(0, 1, At, B1); PG8_BAR; PG8_SCHED;
;             PG8_LDA(At, 0, 1); PG8_STAGE(PG8_SB(0, 0), b2, voffB); PG8_STAGE(PG8_SB(0, 1), b2 + hstep, voffB); PG8_STAGE(PG8_SA(0, 0), a2, voffA);
;             PG8_WAIT_V(8); PG8_WAIT_L(0); PG8_BAR; PG8_MMA(1, 0, At, B0); PG8_MMA(1, 1, At, B1); PG8_BAR; PG8_SCHED;
.LBB0_915:
	s_add_u32 s6, s56, 0xfffc0080
	s_addc_u32 s7, s57, -1
	s_and_b64 s[58:59], s[58:59], exec
	s_cselect_b32 s61, s3, s7
	s_cselect_b32 s60, s12, s6
	s_cselect_b32 s59, s43, s14
	s_cselect_b32 s58, s45, s77
	s_add_i32 s6, 0, 0x10000
	s_add_i32 s7, 0, 0x14000
	v_add_u32_e32 v124, s6, v154
	v_add_u32_e32 v168, s7, v154
	ds_read_b128 v[104:107], v124
	ds_read_b128 v[112:115], v124 offset:1024
	ds_read_b128 v[120:123], v124 offset:2048
	ds_read_b128 v[124:127], v124 offset:3072
	ds_read_b128 v[156:159], v168
	ds_read_b128 v[160:163], v168 offset:1024
	ds_read_b128 v[164:167], v168 offset:2048
	ds_read_b128 v[168:171], v168 offset:3072
	v_lshl_add_u64 v[190:191], s[56:57], 0, v[150:151]
	s_add_i32 m0, s62, 0xc000
	ds_read_b128 v[172:175], v155
	ds_read_b128 v[176:179], v155 offset:1024
	ds_read_b128 v[180:183], v155 offset:2048
	ds_read_b128 v[186:189], v155 offset:3072
	ds_read_b128 v[194:197], v155 offset:4096
	ds_read_b128 v[198:201], v155 offset:5120
	ds_read_b128 v[202:205], v155 offset:6144
	ds_read_b128 v[206:209], v155 offset:7168
	global_load_lds_dwordx4 v[190:191], off
	v_lshl_add_u64 v[190:191], s[56:57], 0, v[152:153]
	s_add_i32 m0, s62, 0xe000
	s_nop 0
	global_load_lds_dwordx4 v[190:191], off
	s_waitcnt vmcnt(8)
	s_waitcnt lgkmcnt(0)
	s_barrier
	s_setprio 1
	s_waitcnt lgkmcnt(0)
	v_mfma_f32_16x16x32_bf16 v[140:143], v[104:107], v[172:175], v[140:143]
	v_mfma_f32_16x16x32_bf16 v[136:139], v[120:123], v[172:175], v[136:139]
	v_mfma_f32_16x16x32_bf16 v[116:119], v[104:107], v[180:183], v[116:119]
	v_mfma_f32_16x16x32_bf16 v[108:111], v[120:123], v[180:183], v[108:111]
	v_mfma_f32_16x16x32_bf16 v[92:95], v[104:107], v[194:197], v[92:95]
	v_mfma_f32_16x16x32_bf16 v[88:91], v[120:123], v[194:197], v[88:91]
	v_mfma_f32_16x16x32_bf16 v[76:79], v[104:107], v[202:205], v[76:79]
	v_mfma_f32_16x16x32_bf16 v[72:75], v[120:123], v[202:205], v[72:75]
	v_mfma_f32_16x16x32_bf16 v[140:143], v[112:115], v[176:179], v[140:143]
	v_mfma_f32_16x16x32_bf16 v[136:139], v[124:127], v[176:179], v[136:139]
	v_mfma_f32_16x16x32_bf16 v[116:119], v[112:115], v[186:189], v[116:119]
	v_mfma_f32_16x16x32_bf16 v[108:111], v[124:127], v[186:189], v[108:111]
	v_mfma_f32_16x16x32_bf16 v[92:95], v[112:115], v[198:201], v[92:95]
	v_mfma_f32_16x16x32_bf16 v[88:91], v[124:127], v[198:201], v[88:91]
	v_mfma_f32_16x16x32_bf16 v[76:79], v[112:115], v[206:209], v[76:79]
	v_mfma_f32_16x16x32_bf16 v[72:75], v[124:127], v[206:209], v[72:75]
	s_setprio 0
	s_setprio 1
	v_mfma_f32_16x16x32_bf16 v[132:135], v[156:159], v[172:175], v[132:135]
	v_mfma_f32_16x16x32_bf16 v[128:131], v[164:167], v[172:175], v[128:131]
	v_mfma_f32_16x16x32_bf16 v[100:103], v[156:159], v[180:183], v[100:103]
	v_mfma_f32_16x16x32_bf16 v[96:99], v[164:167], v[180:183], v[96:99]
	v_mfma_f32_16x16x32_bf16 v[84:87], v[156:159], v[194:197], v[84:87]
	v_mfma_f32_16x16x32_bf16 v[80:83], v[164:167], v[194:197], v[80:83]
	v_mfma_f32_16x16x32_bf16 v[68:71], v[156:159], v[202:205], v[68:71]
	v_mfma_f32_16x16x32_bf16 v[64:67], v[164:167], v[202:205], v[64:67]
	v_mfma_f32_16x16x32_bf16 v[132:135], v[160:163], v[176:179], v[132:135]
	v_mfma_f32_16x16x32_bf16 v[128:131], v[168:171], v[176:179], v[128:131]
	v_mfma_f32_16x16x32_bf16 v[100:103], v[160:163], v[186:189], v[100:103]
	v_mfma_f32_16x16x32_bf16 v[96:99], v[168:171], v[186:189], v[96:99]
	v_mfma_f32_16x16x32_bf16 v[84:87], v[160:163], v[198:201], v[84:87]
	v_mfma_f32_16x16x32_bf16 v[80:83], v[168:171], v[198:201], v[80:83]
	v_mfma_f32_16x16x32_bf16 v[68:71], v[160:163], v[206:209], v[68:71]
	v_mfma_f32_16x16x32_bf16 v[64:67], v[168:171], v[206:209], v[64:67]
	s_setprio 2
	s_barrier
	s_add_i32 s6, s6, s54
	v_lshl_add_u64 v[190:191], s[58:59], 0, v[184:185]
	s_mov_b32 m0, s6
	ds_read_b128 v[172:175], v155 offset:16384
	ds_read_b128 v[176:179], v155 offset:17408
	ds_read_b128 v[180:183], v155 offset:18432
	ds_read_b128 v[186:189], v155 offset:19456
	ds_read_b128 v[194:197], v155 offset:20480
	ds_read_b128 v[198:201], v155 offset:21504
	ds_read_b128 v[202:205], v155 offset:22528
	ds_read_b128 v[206:209], v155 offset:23552
	global_load_lds_dwordx4 v[190:191], off
	s_add_i32 m0, s6, 0x2000
	s_add_u32 vcc_lo, s58, 0x40000
	v_lshl_add_u64 v[192:193], s[58:59], 0, v[148:149]
	s_addc_u32 vcc_hi, s59, 0
	s_add_i32 s6, s7, s54
	global_load_lds_dwordx4 v[192:193], off
	v_lshl_add_u64 v[210:211], vcc, 0, v[184:185]
	s_mov_b32 m0, s6
	v_lshl_add_u64 v[212:213], s[60:61], 0, v[146:147]
	global_load_lds_dwordx4 v[210:211], off
	v_lshl_add_u64 v[210:211], vcc, 0, v[148:149]
	s_add_i32 m0, s6, 0x2000
	s_nop 0
	global_load_lds_dwordx4 v[210:211], off
	v_lshl_add_u64 v[210:211], s[60:61], 0, v[144:145]
	s_mov_b32 m0, s62
	s_nop 0
	global_load_lds_dwordx4 v[210:211], off
	s_mov_b32 m0, s63
	s_nop 0
	global_load_lds_dwordx4 v[212:213], off
	s_waitcnt vmcnt(8)
	s_waitcnt lgkmcnt(0)
	s_barrier
; #define PG8_STAGE(bufoff, gbase, voff) do { _Pragma("unroll") for (int _i = 0; _i < 2; ++_i) \
;         __builtin_amdgcn_global_load_lds((const unsigned*)((const char*)(gbase) + (voff)[_i]), (PG8_LAS unsigned*)(lds + (bufoff) + ldsw + _i * 8192), 16, 0, 0); } while (0)
; #define PG8_LDA(dst, b, h) do { _Pragma("unroll") for (int m = 0; m < 4; ++m) _Pragma("unroll") for (int k = 0; k < 2; ++k) dst[m][k] = *(const PG8_LAS bf16x8*)(lds + PG8_SA(b, h) + aoff + m * 2048 + k * 1024); } while (0)
; #define PG8_LDB(dst, b, h) do { _Pragma("unroll") for (int n = 0; n < 2; ++n) _Pragma("unroll") for (int k = 0; k < 2; ++k) dst[n][k] = *(const PG8_LAS bf16x8*)(lds + PG8_SB(b, h) + boff + n * 2048 + k * 1024); } while (0)
; #define PG8_MMA(ai, bj, At, Bt) do { __builtin_amdgcn_s_setprio(1); _Pragma("unroll") for (int m = 0; m < 4; ++m) _Pragma("unroll") for (int n = 0; n < 2; ++n) _Pragma("unroll") for (int k = 0; k < 2; ++k) \
;         acc[ai][bj][m][n] = __builtin_amdgcn_mfma_f32_16x16x32_bf16(Bt[n][k], At[m][k], acc[ai][bj][m][n], 0, 0, 0); __builtin_amdgcn_s_setprio(0); } while (0)
; #define PG8_WAIT_V(n) asm volatile("s_waitcnt vmcnt(" #n ")" ::: "memory")
; #define PG8_WAIT_L(n) asm volatile("s_waitcnt lgkmcnt(" #n ")" ::: "memory")
; #define PG8_BAR __builtin_amdgcn_s_barrier()
; #define PG8_SCHED __builtin_amdgcn_sched_barrier(0)
; template <class Epi, class Sched, bool ALIGN_EPI = false, bool SP2 = false>
; __device__ __forceinline__ void gemm_phase(PG8_LAS unsigned char* lds, const Gemm g, const Sched& S, const Epi& E, const int tid_in) {
;     ...
;             PG8_WAIT_V(8); PG8_WAIT_L(0); PG8_BAR; PG8_MMA(1, 0, At, B0); PG8_MMA(1, 1, At, B1); PG8_BAR; PG8_SCHED;
;             PG8_LDB(B0, 1, 0); PG8_LDB(B1, 1, 1); PG8_SCHED; PG8_LDA(At, 1, 0); PG8_STAGE(PG8_SA(0, 1), a2 + hstepA, voffA);
;             PG8_WAIT_V(8); PG8_WAIT_L(0); PG8_BAR; PG8_MMA(0, 0, At, B0); PG8_MMA(0, 1, At, B1); PG8_BAR; PG8_SCHED;
	s_setprio 1
	s_waitcnt lgkmcnt(0)
	v_mfma_f32_16x16x32_bf16 v[60:63], v[104:107], v[172:175], v[60:63]
	v_mfma_f32_16x16x32_bf16 v[56:59], v[120:123], v[172:175], v[56:59]
	v_mfma_f32_16x16x32_bf16 v[44:47], v[104:107], v[180:183], v[44:47]
	v_mfma_f32_16x16x32_bf16 v[40:43], v[120:123], v[180:183], v[40:43]
	v_mfma_f32_16x16x32_bf16 v[28:31], v[104:107], v[194:197], v[28:31]
	v_mfma_f32_16x16x32_bf16 v[24:27], v[120:123], v[194:197], v[24:27]
	v_mfma_f32_16x16x32_bf16 v[12:15], v[104:107], v[202:205], v[12:15]
	v_mfma_f32_16x16x32_bf16 v[8:11], v[120:123], v[202:205], v[8:11]
	v_mfma_f32_16x16x32_bf16 v[60:63], v[112:115], v[176:179], v[60:63]
	v_mfma_f32_16x16x32_bf16 v[56:59], v[124:127], v[176:179], v[56:59]
	v_mfma_f32_16x16x32_bf16 v[44:47], v[112:115], v[186:189], v[44:47]
	v_mfma_f32_16x16x32_bf16 v[40:43], v[124:127], v[186:189], v[40:43]
	v_mfma_f32_16x16x32_bf16 v[28:31], v[112:115], v[198:201], v[28:31]
	v_mfma_f32_16x16x32_bf16 v[24:27], v[124:127], v[198:201], v[24:27]
	v_mfma_f32_16x16x32_bf16 v[12:15], v[112:115], v[206:209], v[12:15]
	v_mfma_f32_16x16x32_bf16 v[8:11], v[124:127], v[206:209], v[8:11]
	s_setprio 0
	s_setprio 1
	v_mfma_f32_16x16x32_bf16 v[52:55], v[156:159], v[172:175], v[52:55]
	v_mfma_f32_16x16x32_bf16 v[48:51], v[164:167], v[172:175], v[48:51]
	v_mfma_f32_16x16x32_bf16 v[36:39], v[156:159], v[180:183], v[36:39]
	v_mfma_f32_16x16x32_bf16 v[32:35], v[164:167], v[180:183], v[32:35]
	v_mfma_f32_16x16x32_bf16 v[20:23], v[156:159], v[194:197], v[20:23]
	v_mfma_f32_16x16x32_bf16 v[16:19], v[164:167], v[194:197], v[16:19]
	v_mfma_f32_16x16x32_bf16 v[4:7], v[156:159], v[202:205], v[4:7]
	v_mfma_f32_16x16x32_bf16 v[0:3], v[164:167], v[202:205], v[0:3]
	v_mfma_f32_16x16x32_bf16 v[52:55], v[160:163], v[176:179], v[52:55]
	v_mfma_f32_16x16x32_bf16 v[48:51], v[168:171], v[176:179], v[48:51]
	v_mfma_f32_16x16x32_bf16 v[36:39], v[160:163], v[186:189], v[36:39]
	v_mfma_f32_16x16x32_bf16 v[32:35], v[168:171], v[186:189], v[32:35]
	v_mfma_f32_16x16x32_bf16 v[20:23], v[160:163], v[198:201], v[20:23]
	v_mfma_f32_16x16x32_bf16 v[16:19], v[168:171], v[198:201], v[16:19]
	v_mfma_f32_16x16x32_bf16 v[4:7], v[160:163], v[206:209], v[4:7]
	v_mfma_f32_16x16x32_bf16 v[0:3], v[168:171], v[206:209], v[0:3]
	s_setprio 2
	s_barrier
	s_add_i32 s6, 0, 0x18000
	s_add_i32 s7, 0, 0x1c000
	v_add_u32_e32 v124, s6, v154
	v_add_u32_e32 v168, s7, v154
	ds_read_b128 v[104:107], v124
	ds_read_b128 v[112:115], v124 offset:1024
	ds_read_b128 v[120:123], v124 offset:2048
	ds_read_b128 v[124:127], v124 offset:3072
	ds_read_b128 v[156:159], v168
	ds_read_b128 v[160:163], v168 offset:1024
	ds_read_b128 v[164:167], v168 offset:2048
	ds_read_b128 v[168:171], v168 offset:3072
	s_add_u32 s60, s60, 0x40000
	s_addc_u32 s61, s61, 0
	s_mov_b32 m0, s64
	v_lshl_add_u64 v[214:215], s[60:61], 0, v[144:145]
	ds_read_b128 v[172:175], v155 offset:32768
	ds_read_b128 v[176:179], v155 offset:33792
	ds_read_b128 v[180:183], v155 offset:34816
	ds_read_b128 v[186:189], v155 offset:35840
	ds_read_b128 v[194:197], v155 offset:36864
	ds_read_b128 v[198:201], v155 offset:37888
	ds_read_b128 v[202:205], v155 offset:38912
	ds_read_b128 v[206:209], v155 offset:39936
	global_load_lds_dwordx4 v[214:215], off
	v_lshl_add_u64 v[214:215], s[60:61], 0, v[146:147]
	s_mov_b32 m0, s65
	s_nop 0
	global_load_lds_dwordx4 v[214:215], off
	s_waitcnt vmcnt(8)
	s_waitcnt lgkmcnt(0)
	s_barrier
	s_setprio 1
	s_waitcnt lgkmcnt(0)
	v_mfma_f32_16x16x32_bf16 v[140:143], v[104:107], v[172:175], v[140:143]
	v_mfma_f32_16x16x32_bf16 v[136:139], v[120:123], v[172:175], v[136:139]
	v_mfma_f32_16x16x32_bf16 v[116:119], v[104:107], v[180:183], v[116:119]
	v_mfma_f32_16x16x32_bf16 v[108:111], v[120:123], v[180:183], v[108:111]
	v_mfma_f32_16x16x32_bf16 v[92:95], v[104:107], v[194:197], v[92:95]
	v_mfma_f32_16x16x32_bf16 v[88:91], v[120:123], v[194:197], v[88:91]
	v_mfma_f32_16x16x32_bf16 v[76:79], v[104:107], v[202:205], v[76:79]
	v_mfma_f32_16x16x32_bf16 v[72:75], v[120:123], v[202:205], v[72:75]
	v_mfma_f32_16x16x32_bf16 v[140:143], v[112:115], v[176:179], v[140:143]
	v_mfma_f32_16x16x32_bf16 v[136:139], v[124:127], v[176:179], v[136:139]
	v_mfma_f32_16x16x32_bf16 v[116:119], v[112:115], v[186:189], v[116:119]
	v_mfma_f32_16x16x32_bf16 v[108:111], v[124:127], v[186:189], v[108:111]
	v_mfma_f32_16x16x32_bf16 v[92:95], v[112:115], v[198:201], v[92:95]
	v_mfma_f32_16x16x32_bf16 v[88:91], v[124:127], v[198:201], v[88:91]
	v_mfma_f32_16x16x32_bf16 v[76:79], v[112:115], v[206:209], v[76:79]
	v_mfma_f32_16x16x32_bf16 v[72:75], v[124:127], v[206:209], v[72:75]
	s_setprio 0
	s_setprio 1
	v_mfma_f32_16x16x32_bf16 v[132:135], v[156:159], v[172:175], v[132:135]
	v_mfma_f32_16x16x32_bf16 v[128:131], v[164:167], v[172:175], v[128:131]
	v_mfma_f32_16x16x32_bf16 v[100:103], v[156:159], v[180:183], v[100:103]
	v_mfma_f32_16x16x32_bf16 v[96:99], v[164:167], v[180:183], v[96:99]
	v_mfma_f32_16x16x32_bf16 v[84:87], v[156:159], v[194:197], v[84:87]
	v_mfma_f32_16x16x32_bf16 v[80:83], v[164:167], v[194:197], v[80:83]
	v_mfma_f32_16x16x32_bf16 v[68:71], v[156:159], v[202:205], v[68:71]
	v_mfma_f32_16x16x32_bf16 v[64:67], v[164:167], v[202:205], v[64:67]
	v_mfma_f32_16x16x32_bf16 v[132:135], v[160:163], v[176:179], v[132:135]
	v_mfma_f32_16x16x32_bf16 v[128:131], v[168:171], v[176:179], v[128:131]
	v_mfma_f32_16x16x32_bf16 v[100:103], v[160:163], v[186:189], v[100:103]
	v_mfma_f32_16x16x32_bf16 v[96:99], v[168:171], v[186:189], v[96:99]
	v_mfma_f32_16x16x32_bf16 v[84:87], v[160:163], v[198:201], v[84:87]
	v_mfma_f32_16x16x32_bf16 v[80:83], v[168:171], v[198:201], v[80:83]
	v_mfma_f32_16x16x32_bf16 v[68:71], v[160:163], v[206:209], v[68:71]
	v_mfma_f32_16x16x32_bf16 v[64:67], v[168:171], v[206:209], v[64:67]
	s_setprio 2
	s_barrier
; #define PG8_STAGE(bufoff, gbase, voff) do { _Pragma("unroll") for (int _i = 0; _i < 2; ++_i) \
;         __builtin_amdgcn_global_load_lds((const unsigned*)((const char*)(gbase) + (voff)[_i]), (PG8_LAS unsigned*)(lds + (bufoff) + ldsw + _i * 8192), 16, 0, 0); } while (0)
; #define PG8_LDA(dst, b, h) do { _Pragma("unroll") for (int m = 0; m < 4; ++m) _Pragma("unroll") for (int k = 0; k < 2; ++k) dst[m][k] = *(const PG8_LAS bf16x8*)(lds + PG8_SA(b, h) + aoff + m * 2048 + k * 1024); } while (0)
; #define PG8_MMA(ai, bj, At, Bt) do { __builtin_amdgcn_s_setprio(1); _Pragma("unroll") for (int m = 0; m < 4; ++m) _Pragma("unroll") for (int n = 0; n < 2; ++n) _Pragma("unroll") for (int k = 0; k < 2; ++k) \
;         acc[ai][bj][m][n] = __builtin_amdgcn_mfma_f32_16x16x32_bf16(Bt[n][k], At[m][k], acc[ai][bj][m][n], 0, 0, 0); __builtin_amdgcn_s_setprio(0); } while (0)
; #define PG8_WAIT_V(n) asm volatile("s_waitcnt vmcnt(" #n ")" ::: "memory")
; #define PG8_WAIT_L(n) asm volatile("s_waitcnt lgkmcnt(" #n ")" ::: "memory")
; #define PG8_BAR __builtin_amdgcn_s_barrier()
; #define PG8_SCHED __builtin_amdgcn_sched_barrier(0)
; template <class Epi, class Sched, bool ALIGN_EPI = false, bool SP2 = false>
; __device__ __forceinline__ void gemm_phase(PG8_LAS unsigned char* lds, const Gemm g, const Sched& S, const Epi& E, const int tid_in) {
;     ...
;         for (int t = 0; t < nt; t += 2) {
;     ...
;             PG8_LDA(At, 1, 1); PG8_STAGE(PG8_SB(1, 0), b3, voffB); PG8_STAGE(PG8_SB(1, 1), b3 + hstep, voffB); PG8_STAGE(PG8_SA(1, 0), a3, voffA);
;             PG8_WAIT_V(8); PG8_WAIT_L(0); PG8_BAR; PG8_MMA(1, 0, At, B0); PG8_MMA(1, 1, At, B1); PG8_BAR; PG8_SCHED;
	s_add_i32 s6, s6, s54
	v_lshl_add_u64 v[190:191], v[190:191], 0, s[84:85]
	s_mov_b32 m0, s6
	ds_read_b128 v[172:175], v155 offset:49152
	ds_read_b128 v[176:179], v155 offset:50176
	ds_read_b128 v[180:183], v155 offset:51200
	ds_read_b128 v[186:189], v155 offset:52224
	ds_read_b128 v[194:197], v155 offset:53248
	ds_read_b128 v[198:201], v155 offset:54272
	ds_read_b128 v[202:205], v155 offset:55296
	ds_read_b128 v[206:209], v155 offset:56320
	global_load_lds_dwordx4 v[190:191], off
	s_add_i32 m0, s6, 0x2000
	s_add_u32 s58, s58, 0x40080
	v_lshl_add_u64 v[190:191], v[192:193], 0, s[84:85]
	s_addc_u32 s59, s59, 0
	s_add_i32 s6, s7, s54
	global_load_lds_dwordx4 v[190:191], off
	v_lshl_add_u64 v[190:191], s[58:59], 0, v[184:185]
	s_mov_b32 m0, s6
	s_nop 0
	global_load_lds_dwordx4 v[190:191], off
	v_lshl_add_u64 v[190:191], s[58:59], 0, v[148:149]
	s_add_i32 m0, s6, 0x2000
	s_nop 0
	global_load_lds_dwordx4 v[190:191], off
	v_lshl_add_u64 v[190:191], v[210:211], 0, s[84:85]
	s_mov_b32 m0, s68
	s_nop 0
	global_load_lds_dwordx4 v[190:191], off
	v_lshl_add_u64 v[190:191], v[212:213], 0, s[84:85]
	s_mov_b32 m0, s69
	s_nop 0
	global_load_lds_dwordx4 v[190:191], off
	s_waitcnt vmcnt(8)
	s_waitcnt lgkmcnt(0)
	s_barrier
	s_setprio 1
	s_waitcnt lgkmcnt(0)
	v_mfma_f32_16x16x32_bf16 v[60:63], v[104:107], v[172:175], v[60:63]
	v_mfma_f32_16x16x32_bf16 v[56:59], v[120:123], v[172:175], v[56:59]
	v_mfma_f32_16x16x32_bf16 v[44:47], v[104:107], v[180:183], v[44:47]
	v_mfma_f32_16x16x32_bf16 v[40:43], v[120:123], v[180:183], v[40:43]
	v_mfma_f32_16x16x32_bf16 v[28:31], v[104:107], v[194:197], v[28:31]
	v_mfma_f32_16x16x32_bf16 v[24:27], v[120:123], v[194:197], v[24:27]
	v_mfma_f32_16x16x32_bf16 v[12:15], v[104:107], v[202:205], v[12:15]
	v_mfma_f32_16x16x32_bf16 v[8:11], v[120:123], v[202:205], v[8:11]
	v_mfma_f32_16x16x32_bf16 v[60:63], v[112:115], v[176:179], v[60:63]
	v_mfma_f32_16x16x32_bf16 v[56:59], v[124:127], v[176:179], v[56:59]
	v_mfma_f32_16x16x32_bf16 v[44:47], v[112:115], v[186:189], v[44:47]
	v_mfma_f32_16x16x32_bf16 v[40:43], v[124:127], v[186:189], v[40:43]
	v_mfma_f32_16x16x32_bf16 v[28:31], v[112:115], v[198:201], v[28:31]
	v_mfma_f32_16x16x32_bf16 v[24:27], v[124:127], v[198:201], v[24:27]
	v_mfma_f32_16x16x32_bf16 v[12:15], v[112:115], v[206:209], v[12:15]
	v_mfma_f32_16x16x32_bf16 v[8:11], v[124:127], v[206:209], v[8:11]
	s_setprio 0
	s_setprio 1
	v_mfma_f32_16x16x32_bf16 v[52:55], v[156:159], v[172:175], v[52:55]
	v_mfma_f32_16x16x32_bf16 v[48:51], v[164:167], v[172:175], v[48:51]
	v_mfma_f32_16x16x32_bf16 v[36:39], v[156:159], v[180:183], v[36:39]
	v_mfma_f32_16x16x32_bf16 v[32:35], v[164:167], v[180:183], v[32:35]
	v_mfma_f32_16x16x32_bf16 v[20:23], v[156:159], v[194:197], v[20:23]
	v_mfma_f32_16x16x32_bf16 v[16:19], v[164:167], v[194:197], v[16:19]
	v_mfma_f32_16x16x32_bf16 v[4:7], v[156:159], v[202:205], v[4:7]
	v_mfma_f32_16x16x32_bf16 v[0:3], v[164:167], v[202:205], v[0:3]
	v_mfma_f32_16x16x32_bf16 v[52:55], v[160:163], v[176:179], v[52:55]
	v_mfma_f32_16x16x32_bf16 v[48:51], v[168:171], v[176:179], v[48:51]
	v_mfma_f32_16x16x32_bf16 v[36:39], v[160:163], v[186:189], v[36:39]
	v_mfma_f32_16x16x32_bf16 v[32:35], v[168:171], v[186:189], v[32:35]
	v_mfma_f32_16x16x32_bf16 v[20:23], v[160:163], v[198:201], v[20:23]
	v_mfma_f32_16x16x32_bf16 v[16:19], v[168:171], v[198:201], v[16:19]
	v_mfma_f32_16x16x32_bf16 v[4:7], v[160:163], v[206:209], v[4:7]
	v_mfma_f32_16x16x32_bf16 v[0:3], v[168:171], v[206:209], v[0:3]
	s_setprio 2
	s_barrier
	s_add_i32 s15, s15, 2
	s_add_u32 s56, s56, 0x100
	s_addc_u32 s57, s57, 0
	s_add_u32 s77, s77, 0x100
	s_addc_u32 s14, s14, 0
	s_cmp_gt_u32 s15, 13
	s_cbranch_scc1 .LBB0_921

; #define PG8_STAGE(bufoff, gbase, voff) do { _Pragma("unroll") for (int _i = 0; _i < 2; ++_i) \
;         __builtin_amdgcn_global_load_lds((const unsigned*)((const char*)(gbase) + (voff)[_i]), (PG8_LAS unsigned*)(lds + (bufoff) + ldsw + _i * 8192), 16, 0, 0); } while (0)
; #define PG8_LDA(dst, b, h) do { _Pragma("unroll") for (int m = 0; m < 4; ++m) _Pragma("unroll") for (int k = 0; k < 2; ++k) dst[m][k] = *(const PG8_LAS bf16x8*)(lds + PG8_SA(b, h) + aoff + m * 2048 + k * 1024); } while (0)
; #define PG8_LDB(dst, b, h) do { _Pragma("unroll") for (int n = 0; n < 2; ++n) _Pragma("unroll") for (int k = 0; k < 2; ++k) dst[n][k] = *(const PG8_LAS bf16x8*)(lds + PG8_SB(b, h) + boff + n * 2048 + k * 1024); } while (0)
; #define PG8_MMA(ai, bj, At, Bt) do { __builtin_amdgcn_s_setprio(1); _Pragma("unroll") for (int m = 0; m < 4; ++m) _Pragma("unroll") for (int n = 0; n < 2; ++n) _Pragma("unroll") for (int k = 0; k < 2; ++k) \
;         acc[ai][bj][m][n] = __builtin_amdgcn_mfma_f32_16x16x32_bf16(Bt[n][k], At[m][k], acc[ai][bj][m][n], 0, 0, 0); __builtin_amdgcn_s_setprio(0); } while (0)
; #define PG8_WAIT_V(n) asm volatile("s_waitcnt vmcnt(" #n ")" ::: "memory")
; #define PG8_WAIT_L(n) asm volatile("s_waitcnt lgkmcnt(" #n ")" ::: "memory")
; #define PG8_BAR __builtin_amdgcn_s_barrier()
; #define PG8_SCHED __builtin_amdgcn_sched_barrier(0)
; template <class Epi, class Sched, bool ALIGN_EPI = false, bool SP2 = false>
; __device__ __forceinline__ void gemm_phase(PG8_LAS unsigned char* lds, const Gemm g, const Sched& S, const Epi& E, const int tid_in) {
;     ...
;             const bool last = (t == nt - 2);
;             const char* a1 = cA + (size_t)(t + 1) * kstepA;
;             const char* a2 = last ? nA : cA + (size_t)(t + 2) * kstepA; const char* b2 = last ? nB : cB + (size_t)(t + 2) * kstep;
;             const char* a3 = a2 + kstepA; const char* b3 = b2 + kstep;
;             if (last && has_next) S.a_ready(nxt, ui + 1);
;             if constexpr (SP2) {
;             PG8_LDB(B0, 0, 0); PG8_LDB(B1, 0, 1); PG8_SCHED; PG8_LDA(At, 0, 0); PG8_STAGE(PG8_SA(1, 1), a1 + hstepA, voffA);
;             PG8_WAIT_V(8); PG8_WAIT_L(0); PG8_BAR; PG8_MMA(0, 0, At, B0); PG8_MMA(0, 1, At, B1); PG8_BAR; PG8_SCHED;
;             PG8_LDA(At, 0, 1); PG8_STAGE(PG8_SB(0, 0), b2, voffB); PG8_STAGE(PG8_SB(0, 1), b2 + hstep, voffB); PG8_STAGE(PG8_SA(0, 0), a2, voffA);
.LBB0_940:
	s_add_u32 s58, s56, 0x800000
	s_addc_u32 s59, s57, 0
	s_cmp_eq_u32 s77, 4
	s_cselect_b32 s64, s15, s58
	s_cselect_b32 s65, s14, s59
	s_cselect_b32 s62, s45, s52
	s_cselect_b32 s63, s43, s53
	s_add_u32 s60, s64, 0x400000
	s_addc_u32 s61, s65, 0
	s_add_i32 s6, 0, 0x10000
	s_add_i32 s7, 0, 0x14000
	v_add_u32_e32 v92, s6, v186
	v_add_u32_e32 v156, s7, v186
	ds_read_b128 v[72:75], v92
	ds_read_b128 v[80:83], v92 offset:1024
	ds_read_b128 v[88:91], v92 offset:2048
	ds_read_b128 v[92:95], v92 offset:3072
	ds_read_b128 v[144:147], v156
	ds_read_b128 v[148:151], v156 offset:1024
	ds_read_b128 v[152:155], v156 offset:2048
	ds_read_b128 v[156:159], v156 offset:3072
	v_lshl_add_u64 v[192:193], s[56:57], 0, v[172:173]
	s_add_i32 m0, s66, 0xc000
	ds_read_b128 v[160:163], v187
	ds_read_b128 v[176:179], v187 offset:1024
	ds_read_b128 v[180:183], v187 offset:2048
	ds_read_b128 v[188:191], v187 offset:3072
	ds_read_b128 v[194:197], v187 offset:4096
	ds_read_b128 v[198:201], v187 offset:5120
	ds_read_b128 v[202:205], v187 offset:6144
	ds_read_b128 v[206:209], v187 offset:7168
	global_load_lds_dwordx4 v[192:193], off
	v_lshl_add_u64 v[192:193], s[56:57], 0, v[174:175]
	s_add_i32 m0, s66, 0xe000
	s_nop 0
	global_load_lds_dwordx4 v[192:193], off
	s_waitcnt vmcnt(8)
	s_waitcnt lgkmcnt(0)
	s_barrier
	s_setprio 1
	s_waitcnt lgkmcnt(0)
	v_mfma_f32_16x16x32_bf16 v[140:143], v[72:75], v[160:163], v[140:143]
	v_mfma_f32_16x16x32_bf16 v[136:139], v[88:91], v[160:163], v[136:139]
	v_mfma_f32_16x16x32_bf16 v[124:127], v[72:75], v[180:183], v[124:127]
	v_mfma_f32_16x16x32_bf16 v[120:123], v[88:91], v[180:183], v[120:123]
	v_mfma_f32_16x16x32_bf16 v[108:111], v[72:75], v[194:197], v[108:111]
	v_mfma_f32_16x16x32_bf16 v[104:107], v[88:91], v[194:197], v[104:107]
	v_mfma_f32_16x16x32_bf16 v[84:87], v[72:75], v[202:205], v[84:87]
	v_mfma_f32_16x16x32_bf16 v[76:79], v[88:91], v[202:205], v[76:79]
	v_mfma_f32_16x16x32_bf16 v[140:143], v[80:83], v[176:179], v[140:143]
	v_mfma_f32_16x16x32_bf16 v[136:139], v[92:95], v[176:179], v[136:139]
	v_mfma_f32_16x16x32_bf16 v[124:127], v[80:83], v[188:191], v[124:127]
	v_mfma_f32_16x16x32_bf16 v[120:123], v[92:95], v[188:191], v[120:123]
	v_mfma_f32_16x16x32_bf16 v[108:111], v[80:83], v[198:201], v[108:111]
	v_mfma_f32_16x16x32_bf16 v[104:107], v[92:95], v[198:201], v[104:107]
	v_mfma_f32_16x16x32_bf16 v[84:87], v[80:83], v[206:209], v[84:87]
	v_mfma_f32_16x16x32_bf16 v[76:79], v[92:95], v[206:209], v[76:79]
	s_setprio 0
	s_setprio 1
	v_mfma_f32_16x16x32_bf16 v[132:135], v[144:147], v[160:163], v[132:135]
	v_mfma_f32_16x16x32_bf16 v[128:131], v[152:155], v[160:163], v[128:131]
	v_mfma_f32_16x16x32_bf16 v[116:119], v[144:147], v[180:183], v[116:119]
	v_mfma_f32_16x16x32_bf16 v[112:115], v[152:155], v[180:183], v[112:115]
	v_mfma_f32_16x16x32_bf16 v[100:103], v[144:147], v[194:197], v[100:103]
	v_mfma_f32_16x16x32_bf16 v[96:99], v[152:155], v[194:197], v[96:99]
	v_mfma_f32_16x16x32_bf16 v[68:71], v[144:147], v[202:205], v[68:71]
	v_mfma_f32_16x16x32_bf16 v[64:67], v[152:155], v[202:205], v[64:67]
	v_mfma_f32_16x16x32_bf16 v[132:135], v[148:151], v[176:179], v[132:135]
	v_mfma_f32_16x16x32_bf16 v[128:131], v[156:159], v[176:179], v[128:131]
	v_mfma_f32_16x16x32_bf16 v[116:119], v[148:151], v[188:191], v[116:119]
	v_mfma_f32_16x16x32_bf16 v[112:115], v[156:159], v[188:191], v[112:115]
	v_mfma_f32_16x16x32_bf16 v[100:103], v[148:151], v[198:201], v[100:103]
	v_mfma_f32_16x16x32_bf16 v[96:99], v[156:159], v[198:201], v[96:99]
	v_mfma_f32_16x16x32_bf16 v[68:71], v[148:151], v[206:209], v[68:71]
	v_mfma_f32_16x16x32_bf16 v[64:67], v[156:159], v[206:209], v[64:67]
	s_setprio 2
	s_barrier
	s_add_i32 s6, s6, s16
	v_lshl_add_u64 v[192:193], s[62:63], 0, v[168:169]
	s_mov_b32 m0, s6
	ds_read_b128 v[160:163], v187 offset:16384
	ds_read_b128 v[176:179], v187 offset:17408
	ds_read_b128 v[180:183], v187 offset:18432
	ds_read_b128 v[188:191], v187 offset:19456
	ds_read_b128 v[194:197], v187 offset:20480
	ds_read_b128 v[198:201], v187 offset:21504
	ds_read_b128 v[202:205], v187 offset:22528
	ds_read_b128 v[206:209], v187 offset:23552
	global_load_lds_dwordx4 v[192:193], off
	s_add_i32 m0, s6, 0x2000
	s_add_u32 s56, s62, 0x20000
	v_lshl_add_u64 v[210:211], s[62:63], 0, v[164:165]
	s_addc_u32 s57, s63, 0
	s_add_i32 s6, s7, s16
	global_load_lds_dwordx4 v[210:211], off
	v_lshl_add_u64 v[212:213], s[56:57], 0, v[168:169]
	s_mov_b32 m0, s6
	s_nop 0
	global_load_lds_dwordx4 v[212:213], off
	v_lshl_add_u64 v[212:213], s[56:57], 0, v[164:165]
	s_add_i32 m0, s6, 0x2000
	s_nop 0
	global_load_lds_dwordx4 v[212:213], off
	v_lshl_add_u64 v[212:213], s[64:65], 0, v[170:171]
	s_mov_b32 m0, s66
	s_nop 0
	global_load_lds_dwordx4 v[212:213], off
	v_lshl_add_u64 v[212:213], s[64:65], 0, v[166:167]
	s_mov_b32 m0, s67
	s_nop 0
	global_load_lds_dwordx4 v[212:213], off
	s_waitcnt vmcnt(8)
	s_waitcnt lgkmcnt(0)
	s_barrier
; #define PG8_STAGE(bufoff, gbase, voff) do { _Pragma("unroll") for (int _i = 0; _i < 2; ++_i) \
;         __builtin_amdgcn_global_load_lds((const unsigned*)((const char*)(gbase) + (voff)[_i]), (PG8_LAS unsigned*)(lds + (bufoff) + ldsw + _i * 8192), 16, 0, 0); } while (0)
; #define PG8_LDA(dst, b, h) do { _Pragma("unroll") for (int m = 0; m < 4; ++m) _Pragma("unroll") for (int k = 0; k < 2; ++k) dst[m][k] = *(const PG8_LAS bf16x8*)(lds + PG8_SA(b, h) + aoff + m * 2048 + k * 1024); } while (0)
; #define PG8_LDB(dst, b, h) do { _Pragma("unroll") for (int n = 0; n < 2; ++n) _Pragma("unroll") for (int k = 0; k < 2; ++k) dst[n][k] = *(const PG8_LAS bf16x8*)(lds + PG8_SB(b, h) + boff + n * 2048 + k * 1024); } while (0)
; #define PG8_MMA(ai, bj, At, Bt) do { __builtin_amdgcn_s_setprio(1); _Pragma("unroll") for (int m = 0; m < 4; ++m) _Pragma("unroll") for (int n = 0; n < 2; ++n) _Pragma("unroll") for (int k = 0; k < 2; ++k) \
;         acc[ai][bj][m][n] = __builtin_amdgcn_mfma_f32_16x16x32_bf16(Bt[n][k], At[m][k], acc[ai][bj][m][n], 0, 0, 0); __builtin_amdgcn_s_setprio(0); } while (0)
; #define PG8_WAIT_V(n) asm volatile("s_waitcnt vmcnt(" #n ")" ::: "memory")
; #define PG8_WAIT_L(n) asm volatile("s_waitcnt lgkmcnt(" #n ")" ::: "memory")
; #define PG8_BAR __builtin_amdgcn_s_barrier()
; #define PG8_SCHED __builtin_amdgcn_sched_barrier(0)
; template <class Epi, class Sched, bool ALIGN_EPI = false, bool SP2 = false>
; __device__ __forceinline__ void gemm_phase(PG8_LAS unsigned char* lds, const Gemm g, const Sched& S, const Epi& E, const int tid_in) {
;     ...
;             PG8_WAIT_V(8); PG8_WAIT_L(0); PG8_BAR; PG8_MMA(1, 0, At, B0); PG8_MMA(1, 1, At, B1); PG8_BAR; PG8_SCHED;
;             PG8_LDB(B0, 1, 0); PG8_LDB(B1, 1, 1); PG8_SCHED; PG8_LDA(At, 1, 0); PG8_STAGE(PG8_SA(0, 1), a2 + hstepA, voffA);
;             PG8_WAIT_V(8); PG8_WAIT_L(0); PG8_BAR; PG8_MMA(0, 0, At, B0); PG8_MMA(0, 1, At, B1); PG8_BAR; PG8_SCHED;
	s_setprio 1
	s_waitcnt lgkmcnt(0)
	v_mfma_f32_16x16x32_bf16 v[60:63], v[72:75], v[160:163], v[60:63]
	v_mfma_f32_16x16x32_bf16 v[56:59], v[88:91], v[160:163], v[56:59]
	v_mfma_f32_16x16x32_bf16 v[44:47], v[72:75], v[180:183], v[44:47]
	v_mfma_f32_16x16x32_bf16 v[40:43], v[88:91], v[180:183], v[40:43]
	v_mfma_f32_16x16x32_bf16 v[28:31], v[72:75], v[194:197], v[28:31]
	v_mfma_f32_16x16x32_bf16 v[24:27], v[88:91], v[194:197], v[24:27]
	v_mfma_f32_16x16x32_bf16 v[12:15], v[72:75], v[202:205], v[12:15]
	v_mfma_f32_16x16x32_bf16 v[8:11], v[88:91], v[202:205], v[8:11]
	v_mfma_f32_16x16x32_bf16 v[60:63], v[80:83], v[176:179], v[60:63]
	v_mfma_f32_16x16x32_bf16 v[56:59], v[92:95], v[176:179], v[56:59]
	v_mfma_f32_16x16x32_bf16 v[44:47], v[80:83], v[188:191], v[44:47]
	v_mfma_f32_16x16x32_bf16 v[40:43], v[92:95], v[188:191], v[40:43]
	v_mfma_f32_16x16x32_bf16 v[28:31], v[80:83], v[198:201], v[28:31]
	v_mfma_f32_16x16x32_bf16 v[24:27], v[92:95], v[198:201], v[24:27]
	v_mfma_f32_16x16x32_bf16 v[12:15], v[80:83], v[206:209], v[12:15]
	v_mfma_f32_16x16x32_bf16 v[8:11], v[92:95], v[206:209], v[8:11]
	s_setprio 0
	s_setprio 1
	v_mfma_f32_16x16x32_bf16 v[52:55], v[144:147], v[160:163], v[52:55]
	v_mfma_f32_16x16x32_bf16 v[48:51], v[152:155], v[160:163], v[48:51]
	v_mfma_f32_16x16x32_bf16 v[36:39], v[144:147], v[180:183], v[36:39]
	v_mfma_f32_16x16x32_bf16 v[32:35], v[152:155], v[180:183], v[32:35]
	v_mfma_f32_16x16x32_bf16 v[20:23], v[144:147], v[194:197], v[20:23]
	v_mfma_f32_16x16x32_bf16 v[16:19], v[152:155], v[194:197], v[16:19]
	v_mfma_f32_16x16x32_bf16 v[4:7], v[144:147], v[202:205], v[4:7]
	v_mfma_f32_16x16x32_bf16 v[0:3], v[152:155], v[202:205], v[0:3]
	v_mfma_f32_16x16x32_bf16 v[52:55], v[148:151], v[176:179], v[52:55]
	v_mfma_f32_16x16x32_bf16 v[48:51], v[156:159], v[176:179], v[48:51]
	v_mfma_f32_16x16x32_bf16 v[36:39], v[148:151], v[188:191], v[36:39]
	v_mfma_f32_16x16x32_bf16 v[32:35], v[156:159], v[188:191], v[32:35]
	v_mfma_f32_16x16x32_bf16 v[20:23], v[148:151], v[198:201], v[20:23]
	v_mfma_f32_16x16x32_bf16 v[16:19], v[156:159], v[198:201], v[16:19]
	v_mfma_f32_16x16x32_bf16 v[4:7], v[148:151], v[206:209], v[4:7]
	v_mfma_f32_16x16x32_bf16 v[0:3], v[156:159], v[206:209], v[0:3]
	s_setprio 2
	s_barrier
	s_add_i32 s6, 0, 0x18000
	s_add_i32 s7, 0, 0x1c000
	v_add_u32_e32 v92, s6, v186
	v_add_u32_e32 v156, s7, v186
	ds_read_b128 v[72:75], v92
	ds_read_b128 v[80:83], v92 offset:1024
	ds_read_b128 v[88:91], v92 offset:2048
	ds_read_b128 v[92:95], v92 offset:3072
	ds_read_b128 v[144:147], v156
	ds_read_b128 v[148:151], v156 offset:1024
	ds_read_b128 v[152:155], v156 offset:2048
	ds_read_b128 v[156:159], v156 offset:3072
	s_add_u32 s56, s64, 0x1000
	s_addc_u32 s57, s65, 0
	s_mov_b32 m0, s68
	v_lshl_add_u64 v[212:213], s[56:57], 0, v[170:171]
	ds_read_b128 v[160:163], v187 offset:32768
	ds_read_b128 v[176:179], v187 offset:33792
	ds_read_b128 v[180:183], v187 offset:34816
	ds_read_b128 v[188:191], v187 offset:35840
	ds_read_b128 v[194:197], v187 offset:36864
	ds_read_b128 v[198:201], v187 offset:37888
	ds_read_b128 v[202:205], v187 offset:38912
	ds_read_b128 v[206:209], v187 offset:39936
	global_load_lds_dwordx4 v[212:213], off
	v_lshl_add_u64 v[212:213], s[56:57], 0, v[166:167]
	s_mov_b32 m0, s69
	s_nop 0
	global_load_lds_dwordx4 v[212:213], off
	s_waitcnt vmcnt(8)
	s_waitcnt lgkmcnt(0)
	s_barrier
	s_setprio 1
	s_waitcnt lgkmcnt(0)
	v_mfma_f32_16x16x32_bf16 v[140:143], v[72:75], v[160:163], v[140:143]
	v_mfma_f32_16x16x32_bf16 v[136:139], v[88:91], v[160:163], v[136:139]
	v_mfma_f32_16x16x32_bf16 v[124:127], v[72:75], v[180:183], v[124:127]
	v_mfma_f32_16x16x32_bf16 v[120:123], v[88:91], v[180:183], v[120:123]
	v_mfma_f32_16x16x32_bf16 v[108:111], v[72:75], v[194:197], v[108:111]
	v_mfma_f32_16x16x32_bf16 v[104:107], v[88:91], v[194:197], v[104:107]
	v_mfma_f32_16x16x32_bf16 v[84:87], v[72:75], v[202:205], v[84:87]
	v_mfma_f32_16x16x32_bf16 v[76:79], v[88:91], v[202:205], v[76:79]
	v_mfma_f32_16x16x32_bf16 v[140:143], v[80:83], v[176:179], v[140:143]
	v_mfma_f32_16x16x32_bf16 v[136:139], v[92:95], v[176:179], v[136:139]
	v_mfma_f32_16x16x32_bf16 v[124:127], v[80:83], v[188:191], v[124:127]
	v_mfma_f32_16x16x32_bf16 v[120:123], v[92:95], v[188:191], v[120:123]
	v_mfma_f32_16x16x32_bf16 v[108:111], v[80:83], v[198:201], v[108:111]
	v_mfma_f32_16x16x32_bf16 v[104:107], v[92:95], v[198:201], v[104:107]
	v_mfma_f32_16x16x32_bf16 v[84:87], v[80:83], v[206:209], v[84:87]
	v_mfma_f32_16x16x32_bf16 v[76:79], v[92:95], v[206:209], v[76:79]
	s_setprio 0
	s_setprio 1
	v_mfma_f32_16x16x32_bf16 v[132:135], v[144:147], v[160:163], v[132:135]
	v_mfma_f32_16x16x32_bf16 v[128:131], v[152:155], v[160:163], v[128:131]
	v_mfma_f32_16x16x32_bf16 v[116:119], v[144:147], v[180:183], v[116:119]
	v_mfma_f32_16x16x32_bf16 v[112:115], v[152:155], v[180:183], v[112:115]
	v_mfma_f32_16x16x32_bf16 v[100:103], v[144:147], v[194:197], v[100:103]
	v_mfma_f32_16x16x32_bf16 v[96:99], v[152:155], v[194:197], v[96:99]
	v_mfma_f32_16x16x32_bf16 v[68:71], v[144:147], v[202:205], v[68:71]
	v_mfma_f32_16x16x32_bf16 v[64:67], v[152:155], v[202:205], v[64:67]
	v_mfma_f32_16x16x32_bf16 v[132:135], v[148:151], v[176:179], v[132:135]
	v_mfma_f32_16x16x32_bf16 v[128:131], v[156:159], v[176:179], v[128:131]
	v_mfma_f32_16x16x32_bf16 v[116:119], v[148:151], v[188:191], v[116:119]
	v_mfma_f32_16x16x32_bf16 v[112:115], v[156:159], v[188:191], v[112:115]
	v_mfma_f32_16x16x32_bf16 v[100:103], v[148:151], v[198:201], v[100:103]
	v_mfma_f32_16x16x32_bf16 v[96:99], v[156:159], v[198:201], v[96:99]
	v_mfma_f32_16x16x32_bf16 v[68:71], v[148:151], v[206:209], v[68:71]
	v_mfma_f32_16x16x32_bf16 v[64:67], v[156:159], v[206:209], v[64:67]
	s_setprio 2
	s_barrier
; #define PG8_STAGE(bufoff, gbase, voff) do { _Pragma("unroll") for (int _i = 0; _i < 2; ++_i) \
;         __builtin_amdgcn_global_load_lds((const unsigned*)((const char*)(gbase) + (voff)[_i]), (PG8_LAS unsigned*)(lds + (bufoff) + ldsw + _i * 8192), 16, 0, 0); } while (0)
; #define PG8_LDA(dst, b, h) do { _Pragma("unroll") for (int m = 0; m < 4; ++m) _Pragma("unroll") for (int k = 0; k < 2; ++k) dst[m][k] = *(const PG8_LAS bf16x8*)(lds + PG8_SA(b, h) + aoff + m * 2048 + k * 1024); } while (0)
; #define PG8_MMA(ai, bj, At, Bt) do { __builtin_amdgcn_s_setprio(1); _Pragma("unroll") for (int m = 0; m < 4; ++m) _Pragma("unroll") for (int n = 0; n < 2; ++n) _Pragma("unroll") for (int k = 0; k < 2; ++k) \
;         acc[ai][bj][m][n] = __builtin_amdgcn_mfma_f32_16x16x32_bf16(Bt[n][k], At[m][k], acc[ai][bj][m][n], 0, 0, 0); __builtin_amdgcn_s_setprio(0); } while (0)
; #define PG8_WAIT_V(n) asm volatile("s_waitcnt vmcnt(" #n ")" ::: "memory")
; #define PG8_WAIT_L(n) asm volatile("s_waitcnt lgkmcnt(" #n ")" ::: "memory")
; #define PG8_BAR __builtin_amdgcn_s_barrier()
; #define PG8_SCHED __builtin_amdgcn_sched_barrier(0)
; template <class Epi, class Sched, bool ALIGN_EPI = false, bool SP2 = false>
; __device__ __forceinline__ void gemm_phase(PG8_LAS unsigned char* lds, const Gemm g, const Sched& S, const Epi& E, const int tid_in) {
;     ...
;         for (int t = 0; t < nt; t += 2) {
;     ...
;             PG8_LDA(At, 1, 1); PG8_STAGE(PG8_SB(1, 0), b3, voffB); PG8_STAGE(PG8_SB(1, 1), b3 + hstep, voffB); PG8_STAGE(PG8_SA(1, 0), a3, voffA);
;             PG8_WAIT_V(8); PG8_WAIT_L(0); PG8_BAR; PG8_MMA(1, 0, At, B0); PG8_MMA(1, 1, At, B1); PG8_BAR; PG8_SCHED;
	s_add_i32 s6, s6, s16
	v_lshl_add_u64 v[192:193], v[192:193], 0, s[84:85]
	s_mov_b32 m0, s6
	ds_read_b128 v[160:163], v187 offset:49152
	ds_read_b128 v[176:179], v187 offset:50176
	ds_read_b128 v[180:183], v187 offset:51200
	ds_read_b128 v[188:191], v187 offset:52224
	ds_read_b128 v[194:197], v187 offset:53248
	ds_read_b128 v[198:201], v187 offset:54272
	ds_read_b128 v[202:205], v187 offset:55296
	ds_read_b128 v[206:209], v187 offset:56320
	global_load_lds_dwordx4 v[192:193], off
	s_add_i32 m0, s6, 0x2000
	s_add_u32 s56, s62, 0x20080
	v_lshl_add_u64 v[192:193], v[210:211], 0, s[84:85]
	s_addc_u32 s57, s63, 0
	s_add_i32 s6, s7, s16
	global_load_lds_dwordx4 v[192:193], off
	v_lshl_add_u64 v[192:193], s[56:57], 0, v[168:169]
	s_mov_b32 m0, s6
	s_nop 0
	global_load_lds_dwordx4 v[192:193], off
	v_lshl_add_u64 v[192:193], s[56:57], 0, v[164:165]
	s_add_i32 m0, s6, 0x2000
	s_nop 0
	global_load_lds_dwordx4 v[192:193], off
	v_lshl_add_u64 v[192:193], s[60:61], 0, v[170:171]
	s_mov_b32 m0, s88
	s_nop 0
	global_load_lds_dwordx4 v[192:193], off
	v_lshl_add_u64 v[192:193], s[60:61], 0, v[166:167]
	s_mov_b32 m0, s78
	s_nop 0
	global_load_lds_dwordx4 v[192:193], off
	s_waitcnt vmcnt(8)
	s_waitcnt lgkmcnt(0)
	s_barrier
	s_setprio 1
	s_waitcnt lgkmcnt(0)
	v_mfma_f32_16x16x32_bf16 v[60:63], v[72:75], v[160:163], v[60:63]
	v_mfma_f32_16x16x32_bf16 v[56:59], v[88:91], v[160:163], v[56:59]
	v_mfma_f32_16x16x32_bf16 v[44:47], v[72:75], v[180:183], v[44:47]
	v_mfma_f32_16x16x32_bf16 v[40:43], v[88:91], v[180:183], v[40:43]
	v_mfma_f32_16x16x32_bf16 v[28:31], v[72:75], v[194:197], v[28:31]
	v_mfma_f32_16x16x32_bf16 v[24:27], v[88:91], v[194:197], v[24:27]
	v_mfma_f32_16x16x32_bf16 v[12:15], v[72:75], v[202:205], v[12:15]
	v_mfma_f32_16x16x32_bf16 v[8:11], v[88:91], v[202:205], v[8:11]
	v_mfma_f32_16x16x32_bf16 v[60:63], v[80:83], v[176:179], v[60:63]
	v_mfma_f32_16x16x32_bf16 v[56:59], v[92:95], v[176:179], v[56:59]
	v_mfma_f32_16x16x32_bf16 v[44:47], v[80:83], v[188:191], v[44:47]
	v_mfma_f32_16x16x32_bf16 v[40:43], v[92:95], v[188:191], v[40:43]
	v_mfma_f32_16x16x32_bf16 v[28:31], v[80:83], v[198:201], v[28:31]
	v_mfma_f32_16x16x32_bf16 v[24:27], v[92:95], v[198:201], v[24:27]
	v_mfma_f32_16x16x32_bf16 v[12:15], v[80:83], v[206:209], v[12:15]
	v_mfma_f32_16x16x32_bf16 v[8:11], v[92:95], v[206:209], v[8:11]
	s_setprio 0
	s_setprio 1
	v_mfma_f32_16x16x32_bf16 v[52:55], v[144:147], v[160:163], v[52:55]
	v_mfma_f32_16x16x32_bf16 v[48:51], v[152:155], v[160:163], v[48:51]
	v_mfma_f32_16x16x32_bf16 v[36:39], v[144:147], v[180:183], v[36:39]
	v_mfma_f32_16x16x32_bf16 v[32:35], v[152:155], v[180:183], v[32:35]
	v_mfma_f32_16x16x32_bf16 v[20:23], v[144:147], v[194:197], v[20:23]
	v_mfma_f32_16x16x32_bf16 v[16:19], v[152:155], v[194:197], v[16:19]
	v_mfma_f32_16x16x32_bf16 v[4:7], v[144:147], v[202:205], v[4:7]
	v_mfma_f32_16x16x32_bf16 v[0:3], v[152:155], v[202:205], v[0:3]
	v_mfma_f32_16x16x32_bf16 v[52:55], v[148:151], v[176:179], v[52:55]
	v_mfma_f32_16x16x32_bf16 v[48:51], v[156:159], v[176:179], v[48:51]
	v_mfma_f32_16x16x32_bf16 v[36:39], v[148:151], v[188:191], v[36:39]
	v_mfma_f32_16x16x32_bf16 v[32:35], v[156:159], v[188:191], v[32:35]
	v_mfma_f32_16x16x32_bf16 v[20:23], v[148:151], v[198:201], v[20:23]
	v_mfma_f32_16x16x32_bf16 v[16:19], v[156:159], v[198:201], v[16:19]
	v_mfma_f32_16x16x32_bf16 v[4:7], v[148:151], v[206:209], v[4:7]
	v_mfma_f32_16x16x32_bf16 v[0:3], v[156:159], v[206:209], v[0:3]
	s_setprio 2
	s_barrier
	s_add_i32 s77, s77, 2
	s_add_u32 s52, s52, 0x100
	s_addc_u32 s53, s53, 0
	s_cmp_gt_u32 s77, 5
	s_mov_b64 s[56:57], s[58:59]
	s_cbranch_scc0 .LBB0_940
	s_and_b64 vcc, exec, s[40:41]
	s_cbranch_vccz .LBB0_943
	s_barrier

; #define PG8_STAGE(bufoff, gbase, voff) do { _Pragma("unroll") for (int _i = 0; _i < 2; ++_i) \
;         __builtin_amdgcn_global_load_lds((const unsigned*)((const char*)(gbase) + (voff)[_i]), (PG8_LAS unsigned*)(lds + (bufoff) + ldsw + _i * 8192), 16, 0, 0); } while (0)
; #define PG8_LDA(dst, b, h) do { _Pragma("unroll") for (int m = 0; m < 4; ++m) _Pragma("unroll") for (int k = 0; k < 2; ++k) dst[m][k] = *(const PG8_LAS bf16x8*)(lds + PG8_SA(b, h) + aoff + m * 2048 + k * 1024); } while (0)
; #define PG8_LDB(dst, b, h) do { _Pragma("unroll") for (int n = 0; n < 2; ++n) _Pragma("unroll") for (int k = 0; k < 2; ++k) dst[n][k] = *(const PG8_LAS bf16x8*)(lds + PG8_SB(b, h) + boff + n * 2048 + k * 1024); } while (0)
; #define PG8_MMA(ai, bj, At, Bt) do { __builtin_amdgcn_s_setprio(1); _Pragma("unroll") for (int m = 0; m < 4; ++m) _Pragma("unroll") for (int n = 0; n < 2; ++n) _Pragma("unroll") for (int k = 0; k < 2; ++k) \
;         acc[ai][bj][m][n] = __builtin_amdgcn_mfma_f32_16x16x32_bf16(Bt[n][k], At[m][k], acc[ai][bj][m][n], 0, 0, 0); __builtin_amdgcn_s_setprio(0); } while (0)
; #define PG8_WAIT_V(n) asm volatile("s_waitcnt vmcnt(" #n ")" ::: "memory")
; #define PG8_WAIT_L(n) asm volatile("s_waitcnt lgkmcnt(" #n ")" ::: "memory")
; #define PG8_BAR __builtin_amdgcn_s_barrier()
; #define PG8_SCHED __builtin_amdgcn_sched_barrier(0)
; template <class Epi, class Sched, bool ALIGN_EPI = false, bool SP2 = false>
; __device__ __forceinline__ void gemm_phase(PG8_LAS unsigned char* lds, const Gemm g, const Sched& S, const Epi& E, const int tid_in) {
;     ...
;             const bool last = (t == nt - 2);
;             const char* a1 = cA + (size_t)(t + 1) * kstepA;
;             const char* a2 = last ? nA : cA + (size_t)(t + 2) * kstepA; const char* b2 = last ? nB : cB + (size_t)(t + 2) * kstep;
;             const char* a3 = a2 + kstepA; const char* b3 = b2 + kstep;
;             if (last && has_next) S.a_ready(nxt, ui + 1);
;             if constexpr (SP2) {
;             PG8_LDB(B0, 0, 0); PG8_LDB(B1, 0, 1); PG8_SCHED; PG8_LDA(At, 0, 0); PG8_STAGE(PG8_SA(1, 1), a1 + hstepA, voffA);
;             PG8_WAIT_V(8); PG8_WAIT_L(0); PG8_BAR; PG8_MMA(0, 0, At, B0); PG8_MMA(0, 1, At, B1); PG8_BAR; PG8_SCHED;
;             PG8_LDA(At, 0, 1); PG8_STAGE(PG8_SB(0, 0), b2, voffB); PG8_STAGE(PG8_SB(0, 1), b2 + hstep, voffB); PG8_STAGE(PG8_SA(0, 0), a2, voffA);
.LBB0_1017:
	s_add_u32 s6, s56, 0xfffe0080
	s_addc_u32 s7, s57, -1
	s_add_i32 s53, 0, 0x10000
	s_cmp_eq_u32 s52, 4
	s_cselect_b32 s61, s3, s7
	s_cselect_b32 s60, s12, s6
	s_cselect_b32 s59, s14, s45
	s_cselect_b32 s58, s15, s43
	s_add_i32 s6, 0, 0x14000
	v_add_u32_e32 v140, s53, v164
	v_add_u32_e32 v162, s6, v164
	ds_read_b128 v[128:131], v140
	ds_read_b128 v[132:135], v140 offset:1024
	ds_read_b128 v[136:139], v140 offset:2048
	ds_read_b128 v[140:143], v140 offset:3072
	ds_read_b128 v[144:147], v162
	ds_read_b128 v[148:151], v162 offset:1024
	ds_read_b128 v[166:169], v162 offset:2048
	ds_read_b128 v[170:173], v162 offset:3072
	v_lshl_add_u64 v[162:163], s[56:57], 0, v[158:159]
	s_add_i32 m0, s64, 0xc000
	ds_read_b128 v[174:177], v165
	ds_read_b128 v[178:181], v165 offset:1024
	ds_read_b128 v[186:189], v165 offset:2048
	ds_read_b128 v[194:197], v165 offset:3072
	ds_read_b128 v[198:201], v165 offset:4096
	ds_read_b128 v[202:205], v165 offset:5120
	ds_read_b128 v[206:209], v165 offset:6144
	ds_read_b128 v[210:213], v165 offset:7168
	global_load_lds_dwordx4 v[162:163], off
	v_lshl_add_u64 v[162:163], s[56:57], 0, v[160:161]
	s_add_i32 m0, s64, 0xe000
	s_nop 0
	global_load_lds_dwordx4 v[162:163], off
	s_waitcnt vmcnt(8)
	s_waitcnt lgkmcnt(0)
	s_barrier
	s_setprio 1
	s_waitcnt lgkmcnt(0)
	v_mfma_f32_16x16x32_bf16 v[124:127], v[128:131], v[174:177], v[124:127]
	v_mfma_f32_16x16x32_bf16 v[120:123], v[136:139], v[174:177], v[120:123]
	v_mfma_f32_16x16x32_bf16 v[116:119], v[128:131], v[186:189], v[116:119]
	v_mfma_f32_16x16x32_bf16 v[112:115], v[136:139], v[186:189], v[112:115]
	v_mfma_f32_16x16x32_bf16 v[108:111], v[128:131], v[198:201], v[108:111]
	v_mfma_f32_16x16x32_bf16 v[104:107], v[136:139], v[198:201], v[104:107]
	v_mfma_f32_16x16x32_bf16 v[100:103], v[128:131], v[206:209], v[100:103]
	v_mfma_f32_16x16x32_bf16 v[96:99], v[136:139], v[206:209], v[96:99]
	v_mfma_f32_16x16x32_bf16 v[124:127], v[132:135], v[178:181], v[124:127]
	v_mfma_f32_16x16x32_bf16 v[120:123], v[140:143], v[178:181], v[120:123]
	v_mfma_f32_16x16x32_bf16 v[116:119], v[132:135], v[194:197], v[116:119]
	v_mfma_f32_16x16x32_bf16 v[112:115], v[140:143], v[194:197], v[112:115]
	v_mfma_f32_16x16x32_bf16 v[108:111], v[132:135], v[202:205], v[108:111]
	v_mfma_f32_16x16x32_bf16 v[104:107], v[140:143], v[202:205], v[104:107]
	v_mfma_f32_16x16x32_bf16 v[100:103], v[132:135], v[210:213], v[100:103]
	v_mfma_f32_16x16x32_bf16 v[96:99], v[140:143], v[210:213], v[96:99]
	s_setprio 0
	s_setprio 1
	v_mfma_f32_16x16x32_bf16 v[92:95], v[144:147], v[174:177], v[92:95]
	v_mfma_f32_16x16x32_bf16 v[88:91], v[166:169], v[174:177], v[88:91]
	v_mfma_f32_16x16x32_bf16 v[84:87], v[144:147], v[186:189], v[84:87]
	v_mfma_f32_16x16x32_bf16 v[80:83], v[166:169], v[186:189], v[80:83]
	v_mfma_f32_16x16x32_bf16 v[76:79], v[144:147], v[198:201], v[76:79]
	v_mfma_f32_16x16x32_bf16 v[72:75], v[166:169], v[198:201], v[72:75]
	v_mfma_f32_16x16x32_bf16 v[68:71], v[144:147], v[206:209], v[68:71]
	v_mfma_f32_16x16x32_bf16 v[64:67], v[166:169], v[206:209], v[64:67]
	v_mfma_f32_16x16x32_bf16 v[92:95], v[148:151], v[178:181], v[92:95]
	v_mfma_f32_16x16x32_bf16 v[88:91], v[170:173], v[178:181], v[88:91]
	v_mfma_f32_16x16x32_bf16 v[84:87], v[148:151], v[194:197], v[84:87]
	v_mfma_f32_16x16x32_bf16 v[80:83], v[170:173], v[194:197], v[80:83]
	v_mfma_f32_16x16x32_bf16 v[76:79], v[148:151], v[202:205], v[76:79]
	v_mfma_f32_16x16x32_bf16 v[72:75], v[170:173], v[202:205], v[72:75]
	v_mfma_f32_16x16x32_bf16 v[68:71], v[148:151], v[210:213], v[68:71]
	v_mfma_f32_16x16x32_bf16 v[64:67], v[170:173], v[210:213], v[64:67]
	s_setprio 2
	s_barrier
	s_add_i32 s7, s53, s63
	v_lshl_add_u64 v[162:163], s[58:59], 0, v[184:185]
	s_mov_b32 m0, s7
	ds_read_b128 v[174:177], v165 offset:16384
	ds_read_b128 v[178:181], v165 offset:17408
	ds_read_b128 v[186:189], v165 offset:18432
	ds_read_b128 v[194:197], v165 offset:19456
	ds_read_b128 v[198:201], v165 offset:20480
	ds_read_b128 v[202:205], v165 offset:21504
	ds_read_b128 v[206:209], v165 offset:22528
	ds_read_b128 v[210:213], v165 offset:23552
	global_load_lds_dwordx4 v[162:163], off
	s_add_i32 m0, s7, 0x2000
	s_add_u32 vcc_lo, s58, 0x20000
	v_lshl_add_u64 v[182:183], s[58:59], 0, v[152:153]
	s_addc_u32 vcc_hi, s59, 0
	s_add_i32 s6, s6, s63
	global_load_lds_dwordx4 v[182:183], off
	v_lshl_add_u64 v[190:191], vcc, 0, v[184:185]
	s_mov_b32 m0, s6
	v_lshl_add_u64 v[192:193], s[60:61], 0, v[154:155]
	global_load_lds_dwordx4 v[190:191], off
	v_lshl_add_u64 v[190:191], vcc, 0, v[152:153]
	s_add_i32 m0, s6, 0x2000
	s_nop 0
	global_load_lds_dwordx4 v[190:191], off
	v_lshl_add_u64 v[190:191], s[60:61], 0, v[156:157]
	s_mov_b32 m0, s64
	s_nop 0
	global_load_lds_dwordx4 v[190:191], off
	s_mov_b32 m0, s65
	s_nop 0
	global_load_lds_dwordx4 v[192:193], off
	s_waitcnt vmcnt(8)
	s_waitcnt lgkmcnt(0)
	s_barrier
; #define PG8_STAGE(bufoff, gbase, voff) do { _Pragma("unroll") for (int _i = 0; _i < 2; ++_i) \
;         __builtin_amdgcn_global_load_lds((const unsigned*)((const char*)(gbase) + (voff)[_i]), (PG8_LAS unsigned*)(lds + (bufoff) + ldsw + _i * 8192), 16, 0, 0); } while (0)
; #define PG8_LDA(dst, b, h) do { _Pragma("unroll") for (int m = 0; m < 4; ++m) _Pragma("unroll") for (int k = 0; k < 2; ++k) dst[m][k] = *(const PG8_LAS bf16x8*)(lds + PG8_SA(b, h) + aoff + m * 2048 + k * 1024); } while (0)
; #define PG8_LDB(dst, b, h) do { _Pragma("unroll") for (int n = 0; n < 2; ++n) _Pragma("unroll") for (int k = 0; k < 2; ++k) dst[n][k] = *(const PG8_LAS bf16x8*)(lds + PG8_SB(b, h) + boff + n * 2048 + k * 1024); } while (0)
; #define PG8_MMA(ai, bj, At, Bt) do { __builtin_amdgcn_s_setprio(1); _Pragma("unroll") for (int m = 0; m < 4; ++m) _Pragma("unroll") for (int n = 0; n < 2; ++n) _Pragma("unroll") for (int k = 0; k < 2; ++k) \
;         acc[ai][bj][m][n] = __builtin_amdgcn_mfma_f32_16x16x32_bf16(Bt[n][k], At[m][k], acc[ai][bj][m][n], 0, 0, 0); __builtin_amdgcn_s_setprio(0); } while (0)
; #define PG8_WAIT_V(n) asm volatile("s_waitcnt vmcnt(" #n ")" ::: "memory")
; #define PG8_WAIT_L(n) asm volatile("s_waitcnt lgkmcnt(" #n ")" ::: "memory")
; #define PG8_BAR __builtin_amdgcn_s_barrier()
; #define PG8_SCHED __builtin_amdgcn_sched_barrier(0)
; template <class Epi, class Sched, bool ALIGN_EPI = false, bool SP2 = false>
; __device__ __forceinline__ void gemm_phase(PG8_LAS unsigned char* lds, const Gemm g, const Sched& S, const Epi& E, const int tid_in) {
;     ...
;             PG8_WAIT_V(8); PG8_WAIT_L(0); PG8_BAR; PG8_MMA(1, 0, At, B0); PG8_MMA(1, 1, At, B1); PG8_BAR; PG8_SCHED;
;             PG8_LDB(B0, 1, 0); PG8_LDB(B1, 1, 1); PG8_SCHED; PG8_LDA(At, 1, 0); PG8_STAGE(PG8_SA(0, 1), a2 + hstepA, voffA);
;             PG8_WAIT_V(8); PG8_WAIT_L(0); PG8_BAR; PG8_MMA(0, 0, At, B0); PG8_MMA(0, 1, At, B1); PG8_BAR; PG8_SCHED;
	s_setprio 1
	s_waitcnt lgkmcnt(0)
	v_mfma_f32_16x16x32_bf16 v[60:63], v[128:131], v[174:177], v[60:63]
	v_mfma_f32_16x16x32_bf16 v[56:59], v[136:139], v[174:177], v[56:59]
	v_mfma_f32_16x16x32_bf16 v[52:55], v[128:131], v[186:189], v[52:55]
	v_mfma_f32_16x16x32_bf16 v[48:51], v[136:139], v[186:189], v[48:51]
	v_mfma_f32_16x16x32_bf16 v[44:47], v[128:131], v[198:201], v[44:47]
	v_mfma_f32_16x16x32_bf16 v[40:43], v[136:139], v[198:201], v[40:43]
	v_mfma_f32_16x16x32_bf16 v[36:39], v[128:131], v[206:209], v[36:39]
	v_mfma_f32_16x16x32_bf16 v[32:35], v[136:139], v[206:209], v[32:35]
	v_mfma_f32_16x16x32_bf16 v[60:63], v[132:135], v[178:181], v[60:63]
	v_mfma_f32_16x16x32_bf16 v[56:59], v[140:143], v[178:181], v[56:59]
	v_mfma_f32_16x16x32_bf16 v[52:55], v[132:135], v[194:197], v[52:55]
	v_mfma_f32_16x16x32_bf16 v[48:51], v[140:143], v[194:197], v[48:51]
	v_mfma_f32_16x16x32_bf16 v[44:47], v[132:135], v[202:205], v[44:47]
	v_mfma_f32_16x16x32_bf16 v[40:43], v[140:143], v[202:205], v[40:43]
	v_mfma_f32_16x16x32_bf16 v[36:39], v[132:135], v[210:213], v[36:39]
	v_mfma_f32_16x16x32_bf16 v[32:35], v[140:143], v[210:213], v[32:35]
	s_setprio 0
	s_setprio 1
	v_mfma_f32_16x16x32_bf16 v[28:31], v[144:147], v[174:177], v[28:31]
	v_mfma_f32_16x16x32_bf16 v[24:27], v[166:169], v[174:177], v[24:27]
	v_mfma_f32_16x16x32_bf16 v[20:23], v[144:147], v[186:189], v[20:23]
	v_mfma_f32_16x16x32_bf16 v[16:19], v[166:169], v[186:189], v[16:19]
	v_mfma_f32_16x16x32_bf16 v[12:15], v[144:147], v[198:201], v[12:15]
	v_mfma_f32_16x16x32_bf16 v[8:11], v[166:169], v[198:201], v[8:11]
	v_mfma_f32_16x16x32_bf16 v[4:7], v[144:147], v[206:209], v[4:7]
	v_mfma_f32_16x16x32_bf16 v[0:3], v[166:169], v[206:209], v[0:3]
	v_mfma_f32_16x16x32_bf16 v[28:31], v[148:151], v[178:181], v[28:31]
	v_mfma_f32_16x16x32_bf16 v[24:27], v[170:173], v[178:181], v[24:27]
	v_mfma_f32_16x16x32_bf16 v[20:23], v[148:151], v[194:197], v[20:23]
	v_mfma_f32_16x16x32_bf16 v[16:19], v[170:173], v[194:197], v[16:19]
	v_mfma_f32_16x16x32_bf16 v[12:15], v[148:151], v[202:205], v[12:15]
	v_mfma_f32_16x16x32_bf16 v[8:11], v[170:173], v[202:205], v[8:11]
	v_mfma_f32_16x16x32_bf16 v[4:7], v[148:151], v[210:213], v[4:7]
	v_mfma_f32_16x16x32_bf16 v[0:3], v[170:173], v[210:213], v[0:3]
	s_setprio 2
	s_barrier
	s_add_i32 s6, 0, 0x18000
	s_add_i32 s7, 0, 0x1c000
	v_add_u32_e32 v140, s6, v164
	v_add_u32_e32 v170, s7, v164
	ds_read_b128 v[128:131], v140
	ds_read_b128 v[132:135], v140 offset:1024
	ds_read_b128 v[136:139], v140 offset:2048
	ds_read_b128 v[140:143], v140 offset:3072
	ds_read_b128 v[144:147], v170
	ds_read_b128 v[148:151], v170 offset:1024
	ds_read_b128 v[166:169], v170 offset:2048
	ds_read_b128 v[170:173], v170 offset:3072
	s_add_u32 s60, s60, 0x20000
	s_addc_u32 s61, s61, 0
	s_mov_b32 m0, s66
	v_lshl_add_u64 v[214:215], s[60:61], 0, v[156:157]
	ds_read_b128 v[174:177], v165 offset:32768
	ds_read_b128 v[178:181], v165 offset:33792
	ds_read_b128 v[186:189], v165 offset:34816
	ds_read_b128 v[194:197], v165 offset:35840
	ds_read_b128 v[198:201], v165 offset:36864
	ds_read_b128 v[202:205], v165 offset:37888
	ds_read_b128 v[206:209], v165 offset:38912
	ds_read_b128 v[210:213], v165 offset:39936
	global_load_lds_dwordx4 v[214:215], off
	v_lshl_add_u64 v[214:215], s[60:61], 0, v[154:155]
	s_mov_b32 m0, s67
	s_nop 0
	global_load_lds_dwordx4 v[214:215], off
	s_waitcnt vmcnt(8)
	s_waitcnt lgkmcnt(0)
	s_barrier
	s_setprio 1
	s_waitcnt lgkmcnt(0)
	v_mfma_f32_16x16x32_bf16 v[124:127], v[128:131], v[174:177], v[124:127]
	v_mfma_f32_16x16x32_bf16 v[120:123], v[136:139], v[174:177], v[120:123]
	v_mfma_f32_16x16x32_bf16 v[116:119], v[128:131], v[186:189], v[116:119]
	v_mfma_f32_16x16x32_bf16 v[112:115], v[136:139], v[186:189], v[112:115]
	v_mfma_f32_16x16x32_bf16 v[108:111], v[128:131], v[198:201], v[108:111]
	v_mfma_f32_16x16x32_bf16 v[104:107], v[136:139], v[198:201], v[104:107]
	v_mfma_f32_16x16x32_bf16 v[100:103], v[128:131], v[206:209], v[100:103]
	v_mfma_f32_16x16x32_bf16 v[96:99], v[136:139], v[206:209], v[96:99]
	v_mfma_f32_16x16x32_bf16 v[124:127], v[132:135], v[178:181], v[124:127]
	v_mfma_f32_16x16x32_bf16 v[120:123], v[140:143], v[178:181], v[120:123]
	v_mfma_f32_16x16x32_bf16 v[116:119], v[132:135], v[194:197], v[116:119]
	v_mfma_f32_16x16x32_bf16 v[112:115], v[140:143], v[194:197], v[112:115]
	v_mfma_f32_16x16x32_bf16 v[108:111], v[132:135], v[202:205], v[108:111]
	v_mfma_f32_16x16x32_bf16 v[104:107], v[140:143], v[202:205], v[104:107]
	v_mfma_f32_16x16x32_bf16 v[100:103], v[132:135], v[210:213], v[100:103]
	v_mfma_f32_16x16x32_bf16 v[96:99], v[140:143], v[210:213], v[96:99]
	s_setprio 0
	s_setprio 1
	v_mfma_f32_16x16x32_bf16 v[92:95], v[144:147], v[174:177], v[92:95]
	v_mfma_f32_16x16x32_bf16 v[88:91], v[166:169], v[174:177], v[88:91]
	v_mfma_f32_16x16x32_bf16 v[84:87], v[144:147], v[186:189], v[84:87]
	v_mfma_f32_16x16x32_bf16 v[80:83], v[166:169], v[186:189], v[80:83]
	v_mfma_f32_16x16x32_bf16 v[76:79], v[144:147], v[198:201], v[76:79]
	v_mfma_f32_16x16x32_bf16 v[72:75], v[166:169], v[198:201], v[72:75]
	v_mfma_f32_16x16x32_bf16 v[68:71], v[144:147], v[206:209], v[68:71]
	v_mfma_f32_16x16x32_bf16 v[64:67], v[166:169], v[206:209], v[64:67]
	v_mfma_f32_16x16x32_bf16 v[92:95], v[148:151], v[178:181], v[92:95]
	v_mfma_f32_16x16x32_bf16 v[88:91], v[170:173], v[178:181], v[88:91]
	v_mfma_f32_16x16x32_bf16 v[84:87], v[148:151], v[194:197], v[84:87]
	v_mfma_f32_16x16x32_bf16 v[80:83], v[170:173], v[194:197], v[80:83]
	v_mfma_f32_16x16x32_bf16 v[76:79], v[148:151], v[202:205], v[76:79]
	v_mfma_f32_16x16x32_bf16 v[72:75], v[170:173], v[202:205], v[72:75]
	v_mfma_f32_16x16x32_bf16 v[68:71], v[148:151], v[210:213], v[68:71]
	v_mfma_f32_16x16x32_bf16 v[64:67], v[170:173], v[210:213], v[64:67]
	s_setprio 2
	s_barrier
; #define PG8_STAGE(bufoff, gbase, voff) do { _Pragma("unroll") for (int _i = 0; _i < 2; ++_i) \
;         __builtin_amdgcn_global_load_lds((const unsigned*)((const char*)(gbase) + (voff)[_i]), (PG8_LAS unsigned*)(lds + (bufoff) + ldsw + _i * 8192), 16, 0, 0); } while (0)
; #define PG8_LDA(dst, b, h) do { _Pragma("unroll") for (int m = 0; m < 4; ++m) _Pragma("unroll") for (int k = 0; k < 2; ++k) dst[m][k] = *(const PG8_LAS bf16x8*)(lds + PG8_SA(b, h) + aoff + m * 2048 + k * 1024); } while (0)
; #define PG8_MMA(ai, bj, At, Bt) do { __builtin_amdgcn_s_setprio(1); _Pragma("unroll") for (int m = 0; m < 4; ++m) _Pragma("unroll") for (int n = 0; n < 2; ++n) _Pragma("unroll") for (int k = 0; k < 2; ++k) \
;         acc[ai][bj][m][n] = __builtin_amdgcn_mfma_f32_16x16x32_bf16(Bt[n][k], At[m][k], acc[ai][bj][m][n], 0, 0, 0); __builtin_amdgcn_s_setprio(0); } while (0)
; #define PG8_WAIT_V(n) asm volatile("s_waitcnt vmcnt(" #n ")" ::: "memory")
; #define PG8_WAIT_L(n) asm volatile("s_waitcnt lgkmcnt(" #n ")" ::: "memory")
; #define PG8_BAR __builtin_amdgcn_s_barrier()
; #define PG8_SCHED __builtin_amdgcn_sched_barrier(0)
; template <class Epi, class Sched, bool ALIGN_EPI = false, bool SP2 = false>
; __device__ __forceinline__ void gemm_phase(PG8_LAS unsigned char* lds, const Gemm g, const Sched& S, const Epi& E, const int tid_in) {
;     ...
;         for (int t = 0; t < nt; t += 2) {
;     ...
;             PG8_LDA(At, 1, 1); PG8_STAGE(PG8_SB(1, 0), b3, voffB); PG8_STAGE(PG8_SB(1, 1), b3 + hstep, voffB); PG8_STAGE(PG8_SA(1, 0), a3, voffA);
;             PG8_WAIT_V(8); PG8_WAIT_L(0); PG8_BAR; PG8_MMA(1, 0, At, B0); PG8_MMA(1, 1, At, B1); PG8_BAR; PG8_SCHED;
	s_add_i32 s6, s6, s63
	v_lshl_add_u64 v[162:163], v[162:163], 0, s[84:85]
	s_mov_b32 m0, s6
	ds_read_b128 v[174:177], v165 offset:49152
	ds_read_b128 v[178:181], v165 offset:50176
	ds_read_b128 v[186:189], v165 offset:51200
	ds_read_b128 v[194:197], v165 offset:52224
	ds_read_b128 v[198:201], v165 offset:53248
	ds_read_b128 v[202:205], v165 offset:54272
	ds_read_b128 v[206:209], v165 offset:55296
	ds_read_b128 v[210:213], v165 offset:56320
	global_load_lds_dwordx4 v[162:163], off
	s_add_i32 m0, s6, 0x2000
	s_add_u32 s58, s58, 0x20080
	v_lshl_add_u64 v[162:163], v[182:183], 0, s[84:85]
	s_addc_u32 s59, s59, 0
	s_add_i32 s6, s7, s63
	global_load_lds_dwordx4 v[162:163], off
	v_lshl_add_u64 v[162:163], s[58:59], 0, v[184:185]
	s_mov_b32 m0, s6
	s_nop 0
	global_load_lds_dwordx4 v[162:163], off
	v_lshl_add_u64 v[162:163], s[58:59], 0, v[152:153]
	s_add_i32 m0, s6, 0x2000
	s_nop 0
	global_load_lds_dwordx4 v[162:163], off
	v_lshl_add_u64 v[162:163], v[190:191], 0, s[84:85]
	s_mov_b32 m0, s88
	s_nop 0
	global_load_lds_dwordx4 v[162:163], off
	v_lshl_add_u64 v[162:163], v[192:193], 0, s[84:85]
	s_mov_b32 m0, s34
	s_nop 0
	global_load_lds_dwordx4 v[162:163], off
	s_waitcnt vmcnt(8)
	s_waitcnt lgkmcnt(0)
	s_barrier
	s_setprio 1
	s_waitcnt lgkmcnt(0)
	v_mfma_f32_16x16x32_bf16 v[60:63], v[128:131], v[174:177], v[60:63]
	v_mfma_f32_16x16x32_bf16 v[56:59], v[136:139], v[174:177], v[56:59]
	v_mfma_f32_16x16x32_bf16 v[52:55], v[128:131], v[186:189], v[52:55]
	v_mfma_f32_16x16x32_bf16 v[48:51], v[136:139], v[186:189], v[48:51]
	v_mfma_f32_16x16x32_bf16 v[44:47], v[128:131], v[198:201], v[44:47]
	v_mfma_f32_16x16x32_bf16 v[40:43], v[136:139], v[198:201], v[40:43]
	v_mfma_f32_16x16x32_bf16 v[36:39], v[128:131], v[206:209], v[36:39]
	v_mfma_f32_16x16x32_bf16 v[32:35], v[136:139], v[206:209], v[32:35]
	v_mfma_f32_16x16x32_bf16 v[60:63], v[132:135], v[178:181], v[60:63]
	v_mfma_f32_16x16x32_bf16 v[56:59], v[140:143], v[178:181], v[56:59]
	v_mfma_f32_16x16x32_bf16 v[52:55], v[132:135], v[194:197], v[52:55]
	v_mfma_f32_16x16x32_bf16 v[48:51], v[140:143], v[194:197], v[48:51]
	v_mfma_f32_16x16x32_bf16 v[44:47], v[132:135], v[202:205], v[44:47]
	v_mfma_f32_16x16x32_bf16 v[40:43], v[140:143], v[202:205], v[40:43]
	v_mfma_f32_16x16x32_bf16 v[36:39], v[132:135], v[210:213], v[36:39]
	v_mfma_f32_16x16x32_bf16 v[32:35], v[140:143], v[210:213], v[32:35]
	s_setprio 0
	s_setprio 1
	v_mfma_f32_16x16x32_bf16 v[28:31], v[144:147], v[174:177], v[28:31]
	v_mfma_f32_16x16x32_bf16 v[24:27], v[166:169], v[174:177], v[24:27]
	v_mfma_f32_16x16x32_bf16 v[20:23], v[144:147], v[186:189], v[20:23]
	v_mfma_f32_16x16x32_bf16 v[16:19], v[166:169], v[186:189], v[16:19]
	v_mfma_f32_16x16x32_bf16 v[12:15], v[144:147], v[198:201], v[12:15]
	v_mfma_f32_16x16x32_bf16 v[8:11], v[166:169], v[198:201], v[8:11]
	v_mfma_f32_16x16x32_bf16 v[4:7], v[144:147], v[206:209], v[4:7]
	v_mfma_f32_16x16x32_bf16 v[0:3], v[166:169], v[206:209], v[0:3]
	v_mfma_f32_16x16x32_bf16 v[28:31], v[148:151], v[178:181], v[28:31]
	v_mfma_f32_16x16x32_bf16 v[24:27], v[170:173], v[178:181], v[24:27]
	v_mfma_f32_16x16x32_bf16 v[20:23], v[148:151], v[194:197], v[20:23]
	v_mfma_f32_16x16x32_bf16 v[16:19], v[170:173], v[194:197], v[16:19]
	v_mfma_f32_16x16x32_bf16 v[12:15], v[148:151], v[202:205], v[12:15]
	v_mfma_f32_16x16x32_bf16 v[8:11], v[170:173], v[202:205], v[8:11]
	v_mfma_f32_16x16x32_bf16 v[4:7], v[148:151], v[210:213], v[4:7]
	v_mfma_f32_16x16x32_bf16 v[0:3], v[170:173], v[210:213], v[0:3]
	s_setprio 2
	s_barrier
	s_add_i32 s52, s52, 2
	s_add_u32 s56, s56, 0x100
	s_addc_u32 s57, s57, 0
	s_add_u32 s43, s43, 0x100
	s_addc_u32 s45, s45, 0
	s_cmp_gt_u32 s52, 5
	s_cbranch_scc0 .LBB0_1017
	s_and_b64 vcc, exec, s[40:41]
	s_cbranch_vccz .LBB0_1020
	s_barrier

; #define PG8_STAGE(bufoff, gbase, voff) do { _Pragma("unroll") for (int _i = 0; _i < 2; ++_i) \
;         __builtin_amdgcn_global_load_lds((const unsigned*)((const char*)(gbase) + (voff)[_i]), (PG8_LAS unsigned*)(lds + (bufoff) + ldsw + _i * 8192), 16, 0, 0); } while (0)
; #define PG8_LDA(dst, b, h) do { _Pragma("unroll") for (int m = 0; m < 4; ++m) _Pragma("unroll") for (int k = 0; k < 2; ++k) dst[m][k] = *(const PG8_LAS bf16x8*)(lds + PG8_SA(b, h) + aoff + m * 2048 + k * 1024); } while (0)
; #define PG8_LDB(dst, b, h) do { _Pragma("unroll") for (int n = 0; n < 2; ++n) _Pragma("unroll") for (int k = 0; k < 2; ++k) dst[n][k] = *(const PG8_LAS bf16x8*)(lds + PG8_SB(b, h) + boff + n * 2048 + k * 1024); } while (0)
; #define PG8_MMA(ai, bj, At, Bt) do { __builtin_amdgcn_s_setprio(1); _Pragma("unroll") for (int m = 0; m < 4; ++m) _Pragma("unroll") for (int n = 0; n < 2; ++n) _Pragma("unroll") for (int k = 0; k < 2; ++k) \
;         acc[ai][bj][m][n] = __builtin_amdgcn_mfma_f32_16x16x32_bf16(Bt[n][k], At[m][k], acc[ai][bj][m][n], 0, 0, 0); __builtin_amdgcn_s_setprio(0); } while (0)
; #define PG8_WAIT_V(n) asm volatile("s_waitcnt vmcnt(" #n ")" ::: "memory")
; #define PG8_WAIT_L(n) asm volatile("s_waitcnt lgkmcnt(" #n ")" ::: "memory")
; #define PG8_BAR __builtin_amdgcn_s_barrier()
; #define PG8_SCHED __builtin_amdgcn_sched_barrier(0)
; template <class Epi, class Sched, bool ALIGN_EPI = false, bool SP2 = false>
; __device__ __forceinline__ void gemm_phase(PG8_LAS unsigned char* lds, const Gemm g, const Sched& S, const Epi& E, const int tid_in) {
;     ...
;             const bool last = (t == nt - 2);
;             const char* a1 = cA + (size_t)(t + 1) * kstepA;
;             const char* a2 = last ? nA : cA + (size_t)(t + 2) * kstepA; const char* b2 = last ? nB : cB + (size_t)(t + 2) * kstep;
;             const char* a3 = a2 + kstepA; const char* b3 = b2 + kstep;
;             if (last && has_next) S.a_ready(nxt, ui + 1);
;             if constexpr (SP2) {
;             PG8_LDB(B0, 0, 0); PG8_LDB(B1, 0, 1); PG8_SCHED; PG8_LDA(At, 0, 0); PG8_STAGE(PG8_SA(1, 1), a1 + hstepA, voffA);
;             PG8_WAIT_V(8); PG8_WAIT_L(0); PG8_BAR; PG8_MMA(0, 0, At, B0); PG8_MMA(0, 1, At, B1); PG8_BAR; PG8_SCHED;
;             PG8_LDA(At, 0, 1); PG8_STAGE(PG8_SB(0, 0), b2, voffB); PG8_STAGE(PG8_SB(0, 1), b2 + hstep, voffB); PG8_STAGE(PG8_SA(0, 0), a2, voffA);
.LBB0_1101:
	s_add_u32 s6, s56, 0xfffc0080
	s_addc_u32 s7, s57, -1
	s_add_i32 s70, 0, 0x10000
	s_cmp_eq_u32 s53, 12
	s_cselect_b32 s61, s12, s7
	s_cselect_b32 s60, s14, s6
	s_cselect_b32 s59, s15, s52
	s_cselect_b32 s58, s43, s45
	s_add_i32 s6, 0, 0x14000
	v_add_u32_e32 v140, s70, v186
	v_add_u32_e32 v156, s6, v186
	ds_read_b128 v[128:131], v140
	ds_read_b128 v[132:135], v140 offset:1024
	ds_read_b128 v[136:139], v140 offset:2048
	ds_read_b128 v[140:143], v140 offset:3072
	ds_read_b128 v[144:147], v156
	ds_read_b128 v[148:151], v156 offset:1024
	ds_read_b128 v[152:155], v156 offset:2048
	ds_read_b128 v[156:159], v156 offset:3072
	v_lshl_add_u64 v[192:193], s[56:57], 0, v[194:195]
	s_add_i32 m0, s35, 0xc000
	ds_read_b128 v[160:163], v187
	ds_read_b128 v[164:167], v187 offset:1024
	ds_read_b128 v[168:171], v187 offset:2048
	ds_read_b128 v[172:175], v187 offset:3072
	ds_read_b128 v[188:191], v187 offset:4096
	ds_read_b128 v[198:201], v187 offset:5120
	ds_read_b128 v[202:205], v187 offset:6144
	ds_read_b128 v[206:209], v187 offset:7168
	global_load_lds_dwordx4 v[192:193], off
	v_lshl_add_u64 v[192:193], s[56:57], 0, v[196:197]
	s_add_i32 m0, s35, 0xe000
	s_nop 0
	global_load_lds_dwordx4 v[192:193], off
	s_waitcnt vmcnt(8)
	s_waitcnt lgkmcnt(0)
	s_barrier
	s_setprio 1
	s_waitcnt lgkmcnt(0)
	v_mfma_f32_16x16x32_bf16 v[124:127], v[128:131], v[160:163], v[124:127]
	v_mfma_f32_16x16x32_bf16 v[120:123], v[136:139], v[160:163], v[120:123]
	v_mfma_f32_16x16x32_bf16 v[108:111], v[128:131], v[168:171], v[108:111]
	v_mfma_f32_16x16x32_bf16 v[104:107], v[136:139], v[168:171], v[104:107]
	v_mfma_f32_16x16x32_bf16 v[92:95], v[128:131], v[188:191], v[92:95]
	v_mfma_f32_16x16x32_bf16 v[88:91], v[136:139], v[188:191], v[88:91]
	v_mfma_f32_16x16x32_bf16 v[76:79], v[128:131], v[202:205], v[76:79]
	v_mfma_f32_16x16x32_bf16 v[72:75], v[136:139], v[202:205], v[72:75]
	v_mfma_f32_16x16x32_bf16 v[124:127], v[132:135], v[164:167], v[124:127]
	v_mfma_f32_16x16x32_bf16 v[120:123], v[140:143], v[164:167], v[120:123]
	v_mfma_f32_16x16x32_bf16 v[108:111], v[132:135], v[172:175], v[108:111]
	v_mfma_f32_16x16x32_bf16 v[104:107], v[140:143], v[172:175], v[104:107]
	v_mfma_f32_16x16x32_bf16 v[92:95], v[132:135], v[198:201], v[92:95]
	v_mfma_f32_16x16x32_bf16 v[88:91], v[140:143], v[198:201], v[88:91]
	v_mfma_f32_16x16x32_bf16 v[76:79], v[132:135], v[206:209], v[76:79]
	v_mfma_f32_16x16x32_bf16 v[72:75], v[140:143], v[206:209], v[72:75]
	s_setprio 0
	s_setprio 1
	v_mfma_f32_16x16x32_bf16 v[116:119], v[144:147], v[160:163], v[116:119]
	v_mfma_f32_16x16x32_bf16 v[112:115], v[152:155], v[160:163], v[112:115]
	v_mfma_f32_16x16x32_bf16 v[100:103], v[144:147], v[168:171], v[100:103]
	v_mfma_f32_16x16x32_bf16 v[96:99], v[152:155], v[168:171], v[96:99]
	v_mfma_f32_16x16x32_bf16 v[84:87], v[144:147], v[188:191], v[84:87]
	v_mfma_f32_16x16x32_bf16 v[80:83], v[152:155], v[188:191], v[80:83]
	v_mfma_f32_16x16x32_bf16 v[68:71], v[144:147], v[202:205], v[68:71]
	v_mfma_f32_16x16x32_bf16 v[64:67], v[152:155], v[202:205], v[64:67]
	v_mfma_f32_16x16x32_bf16 v[116:119], v[148:151], v[164:167], v[116:119]
	v_mfma_f32_16x16x32_bf16 v[112:115], v[156:159], v[164:167], v[112:115]
	v_mfma_f32_16x16x32_bf16 v[100:103], v[148:151], v[172:175], v[100:103]
	v_mfma_f32_16x16x32_bf16 v[96:99], v[156:159], v[172:175], v[96:99]
	v_mfma_f32_16x16x32_bf16 v[84:87], v[148:151], v[198:201], v[84:87]
	v_mfma_f32_16x16x32_bf16 v[80:83], v[156:159], v[198:201], v[80:83]
	v_mfma_f32_16x16x32_bf16 v[68:71], v[148:151], v[206:209], v[68:71]
	v_mfma_f32_16x16x32_bf16 v[64:67], v[156:159], v[206:209], v[64:67]
	s_setprio 2
	s_barrier
	s_add_i32 s7, s70, s34
	v_lshl_add_u64 v[192:193], s[58:59], 0, v[180:181]
	s_mov_b32 m0, s7
	ds_read_b128 v[160:163], v187 offset:16384
	ds_read_b128 v[164:167], v187 offset:17408
	ds_read_b128 v[168:171], v187 offset:18432
	ds_read_b128 v[172:175], v187 offset:19456
	ds_read_b128 v[188:191], v187 offset:20480
	ds_read_b128 v[198:201], v187 offset:21504
	ds_read_b128 v[202:205], v187 offset:22528
	ds_read_b128 v[206:209], v187 offset:23552
	global_load_lds_dwordx4 v[192:193], off
	s_add_i32 m0, s7, 0x2000
	s_add_u32 s70, s58, 0x40000
	v_lshl_add_u64 v[210:211], s[58:59], 0, v[176:177]
	s_addc_u32 s71, s59, 0
	s_add_i32 s6, s6, s34
	global_load_lds_dwordx4 v[210:211], off
	v_lshl_add_u64 v[212:213], s[70:71], 0, v[180:181]
	s_mov_b32 m0, s6
	v_lshl_add_u64 v[214:215], s[60:61], 0, v[178:179]
	global_load_lds_dwordx4 v[212:213], off
	v_lshl_add_u64 v[212:213], s[70:71], 0, v[176:177]
	s_add_i32 m0, s6, 0x2000
	s_nop 0
	global_load_lds_dwordx4 v[212:213], off
	v_lshl_add_u64 v[212:213], s[60:61], 0, v[182:183]
	s_mov_b32 m0, s35
	s_nop 0
	global_load_lds_dwordx4 v[212:213], off
	s_mov_b32 m0, s54
	s_nop 0
	global_load_lds_dwordx4 v[214:215], off
	s_waitcnt vmcnt(8)
	s_waitcnt lgkmcnt(0)
	s_barrier
; #define PG8_STAGE(bufoff, gbase, voff) do { _Pragma("unroll") for (int _i = 0; _i < 2; ++_i) \
;         __builtin_amdgcn_global_load_lds((const unsigned*)((const char*)(gbase) + (voff)[_i]), (PG8_LAS unsigned*)(lds + (bufoff) + ldsw + _i * 8192), 16, 0, 0); } while (0)
; #define PG8_LDA(dst, b, h) do { _Pragma("unroll") for (int m = 0; m < 4; ++m) _Pragma("unroll") for (int k = 0; k < 2; ++k) dst[m][k] = *(const PG8_LAS bf16x8*)(lds + PG8_SA(b, h) + aoff + m * 2048 + k * 1024); } while (0)
; #define PG8_LDB(dst, b, h) do { _Pragma("unroll") for (int n = 0; n < 2; ++n) _Pragma("unroll") for (int k = 0; k < 2; ++k) dst[n][k] = *(const PG8_LAS bf16x8*)(lds + PG8_SB(b, h) + boff + n * 2048 + k * 1024); } while (0)
; #define PG8_MMA(ai, bj, At, Bt) do { __builtin_amdgcn_s_setprio(1); _Pragma("unroll") for (int m = 0; m < 4; ++m) _Pragma("unroll") for (int n = 0; n < 2; ++n) _Pragma("unroll") for (int k = 0; k < 2; ++k) \
;         acc[ai][bj][m][n] = __builtin_amdgcn_mfma_f32_16x16x32_bf16(Bt[n][k], At[m][k], acc[ai][bj][m][n], 0, 0, 0); __builtin_amdgcn_s_setprio(0); } while (0)
; #define PG8_WAIT_V(n) asm volatile("s_waitcnt vmcnt(" #n ")" ::: "memory")
; #define PG8_WAIT_L(n) asm volatile("s_waitcnt lgkmcnt(" #n ")" ::: "memory")
; #define PG8_BAR __builtin_amdgcn_s_barrier()
; #define PG8_SCHED __builtin_amdgcn_sched_barrier(0)
; template <class Epi, class Sched, bool ALIGN_EPI = false, bool SP2 = false>
; __device__ __forceinline__ void gemm_phase(PG8_LAS unsigned char* lds, const Gemm g, const Sched& S, const Epi& E, const int tid_in) {
;     ...
;             PG8_WAIT_V(8); PG8_WAIT_L(0); PG8_BAR; PG8_MMA(1, 0, At, B0); PG8_MMA(1, 1, At, B1); PG8_BAR; PG8_SCHED;
;             PG8_LDB(B0, 1, 0); PG8_LDB(B1, 1, 1); PG8_SCHED; PG8_LDA(At, 1, 0); PG8_STAGE(PG8_SA(0, 1), a2 + hstepA, voffA);
;             PG8_WAIT_V(8); PG8_WAIT_L(0); PG8_BAR; PG8_MMA(0, 0, At, B0); PG8_MMA(0, 1, At, B1); PG8_BAR; PG8_SCHED;
	s_setprio 1
	s_waitcnt lgkmcnt(0)
	v_mfma_f32_16x16x32_bf16 v[60:63], v[128:131], v[160:163], v[60:63]
	v_mfma_f32_16x16x32_bf16 v[56:59], v[136:139], v[160:163], v[56:59]
	v_mfma_f32_16x16x32_bf16 v[44:47], v[128:131], v[168:171], v[44:47]
	v_mfma_f32_16x16x32_bf16 v[40:43], v[136:139], v[168:171], v[40:43]
	v_mfma_f32_16x16x32_bf16 v[28:31], v[128:131], v[188:191], v[28:31]
	v_mfma_f32_16x16x32_bf16 v[24:27], v[136:139], v[188:191], v[24:27]
	v_mfma_f32_16x16x32_bf16 v[12:15], v[128:131], v[202:205], v[12:15]
	v_mfma_f32_16x16x32_bf16 v[8:11], v[136:139], v[202:205], v[8:11]
	v_mfma_f32_16x16x32_bf16 v[60:63], v[132:135], v[164:167], v[60:63]
	v_mfma_f32_16x16x32_bf16 v[56:59], v[140:143], v[164:167], v[56:59]
	v_mfma_f32_16x16x32_bf16 v[44:47], v[132:135], v[172:175], v[44:47]
	v_mfma_f32_16x16x32_bf16 v[40:43], v[140:143], v[172:175], v[40:43]
	v_mfma_f32_16x16x32_bf16 v[28:31], v[132:135], v[198:201], v[28:31]
	v_mfma_f32_16x16x32_bf16 v[24:27], v[140:143], v[198:201], v[24:27]
	v_mfma_f32_16x16x32_bf16 v[12:15], v[132:135], v[206:209], v[12:15]
	v_mfma_f32_16x16x32_bf16 v[8:11], v[140:143], v[206:209], v[8:11]
	s_setprio 0
	s_setprio 1
	v_mfma_f32_16x16x32_bf16 v[52:55], v[144:147], v[160:163], v[52:55]
	v_mfma_f32_16x16x32_bf16 v[48:51], v[152:155], v[160:163], v[48:51]
	v_mfma_f32_16x16x32_bf16 v[36:39], v[144:147], v[168:171], v[36:39]
	v_mfma_f32_16x16x32_bf16 v[32:35], v[152:155], v[168:171], v[32:35]
	v_mfma_f32_16x16x32_bf16 v[20:23], v[144:147], v[188:191], v[20:23]
	v_mfma_f32_16x16x32_bf16 v[16:19], v[152:155], v[188:191], v[16:19]
	v_mfma_f32_16x16x32_bf16 v[4:7], v[144:147], v[202:205], v[4:7]
	v_mfma_f32_16x16x32_bf16 v[0:3], v[152:155], v[202:205], v[0:3]
	v_mfma_f32_16x16x32_bf16 v[52:55], v[148:151], v[164:167], v[52:55]
	v_mfma_f32_16x16x32_bf16 v[48:51], v[156:159], v[164:167], v[48:51]
	v_mfma_f32_16x16x32_bf16 v[36:39], v[148:151], v[172:175], v[36:39]
	v_mfma_f32_16x16x32_bf16 v[32:35], v[156:159], v[172:175], v[32:35]
	v_mfma_f32_16x16x32_bf16 v[20:23], v[148:151], v[198:201], v[20:23]
	v_mfma_f32_16x16x32_bf16 v[16:19], v[156:159], v[198:201], v[16:19]
	v_mfma_f32_16x16x32_bf16 v[4:7], v[148:151], v[206:209], v[4:7]
	v_mfma_f32_16x16x32_bf16 v[0:3], v[156:159], v[206:209], v[0:3]
	s_setprio 2
	s_barrier
	s_add_i32 s6, 0, 0x18000
	s_add_i32 s7, 0, 0x1c000
	v_add_u32_e32 v140, s6, v186
	v_add_u32_e32 v156, s7, v186
	ds_read_b128 v[128:131], v140
	ds_read_b128 v[132:135], v140 offset:1024
	ds_read_b128 v[136:139], v140 offset:2048
	ds_read_b128 v[140:143], v140 offset:3072
	ds_read_b128 v[144:147], v156
	ds_read_b128 v[148:151], v156 offset:1024
	ds_read_b128 v[152:155], v156 offset:2048
	ds_read_b128 v[156:159], v156 offset:3072
	s_add_u32 s60, s60, 0x40000
	s_addc_u32 s61, s61, 0
	s_mov_b32 m0, s62
	v_lshl_add_u64 v[216:217], s[60:61], 0, v[182:183]
	ds_read_b128 v[160:163], v187 offset:32768
	ds_read_b128 v[164:167], v187 offset:33792
	ds_read_b128 v[168:171], v187 offset:34816
	ds_read_b128 v[172:175], v187 offset:35840
	ds_read_b128 v[188:191], v187 offset:36864
	ds_read_b128 v[198:201], v187 offset:37888
	ds_read_b128 v[202:205], v187 offset:38912
	ds_read_b128 v[206:209], v187 offset:39936
	global_load_lds_dwordx4 v[216:217], off
	v_lshl_add_u64 v[216:217], s[60:61], 0, v[178:179]
	s_mov_b32 m0, s63
	s_nop 0
	global_load_lds_dwordx4 v[216:217], off
	s_waitcnt vmcnt(8)
	s_waitcnt lgkmcnt(0)
	s_barrier
	s_setprio 1
	s_waitcnt lgkmcnt(0)
	v_mfma_f32_16x16x32_bf16 v[124:127], v[128:131], v[160:163], v[124:127]
	v_mfma_f32_16x16x32_bf16 v[120:123], v[136:139], v[160:163], v[120:123]
	v_mfma_f32_16x16x32_bf16 v[108:111], v[128:131], v[168:171], v[108:111]
	v_mfma_f32_16x16x32_bf16 v[104:107], v[136:139], v[168:171], v[104:107]
	v_mfma_f32_16x16x32_bf16 v[92:95], v[128:131], v[188:191], v[92:95]
	v_mfma_f32_16x16x32_bf16 v[88:91], v[136:139], v[188:191], v[88:91]
	v_mfma_f32_16x16x32_bf16 v[76:79], v[128:131], v[202:205], v[76:79]
	v_mfma_f32_16x16x32_bf16 v[72:75], v[136:139], v[202:205], v[72:75]
	v_mfma_f32_16x16x32_bf16 v[124:127], v[132:135], v[164:167], v[124:127]
	v_mfma_f32_16x16x32_bf16 v[120:123], v[140:143], v[164:167], v[120:123]
	v_mfma_f32_16x16x32_bf16 v[108:111], v[132:135], v[172:175], v[108:111]
	v_mfma_f32_16x16x32_bf16 v[104:107], v[140:143], v[172:175], v[104:107]
	v_mfma_f32_16x16x32_bf16 v[92:95], v[132:135], v[198:201], v[92:95]
	v_mfma_f32_16x16x32_bf16 v[88:91], v[140:143], v[198:201], v[88:91]
	v_mfma_f32_16x16x32_bf16 v[76:79], v[132:135], v[206:209], v[76:79]
	v_mfma_f32_16x16x32_bf16 v[72:75], v[140:143], v[206:209], v[72:75]
	s_setprio 0
	s_setprio 1
	v_mfma_f32_16x16x32_bf16 v[116:119], v[144:147], v[160:163], v[116:119]
	v_mfma_f32_16x16x32_bf16 v[112:115], v[152:155], v[160:163], v[112:115]
	v_mfma_f32_16x16x32_bf16 v[100:103], v[144:147], v[168:171], v[100:103]
	v_mfma_f32_16x16x32_bf16 v[96:99], v[152:155], v[168:171], v[96:99]
	v_mfma_f32_16x16x32_bf16 v[84:87], v[144:147], v[188:191], v[84:87]
	v_mfma_f32_16x16x32_bf16 v[80:83], v[152:155], v[188:191], v[80:83]
	v_mfma_f32_16x16x32_bf16 v[68:71], v[144:147], v[202:205], v[68:71]
	v_mfma_f32_16x16x32_bf16 v[64:67], v[152:155], v[202:205], v[64:67]
	v_mfma_f32_16x16x32_bf16 v[116:119], v[148:151], v[164:167], v[116:119]
	v_mfma_f32_16x16x32_bf16 v[112:115], v[156:159], v[164:167], v[112:115]
	v_mfma_f32_16x16x32_bf16 v[100:103], v[148:151], v[172:175], v[100:103]
	v_mfma_f32_16x16x32_bf16 v[96:99], v[156:159], v[172:175], v[96:99]
	v_mfma_f32_16x16x32_bf16 v[84:87], v[148:151], v[198:201], v[84:87]
	v_mfma_f32_16x16x32_bf16 v[80:83], v[156:159], v[198:201], v[80:83]
	v_mfma_f32_16x16x32_bf16 v[68:71], v[148:151], v[206:209], v[68:71]
	v_mfma_f32_16x16x32_bf16 v[64:67], v[156:159], v[206:209], v[64:67]
	s_setprio 2
	s_barrier
; #define PG8_STAGE(bufoff, gbase, voff) do { _Pragma("unroll") for (int _i = 0; _i < 2; ++_i) \
;         __builtin_amdgcn_global_load_lds((const unsigned*)((const char*)(gbase) + (voff)[_i]), (PG8_LAS unsigned*)(lds + (bufoff) + ldsw + _i * 8192), 16, 0, 0); } while (0)
; #define PG8_LDA(dst, b, h) do { _Pragma("unroll") for (int m = 0; m < 4; ++m) _Pragma("unroll") for (int k = 0; k < 2; ++k) dst[m][k] = *(const PG8_LAS bf16x8*)(lds + PG8_SA(b, h) + aoff + m * 2048 + k * 1024); } while (0)
; #define PG8_MMA(ai, bj, At, Bt) do { __builtin_amdgcn_s_setprio(1); _Pragma("unroll") for (int m = 0; m < 4; ++m) _Pragma("unroll") for (int n = 0; n < 2; ++n) _Pragma("unroll") for (int k = 0; k < 2; ++k) \
;         acc[ai][bj][m][n] = __builtin_amdgcn_mfma_f32_16x16x32_bf16(Bt[n][k], At[m][k], acc[ai][bj][m][n], 0, 0, 0); __builtin_amdgcn_s_setprio(0); } while (0)
; #define PG8_WAIT_V(n) asm volatile("s_waitcnt vmcnt(" #n ")" ::: "memory")
; #define PG8_WAIT_L(n) asm volatile("s_waitcnt lgkmcnt(" #n ")" ::: "memory")
; #define PG8_BAR __builtin_amdgcn_s_barrier()
; #define PG8_SCHED __builtin_amdgcn_sched_barrier(0)
; template <class Epi, class Sched, bool ALIGN_EPI = false, bool SP2 = false>
; __device__ __forceinline__ void gemm_phase(PG8_LAS unsigned char* lds, const Gemm g, const Sched& S, const Epi& E, const int tid_in) {
;     ...
;         for (int t = 0; t < nt; t += 2) {
;     ...
;             PG8_LDA(At, 1, 1); PG8_STAGE(PG8_SB(1, 0), b3, voffB); PG8_STAGE(PG8_SB(1, 1), b3 + hstep, voffB); PG8_STAGE(PG8_SA(1, 0), a3, voffA);
;             PG8_WAIT_V(8); PG8_WAIT_L(0); PG8_BAR; PG8_MMA(1, 0, At, B0); PG8_MMA(1, 1, At, B1); PG8_BAR; PG8_SCHED;
	s_add_i32 s6, s6, s34
	v_lshl_add_u64 v[192:193], v[192:193], 0, s[84:85]
	s_mov_b32 m0, s6
	ds_read_b128 v[160:163], v187 offset:49152
	ds_read_b128 v[164:167], v187 offset:50176
	ds_read_b128 v[168:171], v187 offset:51200
	ds_read_b128 v[172:175], v187 offset:52224
	ds_read_b128 v[188:191], v187 offset:53248
	ds_read_b128 v[198:201], v187 offset:54272
	ds_read_b128 v[202:205], v187 offset:55296
	ds_read_b128 v[206:209], v187 offset:56320
	global_load_lds_dwordx4 v[192:193], off
	s_add_i32 m0, s6, 0x2000
	s_add_u32 s58, s58, 0x40080
	v_lshl_add_u64 v[192:193], v[210:211], 0, s[84:85]
	s_addc_u32 s59, s59, 0
	s_add_i32 s6, s7, s34
	global_load_lds_dwordx4 v[192:193], off
	v_lshl_add_u64 v[192:193], s[58:59], 0, v[180:181]
	s_mov_b32 m0, s6
	s_nop 0
	global_load_lds_dwordx4 v[192:193], off
	v_lshl_add_u64 v[192:193], s[58:59], 0, v[176:177]
	s_add_i32 m0, s6, 0x2000
	s_nop 0
	global_load_lds_dwordx4 v[192:193], off
	v_lshl_add_u64 v[192:193], v[212:213], 0, s[84:85]
	s_mov_b32 m0, s66
	s_nop 0
	global_load_lds_dwordx4 v[192:193], off
	v_lshl_add_u64 v[192:193], v[214:215], 0, s[84:85]
	s_mov_b32 m0, s67
	s_nop 0
	global_load_lds_dwordx4 v[192:193], off
	s_waitcnt vmcnt(8)
	s_waitcnt lgkmcnt(0)
	s_barrier
	s_setprio 1
	s_waitcnt lgkmcnt(0)
	v_mfma_f32_16x16x32_bf16 v[60:63], v[128:131], v[160:163], v[60:63]
	v_mfma_f32_16x16x32_bf16 v[56:59], v[136:139], v[160:163], v[56:59]
	v_mfma_f32_16x16x32_bf16 v[44:47], v[128:131], v[168:171], v[44:47]
	v_mfma_f32_16x16x32_bf16 v[40:43], v[136:139], v[168:171], v[40:43]
	v_mfma_f32_16x16x32_bf16 v[28:31], v[128:131], v[188:191], v[28:31]
	v_mfma_f32_16x16x32_bf16 v[24:27], v[136:139], v[188:191], v[24:27]
	v_mfma_f32_16x16x32_bf16 v[12:15], v[128:131], v[202:205], v[12:15]
	v_mfma_f32_16x16x32_bf16 v[8:11], v[136:139], v[202:205], v[8:11]
	v_mfma_f32_16x16x32_bf16 v[60:63], v[132:135], v[164:167], v[60:63]
	v_mfma_f32_16x16x32_bf16 v[56:59], v[140:143], v[164:167], v[56:59]
	v_mfma_f32_16x16x32_bf16 v[44:47], v[132:135], v[172:175], v[44:47]
	v_mfma_f32_16x16x32_bf16 v[40:43], v[140:143], v[172:175], v[40:43]
	v_mfma_f32_16x16x32_bf16 v[28:31], v[132:135], v[198:201], v[28:31]
	v_mfma_f32_16x16x32_bf16 v[24:27], v[140:143], v[198:201], v[24:27]
	v_mfma_f32_16x16x32_bf16 v[12:15], v[132:135], v[206:209], v[12:15]
	v_mfma_f32_16x16x32_bf16 v[8:11], v[140:143], v[206:209], v[8:11]
	s_setprio 0
	s_setprio 1
	v_mfma_f32_16x16x32_bf16 v[52:55], v[144:147], v[160:163], v[52:55]
	v_mfma_f32_16x16x32_bf16 v[48:51], v[152:155], v[160:163], v[48:51]
	v_mfma_f32_16x16x32_bf16 v[36:39], v[144:147], v[168:171], v[36:39]
	v_mfma_f32_16x16x32_bf16 v[32:35], v[152:155], v[168:171], v[32:35]
	v_mfma_f32_16x16x32_bf16 v[20:23], v[144:147], v[188:191], v[20:23]
	v_mfma_f32_16x16x32_bf16 v[16:19], v[152:155], v[188:191], v[16:19]
	v_mfma_f32_16x16x32_bf16 v[4:7], v[144:147], v[202:205], v[4:7]
	v_mfma_f32_16x16x32_bf16 v[0:3], v[152:155], v[202:205], v[0:3]
	v_mfma_f32_16x16x32_bf16 v[52:55], v[148:151], v[164:167], v[52:55]
	v_mfma_f32_16x16x32_bf16 v[48:51], v[156:159], v[164:167], v[48:51]
	v_mfma_f32_16x16x32_bf16 v[36:39], v[148:151], v[172:175], v[36:39]
	v_mfma_f32_16x16x32_bf16 v[32:35], v[156:159], v[172:175], v[32:35]
	v_mfma_f32_16x16x32_bf16 v[20:23], v[148:151], v[198:201], v[20:23]
	v_mfma_f32_16x16x32_bf16 v[16:19], v[156:159], v[198:201], v[16:19]
	v_mfma_f32_16x16x32_bf16 v[4:7], v[148:151], v[206:209], v[4:7]
	v_mfma_f32_16x16x32_bf16 v[0:3], v[156:159], v[206:209], v[0:3]
	s_setprio 2
	s_barrier
	s_add_i32 s53, s53, 2
	s_add_u32 s56, s56, 0x100
	s_addc_u32 s57, s57, 0
	s_add_u32 s45, s45, 0x100
	s_addc_u32 s52, s52, 0
	s_cmp_gt_u32 s53, 13
	s_cbranch_scc0 .LBB0_1101
	s_and_b64 vcc, exec, s[40:41]
	s_cbranch_vccz .LBB0_1104
	s_barrier

; #define PG8_STAGE(bufoff, gbase, voff) do { _Pragma("unroll") for (int _i = 0; _i < 2; ++_i) \
;         __builtin_amdgcn_global_load_lds((const unsigned*)((const char*)(gbase) + (voff)[_i]), (PG8_LAS unsigned*)(lds + (bufoff) + ldsw + _i * 8192), 16, 0, 0); } while (0)
; #define PG8_LDA(dst, b, h) do { _Pragma("unroll") for (int m = 0; m < 4; ++m) _Pragma("unroll") for (int k = 0; k < 2; ++k) dst[m][k] = *(const PG8_LAS bf16x8*)(lds + PG8_SA(b, h) + aoff + m * 2048 + k * 1024); } while (0)
; #define PG8_LDB(dst, b, h) do { _Pragma("unroll") for (int n = 0; n < 2; ++n) _Pragma("unroll") for (int k = 0; k < 2; ++k) dst[n][k] = *(const PG8_LAS bf16x8*)(lds + PG8_SB(b, h) + boff + n * 2048 + k * 1024); } while (0)
; #define PG8_MMA(ai, bj, At, Bt) do { __builtin_amdgcn_s_setprio(1); _Pragma("unroll") for (int m = 0; m < 4; ++m) _Pragma("unroll") for (int n = 0; n < 2; ++n) _Pragma("unroll") for (int k = 0; k < 2; ++k) \
;         acc[ai][bj][m][n] = __builtin_amdgcn_mfma_f32_16x16x32_bf16(Bt[n][k], At[m][k], acc[ai][bj][m][n], 0, 0, 0); __builtin_amdgcn_s_setprio(0); } while (0)
; #define PG8_WAIT_V(n) asm volatile("s_waitcnt vmcnt(" #n ")" ::: "memory")
; #define PG8_WAIT_L(n) asm volatile("s_waitcnt lgkmcnt(" #n ")" ::: "memory")
; #define PG8_BAR __builtin_amdgcn_s_barrier()
; #define PG8_SCHED __builtin_amdgcn_sched_barrier(0)
; template <class Epi, class Sched, bool ALIGN_EPI = false, bool SP2 = false>
; __device__ __forceinline__ void gemm_phase(PG8_LAS unsigned char* lds, const Gemm g, const Sched& S, const Epi& E, const int tid_in) {
;     ...
;             const bool last = (t == nt - 2);
;             const char* a1 = cA + (size_t)(t + 1) * kstepA;
;             const char* a2 = last ? nA : cA + (size_t)(t + 2) * kstepA; const char* b2 = last ? nB : cB + (size_t)(t + 2) * kstep;
;             const char* a3 = a2 + kstepA; const char* b3 = b2 + kstep;
;             if (last && has_next) S.a_ready(nxt, ui + 1);
;             if constexpr (SP2) {
;             PG8_LDB(B0, 0, 0); PG8_LDB(B1, 0, 1); PG8_SCHED; PG8_LDA(At, 0, 0); PG8_STAGE(PG8_SA(1, 1), a1 + hstepA, voffA);
;             PG8_WAIT_V(8); PG8_WAIT_L(0); PG8_BAR; PG8_MMA(0, 0, At, B0); PG8_MMA(0, 1, At, B1); PG8_BAR; PG8_SCHED;
;             PG8_LDA(At, 0, 1); PG8_STAGE(PG8_SB(0, 0), b2, voffB); PG8_STAGE(PG8_SB(0, 1), b2 + hstep, voffB); PG8_STAGE(PG8_SA(0, 0), a2, voffA);
.LBB0_1139:
	s_add_u32 s6, s56, 0xfffc0080
	s_addc_u32 s7, s57, -1
	s_add_i32 s70, 0, 0x10000
	s_cmp_eq_u32 s53, 12
	s_cselect_b32 s61, s12, s7
	s_cselect_b32 s60, s14, s6
	s_cselect_b32 s59, s15, s52
	s_cselect_b32 s58, s43, s45
	s_add_i32 s6, 0, 0x14000
	v_add_u32_e32 v140, s70, v186
	v_add_u32_e32 v156, s6, v186
	ds_read_b128 v[128:131], v140
	ds_read_b128 v[132:135], v140 offset:1024
	ds_read_b128 v[136:139], v140 offset:2048
	ds_read_b128 v[140:143], v140 offset:3072
	ds_read_b128 v[144:147], v156
	ds_read_b128 v[148:151], v156 offset:1024
	ds_read_b128 v[152:155], v156 offset:2048
	ds_read_b128 v[156:159], v156 offset:3072
	v_lshl_add_u64 v[192:193], s[56:57], 0, v[194:195]
	s_add_i32 m0, s35, 0xc000
	ds_read_b128 v[160:163], v187
	ds_read_b128 v[164:167], v187 offset:1024
	ds_read_b128 v[168:171], v187 offset:2048
	ds_read_b128 v[172:175], v187 offset:3072
	ds_read_b128 v[188:191], v187 offset:4096
	ds_read_b128 v[198:201], v187 offset:5120
	ds_read_b128 v[202:205], v187 offset:6144
	ds_read_b128 v[206:209], v187 offset:7168
	global_load_lds_dwordx4 v[192:193], off
	v_lshl_add_u64 v[192:193], s[56:57], 0, v[196:197]
	s_add_i32 m0, s35, 0xe000
	s_nop 0
	global_load_lds_dwordx4 v[192:193], off
	s_waitcnt vmcnt(8)
	s_waitcnt lgkmcnt(0)
	s_barrier
	s_setprio 1
	s_waitcnt lgkmcnt(0)
	v_mfma_f32_16x16x32_bf16 v[124:127], v[128:131], v[160:163], v[124:127]
	v_mfma_f32_16x16x32_bf16 v[120:123], v[136:139], v[160:163], v[120:123]
	v_mfma_f32_16x16x32_bf16 v[108:111], v[128:131], v[168:171], v[108:111]
	v_mfma_f32_16x16x32_bf16 v[104:107], v[136:139], v[168:171], v[104:107]
	v_mfma_f32_16x16x32_bf16 v[92:95], v[128:131], v[188:191], v[92:95]
	v_mfma_f32_16x16x32_bf16 v[88:91], v[136:139], v[188:191], v[88:91]
	v_mfma_f32_16x16x32_bf16 v[76:79], v[128:131], v[202:205], v[76:79]
	v_mfma_f32_16x16x32_bf16 v[72:75], v[136:139], v[202:205], v[72:75]
	v_mfma_f32_16x16x32_bf16 v[124:127], v[132:135], v[164:167], v[124:127]
	v_mfma_f32_16x16x32_bf16 v[120:123], v[140:143], v[164:167], v[120:123]
	v_mfma_f32_16x16x32_bf16 v[108:111], v[132:135], v[172:175], v[108:111]
	v_mfma_f32_16x16x32_bf16 v[104:107], v[140:143], v[172:175], v[104:107]
	v_mfma_f32_16x16x32_bf16 v[92:95], v[132:135], v[198:201], v[92:95]
	v_mfma_f32_16x16x32_bf16 v[88:91], v[140:143], v[198:201], v[88:91]
	v_mfma_f32_16x16x32_bf16 v[76:79], v[132:135], v[206:209], v[76:79]
	v_mfma_f32_16x16x32_bf16 v[72:75], v[140:143], v[206:209], v[72:75]
	s_setprio 0
	s_setprio 1
	v_mfma_f32_16x16x32_bf16 v[116:119], v[144:147], v[160:163], v[116:119]
	v_mfma_f32_16x16x32_bf16 v[112:115], v[152:155], v[160:163], v[112:115]
	v_mfma_f32_16x16x32_bf16 v[100:103], v[144:147], v[168:171], v[100:103]
	v_mfma_f32_16x16x32_bf16 v[96:99], v[152:155], v[168:171], v[96:99]
	v_mfma_f32_16x16x32_bf16 v[84:87], v[144:147], v[188:191], v[84:87]
	v_mfma_f32_16x16x32_bf16 v[80:83], v[152:155], v[188:191], v[80:83]
	v_mfma_f32_16x16x32_bf16 v[68:71], v[144:147], v[202:205], v[68:71]
	v_mfma_f32_16x16x32_bf16 v[64:67], v[152:155], v[202:205], v[64:67]
	v_mfma_f32_16x16x32_bf16 v[116:119], v[148:151], v[164:167], v[116:119]
	v_mfma_f32_16x16x32_bf16 v[112:115], v[156:159], v[164:167], v[112:115]
	v_mfma_f32_16x16x32_bf16 v[100:103], v[148:151], v[172:175], v[100:103]
	v_mfma_f32_16x16x32_bf16 v[96:99], v[156:159], v[172:175], v[96:99]
	v_mfma_f32_16x16x32_bf16 v[84:87], v[148:151], v[198:201], v[84:87]
	v_mfma_f32_16x16x32_bf16 v[80:83], v[156:159], v[198:201], v[80:83]
	v_mfma_f32_16x16x32_bf16 v[68:71], v[148:151], v[206:209], v[68:71]
	v_mfma_f32_16x16x32_bf16 v[64:67], v[156:159], v[206:209], v[64:67]
	s_setprio 2
	s_barrier
	s_add_i32 s7, s70, s34
	v_lshl_add_u64 v[192:193], s[58:59], 0, v[180:181]
	s_mov_b32 m0, s7
	ds_read_b128 v[160:163], v187 offset:16384
	ds_read_b128 v[164:167], v187 offset:17408
	ds_read_b128 v[168:171], v187 offset:18432
	ds_read_b128 v[172:175], v187 offset:19456
	ds_read_b128 v[188:191], v187 offset:20480
	ds_read_b128 v[198:201], v187 offset:21504
	ds_read_b128 v[202:205], v187 offset:22528
	ds_read_b128 v[206:209], v187 offset:23552
	global_load_lds_dwordx4 v[192:193], off
	s_add_i32 m0, s7, 0x2000
	s_add_u32 s70, s58, 0x40000
	v_lshl_add_u64 v[210:211], s[58:59], 0, v[176:177]
	s_addc_u32 s71, s59, 0
	s_add_i32 s6, s6, s34
	global_load_lds_dwordx4 v[210:211], off
	v_lshl_add_u64 v[212:213], s[70:71], 0, v[180:181]
	s_mov_b32 m0, s6
	v_lshl_add_u64 v[214:215], s[60:61], 0, v[178:179]
	global_load_lds_dwordx4 v[212:213], off
	v_lshl_add_u64 v[212:213], s[70:71], 0, v[176:177]
	s_add_i32 m0, s6, 0x2000
	s_nop 0
	global_load_lds_dwordx4 v[212:213], off
	v_lshl_add_u64 v[212:213], s[60:61], 0, v[182:183]
	s_mov_b32 m0, s35
	s_nop 0
	global_load_lds_dwordx4 v[212:213], off
	s_mov_b32 m0, s77
	s_nop 0
	global_load_lds_dwordx4 v[214:215], off
	s_waitcnt vmcnt(8)
	s_waitcnt lgkmcnt(0)
	s_barrier
; #define PG8_STAGE(bufoff, gbase, voff) do { _Pragma("unroll") for (int _i = 0; _i < 2; ++_i) \
;         __builtin_amdgcn_global_load_lds((const unsigned*)((const char*)(gbase) + (voff)[_i]), (PG8_LAS unsigned*)(lds + (bufoff) + ldsw + _i * 8192), 16, 0, 0); } while (0)
; #define PG8_LDA(dst, b, h) do { _Pragma("unroll") for (int m = 0; m < 4; ++m) _Pragma("unroll") for (int k = 0; k < 2; ++k) dst[m][k] = *(const PG8_LAS bf16x8*)(lds + PG8_SA(b, h) + aoff + m * 2048 + k * 1024); } while (0)
; #define PG8_LDB(dst, b, h) do { _Pragma("unroll") for (int n = 0; n < 2; ++n) _Pragma("unroll") for (int k = 0; k < 2; ++k) dst[n][k] = *(const PG8_LAS bf16x8*)(lds + PG8_SB(b, h) + boff + n * 2048 + k * 1024); } while (0)
; #define PG8_MMA(ai, bj, At, Bt) do { __builtin_amdgcn_s_setprio(1); _Pragma("unroll") for (int m = 0; m < 4; ++m) _Pragma("unroll") for (int n = 0; n < 2; ++n) _Pragma("unroll") for (int k = 0; k < 2; ++k) \
;         acc[ai][bj][m][n] = __builtin_amdgcn_mfma_f32_16x16x32_bf16(Bt[n][k], At[m][k], acc[ai][bj][m][n], 0, 0, 0); __builtin_amdgcn_s_setprio(0); } while (0)
; #define PG8_WAIT_V(n) asm volatile("s_waitcnt vmcnt(" #n ")" ::: "memory")
; #define PG8_WAIT_L(n) asm volatile("s_waitcnt lgkmcnt(" #n ")" ::: "memory")
; #define PG8_BAR __builtin_amdgcn_s_barrier()
; #define PG8_SCHED __builtin_amdgcn_sched_barrier(0)
; template <class Epi, class Sched, bool ALIGN_EPI = false, bool SP2 = false>
; __device__ __forceinline__ void gemm_phase(PG8_LAS unsigned char* lds, const Gemm g, const Sched& S, const Epi& E, const int tid_in) {
;     ...
;             PG8_WAIT_V(8); PG8_WAIT_L(0); PG8_BAR; PG8_MMA(1, 0, At, B0); PG8_MMA(1, 1, At, B1); PG8_BAR; PG8_SCHED;
;             PG8_LDB(B0, 1, 0); PG8_LDB(B1, 1, 1); PG8_SCHED; PG8_LDA(At, 1, 0); PG8_STAGE(PG8_SA(0, 1), a2 + hstepA, voffA);
;             PG8_WAIT_V(8); PG8_WAIT_L(0); PG8_BAR; PG8_MMA(0, 0, At, B0); PG8_MMA(0, 1, At, B1); PG8_BAR; PG8_SCHED;
	s_setprio 1
	s_waitcnt lgkmcnt(0)
	v_mfma_f32_16x16x32_bf16 v[60:63], v[128:131], v[160:163], v[60:63]
	v_mfma_f32_16x16x32_bf16 v[56:59], v[136:139], v[160:163], v[56:59]
	v_mfma_f32_16x16x32_bf16 v[44:47], v[128:131], v[168:171], v[44:47]
	v_mfma_f32_16x16x32_bf16 v[40:43], v[136:139], v[168:171], v[40:43]
	v_mfma_f32_16x16x32_bf16 v[28:31], v[128:131], v[188:191], v[28:31]
	v_mfma_f32_16x16x32_bf16 v[24:27], v[136:139], v[188:191], v[24:27]
	v_mfma_f32_16x16x32_bf16 v[12:15], v[128:131], v[202:205], v[12:15]
	v_mfma_f32_16x16x32_bf16 v[8:11], v[136:139], v[202:205], v[8:11]
	v_mfma_f32_16x16x32_bf16 v[60:63], v[132:135], v[164:167], v[60:63]
	v_mfma_f32_16x16x32_bf16 v[56:59], v[140:143], v[164:167], v[56:59]
	v_mfma_f32_16x16x32_bf16 v[44:47], v[132:135], v[172:175], v[44:47]
	v_mfma_f32_16x16x32_bf16 v[40:43], v[140:143], v[172:175], v[40:43]
	v_mfma_f32_16x16x32_bf16 v[28:31], v[132:135], v[198:201], v[28:31]
	v_mfma_f32_16x16x32_bf16 v[24:27], v[140:143], v[198:201], v[24:27]
	v_mfma_f32_16x16x32_bf16 v[12:15], v[132:135], v[206:209], v[12:15]
	v_mfma_f32_16x16x32_bf16 v[8:11], v[140:143], v[206:209], v[8:11]
	s_setprio 0
	s_setprio 1
	v_mfma_f32_16x16x32_bf16 v[52:55], v[144:147], v[160:163], v[52:55]
	v_mfma_f32_16x16x32_bf16 v[48:51], v[152:155], v[160:163], v[48:51]
	v_mfma_f32_16x16x32_bf16 v[36:39], v[144:147], v[168:171], v[36:39]
	v_mfma_f32_16x16x32_bf16 v[32:35], v[152:155], v[168:171], v[32:35]
	v_mfma_f32_16x16x32_bf16 v[20:23], v[144:147], v[188:191], v[20:23]
	v_mfma_f32_16x16x32_bf16 v[16:19], v[152:155], v[188:191], v[16:19]
	v_mfma_f32_16x16x32_bf16 v[4:7], v[144:147], v[202:205], v[4:7]
	v_mfma_f32_16x16x32_bf16 v[0:3], v[152:155], v[202:205], v[0:3]
	v_mfma_f32_16x16x32_bf16 v[52:55], v[148:151], v[164:167], v[52:55]
	v_mfma_f32_16x16x32_bf16 v[48:51], v[156:159], v[164:167], v[48:51]
	v_mfma_f32_16x16x32_bf16 v[36:39], v[148:151], v[172:175], v[36:39]
	v_mfma_f32_16x16x32_bf16 v[32:35], v[156:159], v[172:175], v[32:35]
	v_mfma_f32_16x16x32_bf16 v[20:23], v[148:151], v[198:201], v[20:23]
	v_mfma_f32_16x16x32_bf16 v[16:19], v[156:159], v[198:201], v[16:19]
	v_mfma_f32_16x16x32_bf16 v[4:7], v[148:151], v[206:209], v[4:7]
	v_mfma_f32_16x16x32_bf16 v[0:3], v[156:159], v[206:209], v[0:3]
	s_setprio 2
	s_barrier
	s_add_i32 s6, 0, 0x18000
	s_add_i32 s7, 0, 0x1c000
	v_add_u32_e32 v140, s6, v186
	v_add_u32_e32 v156, s7, v186
	ds_read_b128 v[128:131], v140
	ds_read_b128 v[132:135], v140 offset:1024
	ds_read_b128 v[136:139], v140 offset:2048
	ds_read_b128 v[140:143], v140 offset:3072
	ds_read_b128 v[144:147], v156
	ds_read_b128 v[148:151], v156 offset:1024
	ds_read_b128 v[152:155], v156 offset:2048
	ds_read_b128 v[156:159], v156 offset:3072
	s_add_u32 s60, s60, 0x40000
	s_addc_u32 s61, s61, 0
	s_mov_b32 m0, s78
	v_lshl_add_u64 v[216:217], s[60:61], 0, v[182:183]
	ds_read_b128 v[160:163], v187 offset:32768
	ds_read_b128 v[164:167], v187 offset:33792
	ds_read_b128 v[168:171], v187 offset:34816
	ds_read_b128 v[172:175], v187 offset:35840
	ds_read_b128 v[188:191], v187 offset:36864
	ds_read_b128 v[198:201], v187 offset:37888
	ds_read_b128 v[202:205], v187 offset:38912
	ds_read_b128 v[206:209], v187 offset:39936
	global_load_lds_dwordx4 v[216:217], off
	v_lshl_add_u64 v[216:217], s[60:61], 0, v[178:179]
	s_mov_b32 m0, s88
	s_nop 0
	global_load_lds_dwordx4 v[216:217], off
	s_waitcnt vmcnt(8)
	s_waitcnt lgkmcnt(0)
	s_barrier
	s_setprio 1
	s_waitcnt lgkmcnt(0)
	v_mfma_f32_16x16x32_bf16 v[124:127], v[128:131], v[160:163], v[124:127]
	v_mfma_f32_16x16x32_bf16 v[120:123], v[136:139], v[160:163], v[120:123]
	v_mfma_f32_16x16x32_bf16 v[108:111], v[128:131], v[168:171], v[108:111]
	v_mfma_f32_16x16x32_bf16 v[104:107], v[136:139], v[168:171], v[104:107]
	v_mfma_f32_16x16x32_bf16 v[92:95], v[128:131], v[188:191], v[92:95]
	v_mfma_f32_16x16x32_bf16 v[88:91], v[136:139], v[188:191], v[88:91]
	v_mfma_f32_16x16x32_bf16 v[76:79], v[128:131], v[202:205], v[76:79]
	v_mfma_f32_16x16x32_bf16 v[72:75], v[136:139], v[202:205], v[72:75]
	v_mfma_f32_16x16x32_bf16 v[124:127], v[132:135], v[164:167], v[124:127]
	v_mfma_f32_16x16x32_bf16 v[120:123], v[140:143], v[164:167], v[120:123]
	v_mfma_f32_16x16x32_bf16 v[108:111], v[132:135], v[172:175], v[108:111]
	v_mfma_f32_16x16x32_bf16 v[104:107], v[140:143], v[172:175], v[104:107]
	v_mfma_f32_16x16x32_bf16 v[92:95], v[132:135], v[198:201], v[92:95]
	v_mfma_f32_16x16x32_bf16 v[88:91], v[140:143], v[198:201], v[88:91]
	v_mfma_f32_16x16x32_bf16 v[76:79], v[132:135], v[206:209], v[76:79]
	v_mfma_f32_16x16x32_bf16 v[72:75], v[140:143], v[206:209], v[72:75]
	s_setprio 0
	s_setprio 1
	v_mfma_f32_16x16x32_bf16 v[116:119], v[144:147], v[160:163], v[116:119]
	v_mfma_f32_16x16x32_bf16 v[112:115], v[152:155], v[160:163], v[112:115]
	v_mfma_f32_16x16x32_bf16 v[100:103], v[144:147], v[168:171], v[100:103]
	v_mfma_f32_16x16x32_bf16 v[96:99], v[152:155], v[168:171], v[96:99]
	v_mfma_f32_16x16x32_bf16 v[84:87], v[144:147], v[188:191], v[84:87]
	v_mfma_f32_16x16x32_bf16 v[80:83], v[152:155], v[188:191], v[80:83]
	v_mfma_f32_16x16x32_bf16 v[68:71], v[144:147], v[202:205], v[68:71]
	v_mfma_f32_16x16x32_bf16 v[64:67], v[152:155], v[202:205], v[64:67]
	v_mfma_f32_16x16x32_bf16 v[116:119], v[148:151], v[164:167], v[116:119]
	v_mfma_f32_16x16x32_bf16 v[112:115], v[156:159], v[164:167], v[112:115]
	v_mfma_f32_16x16x32_bf16 v[100:103], v[148:151], v[172:175], v[100:103]
	v_mfma_f32_16x16x32_bf16 v[96:99], v[156:159], v[172:175], v[96:99]
	v_mfma_f32_16x16x32_bf16 v[84:87], v[148:151], v[198:201], v[84:87]
	v_mfma_f32_16x16x32_bf16 v[80:83], v[156:159], v[198:201], v[80:83]
	v_mfma_f32_16x16x32_bf16 v[68:71], v[148:151], v[206:209], v[68:71]
	v_mfma_f32_16x16x32_bf16 v[64:67], v[156:159], v[206:209], v[64:67]
	s_setprio 2
	s_barrier
; #define PG8_STAGE(bufoff, gbase, voff) do { _Pragma("unroll") for (int _i = 0; _i < 2; ++_i) \
;         __builtin_amdgcn_global_load_lds((const unsigned*)((const char*)(gbase) + (voff)[_i]), (PG8_LAS unsigned*)(lds + (bufoff) + ldsw + _i * 8192), 16, 0, 0); } while (0)
; #define PG8_LDA(dst, b, h) do { _Pragma("unroll") for (int m = 0; m < 4; ++m) _Pragma("unroll") for (int k = 0; k < 2; ++k) dst[m][k] = *(const PG8_LAS bf16x8*)(lds + PG8_SA(b, h) + aoff + m * 2048 + k * 1024); } while (0)
; #define PG8_MMA(ai, bj, At, Bt) do { __builtin_amdgcn_s_setprio(1); _Pragma("unroll") for (int m = 0; m < 4; ++m) _Pragma("unroll") for (int n = 0; n < 2; ++n) _Pragma("unroll") for (int k = 0; k < 2; ++k) \
;         acc[ai][bj][m][n] = __builtin_amdgcn_mfma_f32_16x16x32_bf16(Bt[n][k], At[m][k], acc[ai][bj][m][n], 0, 0, 0); __builtin_amdgcn_s_setprio(0); } while (0)
; #define PG8_WAIT_V(n) asm volatile("s_waitcnt vmcnt(" #n ")" ::: "memory")
; #define PG8_WAIT_L(n) asm volatile("s_waitcnt lgkmcnt(" #n ")" ::: "memory")
; #define PG8_BAR __builtin_amdgcn_s_barrier()
; #define PG8_SCHED __builtin_amdgcn_sched_barrier(0)
; template <class Epi, class Sched, bool ALIGN_EPI = false, bool SP2 = false>
; __device__ __forceinline__ void gemm_phase(PG8_LAS unsigned char* lds, const Gemm g, const Sched& S, const Epi& E, const int tid_in) {
;     ...
;         for (int t = 0; t < nt; t += 2) {
;     ...
;             PG8_LDA(At, 1, 1); PG8_STAGE(PG8_SB(1, 0), b3, voffB); PG8_STAGE(PG8_SB(1, 1), b3 + hstep, voffB); PG8_STAGE(PG8_SA(1, 0), a3, voffA);
;             PG8_WAIT_V(8); PG8_WAIT_L(0); PG8_BAR; PG8_MMA(1, 0, At, B0); PG8_MMA(1, 1, At, B1); PG8_BAR; PG8_SCHED;
	s_add_i32 s6, s6, s34
	v_lshl_add_u64 v[192:193], v[192:193], 0, s[84:85]
	s_mov_b32 m0, s6
	ds_read_b128 v[160:163], v187 offset:49152
	ds_read_b128 v[164:167], v187 offset:50176
	ds_read_b128 v[168:171], v187 offset:51200
	ds_read_b128 v[172:175], v187 offset:52224
	ds_read_b128 v[188:191], v187 offset:53248
	ds_read_b128 v[198:201], v187 offset:54272
	ds_read_b128 v[202:205], v187 offset:55296
	ds_read_b128 v[206:209], v187 offset:56320
	global_load_lds_dwordx4 v[192:193], off
	s_add_i32 m0, s6, 0x2000
	s_add_u32 s58, s58, 0x40080
	v_lshl_add_u64 v[192:193], v[210:211], 0, s[84:85]
	s_addc_u32 s59, s59, 0
	s_add_i32 s6, s7, s34
	global_load_lds_dwordx4 v[192:193], off
	v_lshl_add_u64 v[192:193], s[58:59], 0, v[180:181]
	s_mov_b32 m0, s6
	s_nop 0
	global_load_lds_dwordx4 v[192:193], off
	v_lshl_add_u64 v[192:193], s[58:59], 0, v[176:177]
	s_add_i32 m0, s6, 0x2000
	s_nop 0
	global_load_lds_dwordx4 v[192:193], off
	v_lshl_add_u64 v[192:193], v[212:213], 0, s[84:85]
	s_mov_b32 m0, s38
	s_nop 0
	global_load_lds_dwordx4 v[192:193], off
	v_lshl_add_u64 v[192:193], v[214:215], 0, s[84:85]
	s_mov_b32 m0, s39
	s_nop 0
	global_load_lds_dwordx4 v[192:193], off
	s_waitcnt vmcnt(8)
	s_waitcnt lgkmcnt(0)
	s_barrier
	s_setprio 1
	s_waitcnt lgkmcnt(0)
	v_mfma_f32_16x16x32_bf16 v[60:63], v[128:131], v[160:163], v[60:63]
	v_mfma_f32_16x16x32_bf16 v[56:59], v[136:139], v[160:163], v[56:59]
	v_mfma_f32_16x16x32_bf16 v[44:47], v[128:131], v[168:171], v[44:47]
	v_mfma_f32_16x16x32_bf16 v[40:43], v[136:139], v[168:171], v[40:43]
	v_mfma_f32_16x16x32_bf16 v[28:31], v[128:131], v[188:191], v[28:31]
	v_mfma_f32_16x16x32_bf16 v[24:27], v[136:139], v[188:191], v[24:27]
	v_mfma_f32_16x16x32_bf16 v[12:15], v[128:131], v[202:205], v[12:15]
	v_mfma_f32_16x16x32_bf16 v[8:11], v[136:139], v[202:205], v[8:11]
	v_mfma_f32_16x16x32_bf16 v[60:63], v[132:135], v[164:167], v[60:63]
	v_mfma_f32_16x16x32_bf16 v[56:59], v[140:143], v[164:167], v[56:59]
	v_mfma_f32_16x16x32_bf16 v[44:47], v[132:135], v[172:175], v[44:47]
	v_mfma_f32_16x16x32_bf16 v[40:43], v[140:143], v[172:175], v[40:43]
	v_mfma_f32_16x16x32_bf16 v[28:31], v[132:135], v[198:201], v[28:31]
	v_mfma_f32_16x16x32_bf16 v[24:27], v[140:143], v[198:201], v[24:27]
	v_mfma_f32_16x16x32_bf16 v[12:15], v[132:135], v[206:209], v[12:15]
	v_mfma_f32_16x16x32_bf16 v[8:11], v[140:143], v[206:209], v[8:11]
	s_setprio 0
	s_setprio 1
	v_mfma_f32_16x16x32_bf16 v[52:55], v[144:147], v[160:163], v[52:55]
	v_mfma_f32_16x16x32_bf16 v[48:51], v[152:155], v[160:163], v[48:51]
	v_mfma_f32_16x16x32_bf16 v[36:39], v[144:147], v[168:171], v[36:39]
	v_mfma_f32_16x16x32_bf16 v[32:35], v[152:155], v[168:171], v[32:35]
	v_mfma_f32_16x16x32_bf16 v[20:23], v[144:147], v[188:191], v[20:23]
	v_mfma_f32_16x16x32_bf16 v[16:19], v[152:155], v[188:191], v[16:19]
	v_mfma_f32_16x16x32_bf16 v[4:7], v[144:147], v[202:205], v[4:7]
	v_mfma_f32_16x16x32_bf16 v[0:3], v[152:155], v[202:205], v[0:3]
	v_mfma_f32_16x16x32_bf16 v[52:55], v[148:151], v[164:167], v[52:55]
	v_mfma_f32_16x16x32_bf16 v[48:51], v[156:159], v[164:167], v[48:51]
	v_mfma_f32_16x16x32_bf16 v[36:39], v[148:151], v[172:175], v[36:39]
	v_mfma_f32_16x16x32_bf16 v[32:35], v[156:159], v[172:175], v[32:35]
	v_mfma_f32_16x16x32_bf16 v[20:23], v[148:151], v[198:201], v[20:23]
	v_mfma_f32_16x16x32_bf16 v[16:19], v[156:159], v[198:201], v[16:19]
	v_mfma_f32_16x16x32_bf16 v[4:7], v[148:151], v[206:209], v[4:7]
	v_mfma_f32_16x16x32_bf16 v[0:3], v[156:159], v[206:209], v[0:3]
	s_setprio 2
	s_barrier
	s_add_i32 s53, s53, 2
	s_add_u32 s56, s56, 0x100
	s_addc_u32 s57, s57, 0
	s_add_u32 s45, s45, 0x100
	s_addc_u32 s52, s52, 0
	s_cmp_gt_u32 s53, 13
	s_cbranch_scc0 .LBB0_1139
	s_and_b64 vcc, exec, s[40:41]
	s_cbranch_vccz .LBB0_1142
	s_barrier

; #define PG8_STAGE(bufoff, gbase, voff) do { _Pragma("unroll") for (int _i = 0; _i < 2; ++_i) \
;         __builtin_amdgcn_global_load_lds((const unsigned*)((const char*)(gbase) + (voff)[_i]), (PG8_LAS unsigned*)(lds + (bufoff) + ldsw + _i * 8192), 16, 0, 0); } while (0)
; #define PG8_LDA(dst, b, h) do { _Pragma("unroll") for (int m = 0; m < 4; ++m) _Pragma("unroll") for (int k = 0; k < 2; ++k) dst[m][k] = *(const PG8_LAS bf16x8*)(lds + PG8_SA(b, h) + aoff + m * 2048 + k * 1024); } while (0)
; #define PG8_LDB(dst, b, h) do { _Pragma("unroll") for (int n = 0; n < 2; ++n) _Pragma("unroll") for (int k = 0; k < 2; ++k) dst[n][k] = *(const PG8_LAS bf16x8*)(lds + PG8_SB(b, h) + boff + n * 2048 + k * 1024); } while (0)
; #define PG8_MMA(ai, bj, At, Bt) do { __builtin_amdgcn_s_setprio(1); _Pragma("unroll") for (int m = 0; m < 4; ++m) _Pragma("unroll") for (int n = 0; n < 2; ++n) _Pragma("unroll") for (int k = 0; k < 2; ++k) \
;         acc[ai][bj][m][n] = __builtin_amdgcn_mfma_f32_16x16x32_bf16(Bt[n][k], At[m][k], acc[ai][bj][m][n], 0, 0, 0); __builtin_amdgcn_s_setprio(0); } while (0)
; #define PG8_WAIT_V(n) asm volatile("s_waitcnt vmcnt(" #n ")" ::: "memory")
; #define PG8_WAIT_L(n) asm volatile("s_waitcnt lgkmcnt(" #n ")" ::: "memory")
; #define PG8_BAR __builtin_amdgcn_s_barrier()
; #define PG8_SCHED __builtin_amdgcn_sched_barrier(0)
; template <class Epi, class Sched, bool ALIGN_EPI = false, bool SP2 = false>
; __device__ __forceinline__ void gemm_phase(PG8_LAS unsigned char* lds, const Gemm g, const Sched& S, const Epi& E, const int tid_in) {
;     ...
;             const bool last = (t == nt - 2);
;             const char* a1 = cA + (size_t)(t + 1) * kstepA;
;             const char* a2 = last ? nA : cA + (size_t)(t + 2) * kstepA; const char* b2 = last ? nB : cB + (size_t)(t + 2) * kstep;
;             const char* a3 = a2 + kstepA; const char* b3 = b2 + kstep;
;             if (last && has_next) S.a_ready(nxt, ui + 1);
;             if constexpr (SP2) {
;             PG8_LDB(B0, 0, 0); PG8_LDB(B1, 0, 1); PG8_SCHED; PG8_LDA(At, 0, 0); PG8_STAGE(PG8_SA(1, 1), a1 + hstepA, voffA);
;             PG8_WAIT_V(8); PG8_WAIT_L(0); PG8_BAR; PG8_MMA(0, 0, At, B0); PG8_MMA(0, 1, At, B1); PG8_BAR; PG8_SCHED;
;             PG8_LDA(At, 0, 1); PG8_STAGE(PG8_SB(0, 0), b2, voffB); PG8_STAGE(PG8_SB(0, 1), b2 + hstep, voffB); PG8_STAGE(PG8_SA(0, 0), a2, voffA);
.LBB0_1236:
	s_add_u32 s6, s56, 0xfffc0080
	s_addc_u32 s7, s57, -1
	s_and_b64 s[58:59], s[58:59], exec
	s_cselect_b32 s61, s3, s7
	s_cselect_b32 s60, s12, s6
	s_cselect_b32 s59, s14, s53
	s_cselect_b32 s58, s15, s52
	s_add_i32 s6, 0, 0x10000
	s_add_i32 s7, 0, 0x14000
	v_add_u32_e32 v152, s6, v138
	v_add_u32_e32 v168, s7, v138
	ds_read_b128 v[140:143], v152
	ds_read_b128 v[144:147], v152 offset:1024
	ds_read_b128 v[148:151], v152 offset:2048
	ds_read_b128 v[152:155], v152 offset:3072
	ds_read_b128 v[156:159], v168
	ds_read_b128 v[160:163], v168 offset:1024
	ds_read_b128 v[164:167], v168 offset:2048
	ds_read_b128 v[168:171], v168 offset:3072
	v_lshl_add_u64 v[190:191], s[56:57], 0, v[134:135]
	s_add_i32 m0, s35, 0xc000
	ds_read_b128 v[172:175], v139
	ds_read_b128 v[176:179], v139 offset:1024
	ds_read_b128 v[180:183], v139 offset:2048
	ds_read_b128 v[186:189], v139 offset:3072
	ds_read_b128 v[194:197], v139 offset:4096
	ds_read_b128 v[198:201], v139 offset:5120
	ds_read_b128 v[202:205], v139 offset:6144
	ds_read_b128 v[206:209], v139 offset:7168
	global_load_lds_dwordx4 v[190:191], off
	v_lshl_add_u64 v[190:191], s[56:57], 0, v[136:137]
	s_add_i32 m0, s35, 0xe000
	s_nop 0
	global_load_lds_dwordx4 v[190:191], off
	s_waitcnt vmcnt(8)
	s_waitcnt lgkmcnt(0)
	s_barrier
	s_setprio 1
	s_waitcnt lgkmcnt(0)
	v_mfma_f32_16x16x32_bf16 v[124:127], v[140:143], v[172:175], v[124:127]
	v_mfma_f32_16x16x32_bf16 v[120:123], v[148:151], v[172:175], v[120:123]
	v_mfma_f32_16x16x32_bf16 v[108:111], v[140:143], v[180:183], v[108:111]
	v_mfma_f32_16x16x32_bf16 v[104:107], v[148:151], v[180:183], v[104:107]
	v_mfma_f32_16x16x32_bf16 v[92:95], v[140:143], v[194:197], v[92:95]
	v_mfma_f32_16x16x32_bf16 v[88:91], v[148:151], v[194:197], v[88:91]
	v_mfma_f32_16x16x32_bf16 v[76:79], v[140:143], v[202:205], v[76:79]
	v_mfma_f32_16x16x32_bf16 v[72:75], v[148:151], v[202:205], v[72:75]
	v_mfma_f32_16x16x32_bf16 v[124:127], v[144:147], v[176:179], v[124:127]
	v_mfma_f32_16x16x32_bf16 v[120:123], v[152:155], v[176:179], v[120:123]
	v_mfma_f32_16x16x32_bf16 v[108:111], v[144:147], v[186:189], v[108:111]
	v_mfma_f32_16x16x32_bf16 v[104:107], v[152:155], v[186:189], v[104:107]
	v_mfma_f32_16x16x32_bf16 v[92:95], v[144:147], v[198:201], v[92:95]
	v_mfma_f32_16x16x32_bf16 v[88:91], v[152:155], v[198:201], v[88:91]
	v_mfma_f32_16x16x32_bf16 v[76:79], v[144:147], v[206:209], v[76:79]
	v_mfma_f32_16x16x32_bf16 v[72:75], v[152:155], v[206:209], v[72:75]
	s_setprio 0
	s_setprio 1
	v_mfma_f32_16x16x32_bf16 v[116:119], v[156:159], v[172:175], v[116:119]
	v_mfma_f32_16x16x32_bf16 v[112:115], v[164:167], v[172:175], v[112:115]
	v_mfma_f32_16x16x32_bf16 v[100:103], v[156:159], v[180:183], v[100:103]
	v_mfma_f32_16x16x32_bf16 v[96:99], v[164:167], v[180:183], v[96:99]
	v_mfma_f32_16x16x32_bf16 v[84:87], v[156:159], v[194:197], v[84:87]
	v_mfma_f32_16x16x32_bf16 v[80:83], v[164:167], v[194:197], v[80:83]
	v_mfma_f32_16x16x32_bf16 v[68:71], v[156:159], v[202:205], v[68:71]
	v_mfma_f32_16x16x32_bf16 v[64:67], v[164:167], v[202:205], v[64:67]
	v_mfma_f32_16x16x32_bf16 v[116:119], v[160:163], v[176:179], v[116:119]
	v_mfma_f32_16x16x32_bf16 v[112:115], v[168:171], v[176:179], v[112:115]
	v_mfma_f32_16x16x32_bf16 v[100:103], v[160:163], v[186:189], v[100:103]
	v_mfma_f32_16x16x32_bf16 v[96:99], v[168:171], v[186:189], v[96:99]
	v_mfma_f32_16x16x32_bf16 v[84:87], v[160:163], v[198:201], v[84:87]
	v_mfma_f32_16x16x32_bf16 v[80:83], v[168:171], v[198:201], v[80:83]
	v_mfma_f32_16x16x32_bf16 v[68:71], v[160:163], v[206:209], v[68:71]
	v_mfma_f32_16x16x32_bf16 v[64:67], v[168:171], v[206:209], v[64:67]
	s_setprio 2
	s_barrier
	s_add_i32 s6, s6, s34
	v_lshl_add_u64 v[190:191], s[58:59], 0, v[184:185]
	s_mov_b32 m0, s6
	ds_read_b128 v[172:175], v139 offset:16384
	ds_read_b128 v[176:179], v139 offset:17408
	ds_read_b128 v[180:183], v139 offset:18432
	ds_read_b128 v[186:189], v139 offset:19456
	ds_read_b128 v[194:197], v139 offset:20480
	ds_read_b128 v[198:201], v139 offset:21504
	ds_read_b128 v[202:205], v139 offset:22528
	ds_read_b128 v[206:209], v139 offset:23552
	global_load_lds_dwordx4 v[190:191], off
	s_add_i32 m0, s6, 0x2000
	s_add_u32 s78, s58, 0x40000
	v_lshl_add_u64 v[192:193], s[58:59], 0, v[132:133]
	s_addc_u32 s79, s59, 0
	s_add_i32 s6, s7, s34
	global_load_lds_dwordx4 v[192:193], off
	v_lshl_add_u64 v[210:211], s[78:79], 0, v[184:185]
	s_mov_b32 m0, s6
	v_lshl_add_u64 v[212:213], s[60:61], 0, v[130:131]
	global_load_lds_dwordx4 v[210:211], off
	v_lshl_add_u64 v[210:211], s[78:79], 0, v[132:133]
	s_add_i32 m0, s6, 0x2000
	s_nop 0
	global_load_lds_dwordx4 v[210:211], off
	v_lshl_add_u64 v[210:211], s[60:61], 0, v[128:129]
	s_mov_b32 m0, s35
	s_nop 0
	global_load_lds_dwordx4 v[210:211], off
	s_mov_b32 m0, s54
	s_nop 0
	global_load_lds_dwordx4 v[212:213], off
	s_waitcnt vmcnt(8)
	s_waitcnt lgkmcnt(0)
	s_barrier
; #define PG8_STAGE(bufoff, gbase, voff) do { _Pragma("unroll") for (int _i = 0; _i < 2; ++_i) \
;         __builtin_amdgcn_global_load_lds((const unsigned*)((const char*)(gbase) + (voff)[_i]), (PG8_LAS unsigned*)(lds + (bufoff) + ldsw + _i * 8192), 16, 0, 0); } while (0)
; #define PG8_LDA(dst, b, h) do { _Pragma("unroll") for (int m = 0; m < 4; ++m) _Pragma("unroll") for (int k = 0; k < 2; ++k) dst[m][k] = *(const PG8_LAS bf16x8*)(lds + PG8_SA(b, h) + aoff + m * 2048 + k * 1024); } while (0)
; #define PG8_LDB(dst, b, h) do { _Pragma("unroll") for (int n = 0; n < 2; ++n) _Pragma("unroll") for (int k = 0; k < 2; ++k) dst[n][k] = *(const PG8_LAS bf16x8*)(lds + PG8_SB(b, h) + boff + n * 2048 + k * 1024); } while (0)
; #define PG8_MMA(ai, bj, At, Bt) do { __builtin_amdgcn_s_setprio(1); _Pragma("unroll") for (int m = 0; m < 4; ++m) _Pragma("unroll") for (int n = 0; n < 2; ++n) _Pragma("unroll") for (int k = 0; k < 2; ++k) \
;         acc[ai][bj][m][n] = __builtin_amdgcn_mfma_f32_16x16x32_bf16(Bt[n][k], At[m][k], acc[ai][bj][m][n], 0, 0, 0); __builtin_amdgcn_s_setprio(0); } while (0)
; #define PG8_WAIT_V(n) asm volatile("s_waitcnt vmcnt(" #n ")" ::: "memory")
; #define PG8_WAIT_L(n) asm volatile("s_waitcnt lgkmcnt(" #n ")" ::: "memory")
; #define PG8_BAR __builtin_amdgcn_s_barrier()
; #define PG8_SCHED __builtin_amdgcn_sched_barrier(0)
; template <class Epi, class Sched, bool ALIGN_EPI = false, bool SP2 = false>
; __device__ __forceinline__ void gemm_phase(PG8_LAS unsigned char* lds, const Gemm g, const Sched& S, const Epi& E, const int tid_in) {
;     ...
;             PG8_WAIT_V(8); PG8_WAIT_L(0); PG8_BAR; PG8_MMA(1, 0, At, B0); PG8_MMA(1, 1, At, B1); PG8_BAR; PG8_SCHED;
;             PG8_LDB(B0, 1, 0); PG8_LDB(B1, 1, 1); PG8_SCHED; PG8_LDA(At, 1, 0); PG8_STAGE(PG8_SA(0, 1), a2 + hstepA, voffA);
;             PG8_WAIT_V(8); PG8_WAIT_L(0); PG8_BAR; PG8_MMA(0, 0, At, B0); PG8_MMA(0, 1, At, B1); PG8_BAR; PG8_SCHED;
	s_setprio 1
	s_waitcnt lgkmcnt(0)
	v_mfma_f32_16x16x32_bf16 v[60:63], v[140:143], v[172:175], v[60:63]
	v_mfma_f32_16x16x32_bf16 v[56:59], v[148:151], v[172:175], v[56:59]
	v_mfma_f32_16x16x32_bf16 v[44:47], v[140:143], v[180:183], v[44:47]
	v_mfma_f32_16x16x32_bf16 v[40:43], v[148:151], v[180:183], v[40:43]
	v_mfma_f32_16x16x32_bf16 v[28:31], v[140:143], v[194:197], v[28:31]
	v_mfma_f32_16x16x32_bf16 v[24:27], v[148:151], v[194:197], v[24:27]
	v_mfma_f32_16x16x32_bf16 v[12:15], v[140:143], v[202:205], v[12:15]
	v_mfma_f32_16x16x32_bf16 v[8:11], v[148:151], v[202:205], v[8:11]
	v_mfma_f32_16x16x32_bf16 v[60:63], v[144:147], v[176:179], v[60:63]
	v_mfma_f32_16x16x32_bf16 v[56:59], v[152:155], v[176:179], v[56:59]
	v_mfma_f32_16x16x32_bf16 v[44:47], v[144:147], v[186:189], v[44:47]
	v_mfma_f32_16x16x32_bf16 v[40:43], v[152:155], v[186:189], v[40:43]
	v_mfma_f32_16x16x32_bf16 v[28:31], v[144:147], v[198:201], v[28:31]
	v_mfma_f32_16x16x32_bf16 v[24:27], v[152:155], v[198:201], v[24:27]
	v_mfma_f32_16x16x32_bf16 v[12:15], v[144:147], v[206:209], v[12:15]
	v_mfma_f32_16x16x32_bf16 v[8:11], v[152:155], v[206:209], v[8:11]
	s_setprio 0
	s_setprio 1
	v_mfma_f32_16x16x32_bf16 v[52:55], v[156:159], v[172:175], v[52:55]
	v_mfma_f32_16x16x32_bf16 v[48:51], v[164:167], v[172:175], v[48:51]
	v_mfma_f32_16x16x32_bf16 v[36:39], v[156:159], v[180:183], v[36:39]
	v_mfma_f32_16x16x32_bf16 v[32:35], v[164:167], v[180:183], v[32:35]
	v_mfma_f32_16x16x32_bf16 v[20:23], v[156:159], v[194:197], v[20:23]
	v_mfma_f32_16x16x32_bf16 v[16:19], v[164:167], v[194:197], v[16:19]
	v_mfma_f32_16x16x32_bf16 v[4:7], v[156:159], v[202:205], v[4:7]
	v_mfma_f32_16x16x32_bf16 v[0:3], v[164:167], v[202:205], v[0:3]
	v_mfma_f32_16x16x32_bf16 v[52:55], v[160:163], v[176:179], v[52:55]
	v_mfma_f32_16x16x32_bf16 v[48:51], v[168:171], v[176:179], v[48:51]
	v_mfma_f32_16x16x32_bf16 v[36:39], v[160:163], v[186:189], v[36:39]
	v_mfma_f32_16x16x32_bf16 v[32:35], v[168:171], v[186:189], v[32:35]
	v_mfma_f32_16x16x32_bf16 v[20:23], v[160:163], v[198:201], v[20:23]
	v_mfma_f32_16x16x32_bf16 v[16:19], v[168:171], v[198:201], v[16:19]
	v_mfma_f32_16x16x32_bf16 v[4:7], v[160:163], v[206:209], v[4:7]
	v_mfma_f32_16x16x32_bf16 v[0:3], v[168:171], v[206:209], v[0:3]
	s_setprio 2
	s_barrier
	s_add_i32 s6, 0, 0x18000
	s_add_i32 s7, 0, 0x1c000
	v_add_u32_e32 v152, s6, v138
	v_add_u32_e32 v168, s7, v138
	ds_read_b128 v[140:143], v152
	ds_read_b128 v[144:147], v152 offset:1024
	ds_read_b128 v[148:151], v152 offset:2048
	ds_read_b128 v[152:155], v152 offset:3072
	ds_read_b128 v[156:159], v168
	ds_read_b128 v[160:163], v168 offset:1024
	ds_read_b128 v[164:167], v168 offset:2048
	ds_read_b128 v[168:171], v168 offset:3072
	s_add_u32 s60, s60, 0x40000
	s_addc_u32 s61, s61, 0
	s_mov_b32 m0, s62
	v_lshl_add_u64 v[214:215], s[60:61], 0, v[128:129]
	ds_read_b128 v[172:175], v139 offset:32768
	ds_read_b128 v[176:179], v139 offset:33792
	ds_read_b128 v[180:183], v139 offset:34816
	ds_read_b128 v[186:189], v139 offset:35840
	ds_read_b128 v[194:197], v139 offset:36864
	ds_read_b128 v[198:201], v139 offset:37888
	ds_read_b128 v[202:205], v139 offset:38912
	ds_read_b128 v[206:209], v139 offset:39936
	global_load_lds_dwordx4 v[214:215], off
	v_lshl_add_u64 v[214:215], s[60:61], 0, v[130:131]
	s_mov_b32 m0, s63
	s_nop 0
	global_load_lds_dwordx4 v[214:215], off
	s_waitcnt vmcnt(8)
	s_waitcnt lgkmcnt(0)
	s_barrier
	s_setprio 1
	s_waitcnt lgkmcnt(0)
	v_mfma_f32_16x16x32_bf16 v[124:127], v[140:143], v[172:175], v[124:127]
	v_mfma_f32_16x16x32_bf16 v[120:123], v[148:151], v[172:175], v[120:123]
	v_mfma_f32_16x16x32_bf16 v[108:111], v[140:143], v[180:183], v[108:111]
	v_mfma_f32_16x16x32_bf16 v[104:107], v[148:151], v[180:183], v[104:107]
	v_mfma_f32_16x16x32_bf16 v[92:95], v[140:143], v[194:197], v[92:95]
	v_mfma_f32_16x16x32_bf16 v[88:91], v[148:151], v[194:197], v[88:91]
	v_mfma_f32_16x16x32_bf16 v[76:79], v[140:143], v[202:205], v[76:79]
	v_mfma_f32_16x16x32_bf16 v[72:75], v[148:151], v[202:205], v[72:75]
	v_mfma_f32_16x16x32_bf16 v[124:127], v[144:147], v[176:179], v[124:127]
	v_mfma_f32_16x16x32_bf16 v[120:123], v[152:155], v[176:179], v[120:123]
	v_mfma_f32_16x16x32_bf16 v[108:111], v[144:147], v[186:189], v[108:111]
	v_mfma_f32_16x16x32_bf16 v[104:107], v[152:155], v[186:189], v[104:107]
	v_mfma_f32_16x16x32_bf16 v[92:95], v[144:147], v[198:201], v[92:95]
	v_mfma_f32_16x16x32_bf16 v[88:91], v[152:155], v[198:201], v[88:91]
	v_mfma_f32_16x16x32_bf16 v[76:79], v[144:147], v[206:209], v[76:79]
	v_mfma_f32_16x16x32_bf16 v[72:75], v[152:155], v[206:209], v[72:75]
	s_setprio 0
	s_setprio 1
	v_mfma_f32_16x16x32_bf16 v[116:119], v[156:159], v[172:175], v[116:119]
	v_mfma_f32_16x16x32_bf16 v[112:115], v[164:167], v[172:175], v[112:115]
	v_mfma_f32_16x16x32_bf16 v[100:103], v[156:159], v[180:183], v[100:103]
	v_mfma_f32_16x16x32_bf16 v[96:99], v[164:167], v[180:183], v[96:99]
	v_mfma_f32_16x16x32_bf16 v[84:87], v[156:159], v[194:197], v[84:87]
	v_mfma_f32_16x16x32_bf16 v[80:83], v[164:167], v[194:197], v[80:83]
	v_mfma_f32_16x16x32_bf16 v[68:71], v[156:159], v[202:205], v[68:71]
	v_mfma_f32_16x16x32_bf16 v[64:67], v[164:167], v[202:205], v[64:67]
	v_mfma_f32_16x16x32_bf16 v[116:119], v[160:163], v[176:179], v[116:119]
	v_mfma_f32_16x16x32_bf16 v[112:115], v[168:171], v[176:179], v[112:115]
	v_mfma_f32_16x16x32_bf16 v[100:103], v[160:163], v[186:189], v[100:103]
	v_mfma_f32_16x16x32_bf16 v[96:99], v[168:171], v[186:189], v[96:99]
	v_mfma_f32_16x16x32_bf16 v[84:87], v[160:163], v[198:201], v[84:87]
	v_mfma_f32_16x16x32_bf16 v[80:83], v[168:171], v[198:201], v[80:83]
	v_mfma_f32_16x16x32_bf16 v[68:71], v[160:163], v[206:209], v[68:71]
	v_mfma_f32_16x16x32_bf16 v[64:67], v[168:171], v[206:209], v[64:67]
	s_setprio 2
	s_barrier
; #define PG8_STAGE(bufoff, gbase, voff) do { _Pragma("unroll") for (int _i = 0; _i < 2; ++_i) \
;         __builtin_amdgcn_global_load_lds((const unsigned*)((const char*)(gbase) + (voff)[_i]), (PG8_LAS unsigned*)(lds + (bufoff) + ldsw + _i * 8192), 16, 0, 0); } while (0)
; #define PG8_LDA(dst, b, h) do { _Pragma("unroll") for (int m = 0; m < 4; ++m) _Pragma("unroll") for (int k = 0; k < 2; ++k) dst[m][k] = *(const PG8_LAS bf16x8*)(lds + PG8_SA(b, h) + aoff + m * 2048 + k * 1024); } while (0)
; #define PG8_MMA(ai, bj, At, Bt) do { __builtin_amdgcn_s_setprio(1); _Pragma("unroll") for (int m = 0; m < 4; ++m) _Pragma("unroll") for (int n = 0; n < 2; ++n) _Pragma("unroll") for (int k = 0; k < 2; ++k) \
;         acc[ai][bj][m][n] = __builtin_amdgcn_mfma_f32_16x16x32_bf16(Bt[n][k], At[m][k], acc[ai][bj][m][n], 0, 0, 0); __builtin_amdgcn_s_setprio(0); } while (0)
; #define PG8_WAIT_V(n) asm volatile("s_waitcnt vmcnt(" #n ")" ::: "memory")
; #define PG8_WAIT_L(n) asm volatile("s_waitcnt lgkmcnt(" #n ")" ::: "memory")
; #define PG8_BAR __builtin_amdgcn_s_barrier()
; #define PG8_SCHED __builtin_amdgcn_sched_barrier(0)
; template <class Epi, class Sched, bool ALIGN_EPI = false, bool SP2 = false>
; __device__ __forceinline__ void gemm_phase(PG8_LAS unsigned char* lds, const Gemm g, const Sched& S, const Epi& E, const int tid_in) {
;     ...
;         for (int t = 0; t < nt; t += 2) {
;     ...
;             PG8_LDA(At, 1, 1); PG8_STAGE(PG8_SB(1, 0), b3, voffB); PG8_STAGE(PG8_SB(1, 1), b3 + hstep, voffB); PG8_STAGE(PG8_SA(1, 0), a3, voffA);
;             PG8_WAIT_V(8); PG8_WAIT_L(0); PG8_BAR; PG8_MMA(1, 0, At, B0); PG8_MMA(1, 1, At, B1); PG8_BAR; PG8_SCHED;
	s_add_i32 s6, s6, s34
	v_lshl_add_u64 v[190:191], v[190:191], 0, s[84:85]
	s_mov_b32 m0, s6
	ds_read_b128 v[172:175], v139 offset:49152
	ds_read_b128 v[176:179], v139 offset:50176
	ds_read_b128 v[180:183], v139 offset:51200
	ds_read_b128 v[186:189], v139 offset:52224
	ds_read_b128 v[194:197], v139 offset:53248
	ds_read_b128 v[198:201], v139 offset:54272
	ds_read_b128 v[202:205], v139 offset:55296
	ds_read_b128 v[206:209], v139 offset:56320
	global_load_lds_dwordx4 v[190:191], off
	s_add_i32 m0, s6, 0x2000
	s_add_u32 s58, s58, 0x40080
	v_lshl_add_u64 v[190:191], v[192:193], 0, s[84:85]
	s_addc_u32 s59, s59, 0
	s_add_i32 s6, s7, s34
	global_load_lds_dwordx4 v[190:191], off
	v_lshl_add_u64 v[190:191], s[58:59], 0, v[184:185]
	s_mov_b32 m0, s6
	s_nop 0
	global_load_lds_dwordx4 v[190:191], off
	v_lshl_add_u64 v[190:191], s[58:59], 0, v[132:133]
	s_add_i32 m0, s6, 0x2000
	s_nop 0
	global_load_lds_dwordx4 v[190:191], off
	v_lshl_add_u64 v[190:191], v[210:211], 0, s[84:85]
	s_mov_b32 m0, s66
	s_nop 0
	global_load_lds_dwordx4 v[190:191], off
	v_lshl_add_u64 v[190:191], v[212:213], 0, s[84:85]
	s_mov_b32 m0, s67
	s_nop 0
	global_load_lds_dwordx4 v[190:191], off
	s_waitcnt vmcnt(8)
	s_waitcnt lgkmcnt(0)
	s_barrier
	s_setprio 1
	s_waitcnt lgkmcnt(0)
	v_mfma_f32_16x16x32_bf16 v[60:63], v[140:143], v[172:175], v[60:63]
	v_mfma_f32_16x16x32_bf16 v[56:59], v[148:151], v[172:175], v[56:59]
	v_mfma_f32_16x16x32_bf16 v[44:47], v[140:143], v[180:183], v[44:47]
	v_mfma_f32_16x16x32_bf16 v[40:43], v[148:151], v[180:183], v[40:43]
	v_mfma_f32_16x16x32_bf16 v[28:31], v[140:143], v[194:197], v[28:31]
	v_mfma_f32_16x16x32_bf16 v[24:27], v[148:151], v[194:197], v[24:27]
	v_mfma_f32_16x16x32_bf16 v[12:15], v[140:143], v[202:205], v[12:15]
	v_mfma_f32_16x16x32_bf16 v[8:11], v[148:151], v[202:205], v[8:11]
	v_mfma_f32_16x16x32_bf16 v[60:63], v[144:147], v[176:179], v[60:63]
	v_mfma_f32_16x16x32_bf16 v[56:59], v[152:155], v[176:179], v[56:59]
	v_mfma_f32_16x16x32_bf16 v[44:47], v[144:147], v[186:189], v[44:47]
	v_mfma_f32_16x16x32_bf16 v[40:43], v[152:155], v[186:189], v[40:43]
	v_mfma_f32_16x16x32_bf16 v[28:31], v[144:147], v[198:201], v[28:31]
	v_mfma_f32_16x16x32_bf16 v[24:27], v[152:155], v[198:201], v[24:27]
	v_mfma_f32_16x16x32_bf16 v[12:15], v[144:147], v[206:209], v[12:15]
	v_mfma_f32_16x16x32_bf16 v[8:11], v[152:155], v[206:209], v[8:11]
	s_setprio 0
	s_setprio 1
	v_mfma_f32_16x16x32_bf16 v[52:55], v[156:159], v[172:175], v[52:55]
	v_mfma_f32_16x16x32_bf16 v[48:51], v[164:167], v[172:175], v[48:51]
	v_mfma_f32_16x16x32_bf16 v[36:39], v[156:159], v[180:183], v[36:39]
	v_mfma_f32_16x16x32_bf16 v[32:35], v[164:167], v[180:183], v[32:35]
	v_mfma_f32_16x16x32_bf16 v[20:23], v[156:159], v[194:197], v[20:23]
	v_mfma_f32_16x16x32_bf16 v[16:19], v[164:167], v[194:197], v[16:19]
	v_mfma_f32_16x16x32_bf16 v[4:7], v[156:159], v[202:205], v[4:7]
	v_mfma_f32_16x16x32_bf16 v[0:3], v[164:167], v[202:205], v[0:3]
	v_mfma_f32_16x16x32_bf16 v[52:55], v[160:163], v[176:179], v[52:55]
	v_mfma_f32_16x16x32_bf16 v[48:51], v[168:171], v[176:179], v[48:51]
	v_mfma_f32_16x16x32_bf16 v[36:39], v[160:163], v[186:189], v[36:39]
	v_mfma_f32_16x16x32_bf16 v[32:35], v[168:171], v[186:189], v[32:35]
	v_mfma_f32_16x16x32_bf16 v[20:23], v[160:163], v[198:201], v[20:23]
	v_mfma_f32_16x16x32_bf16 v[16:19], v[168:171], v[198:201], v[16:19]
	v_mfma_f32_16x16x32_bf16 v[4:7], v[160:163], v[206:209], v[4:7]
	v_mfma_f32_16x16x32_bf16 v[0:3], v[168:171], v[206:209], v[0:3]
	s_setprio 2
	s_barrier
	s_add_i32 s77, s77, 2
	s_add_u32 s56, s56, 0x100
	s_addc_u32 s57, s57, 0
	s_add_u32 s52, s52, 0x100
	s_addc_u32 s53, s53, 0
	s_cmp_gt_u32 s77, 13
	s_cbranch_scc1 .LBB0_1240

; #define PG8_STAGE(bufoff, gbase, voff) do { _Pragma("unroll") for (int _i = 0; _i < 2; ++_i) \
;         __builtin_amdgcn_global_load_lds((const unsigned*)((const char*)(gbase) + (voff)[_i]), (PG8_LAS unsigned*)(lds + (bufoff) + ldsw + _i * 8192), 16, 0, 0); } while (0)
; #define PG8_LDA(dst, b, h) do { _Pragma("unroll") for (int m = 0; m < 4; ++m) _Pragma("unroll") for (int k = 0; k < 2; ++k) dst[m][k] = *(const PG8_LAS bf16x8*)(lds + PG8_SA(b, h) + aoff + m * 2048 + k * 1024); } while (0)
; #define PG8_LDB(dst, b, h) do { _Pragma("unroll") for (int n = 0; n < 2; ++n) _Pragma("unroll") for (int k = 0; k < 2; ++k) dst[n][k] = *(const PG8_LAS bf16x8*)(lds + PG8_SB(b, h) + boff + n * 2048 + k * 1024); } while (0)
; #define PG8_MMA(ai, bj, At, Bt) do { __builtin_amdgcn_s_setprio(1); _Pragma("unroll") for (int m = 0; m < 4; ++m) _Pragma("unroll") for (int n = 0; n < 2; ++n) _Pragma("unroll") for (int k = 0; k < 2; ++k) \
;         acc[ai][bj][m][n] = __builtin_amdgcn_mfma_f32_16x16x32_bf16(Bt[n][k], At[m][k], acc[ai][bj][m][n], 0, 0, 0); __builtin_amdgcn_s_setprio(0); } while (0)
; #define PG8_WAIT_V(n) asm volatile("s_waitcnt vmcnt(" #n ")" ::: "memory")
; #define PG8_WAIT_L(n) asm volatile("s_waitcnt lgkmcnt(" #n ")" ::: "memory")
; #define PG8_BAR __builtin_amdgcn_s_barrier()
; #define PG8_SCHED __builtin_amdgcn_sched_barrier(0)
; template <class Epi, class Sched, bool ALIGN_EPI = false, bool SP2 = false>
; __device__ __forceinline__ void gemm_phase(PG8_LAS unsigned char* lds, const Gemm g, const Sched& S, const Epi& E, const int tid_in) {
;     ...
;             const bool last = (t == nt - 2);
;             const char* a1 = cA + (size_t)(t + 1) * kstepA;
;             const char* a2 = last ? nA : cA + (size_t)(t + 2) * kstepA; const char* b2 = last ? nB : cB + (size_t)(t + 2) * kstep;
;             const char* a3 = a2 + kstepA; const char* b3 = b2 + kstep;
;             if (last && has_next) S.a_ready(nxt, ui + 1);
;             if constexpr (SP2) {
;             PG8_LDB(B0, 0, 0); PG8_LDB(B1, 0, 1); PG8_SCHED; PG8_LDA(At, 0, 0); PG8_STAGE(PG8_SA(1, 1), a1 + hstepA, voffA);
;             PG8_WAIT_V(8); PG8_WAIT_L(0); PG8_BAR; PG8_MMA(0, 0, At, B0); PG8_MMA(0, 1, At, B1); PG8_BAR; PG8_SCHED;
;             PG8_LDA(At, 0, 1); PG8_STAGE(PG8_SB(0, 0), b2, voffB); PG8_STAGE(PG8_SB(0, 1), b2 + hstep, voffB); PG8_STAGE(PG8_SA(0, 0), a2, voffA);
.LBB0_1316:
	s_add_u32 s6, s36, 0xfff00080
	s_addc_u32 s7, s37, -1
	s_add_i32 s77, 0, 0x10000
	s_cmp_eq_u32 s53, 60
	s_cselect_b32 s61, s12, s7
	s_cselect_b32 s60, s14, s6
	s_cselect_b32 s59, s15, s52
	s_cselect_b32 s58, s45, s47
	s_add_i32 s6, 0, 0x14000
	v_add_u32_e32 v140, s77, v186
	v_add_u32_e32 v156, s6, v186
	ds_read_b128 v[128:131], v140
	ds_read_b128 v[132:135], v140 offset:1024
	ds_read_b128 v[136:139], v140 offset:2048
	ds_read_b128 v[140:143], v140 offset:3072
	ds_read_b128 v[144:147], v156
	ds_read_b128 v[148:151], v156 offset:1024
	ds_read_b128 v[152:155], v156 offset:2048
	ds_read_b128 v[156:159], v156 offset:3072
	v_lshl_add_u64 v[192:193], s[36:37], 0, v[194:195]
	s_add_i32 m0, s62, 0xc000
	ds_read_b128 v[160:163], v187
	ds_read_b128 v[164:167], v187 offset:1024
	ds_read_b128 v[168:171], v187 offset:2048
	ds_read_b128 v[172:175], v187 offset:3072
	ds_read_b128 v[188:191], v187 offset:4096
	ds_read_b128 v[198:201], v187 offset:5120
	ds_read_b128 v[202:205], v187 offset:6144
	ds_read_b128 v[206:209], v187 offset:7168
	global_load_lds_dwordx4 v[192:193], off
	v_lshl_add_u64 v[192:193], s[36:37], 0, v[196:197]
	s_add_i32 m0, s62, 0xe000
	s_nop 0
	global_load_lds_dwordx4 v[192:193], off
	s_waitcnt vmcnt(8)
	s_waitcnt lgkmcnt(0)
	s_barrier
	s_setprio 1
	s_waitcnt lgkmcnt(0)
	v_mfma_f32_16x16x32_bf16 v[124:127], v[128:131], v[160:163], v[124:127]
	v_mfma_f32_16x16x32_bf16 v[120:123], v[136:139], v[160:163], v[120:123]
	v_mfma_f32_16x16x32_bf16 v[108:111], v[128:131], v[168:171], v[108:111]
	v_mfma_f32_16x16x32_bf16 v[104:107], v[136:139], v[168:171], v[104:107]
	v_mfma_f32_16x16x32_bf16 v[92:95], v[128:131], v[188:191], v[92:95]
	v_mfma_f32_16x16x32_bf16 v[88:91], v[136:139], v[188:191], v[88:91]
	v_mfma_f32_16x16x32_bf16 v[76:79], v[128:131], v[202:205], v[76:79]
	v_mfma_f32_16x16x32_bf16 v[72:75], v[136:139], v[202:205], v[72:75]
	v_mfma_f32_16x16x32_bf16 v[124:127], v[132:135], v[164:167], v[124:127]
	v_mfma_f32_16x16x32_bf16 v[120:123], v[140:143], v[164:167], v[120:123]
	v_mfma_f32_16x16x32_bf16 v[108:111], v[132:135], v[172:175], v[108:111]
	v_mfma_f32_16x16x32_bf16 v[104:107], v[140:143], v[172:175], v[104:107]
	v_mfma_f32_16x16x32_bf16 v[92:95], v[132:135], v[198:201], v[92:95]
	v_mfma_f32_16x16x32_bf16 v[88:91], v[140:143], v[198:201], v[88:91]
	v_mfma_f32_16x16x32_bf16 v[76:79], v[132:135], v[206:209], v[76:79]
	v_mfma_f32_16x16x32_bf16 v[72:75], v[140:143], v[206:209], v[72:75]
	s_setprio 0
	s_setprio 1
	v_mfma_f32_16x16x32_bf16 v[116:119], v[144:147], v[160:163], v[116:119]
	v_mfma_f32_16x16x32_bf16 v[112:115], v[152:155], v[160:163], v[112:115]
	v_mfma_f32_16x16x32_bf16 v[100:103], v[144:147], v[168:171], v[100:103]
	v_mfma_f32_16x16x32_bf16 v[96:99], v[152:155], v[168:171], v[96:99]
	v_mfma_f32_16x16x32_bf16 v[84:87], v[144:147], v[188:191], v[84:87]
	v_mfma_f32_16x16x32_bf16 v[80:83], v[152:155], v[188:191], v[80:83]
	v_mfma_f32_16x16x32_bf16 v[68:71], v[144:147], v[202:205], v[68:71]
	v_mfma_f32_16x16x32_bf16 v[64:67], v[152:155], v[202:205], v[64:67]
	v_mfma_f32_16x16x32_bf16 v[116:119], v[148:151], v[164:167], v[116:119]
	v_mfma_f32_16x16x32_bf16 v[112:115], v[156:159], v[164:167], v[112:115]
	v_mfma_f32_16x16x32_bf16 v[100:103], v[148:151], v[172:175], v[100:103]
	v_mfma_f32_16x16x32_bf16 v[96:99], v[156:159], v[172:175], v[96:99]
	v_mfma_f32_16x16x32_bf16 v[84:87], v[148:151], v[198:201], v[84:87]
	v_mfma_f32_16x16x32_bf16 v[80:83], v[156:159], v[198:201], v[80:83]
	v_mfma_f32_16x16x32_bf16 v[68:71], v[148:151], v[206:209], v[68:71]
	v_mfma_f32_16x16x32_bf16 v[64:67], v[156:159], v[206:209], v[64:67]
	s_setprio 2
	s_barrier
	s_add_i32 s7, s77, s54
	v_lshl_add_u64 v[192:193], s[58:59], 0, v[180:181]
	s_mov_b32 m0, s7
	ds_read_b128 v[160:163], v187 offset:16384
	ds_read_b128 v[164:167], v187 offset:17408
	ds_read_b128 v[168:171], v187 offset:18432
	ds_read_b128 v[172:175], v187 offset:19456
	ds_read_b128 v[188:191], v187 offset:20480
	ds_read_b128 v[198:201], v187 offset:21504
	ds_read_b128 v[202:205], v187 offset:22528
	ds_read_b128 v[206:209], v187 offset:23552
	global_load_lds_dwordx4 v[192:193], off
	s_add_i32 m0, s7, 0x2000
	s_add_u32 s78, s58, 0x100000
	v_lshl_add_u64 v[210:211], s[58:59], 0, v[176:177]
	s_addc_u32 s79, s59, 0
	s_add_i32 s6, s6, s54
	global_load_lds_dwordx4 v[210:211], off
	v_lshl_add_u64 v[212:213], s[78:79], 0, v[180:181]
	s_mov_b32 m0, s6
	v_lshl_add_u64 v[214:215], s[60:61], 0, v[178:179]
	global_load_lds_dwordx4 v[212:213], off
	v_lshl_add_u64 v[212:213], s[78:79], 0, v[176:177]
	s_add_i32 m0, s6, 0x2000
	s_nop 0
	global_load_lds_dwordx4 v[212:213], off
	v_lshl_add_u64 v[212:213], s[60:61], 0, v[182:183]
	s_mov_b32 m0, s62
	s_nop 0
	global_load_lds_dwordx4 v[212:213], off
	s_mov_b32 m0, s63
	s_nop 0
	global_load_lds_dwordx4 v[214:215], off
	s_waitcnt vmcnt(8)
	s_waitcnt lgkmcnt(0)
	s_barrier
; #define PG8_STAGE(bufoff, gbase, voff) do { _Pragma("unroll") for (int _i = 0; _i < 2; ++_i) \
;         __builtin_amdgcn_global_load_lds((const unsigned*)((const char*)(gbase) + (voff)[_i]), (PG8_LAS unsigned*)(lds + (bufoff) + ldsw + _i * 8192), 16, 0, 0); } while (0)
; #define PG8_LDA(dst, b, h) do { _Pragma("unroll") for (int m = 0; m < 4; ++m) _Pragma("unroll") for (int k = 0; k < 2; ++k) dst[m][k] = *(const PG8_LAS bf16x8*)(lds + PG8_SA(b, h) + aoff + m * 2048 + k * 1024); } while (0)
; #define PG8_LDB(dst, b, h) do { _Pragma("unroll") for (int n = 0; n < 2; ++n) _Pragma("unroll") for (int k = 0; k < 2; ++k) dst[n][k] = *(const PG8_LAS bf16x8*)(lds + PG8_SB(b, h) + boff + n * 2048 + k * 1024); } while (0)
; #define PG8_MMA(ai, bj, At, Bt) do { __builtin_amdgcn_s_setprio(1); _Pragma("unroll") for (int m = 0; m < 4; ++m) _Pragma("unroll") for (int n = 0; n < 2; ++n) _Pragma("unroll") for (int k = 0; k < 2; ++k) \
;         acc[ai][bj][m][n] = __builtin_amdgcn_mfma_f32_16x16x32_bf16(Bt[n][k], At[m][k], acc[ai][bj][m][n], 0, 0, 0); __builtin_amdgcn_s_setprio(0); } while (0)
; #define PG8_WAIT_V(n) asm volatile("s_waitcnt vmcnt(" #n ")" ::: "memory")
; #define PG8_WAIT_L(n) asm volatile("s_waitcnt lgkmcnt(" #n ")" ::: "memory")
; #define PG8_BAR __builtin_amdgcn_s_barrier()
; #define PG8_SCHED __builtin_amdgcn_sched_barrier(0)
; template <class Epi, class Sched, bool ALIGN_EPI = false, bool SP2 = false>
; __device__ __forceinline__ void gemm_phase(PG8_LAS unsigned char* lds, const Gemm g, const Sched& S, const Epi& E, const int tid_in) {
;     ...
;             PG8_WAIT_V(8); PG8_WAIT_L(0); PG8_BAR; PG8_MMA(1, 0, At, B0); PG8_MMA(1, 1, At, B1); PG8_BAR; PG8_SCHED;
;             PG8_LDB(B0, 1, 0); PG8_LDB(B1, 1, 1); PG8_SCHED; PG8_LDA(At, 1, 0); PG8_STAGE(PG8_SA(0, 1), a2 + hstepA, voffA);
;             PG8_WAIT_V(8); PG8_WAIT_L(0); PG8_BAR; PG8_MMA(0, 0, At, B0); PG8_MMA(0, 1, At, B1); PG8_BAR; PG8_SCHED;
	s_setprio 1
	s_waitcnt lgkmcnt(0)
	v_mfma_f32_16x16x32_bf16 v[60:63], v[128:131], v[160:163], v[60:63]
	v_mfma_f32_16x16x32_bf16 v[56:59], v[136:139], v[160:163], v[56:59]
	v_mfma_f32_16x16x32_bf16 v[44:47], v[128:131], v[168:171], v[44:47]
	v_mfma_f32_16x16x32_bf16 v[40:43], v[136:139], v[168:171], v[40:43]
	v_mfma_f32_16x16x32_bf16 v[28:31], v[128:131], v[188:191], v[28:31]
	v_mfma_f32_16x16x32_bf16 v[24:27], v[136:139], v[188:191], v[24:27]
	v_mfma_f32_16x16x32_bf16 v[12:15], v[128:131], v[202:205], v[12:15]
	v_mfma_f32_16x16x32_bf16 v[8:11], v[136:139], v[202:205], v[8:11]
	v_mfma_f32_16x16x32_bf16 v[60:63], v[132:135], v[164:167], v[60:63]
	v_mfma_f32_16x16x32_bf16 v[56:59], v[140:143], v[164:167], v[56:59]
	v_mfma_f32_16x16x32_bf16 v[44:47], v[132:135], v[172:175], v[44:47]
	v_mfma_f32_16x16x32_bf16 v[40:43], v[140:143], v[172:175], v[40:43]
	v_mfma_f32_16x16x32_bf16 v[28:31], v[132:135], v[198:201], v[28:31]
	v_mfma_f32_16x16x32_bf16 v[24:27], v[140:143], v[198:201], v[24:27]
	v_mfma_f32_16x16x32_bf16 v[12:15], v[132:135], v[206:209], v[12:15]
	v_mfma_f32_16x16x32_bf16 v[8:11], v[140:143], v[206:209], v[8:11]
	s_setprio 0
	s_setprio 1
	v_mfma_f32_16x16x32_bf16 v[52:55], v[144:147], v[160:163], v[52:55]
	v_mfma_f32_16x16x32_bf16 v[48:51], v[152:155], v[160:163], v[48:51]
	v_mfma_f32_16x16x32_bf16 v[36:39], v[144:147], v[168:171], v[36:39]
	v_mfma_f32_16x16x32_bf16 v[32:35], v[152:155], v[168:171], v[32:35]
	v_mfma_f32_16x16x32_bf16 v[20:23], v[144:147], v[188:191], v[20:23]
	v_mfma_f32_16x16x32_bf16 v[16:19], v[152:155], v[188:191], v[16:19]
	v_mfma_f32_16x16x32_bf16 v[4:7], v[144:147], v[202:205], v[4:7]
	v_mfma_f32_16x16x32_bf16 v[0:3], v[152:155], v[202:205], v[0:3]
	v_mfma_f32_16x16x32_bf16 v[52:55], v[148:151], v[164:167], v[52:55]
	v_mfma_f32_16x16x32_bf16 v[48:51], v[156:159], v[164:167], v[48:51]
	v_mfma_f32_16x16x32_bf16 v[36:39], v[148:151], v[172:175], v[36:39]
	v_mfma_f32_16x16x32_bf16 v[32:35], v[156:159], v[172:175], v[32:35]
	v_mfma_f32_16x16x32_bf16 v[20:23], v[148:151], v[198:201], v[20:23]
	v_mfma_f32_16x16x32_bf16 v[16:19], v[156:159], v[198:201], v[16:19]
	v_mfma_f32_16x16x32_bf16 v[4:7], v[148:151], v[206:209], v[4:7]
	v_mfma_f32_16x16x32_bf16 v[0:3], v[156:159], v[206:209], v[0:3]
	s_setprio 2
	s_barrier
	s_add_i32 s6, 0, 0x18000
	s_add_i32 s7, 0, 0x1c000
	v_add_u32_e32 v140, s6, v186
	v_add_u32_e32 v156, s7, v186
	ds_read_b128 v[128:131], v140
	ds_read_b128 v[132:135], v140 offset:1024
	ds_read_b128 v[136:139], v140 offset:2048
	ds_read_b128 v[140:143], v140 offset:3072
	ds_read_b128 v[144:147], v156
	ds_read_b128 v[148:151], v156 offset:1024
	ds_read_b128 v[152:155], v156 offset:2048
	ds_read_b128 v[156:159], v156 offset:3072
	s_add_u32 s60, s60, 0x100000
	s_addc_u32 s61, s61, 0
	s_mov_b32 m0, s64
	v_lshl_add_u64 v[216:217], s[60:61], 0, v[182:183]
	ds_read_b128 v[160:163], v187 offset:32768
	ds_read_b128 v[164:167], v187 offset:33792
	ds_read_b128 v[168:171], v187 offset:34816
	ds_read_b128 v[172:175], v187 offset:35840
	ds_read_b128 v[188:191], v187 offset:36864
	ds_read_b128 v[198:201], v187 offset:37888
	ds_read_b128 v[202:205], v187 offset:38912
	ds_read_b128 v[206:209], v187 offset:39936
	global_load_lds_dwordx4 v[216:217], off
	v_lshl_add_u64 v[216:217], s[60:61], 0, v[178:179]
	s_mov_b32 m0, s65
	s_nop 0
	global_load_lds_dwordx4 v[216:217], off
	s_waitcnt vmcnt(8)
	s_waitcnt lgkmcnt(0)
	s_barrier
	s_setprio 1
	s_waitcnt lgkmcnt(0)
	v_mfma_f32_16x16x32_bf16 v[124:127], v[128:131], v[160:163], v[124:127]
	v_mfma_f32_16x16x32_bf16 v[120:123], v[136:139], v[160:163], v[120:123]
	v_mfma_f32_16x16x32_bf16 v[108:111], v[128:131], v[168:171], v[108:111]
	v_mfma_f32_16x16x32_bf16 v[104:107], v[136:139], v[168:171], v[104:107]
	v_mfma_f32_16x16x32_bf16 v[92:95], v[128:131], v[188:191], v[92:95]
	v_mfma_f32_16x16x32_bf16 v[88:91], v[136:139], v[188:191], v[88:91]
	v_mfma_f32_16x16x32_bf16 v[76:79], v[128:131], v[202:205], v[76:79]
	v_mfma_f32_16x16x32_bf16 v[72:75], v[136:139], v[202:205], v[72:75]
	v_mfma_f32_16x16x32_bf16 v[124:127], v[132:135], v[164:167], v[124:127]
	v_mfma_f32_16x16x32_bf16 v[120:123], v[140:143], v[164:167], v[120:123]
	v_mfma_f32_16x16x32_bf16 v[108:111], v[132:135], v[172:175], v[108:111]
	v_mfma_f32_16x16x32_bf16 v[104:107], v[140:143], v[172:175], v[104:107]
	v_mfma_f32_16x16x32_bf16 v[92:95], v[132:135], v[198:201], v[92:95]
	v_mfma_f32_16x16x32_bf16 v[88:91], v[140:143], v[198:201], v[88:91]
	v_mfma_f32_16x16x32_bf16 v[76:79], v[132:135], v[206:209], v[76:79]
	v_mfma_f32_16x16x32_bf16 v[72:75], v[140:143], v[206:209], v[72:75]
	s_setprio 0
	s_setprio 1
	v_mfma_f32_16x16x32_bf16 v[116:119], v[144:147], v[160:163], v[116:119]
	v_mfma_f32_16x16x32_bf16 v[112:115], v[152:155], v[160:163], v[112:115]
	v_mfma_f32_16x16x32_bf16 v[100:103], v[144:147], v[168:171], v[100:103]
	v_mfma_f32_16x16x32_bf16 v[96:99], v[152:155], v[168:171], v[96:99]
	v_mfma_f32_16x16x32_bf16 v[84:87], v[144:147], v[188:191], v[84:87]
	v_mfma_f32_16x16x32_bf16 v[80:83], v[152:155], v[188:191], v[80:83]
	v_mfma_f32_16x16x32_bf16 v[68:71], v[144:147], v[202:205], v[68:71]
	v_mfma_f32_16x16x32_bf16 v[64:67], v[152:155], v[202:205], v[64:67]
	v_mfma_f32_16x16x32_bf16 v[116:119], v[148:151], v[164:167], v[116:119]
	v_mfma_f32_16x16x32_bf16 v[112:115], v[156:159], v[164:167], v[112:115]
	v_mfma_f32_16x16x32_bf16 v[100:103], v[148:151], v[172:175], v[100:103]
	v_mfma_f32_16x16x32_bf16 v[96:99], v[156:159], v[172:175], v[96:99]
	v_mfma_f32_16x16x32_bf16 v[84:87], v[148:151], v[198:201], v[84:87]
	v_mfma_f32_16x16x32_bf16 v[80:83], v[156:159], v[198:201], v[80:83]
	v_mfma_f32_16x16x32_bf16 v[68:71], v[148:151], v[206:209], v[68:71]
	v_mfma_f32_16x16x32_bf16 v[64:67], v[156:159], v[206:209], v[64:67]
	s_setprio 2
	s_barrier
; #define PG8_STAGE(bufoff, gbase, voff) do { _Pragma("unroll") for (int _i = 0; _i < 2; ++_i) \
;         __builtin_amdgcn_global_load_lds((const unsigned*)((const char*)(gbase) + (voff)[_i]), (PG8_LAS unsigned*)(lds + (bufoff) + ldsw + _i * 8192), 16, 0, 0); } while (0)
; #define PG8_LDA(dst, b, h) do { _Pragma("unroll") for (int m = 0; m < 4; ++m) _Pragma("unroll") for (int k = 0; k < 2; ++k) dst[m][k] = *(const PG8_LAS bf16x8*)(lds + PG8_SA(b, h) + aoff + m * 2048 + k * 1024); } while (0)
; #define PG8_MMA(ai, bj, At, Bt) do { __builtin_amdgcn_s_setprio(1); _Pragma("unroll") for (int m = 0; m < 4; ++m) _Pragma("unroll") for (int n = 0; n < 2; ++n) _Pragma("unroll") for (int k = 0; k < 2; ++k) \
;         acc[ai][bj][m][n] = __builtin_amdgcn_mfma_f32_16x16x32_bf16(Bt[n][k], At[m][k], acc[ai][bj][m][n], 0, 0, 0); __builtin_amdgcn_s_setprio(0); } while (0)
; #define PG8_WAIT_V(n) asm volatile("s_waitcnt vmcnt(" #n ")" ::: "memory")
; #define PG8_WAIT_L(n) asm volatile("s_waitcnt lgkmcnt(" #n ")" ::: "memory")
; #define PG8_BAR __builtin_amdgcn_s_barrier()
; #define PG8_SCHED __builtin_amdgcn_sched_barrier(0)
; template <class Epi, class Sched, bool ALIGN_EPI = false, bool SP2 = false>
; __device__ __forceinline__ void gemm_phase(PG8_LAS unsigned char* lds, const Gemm g, const Sched& S, const Epi& E, const int tid_in) {
;     ...
;         for (int t = 0; t < nt; t += 2) {
;     ...
;             PG8_LDA(At, 1, 1); PG8_STAGE(PG8_SB(1, 0), b3, voffB); PG8_STAGE(PG8_SB(1, 1), b3 + hstep, voffB); PG8_STAGE(PG8_SA(1, 0), a3, voffA);
;             PG8_WAIT_V(8); PG8_WAIT_L(0); PG8_BAR; PG8_MMA(1, 0, At, B0); PG8_MMA(1, 1, At, B1); PG8_BAR; PG8_SCHED;
	s_add_i32 s6, s6, s54
	v_lshl_add_u64 v[192:193], v[192:193], 0, s[84:85]
	s_mov_b32 m0, s6
	ds_read_b128 v[160:163], v187 offset:49152
	ds_read_b128 v[164:167], v187 offset:50176
	ds_read_b128 v[168:171], v187 offset:51200
	ds_read_b128 v[172:175], v187 offset:52224
	ds_read_b128 v[188:191], v187 offset:53248
	ds_read_b128 v[198:201], v187 offset:54272
	ds_read_b128 v[202:205], v187 offset:55296
	ds_read_b128 v[206:209], v187 offset:56320
	global_load_lds_dwordx4 v[192:193], off
	s_add_i32 m0, s6, 0x2000
	s_add_u32 s58, s58, 0x100080
	v_lshl_add_u64 v[192:193], v[210:211], 0, s[84:85]
	s_addc_u32 s59, s59, 0
	s_add_i32 s6, s7, s54
	global_load_lds_dwordx4 v[192:193], off
	v_lshl_add_u64 v[192:193], s[58:59], 0, v[180:181]
	s_mov_b32 m0, s6
	s_nop 0
	global_load_lds_dwordx4 v[192:193], off
	v_lshl_add_u64 v[192:193], s[58:59], 0, v[176:177]
	s_add_i32 m0, s6, 0x2000
	s_nop 0
	global_load_lds_dwordx4 v[192:193], off
	v_lshl_add_u64 v[192:193], v[212:213], 0, s[84:85]
	s_mov_b32 m0, s68
	s_nop 0
	global_load_lds_dwordx4 v[192:193], off
	v_lshl_add_u64 v[192:193], v[214:215], 0, s[84:85]
	s_mov_b32 m0, s69
	s_nop 0
	global_load_lds_dwordx4 v[192:193], off
	s_waitcnt vmcnt(8)
	s_waitcnt lgkmcnt(0)
	s_barrier
	s_setprio 1
	s_waitcnt lgkmcnt(0)
	v_mfma_f32_16x16x32_bf16 v[60:63], v[128:131], v[160:163], v[60:63]
	v_mfma_f32_16x16x32_bf16 v[56:59], v[136:139], v[160:163], v[56:59]
	v_mfma_f32_16x16x32_bf16 v[44:47], v[128:131], v[168:171], v[44:47]
	v_mfma_f32_16x16x32_bf16 v[40:43], v[136:139], v[168:171], v[40:43]
	v_mfma_f32_16x16x32_bf16 v[28:31], v[128:131], v[188:191], v[28:31]
	v_mfma_f32_16x16x32_bf16 v[24:27], v[136:139], v[188:191], v[24:27]
	v_mfma_f32_16x16x32_bf16 v[12:15], v[128:131], v[202:205], v[12:15]
	v_mfma_f32_16x16x32_bf16 v[8:11], v[136:139], v[202:205], v[8:11]
	v_mfma_f32_16x16x32_bf16 v[60:63], v[132:135], v[164:167], v[60:63]
	v_mfma_f32_16x16x32_bf16 v[56:59], v[140:143], v[164:167], v[56:59]
	v_mfma_f32_16x16x32_bf16 v[44:47], v[132:135], v[172:175], v[44:47]
	v_mfma_f32_16x16x32_bf16 v[40:43], v[140:143], v[172:175], v[40:43]
	v_mfma_f32_16x16x32_bf16 v[28:31], v[132:135], v[198:201], v[28:31]
	v_mfma_f32_16x16x32_bf16 v[24:27], v[140:143], v[198:201], v[24:27]
	v_mfma_f32_16x16x32_bf16 v[12:15], v[132:135], v[206:209], v[12:15]
	v_mfma_f32_16x16x32_bf16 v[8:11], v[140:143], v[206:209], v[8:11]
	s_setprio 0
	s_setprio 1
	v_mfma_f32_16x16x32_bf16 v[52:55], v[144:147], v[160:163], v[52:55]
	v_mfma_f32_16x16x32_bf16 v[48:51], v[152:155], v[160:163], v[48:51]
	v_mfma_f32_16x16x32_bf16 v[36:39], v[144:147], v[168:171], v[36:39]
	v_mfma_f32_16x16x32_bf16 v[32:35], v[152:155], v[168:171], v[32:35]
	v_mfma_f32_16x16x32_bf16 v[20:23], v[144:147], v[188:191], v[20:23]
	v_mfma_f32_16x16x32_bf16 v[16:19], v[152:155], v[188:191], v[16:19]
	v_mfma_f32_16x16x32_bf16 v[4:7], v[144:147], v[202:205], v[4:7]
	v_mfma_f32_16x16x32_bf16 v[0:3], v[152:155], v[202:205], v[0:3]
	v_mfma_f32_16x16x32_bf16 v[52:55], v[148:151], v[164:167], v[52:55]
	v_mfma_f32_16x16x32_bf16 v[48:51], v[156:159], v[164:167], v[48:51]
	v_mfma_f32_16x16x32_bf16 v[36:39], v[148:151], v[172:175], v[36:39]
	v_mfma_f32_16x16x32_bf16 v[32:35], v[156:159], v[172:175], v[32:35]
	v_mfma_f32_16x16x32_bf16 v[20:23], v[148:151], v[198:201], v[20:23]
	v_mfma_f32_16x16x32_bf16 v[16:19], v[156:159], v[198:201], v[16:19]
	v_mfma_f32_16x16x32_bf16 v[4:7], v[148:151], v[206:209], v[4:7]
	v_mfma_f32_16x16x32_bf16 v[0:3], v[156:159], v[206:209], v[0:3]
	s_setprio 2
	s_barrier
	s_add_i32 s53, s53, 2
	s_add_u32 s36, s36, 0x100
	s_addc_u32 s37, s37, 0
	s_add_u32 s47, s47, 0x100
	s_addc_u32 s52, s52, 0
	s_cmp_gt_u32 s53, 61
	s_cbranch_scc0 .LBB0_1316
	s_and_b64 vcc, exec, s[40:41]
	s_cbranch_vccz .LBB0_1319
	s_barrier
